# s_nop pads so that every 16/32-MFMA segment starts 8-byte aligned (code placement), on top of pipelined scans
# speedup vs baseline: 1.0060x; 1.0060x over previous
.Lm4ap_31:
	s_waitcnt lgkmcnt(0)
	s_barrier
	s_nop 0
	v_mfma_f32_16x16x32_bf16 v[124:127], v[128:131], v[162:165], 0
	v_mfma_f32_16x16x32_bf16 v[120:123], v[136:139], v[162:165], 0
	v_mfma_f32_16x16x32_bf16 v[108:111], v[128:131], v[170:173], 0
	v_mfma_f32_16x16x32_bf16 v[104:107], v[136:139], v[170:173], 0
	v_mfma_f32_16x16x32_bf16 v[96:99], v[128:131], v[178:181], 0
	v_mfma_f32_16x16x32_bf16 v[88:91], v[136:139], v[178:181], 0
	v_mfma_f32_16x16x32_bf16 v[84:87], v[128:131], v[194:197], 0
	v_mfma_f32_16x16x32_bf16 v[80:83], v[136:139], v[194:197], 0
	v_mfma_f32_16x16x32_bf16 v[124:127], v[132:135], v[166:169], v[124:127]
	v_mfma_f32_16x16x32_bf16 v[120:123], v[146:149], v[166:169], v[120:123]
	v_mfma_f32_16x16x32_bf16 v[108:111], v[132:135], v[174:177], v[108:111]
	v_mfma_f32_16x16x32_bf16 v[104:107], v[146:149], v[174:177], v[104:107]
	v_mfma_f32_16x16x32_bf16 v[96:99], v[132:135], v[182:185], v[96:99]
	v_mfma_f32_16x16x32_bf16 v[88:91], v[146:149], v[182:185], v[88:91]
	v_mfma_f32_16x16x32_bf16 v[84:87], v[132:135], v[210:213], v[84:87]
	v_mfma_f32_16x16x32_bf16 v[80:83], v[146:149], v[210:213], v[80:83]
	v_mfma_f32_16x16x32_bf16 v[116:119], v[214:217], v[162:165], 0
	v_mfma_f32_16x16x32_bf16 v[112:115], v[222:225], v[162:165], 0
	v_mfma_f32_16x16x32_bf16 v[100:103], v[214:217], v[170:173], 0
	v_mfma_f32_16x16x32_bf16 v[92:95], v[222:225], v[170:173], 0
	v_mfma_f32_16x16x32_bf16 v[76:79], v[214:217], v[178:181], 0
	v_mfma_f32_16x16x32_bf16 v[72:75], v[222:225], v[178:181], 0
	v_mfma_f32_16x16x32_bf16 v[68:71], v[214:217], v[194:197], 0
	v_mfma_f32_16x16x32_bf16 v[64:67], v[222:225], v[194:197], 0
	v_mfma_f32_16x16x32_bf16 v[116:119], v[218:221], v[166:169], v[116:119]
	v_mfma_f32_16x16x32_bf16 v[112:115], v[226:229], v[166:169], v[112:115]
	v_mfma_f32_16x16x32_bf16 v[100:103], v[218:221], v[174:177], v[100:103]
	v_mfma_f32_16x16x32_bf16 v[92:95], v[226:229], v[174:177], v[92:95]
	v_mfma_f32_16x16x32_bf16 v[76:79], v[218:221], v[182:185], v[76:79]
	v_mfma_f32_16x16x32_bf16 v[72:75], v[226:229], v[182:185], v[72:75]
	v_mfma_f32_16x16x32_bf16 v[68:71], v[218:221], v[210:213], v[68:71]
	v_mfma_f32_16x16x32_bf16 v[64:67], v[226:229], v[210:213], v[64:67]
	s_barrier
	s_add_i32 s6, s6, s57
	v_lshl_add_u64 v[230:231], s[48:49], 0, v[140:141]
	s_mov_b32 m0, s6
	s_nop 0
	global_load_lds_dwordx4 v[230:231], off
	v_lshl_add_u64 v[232:233], s[48:49], 0, v[150:151]
	s_add_i32 m0, s6, 0x2000
	s_nop 0
	global_load_lds_dwordx4 v[232:233], off
	s_mov_b32 m0, s58
	v_lshl_add_u64 v[234:235], s[52:53], 0, v[154:155]
	ds_read_b128 v[162:165], v208 offset:16384
	ds_read_b128 v[166:169], v208 offset:17408
	ds_read_b128 v[170:173], v208 offset:18432
	ds_read_b128 v[174:177], v208 offset:19456
	ds_read_b128 v[178:181], v208 offset:20480
	ds_read_b128 v[182:185], v208 offset:21504
	ds_read_b128 v[194:197], v208 offset:22528
	ds_read_b128 v[210:213], v208 offset:23552
	global_load_lds_dwordx4 v[234:235], off
	v_lshl_add_u64 v[236:237], s[52:53], 0, v[152:153]
	s_mov_b32 m0, s59
	s_nop 0
	global_load_lds_dwordx4 v[236:237], off
	s_add_u32 s50, s48, 0xb0000
	s_addc_u32 s51, s49, 0
	s_add_i32 s6, s19, s57
	v_lshl_add_u64 v[250:251], s[50:51], 0, v[140:141]
	s_mov_b32 m0, s6
	s_nop 0
	global_load_lds_dwordx4 v[250:251], off
	v_lshl_add_u64 v[250:251], s[50:51], 0, v[150:151]
	s_add_i32 m0, s6, 0x2000
	s_nop 0
	global_load_lds_dwordx4 v[250:251], off
	s_waitcnt vmcnt(40)
	s_cmp_lg_u32 s100, 0
	s_cbranch_scc1 .Lm4bp_31
	s_waitcnt vmcnt(8)

.LBB0_31:
	s_add_u32 s46, s50, 0x100
	s_addc_u32 s47, s51, 0
	s_add_i32 s6, 0, 0x10000
	v_add_u32_e32 v146, s6, v206
	ds_read_b128 v[128:131], v146
	ds_read_b128 v[132:135], v146 offset:1024
	ds_read_b128 v[136:139], v146 offset:2048
	ds_read_b128 v[146:149], v146 offset:3072
	s_cmp_eq_u32 s12, 40
	s_cselect_b32 s53, s31, s47
	s_cselect_b32 s52, s30, s46
	s_cselect_b32 s49, s35, s11
	s_cselect_b32 s48, s34, s10
	v_lshl_add_u64 v[214:215], s[50:51], 0, v[158:159]
	s_add_i32 m0, s58, 0xc000
	ds_read_b128 v[162:165], v208
	ds_read_b128 v[166:169], v208 offset:1024
	ds_read_b128 v[170:173], v208 offset:2048
	ds_read_b128 v[174:177], v208 offset:3072
	ds_read_b128 v[178:181], v208 offset:4096
	ds_read_b128 v[182:185], v208 offset:5120
	ds_read_b128 v[194:197], v208 offset:6144
	ds_read_b128 v[210:213], v208 offset:7168
	global_load_lds_dwordx4 v[214:215], off
	v_lshl_add_u64 v[214:215], s[50:51], 0, v[160:161]
	s_add_i32 m0, s58, 0xe000
	s_nop 0
	global_load_lds_dwordx4 v[214:215], off
	s_add_i32 s19, 0, 0x14000
	v_add_u32_e32 v192, s19, v206
	ds_read_b128 v[214:217], v192
	ds_read_b128 v[218:221], v192 offset:1024
	ds_read_b128 v[222:225], v192 offset:2048
	ds_read_b128 v[226:229], v192 offset:3072
	s_nop 0
	s_waitcnt vmcnt(8)
	s_waitcnt lgkmcnt(0)
	s_barrier
	v_mfma_f32_16x16x32_bf16 v[124:127], v[128:131], v[162:165], v[124:127]
	v_mfma_f32_16x16x32_bf16 v[120:123], v[136:139], v[162:165], v[120:123]
	v_mfma_f32_16x16x32_bf16 v[108:111], v[128:131], v[170:173], v[108:111]
	v_mfma_f32_16x16x32_bf16 v[104:107], v[136:139], v[170:173], v[104:107]
	v_mfma_f32_16x16x32_bf16 v[96:99], v[128:131], v[178:181], v[96:99]
	v_mfma_f32_16x16x32_bf16 v[88:91], v[136:139], v[178:181], v[88:91]
	v_mfma_f32_16x16x32_bf16 v[84:87], v[128:131], v[194:197], v[84:87]
	v_mfma_f32_16x16x32_bf16 v[80:83], v[136:139], v[194:197], v[80:83]
	v_mfma_f32_16x16x32_bf16 v[124:127], v[132:135], v[166:169], v[124:127]
	v_mfma_f32_16x16x32_bf16 v[120:123], v[146:149], v[166:169], v[120:123]
	v_mfma_f32_16x16x32_bf16 v[108:111], v[132:135], v[174:177], v[108:111]
	v_mfma_f32_16x16x32_bf16 v[104:107], v[146:149], v[174:177], v[104:107]
	v_mfma_f32_16x16x32_bf16 v[96:99], v[132:135], v[182:185], v[96:99]
	v_mfma_f32_16x16x32_bf16 v[88:91], v[146:149], v[182:185], v[88:91]
	v_mfma_f32_16x16x32_bf16 v[84:87], v[132:135], v[210:213], v[84:87]
	v_mfma_f32_16x16x32_bf16 v[80:83], v[146:149], v[210:213], v[80:83]
	v_mfma_f32_16x16x32_bf16 v[116:119], v[214:217], v[162:165], v[116:119]
	v_mfma_f32_16x16x32_bf16 v[112:115], v[222:225], v[162:165], v[112:115]
	v_mfma_f32_16x16x32_bf16 v[100:103], v[214:217], v[170:173], v[100:103]
	v_mfma_f32_16x16x32_bf16 v[92:95], v[222:225], v[170:173], v[92:95]
	v_mfma_f32_16x16x32_bf16 v[76:79], v[214:217], v[178:181], v[76:79]
	v_mfma_f32_16x16x32_bf16 v[72:75], v[222:225], v[178:181], v[72:75]
	v_mfma_f32_16x16x32_bf16 v[68:71], v[214:217], v[194:197], v[68:71]
	v_mfma_f32_16x16x32_bf16 v[64:67], v[222:225], v[194:197], v[64:67]
	v_mfma_f32_16x16x32_bf16 v[116:119], v[218:221], v[166:169], v[116:119]
	v_mfma_f32_16x16x32_bf16 v[112:115], v[226:229], v[166:169], v[112:115]
	v_mfma_f32_16x16x32_bf16 v[100:103], v[218:221], v[174:177], v[100:103]
	v_mfma_f32_16x16x32_bf16 v[92:95], v[226:229], v[174:177], v[92:95]
	v_mfma_f32_16x16x32_bf16 v[76:79], v[218:221], v[182:185], v[76:79]
	v_mfma_f32_16x16x32_bf16 v[72:75], v[226:229], v[182:185], v[72:75]
	v_mfma_f32_16x16x32_bf16 v[68:71], v[218:221], v[210:213], v[68:71]
	v_mfma_f32_16x16x32_bf16 v[64:67], v[226:229], v[210:213], v[64:67]
	s_barrier
	s_add_i32 s6, s6, s57
	v_lshl_add_u64 v[230:231], s[48:49], 0, v[140:141]
	s_mov_b32 m0, s6
	s_nop 0
	global_load_lds_dwordx4 v[230:231], off
	v_lshl_add_u64 v[232:233], s[48:49], 0, v[150:151]
	s_add_i32 m0, s6, 0x2000
	s_nop 0
	global_load_lds_dwordx4 v[232:233], off
	s_mov_b32 m0, s58
	v_lshl_add_u64 v[234:235], s[52:53], 0, v[154:155]
	ds_read_b128 v[162:165], v208 offset:16384
	ds_read_b128 v[166:169], v208 offset:17408
	ds_read_b128 v[170:173], v208 offset:18432
	ds_read_b128 v[174:177], v208 offset:19456
	ds_read_b128 v[178:181], v208 offset:20480
	ds_read_b128 v[182:185], v208 offset:21504
	ds_read_b128 v[194:197], v208 offset:22528
	ds_read_b128 v[210:213], v208 offset:23552
	global_load_lds_dwordx4 v[234:235], off
	v_lshl_add_u64 v[236:237], s[52:53], 0, v[152:153]
	s_mov_b32 m0, s59
	s_nop 0
	global_load_lds_dwordx4 v[236:237], off
	s_add_u32 s50, s48, 0xb0000
	s_addc_u32 s51, s49, 0
	s_add_i32 s6, s19, s57
	v_lshl_add_u64 v[250:251], s[50:51], 0, v[140:141]
	s_mov_b32 m0, s6
	s_nop 0
	global_load_lds_dwordx4 v[250:251], off
	v_lshl_add_u64 v[250:251], s[50:51], 0, v[150:151]
	s_add_i32 m0, s6, 0x2000
	s_nop 0
	global_load_lds_dwordx4 v[250:251], off
	s_waitcnt vmcnt(8)
	s_waitcnt lgkmcnt(0)
	s_barrier
	v_mfma_f32_16x16x32_bf16 v[60:63], v[128:131], v[162:165], v[60:63]
	v_mfma_f32_16x16x32_bf16 v[56:59], v[136:139], v[162:165], v[56:59]
	v_mfma_f32_16x16x32_bf16 v[48:51], v[128:131], v[170:173], v[48:51]
	v_mfma_f32_16x16x32_bf16 v[40:43], v[136:139], v[170:173], v[40:43]
	v_mfma_f32_16x16x32_bf16 v[32:35], v[128:131], v[178:181], v[32:35]
	v_mfma_f32_16x16x32_bf16 v[24:27], v[136:139], v[178:181], v[24:27]
	v_mfma_f32_16x16x32_bf16 v[16:19], v[128:131], v[194:197], v[16:19]
	v_mfma_f32_16x16x32_bf16 v[8:11], v[136:139], v[194:197], v[8:11]
	v_mfma_f32_16x16x32_bf16 v[60:63], v[132:135], v[166:169], v[60:63]
	v_mfma_f32_16x16x32_bf16 v[56:59], v[146:149], v[166:169], v[56:59]
	v_mfma_f32_16x16x32_bf16 v[48:51], v[132:135], v[174:177], v[48:51]
	v_mfma_f32_16x16x32_bf16 v[40:43], v[146:149], v[174:177], v[40:43]
	v_mfma_f32_16x16x32_bf16 v[32:35], v[132:135], v[182:185], v[32:35]
	v_mfma_f32_16x16x32_bf16 v[24:27], v[146:149], v[182:185], v[24:27]
	v_mfma_f32_16x16x32_bf16 v[16:19], v[132:135], v[210:213], v[16:19]
	v_mfma_f32_16x16x32_bf16 v[8:11], v[146:149], v[210:213], v[8:11]
	v_mfma_f32_16x16x32_bf16 v[52:55], v[214:217], v[162:165], v[52:55]
	v_mfma_f32_16x16x32_bf16 v[44:47], v[222:225], v[162:165], v[44:47]
	v_mfma_f32_16x16x32_bf16 v[36:39], v[214:217], v[170:173], v[36:39]
	v_mfma_f32_16x16x32_bf16 v[28:31], v[222:225], v[170:173], v[28:31]
	v_mfma_f32_16x16x32_bf16 v[20:23], v[214:217], v[178:181], v[20:23]
	v_mfma_f32_16x16x32_bf16 v[12:15], v[222:225], v[178:181], v[12:15]
	v_mfma_f32_16x16x32_bf16 v[4:7], v[214:217], v[194:197], v[4:7]
	v_mfma_f32_16x16x32_bf16 v[0:3], v[222:225], v[194:197], v[0:3]
	v_mfma_f32_16x16x32_bf16 v[52:55], v[218:221], v[166:169], v[52:55]
	v_mfma_f32_16x16x32_bf16 v[44:47], v[226:229], v[166:169], v[44:47]
	v_mfma_f32_16x16x32_bf16 v[36:39], v[218:221], v[174:177], v[36:39]
	v_mfma_f32_16x16x32_bf16 v[28:31], v[226:229], v[174:177], v[28:31]
	v_mfma_f32_16x16x32_bf16 v[20:23], v[218:221], v[182:185], v[20:23]
	v_mfma_f32_16x16x32_bf16 v[12:15], v[226:229], v[182:185], v[12:15]
	v_mfma_f32_16x16x32_bf16 v[4:7], v[218:221], v[210:213], v[4:7]
	v_mfma_f32_16x16x32_bf16 v[0:3], v[226:229], v[210:213], v[0:3]
	s_barrier
	s_add_i32 s6, 0, 0x18000
	v_add_u32_e32 v146, s6, v206
	ds_read_b128 v[128:131], v146
	ds_read_b128 v[132:135], v146 offset:1024
	ds_read_b128 v[136:139], v146 offset:2048
	ds_read_b128 v[146:149], v146 offset:3072
	s_add_u32 s50, s52, 0xb0000
	s_addc_u32 s51, s53, 0
	s_mov_b32 m0, s68
	v_lshl_add_u64 v[214:215], s[50:51], 0, v[154:155]
	ds_read_b128 v[162:165], v208 offset:32768
	ds_read_b128 v[166:169], v208 offset:33792
	ds_read_b128 v[170:173], v208 offset:34816
	ds_read_b128 v[174:177], v208 offset:35840
	ds_read_b128 v[178:181], v208 offset:36864
	ds_read_b128 v[182:185], v208 offset:37888
	ds_read_b128 v[194:197], v208 offset:38912
	ds_read_b128 v[210:213], v208 offset:39936
	global_load_lds_dwordx4 v[214:215], off
	v_lshl_add_u64 v[214:215], s[50:51], 0, v[152:153]
	s_mov_b32 m0, s69
	s_nop 0
	global_load_lds_dwordx4 v[214:215], off
	s_add_i32 s19, 0, 0x1c000
	v_add_u32_e32 v192, s19, v206
	ds_read_b128 v[214:217], v192
	ds_read_b128 v[218:221], v192 offset:1024
	ds_read_b128 v[222:225], v192 offset:2048
	ds_read_b128 v[226:229], v192 offset:3072
	s_waitcnt vmcnt(8)
	s_waitcnt lgkmcnt(0)
	s_barrier
	v_mfma_f32_16x16x32_bf16 v[124:127], v[128:131], v[162:165], v[124:127]
	v_mfma_f32_16x16x32_bf16 v[120:123], v[136:139], v[162:165], v[120:123]
	v_mfma_f32_16x16x32_bf16 v[108:111], v[128:131], v[170:173], v[108:111]
	v_mfma_f32_16x16x32_bf16 v[104:107], v[136:139], v[170:173], v[104:107]
	v_mfma_f32_16x16x32_bf16 v[96:99], v[128:131], v[178:181], v[96:99]
	v_mfma_f32_16x16x32_bf16 v[88:91], v[136:139], v[178:181], v[88:91]
	v_mfma_f32_16x16x32_bf16 v[84:87], v[128:131], v[194:197], v[84:87]
	v_mfma_f32_16x16x32_bf16 v[80:83], v[136:139], v[194:197], v[80:83]
	v_mfma_f32_16x16x32_bf16 v[124:127], v[132:135], v[166:169], v[124:127]
	v_mfma_f32_16x16x32_bf16 v[120:123], v[146:149], v[166:169], v[120:123]
	v_mfma_f32_16x16x32_bf16 v[108:111], v[132:135], v[174:177], v[108:111]
	v_mfma_f32_16x16x32_bf16 v[104:107], v[146:149], v[174:177], v[104:107]
	v_mfma_f32_16x16x32_bf16 v[96:99], v[132:135], v[182:185], v[96:99]
	v_mfma_f32_16x16x32_bf16 v[88:91], v[146:149], v[182:185], v[88:91]
	v_mfma_f32_16x16x32_bf16 v[84:87], v[132:135], v[210:213], v[84:87]
	v_mfma_f32_16x16x32_bf16 v[80:83], v[146:149], v[210:213], v[80:83]
	v_mfma_f32_16x16x32_bf16 v[116:119], v[214:217], v[162:165], v[116:119]
	v_mfma_f32_16x16x32_bf16 v[112:115], v[222:225], v[162:165], v[112:115]
	v_mfma_f32_16x16x32_bf16 v[100:103], v[214:217], v[170:173], v[100:103]
	v_mfma_f32_16x16x32_bf16 v[92:95], v[222:225], v[170:173], v[92:95]
	v_mfma_f32_16x16x32_bf16 v[76:79], v[214:217], v[178:181], v[76:79]
	v_mfma_f32_16x16x32_bf16 v[72:75], v[222:225], v[178:181], v[72:75]
	v_mfma_f32_16x16x32_bf16 v[68:71], v[214:217], v[194:197], v[68:71]
	v_mfma_f32_16x16x32_bf16 v[64:67], v[222:225], v[194:197], v[64:67]
	v_mfma_f32_16x16x32_bf16 v[116:119], v[218:221], v[166:169], v[116:119]
	v_mfma_f32_16x16x32_bf16 v[112:115], v[226:229], v[166:169], v[112:115]
	v_mfma_f32_16x16x32_bf16 v[100:103], v[218:221], v[174:177], v[100:103]
	v_mfma_f32_16x16x32_bf16 v[92:95], v[226:229], v[174:177], v[92:95]
	v_mfma_f32_16x16x32_bf16 v[76:79], v[218:221], v[182:185], v[76:79]
	v_mfma_f32_16x16x32_bf16 v[72:75], v[226:229], v[182:185], v[72:75]
	v_mfma_f32_16x16x32_bf16 v[68:71], v[218:221], v[210:213], v[68:71]
	v_mfma_f32_16x16x32_bf16 v[64:67], v[226:229], v[210:213], v[64:67]
	s_barrier
	s_add_i32 s6, s6, s57
	v_lshl_add_u64 v[230:231], v[230:231], 0, s[36:37]
	s_mov_b32 m0, s6
	s_nop 0
	global_load_lds_dwordx4 v[230:231], off
	v_lshl_add_u64 v[230:231], v[232:233], 0, s[36:37]
	s_add_i32 m0, s6, 0x2000
	s_nop 0
	global_load_lds_dwordx4 v[230:231], off
	s_mov_b32 m0, s70
	v_lshl_add_u64 v[230:231], v[234:235], 0, s[36:37]
	ds_read_b128 v[162:165], v208 offset:49152
	ds_read_b128 v[166:169], v208 offset:50176
	ds_read_b128 v[170:173], v208 offset:51200
	ds_read_b128 v[174:177], v208 offset:52224
	ds_read_b128 v[178:181], v208 offset:53248
	ds_read_b128 v[182:185], v208 offset:54272
	ds_read_b128 v[194:197], v208 offset:55296
	ds_read_b128 v[210:213], v208 offset:56320
	global_load_lds_dwordx4 v[230:231], off
	v_lshl_add_u64 v[230:231], v[236:237], 0, s[36:37]
	s_mov_b32 m0, s71
	s_nop 0
	global_load_lds_dwordx4 v[230:231], off
	s_add_u32 s48, s48, 0xb0080
	s_addc_u32 s49, s49, 0
	s_add_i32 s6, s19, s57
	v_lshl_add_u64 v[250:251], s[48:49], 0, v[140:141]
	s_mov_b32 m0, s6
	s_nop 0
	global_load_lds_dwordx4 v[250:251], off
	v_lshl_add_u64 v[250:251], s[48:49], 0, v[150:151]
	s_add_i32 m0, s6, 0x2000
	s_nop 0
	global_load_lds_dwordx4 v[250:251], off
	s_waitcnt vmcnt(8)
	s_waitcnt lgkmcnt(0)
	s_barrier
	v_mfma_f32_16x16x32_bf16 v[60:63], v[128:131], v[162:165], v[60:63]
	v_mfma_f32_16x16x32_bf16 v[56:59], v[136:139], v[162:165], v[56:59]
	v_mfma_f32_16x16x32_bf16 v[48:51], v[128:131], v[170:173], v[48:51]
	v_mfma_f32_16x16x32_bf16 v[40:43], v[136:139], v[170:173], v[40:43]
	v_mfma_f32_16x16x32_bf16 v[32:35], v[128:131], v[178:181], v[32:35]
	v_mfma_f32_16x16x32_bf16 v[24:27], v[136:139], v[178:181], v[24:27]
	v_mfma_f32_16x16x32_bf16 v[16:19], v[128:131], v[194:197], v[16:19]
	v_mfma_f32_16x16x32_bf16 v[8:11], v[136:139], v[194:197], v[8:11]
	v_mfma_f32_16x16x32_bf16 v[60:63], v[132:135], v[166:169], v[60:63]
	v_mfma_f32_16x16x32_bf16 v[56:59], v[146:149], v[166:169], v[56:59]
	v_mfma_f32_16x16x32_bf16 v[48:51], v[132:135], v[174:177], v[48:51]
	v_mfma_f32_16x16x32_bf16 v[40:43], v[146:149], v[174:177], v[40:43]
	v_mfma_f32_16x16x32_bf16 v[32:35], v[132:135], v[182:185], v[32:35]
	v_mfma_f32_16x16x32_bf16 v[24:27], v[146:149], v[182:185], v[24:27]
	v_mfma_f32_16x16x32_bf16 v[16:19], v[132:135], v[210:213], v[16:19]
	v_mfma_f32_16x16x32_bf16 v[8:11], v[146:149], v[210:213], v[8:11]
	v_mfma_f32_16x16x32_bf16 v[52:55], v[214:217], v[162:165], v[52:55]
	v_mfma_f32_16x16x32_bf16 v[44:47], v[222:225], v[162:165], v[44:47]
	v_mfma_f32_16x16x32_bf16 v[36:39], v[214:217], v[170:173], v[36:39]
	v_mfma_f32_16x16x32_bf16 v[28:31], v[222:225], v[170:173], v[28:31]
	v_mfma_f32_16x16x32_bf16 v[20:23], v[214:217], v[178:181], v[20:23]
	v_mfma_f32_16x16x32_bf16 v[12:15], v[222:225], v[178:181], v[12:15]
	v_mfma_f32_16x16x32_bf16 v[4:7], v[214:217], v[194:197], v[4:7]
	v_mfma_f32_16x16x32_bf16 v[0:3], v[222:225], v[194:197], v[0:3]
	v_mfma_f32_16x16x32_bf16 v[52:55], v[218:221], v[166:169], v[52:55]
	v_mfma_f32_16x16x32_bf16 v[44:47], v[226:229], v[166:169], v[44:47]
	v_mfma_f32_16x16x32_bf16 v[36:39], v[218:221], v[174:177], v[36:39]
	v_mfma_f32_16x16x32_bf16 v[28:31], v[226:229], v[174:177], v[28:31]
	v_mfma_f32_16x16x32_bf16 v[20:23], v[218:221], v[182:185], v[20:23]
	v_mfma_f32_16x16x32_bf16 v[12:15], v[226:229], v[182:185], v[12:15]
	v_mfma_f32_16x16x32_bf16 v[4:7], v[218:221], v[210:213], v[4:7]
	v_mfma_f32_16x16x32_bf16 v[0:3], v[226:229], v[210:213], v[0:3]
	s_add_i32 s12, s12, 2
	s_add_u32 s10, s10, 0x100
	s_addc_u32 s11, s11, 0
	s_cmp_gt_u32 s12, 41
	s_mov_b64 s[50:51], s[46:47]
	s_barrier
	s_cbranch_scc0 .LBB0_31
	s_mov_b32 s100, 1
	s_ashr_i32 s39, s38, 31
	v_lshl_or_b32 v128, s81, 8, v207
	s_lshl_b64 s[10:11], s[38:39], 8
	v_ashrrev_i32_e32 v129, 31, v128
	v_lshl_add_u64 v[168:169], s[10:11], 0, v[156:157]
	v_lshlrev_b64 v[170:171], 1, v[128:129]
	v_lshl_add_u64 v[174:175], s[4:5], 0, v[170:171]
	v_lshlrev_b64 v[172:173], 11, v[168:169]
	v_lshl_add_u64 v[128:129], v[174:175], 0, v[172:173]
	global_load_dwordx4 v[146:149], v[128:129], off
	global_load_dwordx4 v[182:185], v[128:129], off offset:256
	v_or_b32_e32 v166, 16, v168
	v_mov_b32_e32 v167, v169
	v_lshlrev_b64 v[176:177], 11, v[166:167]
	v_lshl_add_u64 v[128:129], v[174:175], 0, v[176:177]
	global_load_dwordx4 v[194:197], v[128:129], off
	global_load_dwordx4 v[210:213], v[128:129], off offset:256
	v_or_b32_e32 v164, 32, v168
	v_mov_b32_e32 v165, v169
	v_or_b32_e32 v162, 48, v168
	v_mov_b32_e32 v163, v169
	v_lshlrev_b64 v[180:181], 11, v[164:165]
	v_lshlrev_b64 v[178:179], 11, v[162:163]
	v_lshl_add_u64 v[128:129], v[174:175], 0, v[180:181]
	v_lshl_add_u64 v[130:131], v[174:175], 0, v[178:179]
	global_load_dwordx4 v[214:217], v[128:129], off
	global_load_dwordx4 v[136:139], v[128:129], off offset:256
	global_load_dwordx4 v[132:135], v[130:131], off
	s_nop 0
	global_load_dwordx4 v[128:131], v[130:131], off offset:256
	s_mov_b64 s[10:11], 0x90
	v_lshl_add_u64 v[172:173], s[28:29], 0, v[172:173]
	v_lshl_add_u64 v[172:173], v[172:173], 0, v[170:171]
	s_waitcnt vmcnt(0)
	v_lshlrev_b32_e32 v218, 16, v146
	v_and_b32_e32 v219, 0xffff0000, v146
	v_lshlrev_b32_e32 v220, 16, v148
	v_and_b32_e32 v221, 0xffff0000, v148
	v_lshlrev_b32_e32 v146, 16, v147
	v_and_b32_e32 v147, 0xffff0000, v147
	v_lshlrev_b32_e32 v222, 16, v182
	v_and_b32_e32 v223, 0xffff0000, v182
	v_lshlrev_b32_e32 v224, 16, v184
	v_and_b32_e32 v225, 0xffff0000, v184
	v_lshlrev_b32_e32 v182, 16, v183
	v_and_b32_e32 v183, 0xffff0000, v183
	v_pk_fma_f32 v[124:125], v[124:125], 0.5, v[218:219] op_sel_hi:[1,0,1]
	v_pk_fma_f32 v[120:121], v[120:121], 0.5, v[220:221] op_sel_hi:[1,0,1]
	v_pk_fma_f32 v[126:127], v[126:127], 0.5, v[146:147] op_sel_hi:[1,0,1]
	v_pk_fma_f32 v[116:117], v[116:117], 0.5, v[222:223] op_sel_hi:[1,0,1]
	v_pk_fma_f32 v[146:147], v[112:113], 0.5, v[224:225] op_sel_hi:[1,0,1]
	v_pk_fma_f32 v[118:119], v[118:119], 0.5, v[182:183] op_sel_hi:[1,0,1]
	v_pk_mul_f32 v[220:221], v[124:125], v[124:125]
	v_pk_mul_f32 v[222:223], v[126:127], v[126:127]
	v_cvt_pk_bf16_f32 v112, v124, v125
	v_cvt_pk_bf16_f32 v113, v126, v127
	v_pk_mul_f32 v[124:125], v[116:117], v[116:117]
	v_pk_mul_f32 v[126:127], v[118:119], v[118:119]
	v_pk_mul_f32 v[228:229], v[146:147], v[146:147]
	v_cvt_pk_bf16_f32 v116, v116, v117
	v_cvt_pk_bf16_f32 v117, v118, v119
	v_cvt_pk_bf16_f32 v118, v146, v147
	v_add_f32_e32 v146, v220, v221
	v_add_f32_e32 v146, v222, v146
	v_lshlrev_b32_e32 v148, 16, v149
	v_and_b32_e32 v149, 0xffff0000, v149
	v_pk_mul_f32 v[224:225], v[120:121], v[120:121]
	v_add_f32_e32 v146, v223, v146
	v_pk_fma_f32 v[122:123], v[122:123], 0.5, v[148:149] op_sel_hi:[1,0,1]
	v_add_f32_e32 v146, v224, v146
	v_pk_mul_f32 v[226:227], v[122:123], v[122:123]
	v_add_f32_e32 v146, v225, v146
	v_add_f32_e32 v146, v226, v146
	v_add_f32_e32 v146, v227, v146
	v_add_f32_e32 v124, v124, v146
	v_add_f32_e32 v124, v125, v124
	v_add_f32_e32 v124, v126, v124
	v_lshlrev_b32_e32 v184, 16, v185
	v_and_b32_e32 v185, 0xffff0000, v185
	v_add_f32_e32 v124, v127, v124
	v_pk_fma_f32 v[148:149], v[114:115], 0.5, v[184:185] op_sel_hi:[1,0,1]
	v_add_f32_e32 v124, v228, v124
	v_pk_mul_f32 v[230:231], v[148:149], v[148:149]
	v_add_f32_e32 v124, v229, v124
	v_add_f32_e32 v124, v230, v124
	v_add_f32_e32 v209, v231, v124
	v_lshlrev_b32_e32 v124, 16, v212
	v_and_b32_e32 v125, 0xffff0000, v212
	v_pk_fma_f32 v[124:125], v[92:93], 0.5, v[124:125] op_sel_hi:[1,0,1]
	v_lshlrev_b32_e32 v92, 16, v211
	v_and_b32_e32 v93, 0xffff0000, v211
	v_pk_fma_f32 v[102:103], v[102:103], 0.5, v[92:93] op_sel_hi:[1,0,1]
	v_lshlrev_b32_e32 v92, 16, v213
	v_and_b32_e32 v93, 0xffff0000, v213
	v_pk_fma_f32 v[126:127], v[94:95], 0.5, v[92:93] op_sel_hi:[1,0,1]
	v_lshlrev_b32_e32 v92, 16, v214
	v_and_b32_e32 v93, 0xffff0000, v214
	v_pk_fma_f32 v[92:93], v[96:97], 0.5, v[92:93] op_sel_hi:[1,0,1]
	v_lshlrev_b32_e32 v96, 16, v217
	v_and_b32_e32 v97, 0xffff0000, v217
	v_lshlrev_b32_e32 v94, 16, v216
	v_and_b32_e32 v95, 0xffff0000, v216
	v_pk_fma_f32 v[90:91], v[90:91], 0.5, v[96:97] op_sel_hi:[1,0,1]
	v_lshlrev_b32_e32 v96, 16, v136
	v_and_b32_e32 v97, 0xffff0000, v136
	v_lshlrev_b32_e32 v182, 16, v194
	v_and_b32_e32 v183, 0xffff0000, v194
	v_pk_fma_f32 v[88:89], v[88:89], 0.5, v[94:95] op_sel_hi:[1,0,1]
	v_lshlrev_b32_e32 v94, 16, v215
	v_and_b32_e32 v95, 0xffff0000, v215
	v_pk_fma_f32 v[96:97], v[76:77], 0.5, v[96:97] op_sel_hi:[1,0,1]
	v_lshl_add_u64 v[76:77], v[168:169], 0, s[36:37]
	v_lshlrev_b32_e32 v184, 16, v196
	v_and_b32_e32 v185, 0xffff0000, v196
	v_cvt_pk_bf16_f32 v114, v120, v121
	v_pk_fma_f32 v[120:121], v[108:109], 0.5, v[182:183] op_sel_hi:[1,0,1]
	v_pk_fma_f32 v[94:95], v[98:99], 0.5, v[94:95] op_sel_hi:[1,0,1]
	v_lshlrev_b64 v[182:183], 11, v[76:77]
	v_lshlrev_b32_e32 v98, 16, v138
	v_and_b32_e32 v99, 0xffff0000, v138
	v_pk_fma_f32 v[108:109], v[104:105], 0.5, v[184:185] op_sel_hi:[1,0,1]
	v_lshl_add_u64 v[184:185], v[174:175], 0, v[182:183]
	v_pk_fma_f32 v[98:99], v[72:73], 0.5, v[98:99] op_sel_hi:[1,0,1]
	v_lshlrev_b32_e32 v72, 16, v137
	v_and_b32_e32 v73, 0xffff0000, v137
	v_lshlrev_b32_e32 v218, 16, v210
	v_and_b32_e32 v219, 0xffff0000, v210
	global_load_dwordx4 v[210:213], v[184:185], off
	v_pk_fma_f32 v[136:137], v[78:79], 0.5, v[72:73] op_sel_hi:[1,0,1]
	v_lshlrev_b32_e32 v72, 16, v139
	v_and_b32_e32 v73, 0xffff0000, v139
	v_pk_fma_f32 v[138:139], v[74:75], 0.5, v[72:73] op_sel_hi:[1,0,1]
	v_lshlrev_b32_e32 v72, 16, v132
	v_and_b32_e32 v73, 0xffff0000, v132
	v_pk_fma_f32 v[74:75], v[84:85], 0.5, v[72:73] op_sel_hi:[1,0,1]
	v_lshlrev_b32_e32 v72, 16, v134
	v_and_b32_e32 v73, 0xffff0000, v134
	v_pk_fma_f32 v[78:79], v[80:81], 0.5, v[72:73] op_sel_hi:[1,0,1]
	v_lshlrev_b32_e32 v72, 16, v133
	v_and_b32_e32 v73, 0xffff0000, v133
	v_pk_fma_f32 v[100:101], v[100:101], 0.5, v[218:219] op_sel_hi:[1,0,1]
	global_load_dwordx4 v[218:221], v[184:185], off offset:256
	v_pk_fma_f32 v[80:81], v[86:87], 0.5, v[72:73] op_sel_hi:[1,0,1]
	v_lshlrev_b32_e32 v72, 16, v135
	v_and_b32_e32 v73, 0xffff0000, v135
	v_pk_fma_f32 v[82:83], v[82:83], 0.5, v[72:73] op_sel_hi:[1,0,1]
	v_lshl_add_u64 v[72:73], v[168:169], 0, s[10:11]
	v_lshlrev_b64 v[132:133], 11, v[72:73]
	v_lshl_add_u64 v[134:135], v[174:175], 0, v[132:133]
	v_lshlrev_b32_e32 v84, 16, v128
	v_and_b32_e32 v85, 0xffff0000, v128
	global_load_dwordx4 v[226:229], v[134:135], off
	global_load_dwordx4 v[234:237], v[134:135], off offset:256
	v_pk_fma_f32 v[84:85], v[68:69], 0.5, v[84:85] op_sel_hi:[1,0,1]
	v_lshlrev_b32_e32 v68, 16, v130
	v_and_b32_e32 v69, 0xffff0000, v130
	v_pk_fma_f32 v[86:87], v[64:65], 0.5, v[68:69] op_sel_hi:[1,0,1]
	v_lshlrev_b32_e32 v64, 16, v129
	v_and_b32_e32 v65, 0xffff0000, v129
	s_mov_b64 s[10:11], 0xa0
	v_pk_fma_f32 v[128:129], v[70:71], 0.5, v[64:65] op_sel_hi:[1,0,1]
	v_lshl_add_u64 v[70:71], v[168:169], 0, s[10:11]
	s_mov_b64 s[10:11], 0xb0
	v_lshlrev_b32_e32 v64, 16, v131
	v_and_b32_e32 v65, 0xffff0000, v131
	v_lshlrev_b64 v[134:135], 11, v[70:71]
	v_lshl_add_u64 v[68:69], v[168:169], 0, s[10:11]
	v_pk_fma_f32 v[130:131], v[66:67], 0.5, v[64:65] op_sel_hi:[1,0,1]
	v_lshl_add_u64 v[64:65], v[174:175], 0, v[134:135]
	v_lshlrev_b64 v[184:185], 11, v[68:69]
	global_load_dwordx4 v[238:241], v[64:65], off
	global_load_dwordx4 v[242:245], v[64:65], off offset:256
	v_lshl_add_u64 v[64:65], v[174:175], 0, v[184:185]
	global_load_dwordx4 v[246:249], v[64:65], off
	s_nop 0
	global_load_dwordx4 v[64:67], v[64:65], off offset:256
	v_lshlrev_b32_e32 v194, 16, v195
	v_and_b32_e32 v195, 0xffff0000, v195
	v_lshlrev_b32_e32 v196, 16, v197
	v_and_b32_e32 v197, 0xffff0000, v197
	v_cvt_pk_bf16_f32 v115, v122, v123
	v_cvt_pk_bf16_f32 v119, v148, v149
	v_pk_fma_f32 v[122:123], v[110:111], 0.5, v[194:195] op_sel_hi:[1,0,1]
	v_pk_fma_f32 v[110:111], v[106:107], 0.5, v[196:197] op_sel_hi:[1,0,1]
	global_store_dwordx4 v[172:173], v[112:115], off
	global_store_dwordx4 v[172:173], v[116:119], off offset:256
	v_cvt_pk_bf16_f32 v104, v120, v121
	v_lshl_add_u64 v[112:113], s[28:29], 0, v[176:177]
	v_cvt_pk_bf16_f32 v105, v122, v123
	v_cvt_pk_bf16_f32 v106, v108, v109
	v_cvt_pk_bf16_f32 v107, v110, v111
	v_lshl_add_u64 v[112:113], v[112:113], 0, v[170:171]
	v_cvt_pk_bf16_f32 v146, v100, v101
	v_cvt_pk_bf16_f32 v147, v102, v103
	v_cvt_pk_bf16_f32 v148, v124, v125
	v_cvt_pk_bf16_f32 v149, v126, v127
	global_store_dwordx4 v[112:113], v[104:107], off
	global_store_dwordx4 v[112:113], v[146:149], off offset:256
	v_cvt_pk_bf16_f32 v194, v92, v93
	v_lshl_add_u64 v[104:105], s[28:29], 0, v[180:181]
	v_cvt_pk_bf16_f32 v195, v94, v95
	v_cvt_pk_bf16_f32 v196, v88, v89
	v_cvt_pk_bf16_f32 v197, v90, v91
	v_lshl_add_u64 v[104:105], v[104:105], 0, v[170:171]
	v_cvt_pk_bf16_f32 v214, v96, v97
	v_cvt_pk_bf16_f32 v215, v136, v137
	v_cvt_pk_bf16_f32 v216, v98, v99
	v_cvt_pk_bf16_f32 v217, v138, v139
	global_store_dwordx4 v[104:105], v[194:197], off
	global_store_dwordx4 v[104:105], v[214:217], off offset:256
	v_lshl_add_u64 v[104:105], s[28:29], 0, v[178:179]
	v_cvt_pk_bf16_f32 v222, v74, v75
	v_cvt_pk_bf16_f32 v223, v80, v81
	v_cvt_pk_bf16_f32 v224, v78, v79
	v_cvt_pk_bf16_f32 v225, v82, v83
	v_lshl_add_u64 v[104:105], v[104:105], 0, v[170:171]
	v_cvt_pk_bf16_f32 v230, v84, v85
	v_cvt_pk_bf16_f32 v231, v128, v129
	v_cvt_pk_bf16_f32 v232, v86, v87
	v_cvt_pk_bf16_f32 v233, v130, v131
	global_store_dwordx4 v[104:105], v[222:225], off
	global_store_dwordx4 v[104:105], v[230:233], off offset:256
	s_waitcnt vmcnt(0)
	v_lshlrev_b32_e32 v104, 16, v210
	v_and_b32_e32 v105, 0xffff0000, v210
	v_pk_fma_f32 v[60:61], v[60:61], 0.5, v[104:105] op_sel_hi:[1,0,1]
	v_lshlrev_b32_e32 v104, 16, v212
	v_and_b32_e32 v105, 0xffff0000, v212
	v_pk_fma_f32 v[56:57], v[56:57], 0.5, v[104:105] op_sel_hi:[1,0,1]
	v_lshlrev_b32_e32 v104, 16, v211
	v_and_b32_e32 v105, 0xffff0000, v211
	v_pk_fma_f32 v[62:63], v[62:63], 0.5, v[104:105] op_sel_hi:[1,0,1]
	v_lshlrev_b32_e32 v104, 16, v213
	v_and_b32_e32 v105, 0xffff0000, v213
	v_pk_fma_f32 v[58:59], v[58:59], 0.5, v[104:105] op_sel_hi:[1,0,1]
	v_lshlrev_b32_e32 v104, 16, v218
	v_and_b32_e32 v105, 0xffff0000, v218
	v_pk_fma_f32 v[52:53], v[52:53], 0.5, v[104:105] op_sel_hi:[1,0,1]
	v_lshlrev_b32_e32 v104, 16, v220
	v_and_b32_e32 v105, 0xffff0000, v220
	v_pk_fma_f32 v[104:105], v[44:45], 0.5, v[104:105] op_sel_hi:[1,0,1]
	v_lshlrev_b32_e32 v44, 16, v219
	v_and_b32_e32 v45, 0xffff0000, v219
	v_pk_fma_f32 v[54:55], v[54:55], 0.5, v[44:45] op_sel_hi:[1,0,1]
	v_lshlrev_b32_e32 v44, 16, v221
	v_and_b32_e32 v45, 0xffff0000, v221
	v_pk_fma_f32 v[106:107], v[46:47], 0.5, v[44:45] op_sel_hi:[1,0,1]
	v_lshlrev_b32_e32 v44, 16, v226
	v_and_b32_e32 v45, 0xffff0000, v226
	v_pk_fma_f32 v[44:45], v[48:49], 0.5, v[44:45] op_sel_hi:[1,0,1]
	v_lshlrev_b32_e32 v48, 16, v229
	v_and_b32_e32 v49, 0xffff0000, v229
	v_pk_fma_f32 v[42:43], v[42:43], 0.5, v[48:49] op_sel_hi:[1,0,1]
	v_lshlrev_b32_e32 v48, 16, v234
	v_and_b32_e32 v49, 0xffff0000, v234
	v_pk_fma_f32 v[36:37], v[36:37], 0.5, v[48:49] op_sel_hi:[1,0,1]
	v_lshlrev_b32_e32 v48, 16, v236
	v_and_b32_e32 v49, 0xffff0000, v236
	v_lshlrev_b32_e32 v46, 16, v228
	v_and_b32_e32 v47, 0xffff0000, v228
	v_pk_fma_f32 v[48:49], v[28:29], 0.5, v[48:49] op_sel_hi:[1,0,1]
	v_lshlrev_b32_e32 v28, 16, v235
	v_and_b32_e32 v29, 0xffff0000, v235
	v_pk_fma_f32 v[40:41], v[40:41], 0.5, v[46:47] op_sel_hi:[1,0,1]
	v_lshlrev_b32_e32 v46, 16, v227
	v_and_b32_e32 v47, 0xffff0000, v227
	v_pk_fma_f32 v[38:39], v[38:39], 0.5, v[28:29] op_sel_hi:[1,0,1]
	v_lshlrev_b32_e32 v28, 16, v237
	v_and_b32_e32 v29, 0xffff0000, v237
	v_pk_fma_f32 v[46:47], v[50:51], 0.5, v[46:47] op_sel_hi:[1,0,1]
	v_pk_fma_f32 v[50:51], v[30:31], 0.5, v[28:29] op_sel_hi:[1,0,1]
	v_lshlrev_b32_e32 v28, 16, v238
	v_and_b32_e32 v29, 0xffff0000, v238
	v_lshlrev_b32_e32 v180, 16, v64
	v_and_b32_e32 v181, 0xffff0000, v64
	v_pk_fma_f32 v[28:29], v[32:33], 0.5, v[28:29] op_sel_hi:[1,0,1]
	v_lshlrev_b32_e32 v32, 16, v241
	v_and_b32_e32 v33, 0xffff0000, v241
	v_pk_fma_f32 v[4:5], v[4:5], 0.5, v[180:181] op_sel_hi:[1,0,1]
	v_lshlrev_b32_e32 v180, 16, v66
	v_and_b32_e32 v181, 0xffff0000, v66
	v_pk_fma_f32 v[26:27], v[26:27], 0.5, v[32:33] op_sel_hi:[1,0,1]
	v_lshlrev_b32_e32 v32, 16, v242
	v_and_b32_e32 v33, 0xffff0000, v242
	v_pk_fma_f32 v[0:1], v[0:1], 0.5, v[180:181] op_sel_hi:[1,0,1]
	v_lshl_add_u64 v[180:181], s[28:29], 0, v[182:183]
	v_cvt_pk_bf16_f32 v112, v60, v61
	v_cvt_pk_bf16_f32 v113, v62, v63
	v_cvt_pk_bf16_f32 v114, v56, v57
	v_cvt_pk_bf16_f32 v115, v58, v59
	v_pk_fma_f32 v[20:21], v[20:21], 0.5, v[32:33] op_sel_hi:[1,0,1]
	v_lshlrev_b32_e32 v32, 16, v244
	v_and_b32_e32 v33, 0xffff0000, v244
	v_lshl_add_u64 v[180:181], v[180:181], 0, v[170:171]
	v_cvt_pk_bf16_f32 v116, v52, v53
	v_cvt_pk_bf16_f32 v117, v54, v55
	v_cvt_pk_bf16_f32 v118, v104, v105
	v_cvt_pk_bf16_f32 v119, v106, v107
	v_lshlrev_b32_e32 v30, 16, v240
	v_and_b32_e32 v31, 0xffff0000, v240
	v_pk_fma_f32 v[32:33], v[12:13], 0.5, v[32:33] op_sel_hi:[1,0,1]
	v_lshlrev_b32_e32 v12, 16, v243
	v_and_b32_e32 v13, 0xffff0000, v243
	global_store_dwordx4 v[180:181], v[112:115], off
	global_store_dwordx4 v[180:181], v[116:119], off offset:256
	v_cvt_pk_bf16_f32 v146, v44, v45
	v_lshl_add_u64 v[112:113], s[28:29], 0, v[132:133]
	v_cvt_pk_bf16_f32 v147, v46, v47
	v_cvt_pk_bf16_f32 v148, v40, v41
	v_cvt_pk_bf16_f32 v149, v42, v43
	v_pk_fma_f32 v[24:25], v[24:25], 0.5, v[30:31] op_sel_hi:[1,0,1]
	v_lshlrev_b32_e32 v30, 16, v239
	v_and_b32_e32 v31, 0xffff0000, v239
	v_pk_fma_f32 v[22:23], v[22:23], 0.5, v[12:13] op_sel_hi:[1,0,1]
	v_lshlrev_b32_e32 v12, 16, v245
	v_and_b32_e32 v13, 0xffff0000, v245
	v_lshl_add_u64 v[112:113], v[112:113], 0, v[170:171]
	v_cvt_pk_bf16_f32 v172, v36, v37
	v_cvt_pk_bf16_f32 v173, v38, v39
	v_cvt_pk_bf16_f32 v174, v48, v49
	v_cvt_pk_bf16_f32 v175, v50, v51
	v_pk_fma_f32 v[30:31], v[34:35], 0.5, v[30:31] op_sel_hi:[1,0,1]
	v_pk_fma_f32 v[34:35], v[14:15], 0.5, v[12:13] op_sel_hi:[1,0,1]
	v_lshlrev_b32_e32 v12, 16, v246
	v_and_b32_e32 v13, 0xffff0000, v246
	v_lshlrev_b32_e32 v14, 16, v248
	v_and_b32_e32 v15, 0xffff0000, v248
	global_store_dwordx4 v[112:113], v[146:149], off
	global_store_dwordx4 v[112:113], v[172:175], off offset:256
	v_lshl_add_u64 v[112:113], s[28:29], 0, v[134:135]
	v_cvt_pk_bf16_f32 v176, v28, v29
	v_cvt_pk_bf16_f32 v177, v30, v31
	v_cvt_pk_bf16_f32 v178, v24, v25
	v_cvt_pk_bf16_f32 v179, v26, v27
	v_pk_fma_f32 v[12:13], v[16:17], 0.5, v[12:13] op_sel_hi:[1,0,1]
	v_pk_fma_f32 v[8:9], v[8:9], 0.5, v[14:15] op_sel_hi:[1,0,1]
	v_lshlrev_b32_e32 v14, 16, v247
	v_and_b32_e32 v15, 0xffff0000, v247
	v_lshlrev_b32_e32 v16, 16, v249
	v_and_b32_e32 v17, 0xffff0000, v249
	v_lshlrev_b32_e32 v64, 16, v65
	v_and_b32_e32 v65, 0xffff0000, v65
	v_lshl_add_u64 v[112:113], v[112:113], 0, v[170:171]
	v_cvt_pk_bf16_f32 v194, v20, v21
	v_cvt_pk_bf16_f32 v195, v22, v23
	v_cvt_pk_bf16_f32 v196, v32, v33
	v_cvt_pk_bf16_f32 v197, v34, v35
	v_pk_fma_f32 v[14:15], v[18:19], 0.5, v[14:15] op_sel_hi:[1,0,1]
	v_pk_fma_f32 v[10:11], v[10:11], 0.5, v[16:17] op_sel_hi:[1,0,1]
	v_pk_fma_f32 v[6:7], v[6:7], 0.5, v[64:65] op_sel_hi:[1,0,1]
	v_lshlrev_b32_e32 v64, 16, v67
	v_and_b32_e32 v65, 0xffff0000, v67
	global_store_dwordx4 v[112:113], v[176:179], off
	global_store_dwordx4 v[112:113], v[194:197], off offset:256
	v_lshl_add_u64 v[112:113], s[28:29], 0, v[184:185]
	v_cvt_pk_bf16_f32 v16, v12, v13
	v_cvt_pk_bf16_f32 v17, v14, v15
	v_cvt_pk_bf16_f32 v18, v8, v9
	v_cvt_pk_bf16_f32 v19, v10, v11
	v_pk_fma_f32 v[2:3], v[2:3], 0.5, v[64:65] op_sel_hi:[1,0,1]
	v_lshl_add_u64 v[112:113], v[112:113], 0, v[170:171]
	v_cvt_pk_bf16_f32 v64, v4, v5
	v_cvt_pk_bf16_f32 v65, v6, v7
	v_cvt_pk_bf16_f32 v66, v0, v1
	v_cvt_pk_bf16_f32 v67, v2, v3
	global_store_dwordx4 v[112:113], v[16:19], off
	global_store_dwordx4 v[112:113], v[64:67], off offset:256
	s_lshl_b32 s10, s81, 2
	v_and_b32_e32 v17, 64, v188
	v_xor_b32_e32 v16, 16, v188
	v_add_u32_e32 v17, 64, v17
	v_cmp_lt_i32_e32 vcc, v16, v17
	v_xor_b32_e32 v18, 32, v188
	s_ashr_i32 s11, s10, 31
	v_cndmask_b32_e32 v16, v188, v16, vcc
	v_lshlrev_b32_e32 v16, 2, v16
	ds_bpermute_b32 v19, v16, v209
	v_cmp_lt_i32_e32 vcc, v18, v17
	s_lshl_b64 s[10:11], s[10:11], 2
	s_add_u32 s38, s73, s10
	v_cndmask_b32_e32 v17, v188, v18, vcc
	v_lshlrev_b32_e32 v17, 2, v17
	s_waitcnt lgkmcnt(0)
	v_add_f32_e32 v18, v209, v19
	ds_bpermute_b32 v19, v17, v18
	s_addc_u32 s39, s74, s11
	s_and_saveexec_b64 s[46:47], s[42:43]
	s_cbranch_execz .LBB0_34
	s_waitcnt lgkmcnt(0)
	v_add_f32_e32 v64, v18, v19
	v_lshlrev_b64 v[18:19], 6, v[168:169]
	v_lshl_add_u64 v[18:19], s[38:39], 0, v[18:19]
	global_store_dword v[18:19], v64, off

.Lm4ap_77:
	s_waitcnt lgkmcnt(0)
	s_barrier
	s_nop 0
	v_mfma_f32_16x16x32_bf16 v[124:127], v[158:161], v[174:177], 0
	v_mfma_f32_16x16x32_bf16 v[120:123], v[166:169], v[174:177], 0
	v_mfma_f32_16x16x32_bf16 v[116:119], v[158:161], v[182:185], 0
	v_mfma_f32_16x16x32_bf16 v[112:115], v[166:169], v[182:185], 0
	v_mfma_f32_16x16x32_bf16 v[108:111], v[158:161], v[210:213], 0
	v_mfma_f32_16x16x32_bf16 v[104:107], v[166:169], v[210:213], 0
	v_mfma_f32_16x16x32_bf16 v[100:103], v[158:161], v[218:221], 0
	v_mfma_f32_16x16x32_bf16 v[96:99], v[166:169], v[218:221], 0
	v_mfma_f32_16x16x32_bf16 v[124:127], v[162:165], v[178:181], v[124:127]
	v_mfma_f32_16x16x32_bf16 v[120:123], v[170:173], v[178:181], v[120:123]
	v_mfma_f32_16x16x32_bf16 v[116:119], v[162:165], v[206:209], v[116:119]
	v_mfma_f32_16x16x32_bf16 v[112:115], v[170:173], v[206:209], v[112:115]
	v_mfma_f32_16x16x32_bf16 v[108:111], v[162:165], v[214:217], v[108:111]
	v_mfma_f32_16x16x32_bf16 v[104:107], v[170:173], v[214:217], v[104:107]
	v_mfma_f32_16x16x32_bf16 v[100:103], v[162:165], v[222:225], v[100:103]
	v_mfma_f32_16x16x32_bf16 v[96:99], v[170:173], v[222:225], v[96:99]
	v_mfma_f32_16x16x32_bf16 v[92:95], v[226:229], v[174:177], 0
	v_mfma_f32_16x16x32_bf16 v[88:91], v[234:237], v[174:177], 0
	v_mfma_f32_16x16x32_bf16 v[84:87], v[226:229], v[182:185], 0
	v_mfma_f32_16x16x32_bf16 v[80:83], v[234:237], v[182:185], 0
	v_mfma_f32_16x16x32_bf16 v[76:79], v[226:229], v[210:213], 0
	v_mfma_f32_16x16x32_bf16 v[72:75], v[234:237], v[210:213], 0
	v_mfma_f32_16x16x32_bf16 v[68:71], v[226:229], v[218:221], 0
	v_mfma_f32_16x16x32_bf16 v[64:67], v[234:237], v[218:221], 0
	v_mfma_f32_16x16x32_bf16 v[92:95], v[230:233], v[178:181], v[92:95]
	v_mfma_f32_16x16x32_bf16 v[88:91], v[238:241], v[178:181], v[88:91]
	v_mfma_f32_16x16x32_bf16 v[84:87], v[230:233], v[206:209], v[84:87]
	v_mfma_f32_16x16x32_bf16 v[80:83], v[238:241], v[206:209], v[80:83]
	v_mfma_f32_16x16x32_bf16 v[76:79], v[230:233], v[214:217], v[76:79]
	v_mfma_f32_16x16x32_bf16 v[72:75], v[238:241], v[214:217], v[72:75]
	v_mfma_f32_16x16x32_bf16 v[68:71], v[230:233], v[222:225], v[68:71]
	v_mfma_f32_16x16x32_bf16 v[64:67], v[238:241], v[222:225], v[64:67]
	s_barrier
	s_add_i32 s19, s82, s59
	v_lshl_add_u64 v[146:147], s[52:53], 0, v[140:141]
	s_mov_b32 m0, s19
	v_lshl_add_u64 v[148:149], s[52:53], 0, v[132:133]
	global_load_lds_dwordx4 v[146:147], off
	s_add_i32 m0, s19, 0x2000
	s_nop 0
	global_load_lds_dwordx4 v[148:149], off
	s_mov_b32 m0, s68
	v_lshl_add_u64 v[194:195], s[54:55], 0, v[128:129]
	ds_read_b128 v[174:177], v157 offset:16384
	ds_read_b128 v[178:181], v157 offset:17408
	ds_read_b128 v[182:185], v157 offset:18432
	ds_read_b128 v[206:209], v157 offset:19456
	ds_read_b128 v[210:213], v157 offset:20480
	ds_read_b128 v[214:217], v157 offset:21504
	ds_read_b128 v[218:221], v157 offset:22528
	ds_read_b128 v[222:225], v157 offset:23552
	global_load_lds_dwordx4 v[194:195], off
	v_lshl_add_u64 v[196:197], s[54:55], 0, v[130:131]
	s_mov_b32 m0, s69
	s_nop 0
	global_load_lds_dwordx4 v[196:197], off
	s_add_u32 s82, s52, 0x40000
	s_addc_u32 s83, s53, 0
	s_add_i32 s6, s6, s59
	v_lshl_add_u64 v[250:251], s[82:83], 0, v[140:141]
	s_mov_b32 m0, s6
	s_nop 0
	global_load_lds_dwordx4 v[250:251], off
	v_lshl_add_u64 v[250:251], s[82:83], 0, v[132:133]
	s_add_i32 m0, s6, 0x2000
	s_nop 0
	global_load_lds_dwordx4 v[250:251], off
	s_waitcnt vmcnt(16)
	s_cmp_lg_u32 s100, 0
	s_cbranch_scc1 .Lm4bp_77
	s_waitcnt vmcnt(8)
.Lm4bp_77:
	s_waitcnt lgkmcnt(0)
	s_mov_b32 s100, 0
	s_barrier
	s_nop 0
	v_mfma_f32_16x16x32_bf16 v[60:63], v[158:161], v[174:177], 0
	v_mfma_f32_16x16x32_bf16 v[56:59], v[166:169], v[174:177], 0
	v_mfma_f32_16x16x32_bf16 v[52:55], v[158:161], v[182:185], 0
	v_mfma_f32_16x16x32_bf16 v[48:51], v[166:169], v[182:185], 0
	v_mfma_f32_16x16x32_bf16 v[44:47], v[158:161], v[210:213], 0
	v_mfma_f32_16x16x32_bf16 v[40:43], v[166:169], v[210:213], 0
	v_mfma_f32_16x16x32_bf16 v[36:39], v[158:161], v[218:221], 0
	v_mfma_f32_16x16x32_bf16 v[32:35], v[166:169], v[218:221], 0
	v_mfma_f32_16x16x32_bf16 v[60:63], v[162:165], v[178:181], v[60:63]
	v_mfma_f32_16x16x32_bf16 v[56:59], v[170:173], v[178:181], v[56:59]
	v_mfma_f32_16x16x32_bf16 v[52:55], v[162:165], v[206:209], v[52:55]
	v_mfma_f32_16x16x32_bf16 v[48:51], v[170:173], v[206:209], v[48:51]
	v_mfma_f32_16x16x32_bf16 v[44:47], v[162:165], v[214:217], v[44:47]
	v_mfma_f32_16x16x32_bf16 v[40:43], v[170:173], v[214:217], v[40:43]
	v_mfma_f32_16x16x32_bf16 v[36:39], v[162:165], v[222:225], v[36:39]
	v_mfma_f32_16x16x32_bf16 v[32:35], v[170:173], v[222:225], v[32:35]
	v_mfma_f32_16x16x32_bf16 v[28:31], v[226:229], v[174:177], 0
	v_mfma_f32_16x16x32_bf16 v[24:27], v[234:237], v[174:177], 0
	v_mfma_f32_16x16x32_bf16 v[20:23], v[226:229], v[182:185], 0
	v_mfma_f32_16x16x32_bf16 v[16:19], v[234:237], v[182:185], 0
	v_mfma_f32_16x16x32_bf16 v[12:15], v[226:229], v[210:213], 0
	v_mfma_f32_16x16x32_bf16 v[8:11], v[234:237], v[210:213], 0
	v_mfma_f32_16x16x32_bf16 v[4:7], v[226:229], v[218:221], 0
	v_mfma_f32_16x16x32_bf16 v[0:3], v[234:237], v[218:221], 0
	v_mfma_f32_16x16x32_bf16 v[28:31], v[230:233], v[178:181], v[28:31]
	v_mfma_f32_16x16x32_bf16 v[24:27], v[238:241], v[178:181], v[24:27]
	v_mfma_f32_16x16x32_bf16 v[20:23], v[230:233], v[206:209], v[20:23]
	v_mfma_f32_16x16x32_bf16 v[16:19], v[238:241], v[206:209], v[16:19]
	v_mfma_f32_16x16x32_bf16 v[12:15], v[230:233], v[214:217], v[12:15]
	v_mfma_f32_16x16x32_bf16 v[8:11], v[238:241], v[214:217], v[8:11]
	v_mfma_f32_16x16x32_bf16 v[4:7], v[230:233], v[222:225], v[4:7]
	v_mfma_f32_16x16x32_bf16 v[0:3], v[238:241], v[222:225], v[0:3]
	s_barrier
	s_add_i32 s6, 0, 0x18000
	v_add_u32_e32 v170, s6, v154
	ds_read_b128 v[158:161], v170
	ds_read_b128 v[162:165], v170 offset:1024
	ds_read_b128 v[166:169], v170 offset:2048
	ds_read_b128 v[170:173], v170 offset:3072
	s_add_u32 s54, s54, 0x40000
	s_addc_u32 s55, s55, 0
	s_mov_b32 m0, s70
	v_lshl_add_u64 v[226:227], s[54:55], 0, v[128:129]
	ds_read_b128 v[174:177], v157 offset:32768
	ds_read_b128 v[178:181], v157 offset:33792
	ds_read_b128 v[182:185], v157 offset:34816
	ds_read_b128 v[206:209], v157 offset:35840
	ds_read_b128 v[210:213], v157 offset:36864
	ds_read_b128 v[214:217], v157 offset:37888
	ds_read_b128 v[218:221], v157 offset:38912
	ds_read_b128 v[222:225], v157 offset:39936
	global_load_lds_dwordx4 v[226:227], off
	v_lshl_add_u64 v[226:227], s[54:55], 0, v[130:131]
	s_mov_b32 m0, s71
	s_nop 0
	global_load_lds_dwordx4 v[226:227], off
	s_add_i32 s19, 0, 0x1c000
	v_add_u32_e32 v192, s19, v154
	ds_read_b128 v[226:229], v192
	ds_read_b128 v[230:233], v192 offset:1024
	ds_read_b128 v[234:237], v192 offset:2048
	ds_read_b128 v[238:241], v192 offset:3072
	s_waitcnt vmcnt(8)
	s_waitcnt lgkmcnt(0)
	s_barrier
	v_mfma_f32_16x16x32_bf16 v[124:127], v[158:161], v[174:177], v[124:127]
	v_mfma_f32_16x16x32_bf16 v[120:123], v[166:169], v[174:177], v[120:123]
	v_mfma_f32_16x16x32_bf16 v[116:119], v[158:161], v[182:185], v[116:119]
	v_mfma_f32_16x16x32_bf16 v[112:115], v[166:169], v[182:185], v[112:115]
	v_mfma_f32_16x16x32_bf16 v[108:111], v[158:161], v[210:213], v[108:111]
	v_mfma_f32_16x16x32_bf16 v[104:107], v[166:169], v[210:213], v[104:107]
	v_mfma_f32_16x16x32_bf16 v[100:103], v[158:161], v[218:221], v[100:103]
	v_mfma_f32_16x16x32_bf16 v[96:99], v[166:169], v[218:221], v[96:99]
	v_mfma_f32_16x16x32_bf16 v[124:127], v[162:165], v[178:181], v[124:127]
	v_mfma_f32_16x16x32_bf16 v[120:123], v[170:173], v[178:181], v[120:123]
	v_mfma_f32_16x16x32_bf16 v[116:119], v[162:165], v[206:209], v[116:119]
	v_mfma_f32_16x16x32_bf16 v[112:115], v[170:173], v[206:209], v[112:115]
	v_mfma_f32_16x16x32_bf16 v[108:111], v[162:165], v[214:217], v[108:111]
	v_mfma_f32_16x16x32_bf16 v[104:107], v[170:173], v[214:217], v[104:107]
	v_mfma_f32_16x16x32_bf16 v[100:103], v[162:165], v[222:225], v[100:103]
	v_mfma_f32_16x16x32_bf16 v[96:99], v[170:173], v[222:225], v[96:99]
	v_mfma_f32_16x16x32_bf16 v[92:95], v[226:229], v[174:177], v[92:95]
	v_mfma_f32_16x16x32_bf16 v[88:91], v[234:237], v[174:177], v[88:91]
	v_mfma_f32_16x16x32_bf16 v[84:87], v[226:229], v[182:185], v[84:87]
	v_mfma_f32_16x16x32_bf16 v[80:83], v[234:237], v[182:185], v[80:83]
	v_mfma_f32_16x16x32_bf16 v[76:79], v[226:229], v[210:213], v[76:79]
	v_mfma_f32_16x16x32_bf16 v[72:75], v[234:237], v[210:213], v[72:75]
	v_mfma_f32_16x16x32_bf16 v[68:71], v[226:229], v[218:221], v[68:71]
	v_mfma_f32_16x16x32_bf16 v[64:67], v[234:237], v[218:221], v[64:67]
	v_mfma_f32_16x16x32_bf16 v[92:95], v[230:233], v[178:181], v[92:95]
	v_mfma_f32_16x16x32_bf16 v[88:91], v[238:241], v[178:181], v[88:91]
	v_mfma_f32_16x16x32_bf16 v[84:87], v[230:233], v[206:209], v[84:87]
	v_mfma_f32_16x16x32_bf16 v[80:83], v[238:241], v[206:209], v[80:83]
	v_mfma_f32_16x16x32_bf16 v[76:79], v[230:233], v[214:217], v[76:79]
	v_mfma_f32_16x16x32_bf16 v[72:75], v[238:241], v[214:217], v[72:75]
	v_mfma_f32_16x16x32_bf16 v[68:71], v[230:233], v[222:225], v[68:71]
	v_mfma_f32_16x16x32_bf16 v[64:67], v[238:241], v[222:225], v[64:67]
	s_barrier
	s_add_i32 s6, s6, s59
	v_lshl_add_u64 v[146:147], v[146:147], 0, s[36:37]
	s_mov_b32 m0, s6
	s_nop 0
	global_load_lds_dwordx4 v[146:147], off
	v_lshl_add_u64 v[146:147], v[148:149], 0, s[36:37]
	s_add_i32 m0, s6, 0x2000
	s_nop 0
	global_load_lds_dwordx4 v[146:147], off
	s_mov_b32 m0, s72
	v_lshl_add_u64 v[146:147], v[194:195], 0, s[36:37]
	ds_read_b128 v[174:177], v157 offset:49152
	ds_read_b128 v[178:181], v157 offset:50176
	ds_read_b128 v[182:185], v157 offset:51200
	ds_read_b128 v[206:209], v157 offset:52224
	ds_read_b128 v[210:213], v157 offset:53248
	ds_read_b128 v[214:217], v157 offset:54272
	ds_read_b128 v[218:221], v157 offset:55296
	ds_read_b128 v[222:225], v157 offset:56320
	global_load_lds_dwordx4 v[146:147], off
	v_lshl_add_u64 v[146:147], v[196:197], 0, s[36:37]
	s_mov_b32 m0, s73
	s_nop 0
	global_load_lds_dwordx4 v[146:147], off
	s_add_u32 s52, s52, 0x40080
	s_addc_u32 s53, s53, 0
	s_add_i32 s6, s19, s59
	v_lshl_add_u64 v[146:147], s[52:53], 0, v[140:141]
	s_mov_b32 m0, s6
	s_nop 0
	global_load_lds_dwordx4 v[146:147], off
	v_lshl_add_u64 v[146:147], s[52:53], 0, v[132:133]
	s_add_i32 m0, s6, 0x2000
	s_nop 0
	global_load_lds_dwordx4 v[146:147], off
	s_waitcnt vmcnt(8)
	s_waitcnt lgkmcnt(0)
	s_barrier
	v_mfma_f32_16x16x32_bf16 v[60:63], v[158:161], v[174:177], v[60:63]
	v_mfma_f32_16x16x32_bf16 v[56:59], v[166:169], v[174:177], v[56:59]
	v_mfma_f32_16x16x32_bf16 v[52:55], v[158:161], v[182:185], v[52:55]
	v_mfma_f32_16x16x32_bf16 v[48:51], v[166:169], v[182:185], v[48:51]
	v_mfma_f32_16x16x32_bf16 v[44:47], v[158:161], v[210:213], v[44:47]
	v_mfma_f32_16x16x32_bf16 v[40:43], v[166:169], v[210:213], v[40:43]
	v_mfma_f32_16x16x32_bf16 v[36:39], v[158:161], v[218:221], v[36:39]
	v_mfma_f32_16x16x32_bf16 v[32:35], v[166:169], v[218:221], v[32:35]
	v_mfma_f32_16x16x32_bf16 v[60:63], v[162:165], v[178:181], v[60:63]
	v_mfma_f32_16x16x32_bf16 v[56:59], v[170:173], v[178:181], v[56:59]
	v_mfma_f32_16x16x32_bf16 v[52:55], v[162:165], v[206:209], v[52:55]
	v_mfma_f32_16x16x32_bf16 v[48:51], v[170:173], v[206:209], v[48:51]
	v_mfma_f32_16x16x32_bf16 v[44:47], v[162:165], v[214:217], v[44:47]
	v_mfma_f32_16x16x32_bf16 v[40:43], v[170:173], v[214:217], v[40:43]
	v_mfma_f32_16x16x32_bf16 v[36:39], v[162:165], v[222:225], v[36:39]
	v_mfma_f32_16x16x32_bf16 v[32:35], v[170:173], v[222:225], v[32:35]
	v_mfma_f32_16x16x32_bf16 v[28:31], v[226:229], v[174:177], v[28:31]
	v_mfma_f32_16x16x32_bf16 v[24:27], v[234:237], v[174:177], v[24:27]
	v_mfma_f32_16x16x32_bf16 v[20:23], v[226:229], v[182:185], v[20:23]
	v_mfma_f32_16x16x32_bf16 v[16:19], v[234:237], v[182:185], v[16:19]
	v_mfma_f32_16x16x32_bf16 v[12:15], v[226:229], v[210:213], v[12:15]
	v_mfma_f32_16x16x32_bf16 v[8:11], v[234:237], v[210:213], v[8:11]
	v_mfma_f32_16x16x32_bf16 v[4:7], v[226:229], v[218:221], v[4:7]
	v_mfma_f32_16x16x32_bf16 v[0:3], v[234:237], v[218:221], v[0:3]
	v_mfma_f32_16x16x32_bf16 v[28:31], v[230:233], v[178:181], v[28:31]
	v_mfma_f32_16x16x32_bf16 v[24:27], v[238:241], v[178:181], v[24:27]
	v_mfma_f32_16x16x32_bf16 v[20:23], v[230:233], v[206:209], v[20:23]
	v_mfma_f32_16x16x32_bf16 v[16:19], v[238:241], v[206:209], v[16:19]
	v_mfma_f32_16x16x32_bf16 v[12:15], v[230:233], v[214:217], v[12:15]
	v_mfma_f32_16x16x32_bf16 v[8:11], v[238:241], v[214:217], v[8:11]
	v_mfma_f32_16x16x32_bf16 v[4:7], v[230:233], v[222:225], v[4:7]
	v_mfma_f32_16x16x32_bf16 v[0:3], v[238:241], v[222:225], v[0:3]
	s_add_i32 s81, s81, 2
	s_add_u32 s50, s50, 0x100
	s_addc_u32 s51, s51, 0
	s_cmp_gt_u32 s81, 13
	s_barrier
.LBB0_77:
	s_add_u32 s6, s26, s50
	s_addc_u32 s19, s27, s51
	s_add_u32 s6, s6, 0x100
	s_addc_u32 s19, s19, 0
	s_add_u32 s23, s10, s50
	s_addc_u32 s52, s11, s51
	s_add_i32 s82, 0, 0x10000
	v_add_u32_e32 v146, s82, v154
	ds_read_b128 v[158:161], v146
	ds_read_b128 v[162:165], v146 offset:1024
	ds_read_b128 v[166:169], v146 offset:2048
	ds_read_b128 v[170:173], v146 offset:3072
	s_cmpk_eq_i32 s50, 0x700
	s_cselect_b32 s55, s12, s19
	s_cselect_b32 s54, s31, s6
	s_cselect_b32 s53, s35, s52
	s_cselect_b32 s52, s39, s23
	v_lshl_add_u64 v[146:147], v[150:151], 0, s[50:51]
	s_add_i32 m0, s68, 0xc000
	ds_read_b128 v[174:177], v157
	ds_read_b128 v[178:181], v157 offset:1024
	ds_read_b128 v[182:185], v157 offset:2048
	ds_read_b128 v[206:209], v157 offset:3072
	ds_read_b128 v[210:213], v157 offset:4096
	ds_read_b128 v[214:217], v157 offset:5120
	ds_read_b128 v[218:221], v157 offset:6144
	ds_read_b128 v[222:225], v157 offset:7168
	global_load_lds_dwordx4 v[146:147], off
	v_lshl_add_u64 v[146:147], v[152:153], 0, s[50:51]
	s_add_i32 m0, s68, 0xe000
	s_nop 0
	global_load_lds_dwordx4 v[146:147], off
	s_add_i32 s6, 0, 0x14000
	v_add_u32_e32 v146, s6, v154
	ds_read_b128 v[226:229], v146
	ds_read_b128 v[230:233], v146 offset:1024
	ds_read_b128 v[234:237], v146 offset:2048
	ds_read_b128 v[238:241], v146 offset:3072
	s_waitcnt vmcnt(8)
	s_waitcnt lgkmcnt(0)
	s_barrier
	v_mfma_f32_16x16x32_bf16 v[124:127], v[158:161], v[174:177], v[124:127]
	v_mfma_f32_16x16x32_bf16 v[120:123], v[166:169], v[174:177], v[120:123]
	v_mfma_f32_16x16x32_bf16 v[116:119], v[158:161], v[182:185], v[116:119]
	v_mfma_f32_16x16x32_bf16 v[112:115], v[166:169], v[182:185], v[112:115]
	v_mfma_f32_16x16x32_bf16 v[108:111], v[158:161], v[210:213], v[108:111]
	v_mfma_f32_16x16x32_bf16 v[104:107], v[166:169], v[210:213], v[104:107]
	v_mfma_f32_16x16x32_bf16 v[100:103], v[158:161], v[218:221], v[100:103]
	v_mfma_f32_16x16x32_bf16 v[96:99], v[166:169], v[218:221], v[96:99]
	v_mfma_f32_16x16x32_bf16 v[124:127], v[162:165], v[178:181], v[124:127]
	v_mfma_f32_16x16x32_bf16 v[120:123], v[170:173], v[178:181], v[120:123]
	v_mfma_f32_16x16x32_bf16 v[116:119], v[162:165], v[206:209], v[116:119]
	v_mfma_f32_16x16x32_bf16 v[112:115], v[170:173], v[206:209], v[112:115]
	v_mfma_f32_16x16x32_bf16 v[108:111], v[162:165], v[214:217], v[108:111]
	v_mfma_f32_16x16x32_bf16 v[104:107], v[170:173], v[214:217], v[104:107]
	v_mfma_f32_16x16x32_bf16 v[100:103], v[162:165], v[222:225], v[100:103]
	v_mfma_f32_16x16x32_bf16 v[96:99], v[170:173], v[222:225], v[96:99]
	v_mfma_f32_16x16x32_bf16 v[92:95], v[226:229], v[174:177], v[92:95]
	v_mfma_f32_16x16x32_bf16 v[88:91], v[234:237], v[174:177], v[88:91]
	v_mfma_f32_16x16x32_bf16 v[84:87], v[226:229], v[182:185], v[84:87]
	v_mfma_f32_16x16x32_bf16 v[80:83], v[234:237], v[182:185], v[80:83]
	v_mfma_f32_16x16x32_bf16 v[76:79], v[226:229], v[210:213], v[76:79]
	v_mfma_f32_16x16x32_bf16 v[72:75], v[234:237], v[210:213], v[72:75]
	v_mfma_f32_16x16x32_bf16 v[68:71], v[226:229], v[218:221], v[68:71]
	v_mfma_f32_16x16x32_bf16 v[64:67], v[234:237], v[218:221], v[64:67]
	v_mfma_f32_16x16x32_bf16 v[92:95], v[230:233], v[178:181], v[92:95]
	v_mfma_f32_16x16x32_bf16 v[88:91], v[238:241], v[178:181], v[88:91]
	v_mfma_f32_16x16x32_bf16 v[84:87], v[230:233], v[206:209], v[84:87]
	v_mfma_f32_16x16x32_bf16 v[80:83], v[238:241], v[206:209], v[80:83]
	v_mfma_f32_16x16x32_bf16 v[76:79], v[230:233], v[214:217], v[76:79]
	v_mfma_f32_16x16x32_bf16 v[72:75], v[238:241], v[214:217], v[72:75]
	v_mfma_f32_16x16x32_bf16 v[68:71], v[230:233], v[222:225], v[68:71]
	v_mfma_f32_16x16x32_bf16 v[64:67], v[238:241], v[222:225], v[64:67]
	s_barrier
	s_add_i32 s19, s82, s59
	v_lshl_add_u64 v[146:147], s[52:53], 0, v[140:141]
	s_mov_b32 m0, s19
	v_lshl_add_u64 v[148:149], s[52:53], 0, v[132:133]
	global_load_lds_dwordx4 v[146:147], off
	s_add_i32 m0, s19, 0x2000
	s_nop 0
	global_load_lds_dwordx4 v[148:149], off
	s_mov_b32 m0, s68
	v_lshl_add_u64 v[194:195], s[54:55], 0, v[128:129]
	ds_read_b128 v[174:177], v157 offset:16384
	ds_read_b128 v[178:181], v157 offset:17408
	ds_read_b128 v[182:185], v157 offset:18432
	ds_read_b128 v[206:209], v157 offset:19456
	ds_read_b128 v[210:213], v157 offset:20480
	ds_read_b128 v[214:217], v157 offset:21504
	ds_read_b128 v[218:221], v157 offset:22528
	ds_read_b128 v[222:225], v157 offset:23552
	global_load_lds_dwordx4 v[194:195], off
	v_lshl_add_u64 v[196:197], s[54:55], 0, v[130:131]
	s_mov_b32 m0, s69
	s_nop 0
	global_load_lds_dwordx4 v[196:197], off
	s_add_u32 s82, s52, 0x40000
	s_addc_u32 s83, s53, 0
	s_add_i32 s6, s6, s59
	v_lshl_add_u64 v[250:251], s[82:83], 0, v[140:141]
	s_mov_b32 m0, s6
	s_nop 0
	global_load_lds_dwordx4 v[250:251], off
	v_lshl_add_u64 v[250:251], s[82:83], 0, v[132:133]
	s_add_i32 m0, s6, 0x2000
	s_nop 0
	global_load_lds_dwordx4 v[250:251], off
	s_nop 0
	s_waitcnt vmcnt(8)
	s_waitcnt lgkmcnt(0)
	s_barrier
	v_mfma_f32_16x16x32_bf16 v[60:63], v[158:161], v[174:177], v[60:63]
	v_mfma_f32_16x16x32_bf16 v[56:59], v[166:169], v[174:177], v[56:59]
	v_mfma_f32_16x16x32_bf16 v[52:55], v[158:161], v[182:185], v[52:55]
	v_mfma_f32_16x16x32_bf16 v[48:51], v[166:169], v[182:185], v[48:51]
	v_mfma_f32_16x16x32_bf16 v[44:47], v[158:161], v[210:213], v[44:47]
	v_mfma_f32_16x16x32_bf16 v[40:43], v[166:169], v[210:213], v[40:43]
	v_mfma_f32_16x16x32_bf16 v[36:39], v[158:161], v[218:221], v[36:39]
	v_mfma_f32_16x16x32_bf16 v[32:35], v[166:169], v[218:221], v[32:35]
	v_mfma_f32_16x16x32_bf16 v[60:63], v[162:165], v[178:181], v[60:63]
	v_mfma_f32_16x16x32_bf16 v[56:59], v[170:173], v[178:181], v[56:59]
	v_mfma_f32_16x16x32_bf16 v[52:55], v[162:165], v[206:209], v[52:55]
	v_mfma_f32_16x16x32_bf16 v[48:51], v[170:173], v[206:209], v[48:51]
	v_mfma_f32_16x16x32_bf16 v[44:47], v[162:165], v[214:217], v[44:47]
	v_mfma_f32_16x16x32_bf16 v[40:43], v[170:173], v[214:217], v[40:43]
	v_mfma_f32_16x16x32_bf16 v[36:39], v[162:165], v[222:225], v[36:39]
	v_mfma_f32_16x16x32_bf16 v[32:35], v[170:173], v[222:225], v[32:35]
	v_mfma_f32_16x16x32_bf16 v[28:31], v[226:229], v[174:177], v[28:31]
	v_mfma_f32_16x16x32_bf16 v[24:27], v[234:237], v[174:177], v[24:27]
	v_mfma_f32_16x16x32_bf16 v[20:23], v[226:229], v[182:185], v[20:23]
	v_mfma_f32_16x16x32_bf16 v[16:19], v[234:237], v[182:185], v[16:19]
	v_mfma_f32_16x16x32_bf16 v[12:15], v[226:229], v[210:213], v[12:15]
	v_mfma_f32_16x16x32_bf16 v[8:11], v[234:237], v[210:213], v[8:11]
	v_mfma_f32_16x16x32_bf16 v[4:7], v[226:229], v[218:221], v[4:7]
	v_mfma_f32_16x16x32_bf16 v[0:3], v[234:237], v[218:221], v[0:3]
	v_mfma_f32_16x16x32_bf16 v[28:31], v[230:233], v[178:181], v[28:31]
	v_mfma_f32_16x16x32_bf16 v[24:27], v[238:241], v[178:181], v[24:27]
	v_mfma_f32_16x16x32_bf16 v[20:23], v[230:233], v[206:209], v[20:23]
	v_mfma_f32_16x16x32_bf16 v[16:19], v[238:241], v[206:209], v[16:19]
	v_mfma_f32_16x16x32_bf16 v[12:15], v[230:233], v[214:217], v[12:15]
	v_mfma_f32_16x16x32_bf16 v[8:11], v[238:241], v[214:217], v[8:11]
	v_mfma_f32_16x16x32_bf16 v[4:7], v[230:233], v[222:225], v[4:7]
	v_mfma_f32_16x16x32_bf16 v[0:3], v[238:241], v[222:225], v[0:3]
	s_barrier
	s_add_i32 s6, 0, 0x18000
	v_add_u32_e32 v170, s6, v154
	ds_read_b128 v[158:161], v170
	ds_read_b128 v[162:165], v170 offset:1024
	ds_read_b128 v[166:169], v170 offset:2048
	ds_read_b128 v[170:173], v170 offset:3072
	s_add_u32 s54, s54, 0x40000
	s_addc_u32 s55, s55, 0
	s_mov_b32 m0, s70
	v_lshl_add_u64 v[226:227], s[54:55], 0, v[128:129]
	ds_read_b128 v[174:177], v157 offset:32768
	ds_read_b128 v[178:181], v157 offset:33792
	ds_read_b128 v[182:185], v157 offset:34816
	ds_read_b128 v[206:209], v157 offset:35840
	ds_read_b128 v[210:213], v157 offset:36864
	ds_read_b128 v[214:217], v157 offset:37888
	ds_read_b128 v[218:221], v157 offset:38912
	ds_read_b128 v[222:225], v157 offset:39936
	global_load_lds_dwordx4 v[226:227], off
	v_lshl_add_u64 v[226:227], s[54:55], 0, v[130:131]
	s_mov_b32 m0, s71
	s_nop 0
	global_load_lds_dwordx4 v[226:227], off
	s_add_i32 s19, 0, 0x1c000
	v_add_u32_e32 v192, s19, v154
	ds_read_b128 v[226:229], v192
	ds_read_b128 v[230:233], v192 offset:1024
	ds_read_b128 v[234:237], v192 offset:2048
	ds_read_b128 v[238:241], v192 offset:3072
	s_waitcnt vmcnt(8)
	s_waitcnt lgkmcnt(0)
	s_barrier
	v_mfma_f32_16x16x32_bf16 v[124:127], v[158:161], v[174:177], v[124:127]
	v_mfma_f32_16x16x32_bf16 v[120:123], v[166:169], v[174:177], v[120:123]
	v_mfma_f32_16x16x32_bf16 v[116:119], v[158:161], v[182:185], v[116:119]
	v_mfma_f32_16x16x32_bf16 v[112:115], v[166:169], v[182:185], v[112:115]
	v_mfma_f32_16x16x32_bf16 v[108:111], v[158:161], v[210:213], v[108:111]
	v_mfma_f32_16x16x32_bf16 v[104:107], v[166:169], v[210:213], v[104:107]
	v_mfma_f32_16x16x32_bf16 v[100:103], v[158:161], v[218:221], v[100:103]
	v_mfma_f32_16x16x32_bf16 v[96:99], v[166:169], v[218:221], v[96:99]
	v_mfma_f32_16x16x32_bf16 v[124:127], v[162:165], v[178:181], v[124:127]
	v_mfma_f32_16x16x32_bf16 v[120:123], v[170:173], v[178:181], v[120:123]
	v_mfma_f32_16x16x32_bf16 v[116:119], v[162:165], v[206:209], v[116:119]
	v_mfma_f32_16x16x32_bf16 v[112:115], v[170:173], v[206:209], v[112:115]
	v_mfma_f32_16x16x32_bf16 v[108:111], v[162:165], v[214:217], v[108:111]
	v_mfma_f32_16x16x32_bf16 v[104:107], v[170:173], v[214:217], v[104:107]
	v_mfma_f32_16x16x32_bf16 v[100:103], v[162:165], v[222:225], v[100:103]
	v_mfma_f32_16x16x32_bf16 v[96:99], v[170:173], v[222:225], v[96:99]
	v_mfma_f32_16x16x32_bf16 v[92:95], v[226:229], v[174:177], v[92:95]
	v_mfma_f32_16x16x32_bf16 v[88:91], v[234:237], v[174:177], v[88:91]
	v_mfma_f32_16x16x32_bf16 v[84:87], v[226:229], v[182:185], v[84:87]
	v_mfma_f32_16x16x32_bf16 v[80:83], v[234:237], v[182:185], v[80:83]
	v_mfma_f32_16x16x32_bf16 v[76:79], v[226:229], v[210:213], v[76:79]
	v_mfma_f32_16x16x32_bf16 v[72:75], v[234:237], v[210:213], v[72:75]
	v_mfma_f32_16x16x32_bf16 v[68:71], v[226:229], v[218:221], v[68:71]
	v_mfma_f32_16x16x32_bf16 v[64:67], v[234:237], v[218:221], v[64:67]
	v_mfma_f32_16x16x32_bf16 v[92:95], v[230:233], v[178:181], v[92:95]
	v_mfma_f32_16x16x32_bf16 v[88:91], v[238:241], v[178:181], v[88:91]
	v_mfma_f32_16x16x32_bf16 v[84:87], v[230:233], v[206:209], v[84:87]
	v_mfma_f32_16x16x32_bf16 v[80:83], v[238:241], v[206:209], v[80:83]
	v_mfma_f32_16x16x32_bf16 v[76:79], v[230:233], v[214:217], v[76:79]
	v_mfma_f32_16x16x32_bf16 v[72:75], v[238:241], v[214:217], v[72:75]
	v_mfma_f32_16x16x32_bf16 v[68:71], v[230:233], v[222:225], v[68:71]
	v_mfma_f32_16x16x32_bf16 v[64:67], v[238:241], v[222:225], v[64:67]
	s_barrier
	s_add_i32 s6, s6, s59
	v_lshl_add_u64 v[146:147], v[146:147], 0, s[36:37]
	s_mov_b32 m0, s6
	s_nop 0
	global_load_lds_dwordx4 v[146:147], off
	v_lshl_add_u64 v[146:147], v[148:149], 0, s[36:37]
	s_add_i32 m0, s6, 0x2000
	s_nop 0
	global_load_lds_dwordx4 v[146:147], off
	s_mov_b32 m0, s72
	v_lshl_add_u64 v[146:147], v[194:195], 0, s[36:37]
	ds_read_b128 v[174:177], v157 offset:49152
	ds_read_b128 v[178:181], v157 offset:50176
	ds_read_b128 v[182:185], v157 offset:51200
	ds_read_b128 v[206:209], v157 offset:52224
	ds_read_b128 v[210:213], v157 offset:53248
	ds_read_b128 v[214:217], v157 offset:54272
	ds_read_b128 v[218:221], v157 offset:55296
	ds_read_b128 v[222:225], v157 offset:56320
	global_load_lds_dwordx4 v[146:147], off
	v_lshl_add_u64 v[146:147], v[196:197], 0, s[36:37]
	s_mov_b32 m0, s73
	s_nop 0
	global_load_lds_dwordx4 v[146:147], off
	s_add_u32 s52, s52, 0x40080
	s_addc_u32 s53, s53, 0
	s_add_i32 s6, s19, s59
	v_lshl_add_u64 v[146:147], s[52:53], 0, v[140:141]
	s_mov_b32 m0, s6
	s_nop 0
	global_load_lds_dwordx4 v[146:147], off
	v_lshl_add_u64 v[146:147], s[52:53], 0, v[132:133]
	s_add_i32 m0, s6, 0x2000
	s_nop 0
	global_load_lds_dwordx4 v[146:147], off
	s_waitcnt vmcnt(8)
	s_waitcnt lgkmcnt(0)
	s_barrier
	v_mfma_f32_16x16x32_bf16 v[60:63], v[158:161], v[174:177], v[60:63]
	v_mfma_f32_16x16x32_bf16 v[56:59], v[166:169], v[174:177], v[56:59]
	v_mfma_f32_16x16x32_bf16 v[52:55], v[158:161], v[182:185], v[52:55]
	v_mfma_f32_16x16x32_bf16 v[48:51], v[166:169], v[182:185], v[48:51]
	v_mfma_f32_16x16x32_bf16 v[44:47], v[158:161], v[210:213], v[44:47]
	v_mfma_f32_16x16x32_bf16 v[40:43], v[166:169], v[210:213], v[40:43]
	v_mfma_f32_16x16x32_bf16 v[36:39], v[158:161], v[218:221], v[36:39]
	v_mfma_f32_16x16x32_bf16 v[32:35], v[166:169], v[218:221], v[32:35]
	v_mfma_f32_16x16x32_bf16 v[60:63], v[162:165], v[178:181], v[60:63]
	v_mfma_f32_16x16x32_bf16 v[56:59], v[170:173], v[178:181], v[56:59]
	v_mfma_f32_16x16x32_bf16 v[52:55], v[162:165], v[206:209], v[52:55]
	v_mfma_f32_16x16x32_bf16 v[48:51], v[170:173], v[206:209], v[48:51]
	v_mfma_f32_16x16x32_bf16 v[44:47], v[162:165], v[214:217], v[44:47]
	v_mfma_f32_16x16x32_bf16 v[40:43], v[170:173], v[214:217], v[40:43]
	v_mfma_f32_16x16x32_bf16 v[36:39], v[162:165], v[222:225], v[36:39]
	v_mfma_f32_16x16x32_bf16 v[32:35], v[170:173], v[222:225], v[32:35]
	v_mfma_f32_16x16x32_bf16 v[28:31], v[226:229], v[174:177], v[28:31]
	v_mfma_f32_16x16x32_bf16 v[24:27], v[234:237], v[174:177], v[24:27]
	v_mfma_f32_16x16x32_bf16 v[20:23], v[226:229], v[182:185], v[20:23]
	v_mfma_f32_16x16x32_bf16 v[16:19], v[234:237], v[182:185], v[16:19]
	v_mfma_f32_16x16x32_bf16 v[12:15], v[226:229], v[210:213], v[12:15]
	v_mfma_f32_16x16x32_bf16 v[8:11], v[234:237], v[210:213], v[8:11]
	v_mfma_f32_16x16x32_bf16 v[4:7], v[226:229], v[218:221], v[4:7]
	v_mfma_f32_16x16x32_bf16 v[0:3], v[234:237], v[218:221], v[0:3]
	v_mfma_f32_16x16x32_bf16 v[28:31], v[230:233], v[178:181], v[28:31]
	v_mfma_f32_16x16x32_bf16 v[24:27], v[238:241], v[178:181], v[24:27]
	v_mfma_f32_16x16x32_bf16 v[20:23], v[230:233], v[206:209], v[20:23]
	v_mfma_f32_16x16x32_bf16 v[16:19], v[238:241], v[206:209], v[16:19]
	v_mfma_f32_16x16x32_bf16 v[12:15], v[230:233], v[214:217], v[12:15]
	v_mfma_f32_16x16x32_bf16 v[8:11], v[238:241], v[214:217], v[8:11]
	v_mfma_f32_16x16x32_bf16 v[4:7], v[230:233], v[222:225], v[4:7]
	v_mfma_f32_16x16x32_bf16 v[0:3], v[238:241], v[222:225], v[0:3]
	s_add_i32 s81, s81, 2
	s_add_u32 s50, s50, 0x100
	s_addc_u32 s51, s51, 0
	s_cmp_gt_u32 s81, 13
	s_barrier
	s_cbranch_scc0 .LBB0_77
	s_mov_b32 s100, 1
	v_lshl_add_u32 v158, s75, 10, v155
	ds_read2_b32 v[146:147], v158 offset1:16
	s_add_u32 s50, s10, 0xffffff00
	s_addc_u32 s51, s11, -1
	s_ashr_i32 s31, s30, 31
	s_lshl_b64 s[10:11], s[30:31], 8
	s_waitcnt lgkmcnt(0)
	v_mul_f32_e32 v184, 0xbfb8aa3b, v146
	v_mul_f32_e32 v206, v146, v146
	v_pk_mul_f32 v[168:169], v[124:125], v[184:185] op_sel_hi:[1,0]
	v_pk_mul_f32 v[170:171], v[126:127], v[184:185] op_sel_hi:[1,0]
	v_pk_mul_f32 v[172:173], v[120:121], v[184:185] op_sel_hi:[1,0]
	v_pk_mul_f32 v[174:175], v[122:123], v[184:185] op_sel_hi:[1,0]
	v_exp_f32_e32 v168, v168
	v_exp_f32_e32 v169, v169
	v_exp_f32_e32 v170, v170
	v_exp_f32_e32 v171, v171
	v_exp_f32_e32 v172, v172
	v_exp_f32_e32 v173, v173
	v_exp_f32_e32 v174, v174
	v_exp_f32_e32 v175, v175
	v_pk_mul_f32 v[176:177], v[124:125], v[92:93]
	v_pk_mul_f32 v[178:179], v[126:127], v[94:95]
	v_pk_mul_f32 v[180:181], v[120:121], v[88:89]
	v_pk_mul_f32 v[182:183], v[122:123], v[90:91]
	v_pk_add_f32 v[168:169], v[168:169], 1.0 op_sel_hi:[1,0]
	v_pk_add_f32 v[170:171], v[170:171], 1.0 op_sel_hi:[1,0]
	v_pk_add_f32 v[172:173], v[172:173], 1.0 op_sel_hi:[1,0]
	v_pk_add_f32 v[174:175], v[174:175], 1.0 op_sel_hi:[1,0]
	v_rcp_f32_e32 v168, v168
	v_rcp_f32_e32 v169, v169
	v_rcp_f32_e32 v170, v170
	v_rcp_f32_e32 v171, v171
	v_rcp_f32_e32 v172, v172
	v_rcp_f32_e32 v173, v173
	v_rcp_f32_e32 v174, v174
	v_rcp_f32_e32 v175, v175
	v_pk_mul_f32 v[176:177], v[176:177], v[206:207] op_sel_hi:[1,0]
	v_pk_mul_f32 v[178:179], v[178:179], v[206:207] op_sel_hi:[1,0]
	v_pk_mul_f32 v[180:181], v[180:181], v[206:207] op_sel_hi:[1,0]
	v_pk_mul_f32 v[182:183], v[182:183], v[206:207] op_sel_hi:[1,0]
	v_pk_mul_f32 v[176:177], v[176:177], v[168:169]
	v_pk_mul_f32 v[178:179], v[178:179], v[170:171]
	v_pk_mul_f32 v[180:181], v[180:181], v[172:173]
	v_pk_mul_f32 v[182:183], v[182:183], v[174:175]
	v_cvt_pk_bf16_f32 v160, v176, v177
	v_cvt_pk_bf16_f32 v161, v178, v179
	v_cvt_pk_bf16_f32 v162, v180, v181
	v_cvt_pk_bf16_f32 v163, v182, v183
	v_lshl_add_u64 v[152:153], v[134:135], 0, s[10:11]
	s_movk_i32 s6, 0x1600
	v_lshl_or_b32 v150, s74, 7, v156
	v_ashrrev_i32_e32 v151, 31, v150
	s_nop 1
	v_mov_b64_e32 v[148:149], s[28:29]
	v_mad_u64_u32 v[148:149], s[10:11], v152, s6, v[148:149]
	v_mov_b32_e32 v146, v149
	v_mad_u64_u32 v[152:153], s[10:11], v153, s6, v[146:147]
	v_mov_b32_e32 v149, v152
	v_mov_b32_e32 v146, v147
	v_lshl_add_u64 v[150:151], v[150:151], 1, v[148:149]
	global_store_dwordx4 v[150:151], v[160:163], off
	v_mul_f32_e32 v184, 0xbfb8aa3b, v146
	v_mul_f32_e32 v206, v146, v146
	v_pk_mul_f32 v[168:169], v[116:117], v[184:185] op_sel_hi:[1,0]
	v_pk_mul_f32 v[170:171], v[118:119], v[184:185] op_sel_hi:[1,0]
	v_pk_mul_f32 v[172:173], v[112:113], v[184:185] op_sel_hi:[1,0]
	v_pk_mul_f32 v[174:175], v[114:115], v[184:185] op_sel_hi:[1,0]
	v_exp_f32_e32 v168, v168
	v_exp_f32_e32 v169, v169
	v_exp_f32_e32 v170, v170
	v_exp_f32_e32 v171, v171
	v_exp_f32_e32 v172, v172
	v_exp_f32_e32 v173, v173
	v_exp_f32_e32 v174, v174
	v_exp_f32_e32 v175, v175
	v_pk_mul_f32 v[176:177], v[116:117], v[84:85]
	v_pk_mul_f32 v[178:179], v[118:119], v[86:87]
	v_pk_mul_f32 v[180:181], v[112:113], v[80:81]
	v_pk_mul_f32 v[182:183], v[114:115], v[82:83]
	v_pk_add_f32 v[168:169], v[168:169], 1.0 op_sel_hi:[1,0]
	v_pk_add_f32 v[170:171], v[170:171], 1.0 op_sel_hi:[1,0]
	v_pk_add_f32 v[172:173], v[172:173], 1.0 op_sel_hi:[1,0]
	v_pk_add_f32 v[174:175], v[174:175], 1.0 op_sel_hi:[1,0]
	v_rcp_f32_e32 v168, v168
	v_rcp_f32_e32 v169, v169
	v_rcp_f32_e32 v170, v170
	v_rcp_f32_e32 v171, v171
	v_rcp_f32_e32 v172, v172
	v_rcp_f32_e32 v173, v173
	v_rcp_f32_e32 v174, v174
	v_rcp_f32_e32 v175, v175
	v_pk_mul_f32 v[176:177], v[176:177], v[206:207] op_sel_hi:[1,0]
	v_pk_mul_f32 v[178:179], v[178:179], v[206:207] op_sel_hi:[1,0]
	v_pk_mul_f32 v[180:181], v[180:181], v[206:207] op_sel_hi:[1,0]
	v_pk_mul_f32 v[182:183], v[182:183], v[206:207] op_sel_hi:[1,0]
	v_pk_mul_f32 v[176:177], v[176:177], v[168:169]
	v_pk_mul_f32 v[178:179], v[178:179], v[170:171]
	v_pk_mul_f32 v[180:181], v[180:181], v[172:173]
	v_pk_mul_f32 v[182:183], v[182:183], v[174:175]
	v_cvt_pk_bf16_f32 v160, v176, v177
	v_cvt_pk_bf16_f32 v161, v178, v179
	v_cvt_pk_bf16_f32 v162, v180, v181
	v_cvt_pk_bf16_f32 v163, v182, v183
	s_mov_b32 s6, 0x16000
	s_nop 1
	v_add_co_u32_e32 v146, vcc, s6, v150
	s_nop 0
	v_addc_co_u32_e32 v147, vcc, 0, v151, vcc
	global_store_dwordx4 v[146:147], v[160:163], off
	ds_read2_b32 v[146:147], v158 offset0:32 offset1:48
	s_mov_b32 s6, 0x2c000
	s_waitcnt lgkmcnt(0)
	v_mul_f32_e32 v184, 0xbfb8aa3b, v146
	v_mul_f32_e32 v206, v146, v146
	v_pk_mul_f32 v[168:169], v[108:109], v[184:185] op_sel_hi:[1,0]
	v_pk_mul_f32 v[170:171], v[110:111], v[184:185] op_sel_hi:[1,0]
	v_pk_mul_f32 v[172:173], v[104:105], v[184:185] op_sel_hi:[1,0]
	v_pk_mul_f32 v[174:175], v[106:107], v[184:185] op_sel_hi:[1,0]
	v_exp_f32_e32 v168, v168
	v_exp_f32_e32 v169, v169
	v_exp_f32_e32 v170, v170
	v_exp_f32_e32 v171, v171
	v_exp_f32_e32 v172, v172
	v_exp_f32_e32 v173, v173
	v_exp_f32_e32 v174, v174
	v_exp_f32_e32 v175, v175
	v_pk_mul_f32 v[176:177], v[108:109], v[76:77]
	v_pk_mul_f32 v[178:179], v[110:111], v[78:79]
	v_pk_mul_f32 v[180:181], v[104:105], v[72:73]
	v_pk_mul_f32 v[182:183], v[106:107], v[74:75]
	v_pk_add_f32 v[168:169], v[168:169], 1.0 op_sel_hi:[1,0]
	v_pk_add_f32 v[170:171], v[170:171], 1.0 op_sel_hi:[1,0]
	v_pk_add_f32 v[172:173], v[172:173], 1.0 op_sel_hi:[1,0]
	v_pk_add_f32 v[174:175], v[174:175], 1.0 op_sel_hi:[1,0]
	v_rcp_f32_e32 v168, v168
	v_rcp_f32_e32 v169, v169
	v_rcp_f32_e32 v170, v170
	v_rcp_f32_e32 v171, v171
	v_rcp_f32_e32 v172, v172
	v_rcp_f32_e32 v173, v173
	v_rcp_f32_e32 v174, v174
	v_rcp_f32_e32 v175, v175
	v_pk_mul_f32 v[176:177], v[176:177], v[206:207] op_sel_hi:[1,0]
	v_pk_mul_f32 v[178:179], v[178:179], v[206:207] op_sel_hi:[1,0]
	v_pk_mul_f32 v[180:181], v[180:181], v[206:207] op_sel_hi:[1,0]
	v_pk_mul_f32 v[182:183], v[182:183], v[206:207] op_sel_hi:[1,0]
	v_pk_mul_f32 v[176:177], v[176:177], v[168:169]
	v_pk_mul_f32 v[178:179], v[178:179], v[170:171]
	v_pk_mul_f32 v[180:181], v[180:181], v[172:173]
	v_pk_mul_f32 v[182:183], v[182:183], v[174:175]
	v_cvt_pk_bf16_f32 v160, v176, v177
	v_cvt_pk_bf16_f32 v161, v178, v179
	v_cvt_pk_bf16_f32 v162, v180, v181
	v_cvt_pk_bf16_f32 v163, v182, v183
	s_nop 1
	v_mov_b32_e32 v146, v147
	v_add_co_u32_e32 v148, vcc, s6, v150
	v_addc_co_u32_e32 v149, vcc, 0, v151, vcc
	global_store_dwordx4 v[148:149], v[160:163], off
	v_mul_f32_e32 v184, 0xbfb8aa3b, v146
	v_mul_f32_e32 v206, v146, v146
	v_pk_mul_f32 v[168:169], v[100:101], v[184:185] op_sel_hi:[1,0]
	v_pk_mul_f32 v[170:171], v[102:103], v[184:185] op_sel_hi:[1,0]
	v_pk_mul_f32 v[172:173], v[96:97], v[184:185] op_sel_hi:[1,0]
	v_pk_mul_f32 v[174:175], v[98:99], v[184:185] op_sel_hi:[1,0]
	v_exp_f32_e32 v168, v168
	v_exp_f32_e32 v169, v169
	v_exp_f32_e32 v170, v170
	v_exp_f32_e32 v171, v171
	v_exp_f32_e32 v172, v172
	v_exp_f32_e32 v173, v173
	v_exp_f32_e32 v174, v174
	v_exp_f32_e32 v175, v175
	v_pk_mul_f32 v[176:177], v[100:101], v[68:69]
	v_pk_mul_f32 v[178:179], v[102:103], v[70:71]
	v_pk_mul_f32 v[180:181], v[96:97], v[64:65]
	v_pk_mul_f32 v[182:183], v[98:99], v[66:67]
	v_pk_add_f32 v[168:169], v[168:169], 1.0 op_sel_hi:[1,0]
	v_pk_add_f32 v[170:171], v[170:171], 1.0 op_sel_hi:[1,0]
	v_pk_add_f32 v[172:173], v[172:173], 1.0 op_sel_hi:[1,0]
	v_pk_add_f32 v[174:175], v[174:175], 1.0 op_sel_hi:[1,0]
	v_rcp_f32_e32 v168, v168
	v_rcp_f32_e32 v169, v169
	v_rcp_f32_e32 v170, v170
	v_rcp_f32_e32 v171, v171
	v_rcp_f32_e32 v172, v172
	v_rcp_f32_e32 v173, v173
	v_rcp_f32_e32 v174, v174
	v_rcp_f32_e32 v175, v175
	v_pk_mul_f32 v[176:177], v[176:177], v[206:207] op_sel_hi:[1,0]
	v_pk_mul_f32 v[178:179], v[178:179], v[206:207] op_sel_hi:[1,0]
	v_pk_mul_f32 v[180:181], v[180:181], v[206:207] op_sel_hi:[1,0]
	v_pk_mul_f32 v[182:183], v[182:183], v[206:207] op_sel_hi:[1,0]
	v_pk_mul_f32 v[176:177], v[176:177], v[168:169]
	v_pk_mul_f32 v[178:179], v[178:179], v[170:171]
	v_pk_mul_f32 v[180:181], v[180:181], v[172:173]
	v_pk_mul_f32 v[182:183], v[182:183], v[174:175]
	v_cvt_pk_bf16_f32 v160, v176, v177
	v_cvt_pk_bf16_f32 v161, v178, v179
	v_cvt_pk_bf16_f32 v162, v180, v181
	v_cvt_pk_bf16_f32 v163, v182, v183
	s_mov_b32 s6, 0x42000
	s_nop 1
	v_add_co_u32_e32 v146, vcc, s6, v150
	s_nop 0
	v_addc_co_u32_e32 v147, vcc, 0, v151, vcc
	global_store_dwordx4 v[146:147], v[160:163], off
	ds_read2_b32 v[146:147], v158 offset0:128 offset1:144
	s_mov_b32 s6, 0xb0000
	s_waitcnt lgkmcnt(0)
	v_mul_f32_e32 v184, 0xbfb8aa3b, v146
	v_mul_f32_e32 v206, v146, v146
	v_pk_mul_f32 v[168:169], v[60:61], v[184:185] op_sel_hi:[1,0]
	v_pk_mul_f32 v[170:171], v[62:63], v[184:185] op_sel_hi:[1,0]
	v_pk_mul_f32 v[172:173], v[56:57], v[184:185] op_sel_hi:[1,0]
	v_pk_mul_f32 v[174:175], v[58:59], v[184:185] op_sel_hi:[1,0]
	v_exp_f32_e32 v168, v168
	v_exp_f32_e32 v169, v169
	v_exp_f32_e32 v170, v170
	v_exp_f32_e32 v171, v171
	v_exp_f32_e32 v172, v172
	v_exp_f32_e32 v173, v173
	v_exp_f32_e32 v174, v174
	v_exp_f32_e32 v175, v175
	v_pk_mul_f32 v[176:177], v[60:61], v[28:29]
	v_pk_mul_f32 v[178:179], v[62:63], v[30:31]
	v_pk_mul_f32 v[180:181], v[56:57], v[24:25]
	v_pk_mul_f32 v[182:183], v[58:59], v[26:27]
	v_pk_add_f32 v[168:169], v[168:169], 1.0 op_sel_hi:[1,0]
	v_pk_add_f32 v[170:171], v[170:171], 1.0 op_sel_hi:[1,0]
	v_pk_add_f32 v[172:173], v[172:173], 1.0 op_sel_hi:[1,0]
	v_pk_add_f32 v[174:175], v[174:175], 1.0 op_sel_hi:[1,0]
	v_rcp_f32_e32 v168, v168
	v_rcp_f32_e32 v169, v169
	v_rcp_f32_e32 v170, v170
	v_rcp_f32_e32 v171, v171
	v_rcp_f32_e32 v172, v172
	v_rcp_f32_e32 v173, v173
	v_rcp_f32_e32 v174, v174
	v_rcp_f32_e32 v175, v175
	v_pk_mul_f32 v[176:177], v[176:177], v[206:207] op_sel_hi:[1,0]
	v_pk_mul_f32 v[178:179], v[178:179], v[206:207] op_sel_hi:[1,0]
	v_pk_mul_f32 v[180:181], v[180:181], v[206:207] op_sel_hi:[1,0]
	v_pk_mul_f32 v[182:183], v[182:183], v[206:207] op_sel_hi:[1,0]
	v_pk_mul_f32 v[176:177], v[176:177], v[168:169]
	v_pk_mul_f32 v[178:179], v[178:179], v[170:171]
	v_pk_mul_f32 v[180:181], v[180:181], v[172:173]
	v_pk_mul_f32 v[182:183], v[182:183], v[174:175]
	v_cvt_pk_bf16_f32 v160, v176, v177
	v_cvt_pk_bf16_f32 v161, v178, v179
	v_cvt_pk_bf16_f32 v162, v180, v181
	v_cvt_pk_bf16_f32 v163, v182, v183
	s_nop 1
	v_mov_b32_e32 v146, v147
	v_add_co_u32_e32 v148, vcc, s6, v150
	v_addc_co_u32_e32 v149, vcc, 0, v151, vcc
	global_store_dwordx4 v[148:149], v[160:163], off
	v_mul_f32_e32 v184, 0xbfb8aa3b, v146
	v_mul_f32_e32 v206, v146, v146
	v_pk_mul_f32 v[168:169], v[52:53], v[184:185] op_sel_hi:[1,0]
	v_pk_mul_f32 v[170:171], v[54:55], v[184:185] op_sel_hi:[1,0]
	v_pk_mul_f32 v[172:173], v[48:49], v[184:185] op_sel_hi:[1,0]
	v_pk_mul_f32 v[174:175], v[50:51], v[184:185] op_sel_hi:[1,0]
	v_exp_f32_e32 v168, v168
	v_exp_f32_e32 v169, v169
	v_exp_f32_e32 v170, v170
	v_exp_f32_e32 v171, v171
	v_exp_f32_e32 v172, v172
	v_exp_f32_e32 v173, v173
	v_exp_f32_e32 v174, v174
	v_exp_f32_e32 v175, v175
	v_pk_mul_f32 v[176:177], v[52:53], v[20:21]
	v_pk_mul_f32 v[178:179], v[54:55], v[22:23]
	v_pk_mul_f32 v[180:181], v[48:49], v[16:17]
	v_pk_mul_f32 v[182:183], v[50:51], v[18:19]
	v_pk_add_f32 v[168:169], v[168:169], 1.0 op_sel_hi:[1,0]
	v_pk_add_f32 v[170:171], v[170:171], 1.0 op_sel_hi:[1,0]
	v_pk_add_f32 v[172:173], v[172:173], 1.0 op_sel_hi:[1,0]
	v_pk_add_f32 v[174:175], v[174:175], 1.0 op_sel_hi:[1,0]
	v_rcp_f32_e32 v168, v168
	v_rcp_f32_e32 v169, v169
	v_rcp_f32_e32 v170, v170
	v_rcp_f32_e32 v171, v171
	v_rcp_f32_e32 v172, v172
	v_rcp_f32_e32 v173, v173
	v_rcp_f32_e32 v174, v174
	v_rcp_f32_e32 v175, v175
	v_pk_mul_f32 v[176:177], v[176:177], v[206:207] op_sel_hi:[1,0]
	v_pk_mul_f32 v[178:179], v[178:179], v[206:207] op_sel_hi:[1,0]
	v_pk_mul_f32 v[180:181], v[180:181], v[206:207] op_sel_hi:[1,0]
	v_pk_mul_f32 v[182:183], v[182:183], v[206:207] op_sel_hi:[1,0]
	v_pk_mul_f32 v[176:177], v[176:177], v[168:169]
	v_pk_mul_f32 v[178:179], v[178:179], v[170:171]
	v_pk_mul_f32 v[180:181], v[180:181], v[172:173]
	v_pk_mul_f32 v[182:183], v[182:183], v[174:175]
	v_cvt_pk_bf16_f32 v160, v176, v177
	v_cvt_pk_bf16_f32 v161, v178, v179
	v_cvt_pk_bf16_f32 v162, v180, v181
	v_cvt_pk_bf16_f32 v163, v182, v183
	s_mov_b32 s6, 0xc6000
	s_nop 1
	v_add_co_u32_e32 v146, vcc, s6, v150
	s_nop 0
	v_addc_co_u32_e32 v147, vcc, 0, v151, vcc
	global_store_dwordx4 v[146:147], v[160:163], off
	ds_read2_b32 v[146:147], v158 offset0:160 offset1:176
	s_mov_b32 s6, 0xdc000
	s_waitcnt lgkmcnt(0)
	v_mul_f32_e32 v184, 0xbfb8aa3b, v146
	v_mul_f32_e32 v206, v146, v146
	v_pk_mul_f32 v[168:169], v[44:45], v[184:185] op_sel_hi:[1,0]
	v_pk_mul_f32 v[170:171], v[46:47], v[184:185] op_sel_hi:[1,0]
	v_pk_mul_f32 v[172:173], v[40:41], v[184:185] op_sel_hi:[1,0]
	v_pk_mul_f32 v[174:175], v[42:43], v[184:185] op_sel_hi:[1,0]
	v_exp_f32_e32 v168, v168
	v_exp_f32_e32 v169, v169
	v_exp_f32_e32 v170, v170
	v_exp_f32_e32 v171, v171
	v_exp_f32_e32 v172, v172
	v_exp_f32_e32 v173, v173
	v_exp_f32_e32 v174, v174
	v_exp_f32_e32 v175, v175
	v_pk_mul_f32 v[176:177], v[44:45], v[12:13]
	v_pk_mul_f32 v[178:179], v[46:47], v[14:15]
	v_pk_mul_f32 v[180:181], v[40:41], v[8:9]
	v_pk_mul_f32 v[182:183], v[42:43], v[10:11]
	v_pk_add_f32 v[168:169], v[168:169], 1.0 op_sel_hi:[1,0]
	v_pk_add_f32 v[170:171], v[170:171], 1.0 op_sel_hi:[1,0]
	v_pk_add_f32 v[172:173], v[172:173], 1.0 op_sel_hi:[1,0]
	v_pk_add_f32 v[174:175], v[174:175], 1.0 op_sel_hi:[1,0]
	v_rcp_f32_e32 v168, v168
	v_rcp_f32_e32 v169, v169
	v_rcp_f32_e32 v170, v170
	v_rcp_f32_e32 v171, v171
	v_rcp_f32_e32 v172, v172
	v_rcp_f32_e32 v173, v173
	v_rcp_f32_e32 v174, v174
	v_rcp_f32_e32 v175, v175
	v_pk_mul_f32 v[176:177], v[176:177], v[206:207] op_sel_hi:[1,0]
	v_pk_mul_f32 v[178:179], v[178:179], v[206:207] op_sel_hi:[1,0]
	v_pk_mul_f32 v[180:181], v[180:181], v[206:207] op_sel_hi:[1,0]
	v_pk_mul_f32 v[182:183], v[182:183], v[206:207] op_sel_hi:[1,0]
	v_pk_mul_f32 v[176:177], v[176:177], v[168:169]
	v_pk_mul_f32 v[178:179], v[178:179], v[170:171]
	v_pk_mul_f32 v[180:181], v[180:181], v[172:173]
	v_pk_mul_f32 v[182:183], v[182:183], v[174:175]
	v_cvt_pk_bf16_f32 v158, v176, v177
	v_cvt_pk_bf16_f32 v159, v178, v179
	v_cvt_pk_bf16_f32 v160, v180, v181
	v_cvt_pk_bf16_f32 v161, v182, v183
	s_nop 1
	v_mov_b32_e32 v146, v147
	v_add_co_u32_e32 v148, vcc, s6, v150
	v_addc_co_u32_e32 v149, vcc, 0, v151, vcc
	global_store_dwordx4 v[148:149], v[158:161], off
	v_mul_f32_e32 v184, 0xbfb8aa3b, v146
	v_mul_f32_e32 v206, v146, v146
	v_pk_mul_f32 v[168:169], v[36:37], v[184:185] op_sel_hi:[1,0]
	v_pk_mul_f32 v[170:171], v[38:39], v[184:185] op_sel_hi:[1,0]
	v_pk_mul_f32 v[172:173], v[32:33], v[184:185] op_sel_hi:[1,0]
	v_pk_mul_f32 v[174:175], v[34:35], v[184:185] op_sel_hi:[1,0]
	v_exp_f32_e32 v168, v168
	v_exp_f32_e32 v169, v169
	v_exp_f32_e32 v170, v170
	v_exp_f32_e32 v171, v171
	v_exp_f32_e32 v172, v172
	v_exp_f32_e32 v173, v173
	v_exp_f32_e32 v174, v174
	v_exp_f32_e32 v175, v175
	v_pk_mul_f32 v[176:177], v[36:37], v[4:5]
	v_pk_mul_f32 v[178:179], v[38:39], v[6:7]
	v_pk_mul_f32 v[180:181], v[32:33], v[0:1]
	v_pk_mul_f32 v[182:183], v[34:35], v[2:3]
	v_pk_add_f32 v[168:169], v[168:169], 1.0 op_sel_hi:[1,0]
	v_pk_add_f32 v[170:171], v[170:171], 1.0 op_sel_hi:[1,0]
	v_pk_add_f32 v[172:173], v[172:173], 1.0 op_sel_hi:[1,0]
	v_pk_add_f32 v[174:175], v[174:175], 1.0 op_sel_hi:[1,0]
	v_rcp_f32_e32 v168, v168
	v_rcp_f32_e32 v169, v169
	v_rcp_f32_e32 v170, v170
	v_rcp_f32_e32 v171, v171
	v_rcp_f32_e32 v172, v172
	v_rcp_f32_e32 v173, v173
	v_rcp_f32_e32 v174, v174
	v_rcp_f32_e32 v175, v175
	v_pk_mul_f32 v[176:177], v[176:177], v[206:207] op_sel_hi:[1,0]
	v_pk_mul_f32 v[178:179], v[178:179], v[206:207] op_sel_hi:[1,0]
	v_pk_mul_f32 v[180:181], v[180:181], v[206:207] op_sel_hi:[1,0]
	v_pk_mul_f32 v[182:183], v[182:183], v[206:207] op_sel_hi:[1,0]
	v_pk_mul_f32 v[176:177], v[176:177], v[168:169]
	v_pk_mul_f32 v[178:179], v[178:179], v[170:171]
	v_pk_mul_f32 v[180:181], v[180:181], v[172:173]
	v_pk_mul_f32 v[182:183], v[182:183], v[174:175]
	v_cvt_pk_bf16_f32 v158, v176, v177
	v_cvt_pk_bf16_f32 v159, v178, v179
	v_cvt_pk_bf16_f32 v160, v180, v181
	v_cvt_pk_bf16_f32 v161, v182, v183
	s_nop 1
	v_add_co_u32_e32 v146, vcc, 0xf2000, v150
	s_nop 0
	v_addc_co_u32_e32 v147, vcc, 0, v151, vcc
	s_andn2_b64 vcc, exec, s[44:45]
	global_store_dwordx4 v[146:147], v[158:161], off
	s_cbranch_vccz .LBB0_73
	s_mov_b64 s[46:47], s[50:51]
	s_andn2_b64 vcc, exec, s[42:43]
	s_mov_b64 s[50:51], s[46:47]
	s_cbranch_vccnz .LBB0_74

.Lm4ap_103:
	s_waitcnt lgkmcnt(0)
	s_barrier
	s_nop 0
	v_mfma_f32_16x16x32_bf16 v[124:127], v[128:131], v[162:165], 0
	v_mfma_f32_16x16x32_bf16 v[120:123], v[136:139], v[162:165], 0
	v_mfma_f32_16x16x32_bf16 v[108:111], v[128:131], v[170:173], 0
	v_mfma_f32_16x16x32_bf16 v[104:107], v[136:139], v[170:173], 0
	v_mfma_f32_16x16x32_bf16 v[96:99], v[128:131], v[178:181], 0
	v_mfma_f32_16x16x32_bf16 v[88:91], v[136:139], v[178:181], 0
	v_mfma_f32_16x16x32_bf16 v[84:87], v[128:131], v[194:197], 0
	v_mfma_f32_16x16x32_bf16 v[80:83], v[136:139], v[194:197], 0
	v_mfma_f32_16x16x32_bf16 v[124:127], v[132:135], v[166:169], v[124:127]
	v_mfma_f32_16x16x32_bf16 v[120:123], v[146:149], v[166:169], v[120:123]
	v_mfma_f32_16x16x32_bf16 v[108:111], v[132:135], v[174:177], v[108:111]
	v_mfma_f32_16x16x32_bf16 v[104:107], v[146:149], v[174:177], v[104:107]
	v_mfma_f32_16x16x32_bf16 v[96:99], v[132:135], v[182:185], v[96:99]
	v_mfma_f32_16x16x32_bf16 v[88:91], v[146:149], v[182:185], v[88:91]
	v_mfma_f32_16x16x32_bf16 v[84:87], v[132:135], v[210:213], v[84:87]
	v_mfma_f32_16x16x32_bf16 v[80:83], v[146:149], v[210:213], v[80:83]
	v_mfma_f32_16x16x32_bf16 v[116:119], v[214:217], v[162:165], 0
	v_mfma_f32_16x16x32_bf16 v[112:115], v[222:225], v[162:165], 0
	v_mfma_f32_16x16x32_bf16 v[100:103], v[214:217], v[170:173], 0
	v_mfma_f32_16x16x32_bf16 v[92:95], v[222:225], v[170:173], 0
	v_mfma_f32_16x16x32_bf16 v[76:79], v[214:217], v[178:181], 0
	v_mfma_f32_16x16x32_bf16 v[72:75], v[222:225], v[178:181], 0
	v_mfma_f32_16x16x32_bf16 v[68:71], v[214:217], v[194:197], 0
	v_mfma_f32_16x16x32_bf16 v[64:67], v[222:225], v[194:197], 0
	v_mfma_f32_16x16x32_bf16 v[116:119], v[218:221], v[166:169], v[116:119]
	v_mfma_f32_16x16x32_bf16 v[112:115], v[226:229], v[166:169], v[112:115]
	v_mfma_f32_16x16x32_bf16 v[100:103], v[218:221], v[174:177], v[100:103]
	v_mfma_f32_16x16x32_bf16 v[92:95], v[226:229], v[174:177], v[92:95]
	v_mfma_f32_16x16x32_bf16 v[76:79], v[218:221], v[182:185], v[76:79]
	v_mfma_f32_16x16x32_bf16 v[72:75], v[226:229], v[182:185], v[72:75]
	v_mfma_f32_16x16x32_bf16 v[68:71], v[218:221], v[210:213], v[68:71]
	v_mfma_f32_16x16x32_bf16 v[64:67], v[226:229], v[210:213], v[64:67]
	s_barrier
	s_add_i32 s19, s23, s71
	v_lshl_add_u64 v[192:193], s[58:59], 0, v[140:141]
	s_mov_b32 m0, s19
	v_lshl_add_u64 v[230:231], s[58:59], 0, v[150:151]
	global_load_lds_dwordx4 v[192:193], off
	s_add_i32 m0, s19, 0x2000
	s_nop 0
	global_load_lds_dwordx4 v[230:231], off
	s_mov_b32 m0, s72
	v_lshl_add_u64 v[232:233], s[68:69], 0, v[154:155]
	ds_read_b128 v[162:165], v208 offset:16384
	ds_read_b128 v[166:169], v208 offset:17408
	ds_read_b128 v[170:173], v208 offset:18432
	ds_read_b128 v[174:177], v208 offset:19456
	ds_read_b128 v[178:181], v208 offset:20480
	ds_read_b128 v[182:185], v208 offset:21504
	ds_read_b128 v[194:197], v208 offset:22528
	ds_read_b128 v[210:213], v208 offset:23552
	global_load_lds_dwordx4 v[232:233], off
	v_lshl_add_u64 v[234:235], s[68:69], 0, v[152:153]
	s_mov_b32 m0, s73
	s_nop 0
	global_load_lds_dwordx4 v[234:235], off
	s_add_u32 s86, s58, 0x40000
	s_addc_u32 s87, s59, 0
	s_add_i32 s6, s6, s71
	v_lshl_add_u64 v[250:251], s[86:87], 0, v[140:141]
	s_mov_b32 m0, s6
	s_nop 0
	global_load_lds_dwordx4 v[250:251], off
	v_lshl_add_u64 v[250:251], s[86:87], 0, v[150:151]
	s_add_i32 m0, s6, 0x2000
	s_nop 0
	global_load_lds_dwordx4 v[250:251], off
	s_waitcnt vmcnt(40)
	s_cmp_lg_u32 s100, 0
	s_cbranch_scc1 .Lm4bp_103
	s_waitcnt vmcnt(8)
.Lm4bp_103:
	s_waitcnt lgkmcnt(0)
	s_mov_b32 s100, 0
	s_barrier
	s_nop 0
	v_mfma_f32_16x16x32_bf16 v[60:63], v[128:131], v[162:165], 0
	v_mfma_f32_16x16x32_bf16 v[56:59], v[136:139], v[162:165], 0
	v_mfma_f32_16x16x32_bf16 v[48:51], v[128:131], v[170:173], 0
	v_mfma_f32_16x16x32_bf16 v[40:43], v[136:139], v[170:173], 0
	v_mfma_f32_16x16x32_bf16 v[32:35], v[128:131], v[178:181], 0
	v_mfma_f32_16x16x32_bf16 v[24:27], v[136:139], v[178:181], 0
	v_mfma_f32_16x16x32_bf16 v[16:19], v[128:131], v[194:197], 0
	v_mfma_f32_16x16x32_bf16 v[8:11], v[136:139], v[194:197], 0
	v_mfma_f32_16x16x32_bf16 v[60:63], v[132:135], v[166:169], v[60:63]
	v_mfma_f32_16x16x32_bf16 v[56:59], v[146:149], v[166:169], v[56:59]
	v_mfma_f32_16x16x32_bf16 v[48:51], v[132:135], v[174:177], v[48:51]
	v_mfma_f32_16x16x32_bf16 v[40:43], v[146:149], v[174:177], v[40:43]
	v_mfma_f32_16x16x32_bf16 v[32:35], v[132:135], v[182:185], v[32:35]
	v_mfma_f32_16x16x32_bf16 v[24:27], v[146:149], v[182:185], v[24:27]
	v_mfma_f32_16x16x32_bf16 v[16:19], v[132:135], v[210:213], v[16:19]
	v_mfma_f32_16x16x32_bf16 v[8:11], v[146:149], v[210:213], v[8:11]
	v_mfma_f32_16x16x32_bf16 v[52:55], v[214:217], v[162:165], 0
	v_mfma_f32_16x16x32_bf16 v[44:47], v[222:225], v[162:165], 0
	v_mfma_f32_16x16x32_bf16 v[36:39], v[214:217], v[170:173], 0
	v_mfma_f32_16x16x32_bf16 v[28:31], v[222:225], v[170:173], 0
	v_mfma_f32_16x16x32_bf16 v[20:23], v[214:217], v[178:181], 0
	v_mfma_f32_16x16x32_bf16 v[12:15], v[222:225], v[178:181], 0
	v_mfma_f32_16x16x32_bf16 v[4:7], v[214:217], v[194:197], 0
	v_mfma_f32_16x16x32_bf16 v[0:3], v[222:225], v[194:197], 0
	v_mfma_f32_16x16x32_bf16 v[52:55], v[218:221], v[166:169], v[52:55]
	v_mfma_f32_16x16x32_bf16 v[44:47], v[226:229], v[166:169], v[44:47]
	v_mfma_f32_16x16x32_bf16 v[36:39], v[218:221], v[174:177], v[36:39]
	v_mfma_f32_16x16x32_bf16 v[28:31], v[226:229], v[174:177], v[28:31]
	v_mfma_f32_16x16x32_bf16 v[20:23], v[218:221], v[182:185], v[20:23]
	v_mfma_f32_16x16x32_bf16 v[12:15], v[226:229], v[182:185], v[12:15]
	v_mfma_f32_16x16x32_bf16 v[4:7], v[218:221], v[210:213], v[4:7]
	v_mfma_f32_16x16x32_bf16 v[0:3], v[226:229], v[210:213], v[0:3]
	s_barrier
	s_add_i32 s6, 0, 0x18000
	v_add_u32_e32 v146, s6, v206
	ds_read_b128 v[128:131], v146
	ds_read_b128 v[132:135], v146 offset:1024
	ds_read_b128 v[136:139], v146 offset:2048
	ds_read_b128 v[146:149], v146 offset:3072
	s_add_u32 s68, s68, 0x40000
	s_addc_u32 s69, s69, 0
	s_mov_b32 m0, s74
	v_lshl_add_u64 v[214:215], s[68:69], 0, v[154:155]
	ds_read_b128 v[162:165], v208 offset:32768
	ds_read_b128 v[166:169], v208 offset:33792
	ds_read_b128 v[170:173], v208 offset:34816
	ds_read_b128 v[174:177], v208 offset:35840
	ds_read_b128 v[178:181], v208 offset:36864
	ds_read_b128 v[182:185], v208 offset:37888
	ds_read_b128 v[194:197], v208 offset:38912
	ds_read_b128 v[210:213], v208 offset:39936
	global_load_lds_dwordx4 v[214:215], off
	v_lshl_add_u64 v[214:215], s[68:69], 0, v[152:153]
	s_mov_b32 m0, s75
	s_nop 0
	global_load_lds_dwordx4 v[214:215], off
	s_add_i32 s19, 0, 0x1c000
	v_add_u32_e32 v209, s19, v206
	ds_read_b128 v[214:217], v209
	ds_read_b128 v[218:221], v209 offset:1024
	ds_read_b128 v[222:225], v209 offset:2048
	ds_read_b128 v[226:229], v209 offset:3072
	s_waitcnt vmcnt(8)
	s_waitcnt lgkmcnt(0)
	s_barrier
	v_mfma_f32_16x16x32_bf16 v[124:127], v[128:131], v[162:165], v[124:127]
	v_mfma_f32_16x16x32_bf16 v[120:123], v[136:139], v[162:165], v[120:123]
	v_mfma_f32_16x16x32_bf16 v[108:111], v[128:131], v[170:173], v[108:111]
	v_mfma_f32_16x16x32_bf16 v[104:107], v[136:139], v[170:173], v[104:107]
	v_mfma_f32_16x16x32_bf16 v[96:99], v[128:131], v[178:181], v[96:99]
	v_mfma_f32_16x16x32_bf16 v[88:91], v[136:139], v[178:181], v[88:91]
	v_mfma_f32_16x16x32_bf16 v[84:87], v[128:131], v[194:197], v[84:87]
	v_mfma_f32_16x16x32_bf16 v[80:83], v[136:139], v[194:197], v[80:83]
	v_mfma_f32_16x16x32_bf16 v[124:127], v[132:135], v[166:169], v[124:127]
	v_mfma_f32_16x16x32_bf16 v[120:123], v[146:149], v[166:169], v[120:123]
	v_mfma_f32_16x16x32_bf16 v[108:111], v[132:135], v[174:177], v[108:111]
	v_mfma_f32_16x16x32_bf16 v[104:107], v[146:149], v[174:177], v[104:107]
	v_mfma_f32_16x16x32_bf16 v[96:99], v[132:135], v[182:185], v[96:99]
	v_mfma_f32_16x16x32_bf16 v[88:91], v[146:149], v[182:185], v[88:91]
	v_mfma_f32_16x16x32_bf16 v[84:87], v[132:135], v[210:213], v[84:87]
	v_mfma_f32_16x16x32_bf16 v[80:83], v[146:149], v[210:213], v[80:83]
	v_mfma_f32_16x16x32_bf16 v[116:119], v[214:217], v[162:165], v[116:119]
	v_mfma_f32_16x16x32_bf16 v[112:115], v[222:225], v[162:165], v[112:115]
	v_mfma_f32_16x16x32_bf16 v[100:103], v[214:217], v[170:173], v[100:103]
	v_mfma_f32_16x16x32_bf16 v[92:95], v[222:225], v[170:173], v[92:95]
	v_mfma_f32_16x16x32_bf16 v[76:79], v[214:217], v[178:181], v[76:79]
	v_mfma_f32_16x16x32_bf16 v[72:75], v[222:225], v[178:181], v[72:75]
	v_mfma_f32_16x16x32_bf16 v[68:71], v[214:217], v[194:197], v[68:71]
	v_mfma_f32_16x16x32_bf16 v[64:67], v[222:225], v[194:197], v[64:67]
	v_mfma_f32_16x16x32_bf16 v[116:119], v[218:221], v[166:169], v[116:119]
	v_mfma_f32_16x16x32_bf16 v[112:115], v[226:229], v[166:169], v[112:115]
	v_mfma_f32_16x16x32_bf16 v[100:103], v[218:221], v[174:177], v[100:103]
	v_mfma_f32_16x16x32_bf16 v[92:95], v[226:229], v[174:177], v[92:95]
	v_mfma_f32_16x16x32_bf16 v[76:79], v[218:221], v[182:185], v[76:79]
	v_mfma_f32_16x16x32_bf16 v[72:75], v[226:229], v[182:185], v[72:75]
	v_mfma_f32_16x16x32_bf16 v[68:71], v[218:221], v[210:213], v[68:71]
	v_mfma_f32_16x16x32_bf16 v[64:67], v[226:229], v[210:213], v[64:67]
	s_barrier
	s_add_i32 s6, s6, s71
	v_lshl_add_u64 v[192:193], v[192:193], 0, s[36:37]
	s_mov_b32 m0, s6
	s_nop 0
	global_load_lds_dwordx4 v[192:193], off
	v_lshl_add_u64 v[192:193], v[230:231], 0, s[36:37]
	s_add_i32 m0, s6, 0x2000
	s_nop 0
	global_load_lds_dwordx4 v[192:193], off
	s_mov_b32 m0, s80
	v_lshl_add_u64 v[192:193], v[232:233], 0, s[36:37]
	ds_read_b128 v[162:165], v208 offset:49152
	ds_read_b128 v[166:169], v208 offset:50176
	ds_read_b128 v[170:173], v208 offset:51200
	ds_read_b128 v[174:177], v208 offset:52224
	ds_read_b128 v[178:181], v208 offset:53248
	ds_read_b128 v[182:185], v208 offset:54272
	ds_read_b128 v[194:197], v208 offset:55296
	ds_read_b128 v[210:213], v208 offset:56320
	global_load_lds_dwordx4 v[192:193], off
	v_lshl_add_u64 v[192:193], v[234:235], 0, s[36:37]
	s_mov_b32 m0, s81
	s_nop 0
	global_load_lds_dwordx4 v[192:193], off
	s_add_u32 s58, s58, 0x40080
	s_addc_u32 s59, s59, 0
	s_add_i32 s6, s19, s71
	v_lshl_add_u64 v[250:251], s[58:59], 0, v[140:141]
	s_mov_b32 m0, s6
	s_nop 0
	global_load_lds_dwordx4 v[250:251], off
	v_lshl_add_u64 v[250:251], s[58:59], 0, v[150:151]
	s_add_i32 m0, s6, 0x2000
	s_nop 0
	global_load_lds_dwordx4 v[250:251], off
	s_waitcnt vmcnt(8)
	s_waitcnt lgkmcnt(0)
	s_barrier
	v_mfma_f32_16x16x32_bf16 v[60:63], v[128:131], v[162:165], v[60:63]
	v_mfma_f32_16x16x32_bf16 v[56:59], v[136:139], v[162:165], v[56:59]
	v_mfma_f32_16x16x32_bf16 v[48:51], v[128:131], v[170:173], v[48:51]
	v_mfma_f32_16x16x32_bf16 v[40:43], v[136:139], v[170:173], v[40:43]
	v_mfma_f32_16x16x32_bf16 v[32:35], v[128:131], v[178:181], v[32:35]
	v_mfma_f32_16x16x32_bf16 v[24:27], v[136:139], v[178:181], v[24:27]
	v_mfma_f32_16x16x32_bf16 v[16:19], v[128:131], v[194:197], v[16:19]
	v_mfma_f32_16x16x32_bf16 v[8:11], v[136:139], v[194:197], v[8:11]
	v_mfma_f32_16x16x32_bf16 v[60:63], v[132:135], v[166:169], v[60:63]
	v_mfma_f32_16x16x32_bf16 v[56:59], v[146:149], v[166:169], v[56:59]
	v_mfma_f32_16x16x32_bf16 v[48:51], v[132:135], v[174:177], v[48:51]
	v_mfma_f32_16x16x32_bf16 v[40:43], v[146:149], v[174:177], v[40:43]
	v_mfma_f32_16x16x32_bf16 v[32:35], v[132:135], v[182:185], v[32:35]
	v_mfma_f32_16x16x32_bf16 v[24:27], v[146:149], v[182:185], v[24:27]
	v_mfma_f32_16x16x32_bf16 v[16:19], v[132:135], v[210:213], v[16:19]
	v_mfma_f32_16x16x32_bf16 v[8:11], v[146:149], v[210:213], v[8:11]
	v_mfma_f32_16x16x32_bf16 v[52:55], v[214:217], v[162:165], v[52:55]
	v_mfma_f32_16x16x32_bf16 v[44:47], v[222:225], v[162:165], v[44:47]
	v_mfma_f32_16x16x32_bf16 v[36:39], v[214:217], v[170:173], v[36:39]
	v_mfma_f32_16x16x32_bf16 v[28:31], v[222:225], v[170:173], v[28:31]
	v_mfma_f32_16x16x32_bf16 v[20:23], v[214:217], v[178:181], v[20:23]
	v_mfma_f32_16x16x32_bf16 v[12:15], v[222:225], v[178:181], v[12:15]
	v_mfma_f32_16x16x32_bf16 v[4:7], v[214:217], v[194:197], v[4:7]
	v_mfma_f32_16x16x32_bf16 v[0:3], v[222:225], v[194:197], v[0:3]
	v_mfma_f32_16x16x32_bf16 v[52:55], v[218:221], v[166:169], v[52:55]
	v_mfma_f32_16x16x32_bf16 v[44:47], v[226:229], v[166:169], v[44:47]
	v_mfma_f32_16x16x32_bf16 v[36:39], v[218:221], v[174:177], v[36:39]
	v_mfma_f32_16x16x32_bf16 v[28:31], v[226:229], v[174:177], v[28:31]
	v_mfma_f32_16x16x32_bf16 v[20:23], v[218:221], v[182:185], v[20:23]
	v_mfma_f32_16x16x32_bf16 v[12:15], v[226:229], v[182:185], v[12:15]
	v_mfma_f32_16x16x32_bf16 v[4:7], v[218:221], v[210:213], v[4:7]
	v_mfma_f32_16x16x32_bf16 v[0:3], v[226:229], v[210:213], v[0:3]
	s_add_i32 s12, s12, 2
	s_add_u32 s54, s54, 0x100
	s_addc_u32 s55, s55, 0
	s_add_u32 s10, s10, 0x100
	s_addc_u32 s11, s11, 0
	s_cmp_gt_u32 s12, 13
	s_barrier
.LBB0_103:
	s_add_u32 s6, s54, 0xfffc0080
	s_addc_u32 s19, s55, -1
	s_add_i32 s23, 0, 0x10000
	v_add_u32_e32 v146, s23, v206
	ds_read_b128 v[128:131], v146
	ds_read_b128 v[132:135], v146 offset:1024
	ds_read_b128 v[136:139], v146 offset:2048
	ds_read_b128 v[146:149], v146 offset:3072
	s_cmp_eq_u32 s12, 12
	s_cselect_b32 s69, s47, s19
	s_cselect_b32 s68, s46, s6
	s_cselect_b32 s59, s49, s11
	s_cselect_b32 s58, s48, s10
	v_lshl_add_u64 v[192:193], s[54:55], 0, v[158:159]
	s_add_i32 m0, s72, 0xc000
	ds_read_b128 v[162:165], v208
	ds_read_b128 v[166:169], v208 offset:1024
	ds_read_b128 v[170:173], v208 offset:2048
	ds_read_b128 v[174:177], v208 offset:3072
	ds_read_b128 v[178:181], v208 offset:4096
	ds_read_b128 v[182:185], v208 offset:5120
	ds_read_b128 v[194:197], v208 offset:6144
	ds_read_b128 v[210:213], v208 offset:7168
	global_load_lds_dwordx4 v[192:193], off
	v_lshl_add_u64 v[192:193], s[54:55], 0, v[160:161]
	s_add_i32 m0, s72, 0xe000
	s_nop 0
	global_load_lds_dwordx4 v[192:193], off
	s_add_i32 s6, 0, 0x14000
	v_add_u32_e32 v192, s6, v206
	ds_read_b128 v[214:217], v192
	ds_read_b128 v[218:221], v192 offset:1024
	ds_read_b128 v[222:225], v192 offset:2048
	ds_read_b128 v[226:229], v192 offset:3072
	s_nop 0
	s_waitcnt vmcnt(8)
	s_waitcnt lgkmcnt(0)
	s_barrier
	v_mfma_f32_16x16x32_bf16 v[124:127], v[128:131], v[162:165], v[124:127]
	v_mfma_f32_16x16x32_bf16 v[120:123], v[136:139], v[162:165], v[120:123]
	v_mfma_f32_16x16x32_bf16 v[108:111], v[128:131], v[170:173], v[108:111]
	v_mfma_f32_16x16x32_bf16 v[104:107], v[136:139], v[170:173], v[104:107]
	v_mfma_f32_16x16x32_bf16 v[96:99], v[128:131], v[178:181], v[96:99]
	v_mfma_f32_16x16x32_bf16 v[88:91], v[136:139], v[178:181], v[88:91]
	v_mfma_f32_16x16x32_bf16 v[84:87], v[128:131], v[194:197], v[84:87]
	v_mfma_f32_16x16x32_bf16 v[80:83], v[136:139], v[194:197], v[80:83]
	v_mfma_f32_16x16x32_bf16 v[124:127], v[132:135], v[166:169], v[124:127]
	v_mfma_f32_16x16x32_bf16 v[120:123], v[146:149], v[166:169], v[120:123]
	v_mfma_f32_16x16x32_bf16 v[108:111], v[132:135], v[174:177], v[108:111]
	v_mfma_f32_16x16x32_bf16 v[104:107], v[146:149], v[174:177], v[104:107]
	v_mfma_f32_16x16x32_bf16 v[96:99], v[132:135], v[182:185], v[96:99]
	v_mfma_f32_16x16x32_bf16 v[88:91], v[146:149], v[182:185], v[88:91]
	v_mfma_f32_16x16x32_bf16 v[84:87], v[132:135], v[210:213], v[84:87]
	v_mfma_f32_16x16x32_bf16 v[80:83], v[146:149], v[210:213], v[80:83]
	v_mfma_f32_16x16x32_bf16 v[116:119], v[214:217], v[162:165], v[116:119]
	v_mfma_f32_16x16x32_bf16 v[112:115], v[222:225], v[162:165], v[112:115]
	v_mfma_f32_16x16x32_bf16 v[100:103], v[214:217], v[170:173], v[100:103]
	v_mfma_f32_16x16x32_bf16 v[92:95], v[222:225], v[170:173], v[92:95]
	v_mfma_f32_16x16x32_bf16 v[76:79], v[214:217], v[178:181], v[76:79]
	v_mfma_f32_16x16x32_bf16 v[72:75], v[222:225], v[178:181], v[72:75]
	v_mfma_f32_16x16x32_bf16 v[68:71], v[214:217], v[194:197], v[68:71]
	v_mfma_f32_16x16x32_bf16 v[64:67], v[222:225], v[194:197], v[64:67]
	v_mfma_f32_16x16x32_bf16 v[116:119], v[218:221], v[166:169], v[116:119]
	v_mfma_f32_16x16x32_bf16 v[112:115], v[226:229], v[166:169], v[112:115]
	v_mfma_f32_16x16x32_bf16 v[100:103], v[218:221], v[174:177], v[100:103]
	v_mfma_f32_16x16x32_bf16 v[92:95], v[226:229], v[174:177], v[92:95]
	v_mfma_f32_16x16x32_bf16 v[76:79], v[218:221], v[182:185], v[76:79]
	v_mfma_f32_16x16x32_bf16 v[72:75], v[226:229], v[182:185], v[72:75]
	v_mfma_f32_16x16x32_bf16 v[68:71], v[218:221], v[210:213], v[68:71]
	v_mfma_f32_16x16x32_bf16 v[64:67], v[226:229], v[210:213], v[64:67]
	s_barrier
	s_add_i32 s19, s23, s71
	v_lshl_add_u64 v[192:193], s[58:59], 0, v[140:141]
	s_mov_b32 m0, s19
	v_lshl_add_u64 v[230:231], s[58:59], 0, v[150:151]
	global_load_lds_dwordx4 v[192:193], off
	s_add_i32 m0, s19, 0x2000
	s_nop 0
	global_load_lds_dwordx4 v[230:231], off
	s_mov_b32 m0, s72
	v_lshl_add_u64 v[232:233], s[68:69], 0, v[154:155]
	ds_read_b128 v[162:165], v208 offset:16384
	ds_read_b128 v[166:169], v208 offset:17408
	ds_read_b128 v[170:173], v208 offset:18432
	ds_read_b128 v[174:177], v208 offset:19456
	ds_read_b128 v[178:181], v208 offset:20480
	ds_read_b128 v[182:185], v208 offset:21504
	ds_read_b128 v[194:197], v208 offset:22528
	ds_read_b128 v[210:213], v208 offset:23552
	global_load_lds_dwordx4 v[232:233], off
	v_lshl_add_u64 v[234:235], s[68:69], 0, v[152:153]
	s_mov_b32 m0, s73
	s_nop 0
	global_load_lds_dwordx4 v[234:235], off
	s_add_u32 s86, s58, 0x40000
	s_addc_u32 s87, s59, 0
	s_add_i32 s6, s6, s71
	v_lshl_add_u64 v[250:251], s[86:87], 0, v[140:141]
	s_mov_b32 m0, s6
	s_nop 0
	global_load_lds_dwordx4 v[250:251], off
	v_lshl_add_u64 v[250:251], s[86:87], 0, v[150:151]
	s_add_i32 m0, s6, 0x2000
	s_nop 0
	global_load_lds_dwordx4 v[250:251], off
	s_nop 0
	s_waitcnt vmcnt(8)
	s_waitcnt lgkmcnt(0)
	s_barrier
	v_mfma_f32_16x16x32_bf16 v[60:63], v[128:131], v[162:165], v[60:63]
	v_mfma_f32_16x16x32_bf16 v[56:59], v[136:139], v[162:165], v[56:59]
	v_mfma_f32_16x16x32_bf16 v[48:51], v[128:131], v[170:173], v[48:51]
	v_mfma_f32_16x16x32_bf16 v[40:43], v[136:139], v[170:173], v[40:43]
	v_mfma_f32_16x16x32_bf16 v[32:35], v[128:131], v[178:181], v[32:35]
	v_mfma_f32_16x16x32_bf16 v[24:27], v[136:139], v[178:181], v[24:27]
	v_mfma_f32_16x16x32_bf16 v[16:19], v[128:131], v[194:197], v[16:19]
	v_mfma_f32_16x16x32_bf16 v[8:11], v[136:139], v[194:197], v[8:11]
	v_mfma_f32_16x16x32_bf16 v[60:63], v[132:135], v[166:169], v[60:63]
	v_mfma_f32_16x16x32_bf16 v[56:59], v[146:149], v[166:169], v[56:59]
	v_mfma_f32_16x16x32_bf16 v[48:51], v[132:135], v[174:177], v[48:51]
	v_mfma_f32_16x16x32_bf16 v[40:43], v[146:149], v[174:177], v[40:43]
	v_mfma_f32_16x16x32_bf16 v[32:35], v[132:135], v[182:185], v[32:35]
	v_mfma_f32_16x16x32_bf16 v[24:27], v[146:149], v[182:185], v[24:27]
	v_mfma_f32_16x16x32_bf16 v[16:19], v[132:135], v[210:213], v[16:19]
	v_mfma_f32_16x16x32_bf16 v[8:11], v[146:149], v[210:213], v[8:11]
	v_mfma_f32_16x16x32_bf16 v[52:55], v[214:217], v[162:165], v[52:55]
	v_mfma_f32_16x16x32_bf16 v[44:47], v[222:225], v[162:165], v[44:47]
	v_mfma_f32_16x16x32_bf16 v[36:39], v[214:217], v[170:173], v[36:39]
	v_mfma_f32_16x16x32_bf16 v[28:31], v[222:225], v[170:173], v[28:31]
	v_mfma_f32_16x16x32_bf16 v[20:23], v[214:217], v[178:181], v[20:23]
	v_mfma_f32_16x16x32_bf16 v[12:15], v[222:225], v[178:181], v[12:15]
	v_mfma_f32_16x16x32_bf16 v[4:7], v[214:217], v[194:197], v[4:7]
	v_mfma_f32_16x16x32_bf16 v[0:3], v[222:225], v[194:197], v[0:3]
	v_mfma_f32_16x16x32_bf16 v[52:55], v[218:221], v[166:169], v[52:55]
	v_mfma_f32_16x16x32_bf16 v[44:47], v[226:229], v[166:169], v[44:47]
	v_mfma_f32_16x16x32_bf16 v[36:39], v[218:221], v[174:177], v[36:39]
	v_mfma_f32_16x16x32_bf16 v[28:31], v[226:229], v[174:177], v[28:31]
	v_mfma_f32_16x16x32_bf16 v[20:23], v[218:221], v[182:185], v[20:23]
	v_mfma_f32_16x16x32_bf16 v[12:15], v[226:229], v[182:185], v[12:15]
	v_mfma_f32_16x16x32_bf16 v[4:7], v[218:221], v[210:213], v[4:7]
	v_mfma_f32_16x16x32_bf16 v[0:3], v[226:229], v[210:213], v[0:3]
	s_barrier
	s_add_i32 s6, 0, 0x18000
	v_add_u32_e32 v146, s6, v206
	ds_read_b128 v[128:131], v146
	ds_read_b128 v[132:135], v146 offset:1024
	ds_read_b128 v[136:139], v146 offset:2048
	ds_read_b128 v[146:149], v146 offset:3072
	s_add_u32 s68, s68, 0x40000
	s_addc_u32 s69, s69, 0
	s_mov_b32 m0, s74
	v_lshl_add_u64 v[214:215], s[68:69], 0, v[154:155]
	ds_read_b128 v[162:165], v208 offset:32768
	ds_read_b128 v[166:169], v208 offset:33792
	ds_read_b128 v[170:173], v208 offset:34816
	ds_read_b128 v[174:177], v208 offset:35840
	ds_read_b128 v[178:181], v208 offset:36864
	ds_read_b128 v[182:185], v208 offset:37888
	ds_read_b128 v[194:197], v208 offset:38912
	ds_read_b128 v[210:213], v208 offset:39936
	global_load_lds_dwordx4 v[214:215], off
	v_lshl_add_u64 v[214:215], s[68:69], 0, v[152:153]
	s_mov_b32 m0, s75
	s_nop 0
	global_load_lds_dwordx4 v[214:215], off
	s_add_i32 s19, 0, 0x1c000
	v_add_u32_e32 v209, s19, v206
	ds_read_b128 v[214:217], v209
	ds_read_b128 v[218:221], v209 offset:1024
	ds_read_b128 v[222:225], v209 offset:2048
	ds_read_b128 v[226:229], v209 offset:3072
	s_waitcnt vmcnt(8)
	s_waitcnt lgkmcnt(0)
	s_barrier
	v_mfma_f32_16x16x32_bf16 v[124:127], v[128:131], v[162:165], v[124:127]
	v_mfma_f32_16x16x32_bf16 v[120:123], v[136:139], v[162:165], v[120:123]
	v_mfma_f32_16x16x32_bf16 v[108:111], v[128:131], v[170:173], v[108:111]
	v_mfma_f32_16x16x32_bf16 v[104:107], v[136:139], v[170:173], v[104:107]
	v_mfma_f32_16x16x32_bf16 v[96:99], v[128:131], v[178:181], v[96:99]
	v_mfma_f32_16x16x32_bf16 v[88:91], v[136:139], v[178:181], v[88:91]
	v_mfma_f32_16x16x32_bf16 v[84:87], v[128:131], v[194:197], v[84:87]
	v_mfma_f32_16x16x32_bf16 v[80:83], v[136:139], v[194:197], v[80:83]
	v_mfma_f32_16x16x32_bf16 v[124:127], v[132:135], v[166:169], v[124:127]
	v_mfma_f32_16x16x32_bf16 v[120:123], v[146:149], v[166:169], v[120:123]
	v_mfma_f32_16x16x32_bf16 v[108:111], v[132:135], v[174:177], v[108:111]
	v_mfma_f32_16x16x32_bf16 v[104:107], v[146:149], v[174:177], v[104:107]
	v_mfma_f32_16x16x32_bf16 v[96:99], v[132:135], v[182:185], v[96:99]
	v_mfma_f32_16x16x32_bf16 v[88:91], v[146:149], v[182:185], v[88:91]
	v_mfma_f32_16x16x32_bf16 v[84:87], v[132:135], v[210:213], v[84:87]
	v_mfma_f32_16x16x32_bf16 v[80:83], v[146:149], v[210:213], v[80:83]
	v_mfma_f32_16x16x32_bf16 v[116:119], v[214:217], v[162:165], v[116:119]
	v_mfma_f32_16x16x32_bf16 v[112:115], v[222:225], v[162:165], v[112:115]
	v_mfma_f32_16x16x32_bf16 v[100:103], v[214:217], v[170:173], v[100:103]
	v_mfma_f32_16x16x32_bf16 v[92:95], v[222:225], v[170:173], v[92:95]
	v_mfma_f32_16x16x32_bf16 v[76:79], v[214:217], v[178:181], v[76:79]
	v_mfma_f32_16x16x32_bf16 v[72:75], v[222:225], v[178:181], v[72:75]
	v_mfma_f32_16x16x32_bf16 v[68:71], v[214:217], v[194:197], v[68:71]
	v_mfma_f32_16x16x32_bf16 v[64:67], v[222:225], v[194:197], v[64:67]
	v_mfma_f32_16x16x32_bf16 v[116:119], v[218:221], v[166:169], v[116:119]
	v_mfma_f32_16x16x32_bf16 v[112:115], v[226:229], v[166:169], v[112:115]
	v_mfma_f32_16x16x32_bf16 v[100:103], v[218:221], v[174:177], v[100:103]
	v_mfma_f32_16x16x32_bf16 v[92:95], v[226:229], v[174:177], v[92:95]
	v_mfma_f32_16x16x32_bf16 v[76:79], v[218:221], v[182:185], v[76:79]
	v_mfma_f32_16x16x32_bf16 v[72:75], v[226:229], v[182:185], v[72:75]
	v_mfma_f32_16x16x32_bf16 v[68:71], v[218:221], v[210:213], v[68:71]
	v_mfma_f32_16x16x32_bf16 v[64:67], v[226:229], v[210:213], v[64:67]
	s_barrier
	s_add_i32 s6, s6, s71
	v_lshl_add_u64 v[192:193], v[192:193], 0, s[36:37]
	s_mov_b32 m0, s6
	s_nop 0
	global_load_lds_dwordx4 v[192:193], off
	v_lshl_add_u64 v[192:193], v[230:231], 0, s[36:37]
	s_add_i32 m0, s6, 0x2000
	s_nop 0
	global_load_lds_dwordx4 v[192:193], off
	s_mov_b32 m0, s80
	v_lshl_add_u64 v[192:193], v[232:233], 0, s[36:37]
	ds_read_b128 v[162:165], v208 offset:49152
	ds_read_b128 v[166:169], v208 offset:50176
	ds_read_b128 v[170:173], v208 offset:51200
	ds_read_b128 v[174:177], v208 offset:52224
	ds_read_b128 v[178:181], v208 offset:53248
	ds_read_b128 v[182:185], v208 offset:54272
	ds_read_b128 v[194:197], v208 offset:55296
	ds_read_b128 v[210:213], v208 offset:56320
	global_load_lds_dwordx4 v[192:193], off
	v_lshl_add_u64 v[192:193], v[234:235], 0, s[36:37]
	s_mov_b32 m0, s81
	s_nop 0
	global_load_lds_dwordx4 v[192:193], off
	s_add_u32 s58, s58, 0x40080
	s_addc_u32 s59, s59, 0
	s_add_i32 s6, s19, s71
	v_lshl_add_u64 v[250:251], s[58:59], 0, v[140:141]
	s_mov_b32 m0, s6
	s_nop 0
	global_load_lds_dwordx4 v[250:251], off
	v_lshl_add_u64 v[250:251], s[58:59], 0, v[150:151]
	s_add_i32 m0, s6, 0x2000
	s_nop 0
	global_load_lds_dwordx4 v[250:251], off
	s_waitcnt vmcnt(8)
	s_waitcnt lgkmcnt(0)
	s_barrier
	v_mfma_f32_16x16x32_bf16 v[60:63], v[128:131], v[162:165], v[60:63]
	v_mfma_f32_16x16x32_bf16 v[56:59], v[136:139], v[162:165], v[56:59]
	v_mfma_f32_16x16x32_bf16 v[48:51], v[128:131], v[170:173], v[48:51]
	v_mfma_f32_16x16x32_bf16 v[40:43], v[136:139], v[170:173], v[40:43]
	v_mfma_f32_16x16x32_bf16 v[32:35], v[128:131], v[178:181], v[32:35]
	v_mfma_f32_16x16x32_bf16 v[24:27], v[136:139], v[178:181], v[24:27]
	v_mfma_f32_16x16x32_bf16 v[16:19], v[128:131], v[194:197], v[16:19]
	v_mfma_f32_16x16x32_bf16 v[8:11], v[136:139], v[194:197], v[8:11]
	v_mfma_f32_16x16x32_bf16 v[60:63], v[132:135], v[166:169], v[60:63]
	v_mfma_f32_16x16x32_bf16 v[56:59], v[146:149], v[166:169], v[56:59]
	v_mfma_f32_16x16x32_bf16 v[48:51], v[132:135], v[174:177], v[48:51]
	v_mfma_f32_16x16x32_bf16 v[40:43], v[146:149], v[174:177], v[40:43]
	v_mfma_f32_16x16x32_bf16 v[32:35], v[132:135], v[182:185], v[32:35]
	v_mfma_f32_16x16x32_bf16 v[24:27], v[146:149], v[182:185], v[24:27]
	v_mfma_f32_16x16x32_bf16 v[16:19], v[132:135], v[210:213], v[16:19]
	v_mfma_f32_16x16x32_bf16 v[8:11], v[146:149], v[210:213], v[8:11]
	v_mfma_f32_16x16x32_bf16 v[52:55], v[214:217], v[162:165], v[52:55]
	v_mfma_f32_16x16x32_bf16 v[44:47], v[222:225], v[162:165], v[44:47]
	v_mfma_f32_16x16x32_bf16 v[36:39], v[214:217], v[170:173], v[36:39]
	v_mfma_f32_16x16x32_bf16 v[28:31], v[222:225], v[170:173], v[28:31]
	v_mfma_f32_16x16x32_bf16 v[20:23], v[214:217], v[178:181], v[20:23]
	v_mfma_f32_16x16x32_bf16 v[12:15], v[222:225], v[178:181], v[12:15]
	v_mfma_f32_16x16x32_bf16 v[4:7], v[214:217], v[194:197], v[4:7]
	v_mfma_f32_16x16x32_bf16 v[0:3], v[222:225], v[194:197], v[0:3]
	v_mfma_f32_16x16x32_bf16 v[52:55], v[218:221], v[166:169], v[52:55]
	v_mfma_f32_16x16x32_bf16 v[44:47], v[226:229], v[166:169], v[44:47]
	v_mfma_f32_16x16x32_bf16 v[36:39], v[218:221], v[174:177], v[36:39]
	v_mfma_f32_16x16x32_bf16 v[28:31], v[226:229], v[174:177], v[28:31]
	v_mfma_f32_16x16x32_bf16 v[20:23], v[218:221], v[182:185], v[20:23]
	v_mfma_f32_16x16x32_bf16 v[12:15], v[226:229], v[182:185], v[12:15]
	v_mfma_f32_16x16x32_bf16 v[4:7], v[218:221], v[210:213], v[4:7]
	v_mfma_f32_16x16x32_bf16 v[0:3], v[226:229], v[210:213], v[0:3]
	s_add_i32 s12, s12, 2
	s_add_u32 s54, s54, 0x100
	s_addc_u32 s55, s55, 0
	s_add_u32 s10, s10, 0x100
	s_addc_u32 s11, s11, 0
	s_cmp_gt_u32 s12, 13
	s_barrier
	s_cbranch_scc0 .LBB0_103
	s_mov_b32 s100, 1
	s_ashr_i32 s51, s50, 31
	s_ashr_i32 s53, s52, 31
	s_lshl_b64 s[10:11], s[50:51], 13
	s_lshl_b64 s[50:51], s[52:53], 8
	s_add_u32 s10, s50, s10
	v_lshl_or_b32 v128, s85, 8, v207
	s_addc_u32 s11, s51, s11
	v_ashrrev_i32_e32 v129, 31, v128
	v_lshl_add_u64 v[168:169], s[10:11], 0, v[156:157]
	v_lshlrev_b64 v[170:171], 1, v[128:129]
	v_lshl_add_u64 v[174:175], s[26:27], 0, v[170:171]
	v_lshlrev_b64 v[172:173], 11, v[168:169]
	v_or_b32_e32 v166, 16, v168
	v_mov_b32_e32 v167, v169
	v_lshl_add_u64 v[128:129], v[174:175], 0, v[172:173]
	v_lshlrev_b64 v[176:177], 11, v[166:167]
	global_load_dwordx4 v[146:149], v[128:129], off
	global_load_dwordx4 v[182:185], v[128:129], off offset:256
	v_lshl_add_u64 v[128:129], v[174:175], 0, v[176:177]
	global_load_dwordx4 v[194:197], v[128:129], off
	global_load_dwordx4 v[210:213], v[128:129], off offset:256
	v_or_b32_e32 v164, 32, v168
	v_mov_b32_e32 v165, v169
	v_or_b32_e32 v162, 48, v168
	v_mov_b32_e32 v163, v169
	v_lshlrev_b64 v[180:181], 11, v[164:165]
	v_lshlrev_b64 v[178:179], 11, v[162:163]
	v_lshl_add_u64 v[128:129], v[174:175], 0, v[180:181]
	v_lshl_add_u64 v[130:131], v[174:175], 0, v[178:179]
	global_load_dwordx4 v[214:217], v[128:129], off
	global_load_dwordx4 v[136:139], v[128:129], off offset:256
	global_load_dwordx4 v[132:135], v[130:131], off
	s_nop 0
	global_load_dwordx4 v[128:131], v[130:131], off offset:256
	s_mov_b64 s[10:11], 0x90
	v_lshl_add_u64 v[172:173], s[28:29], 0, v[172:173]
	v_lshl_add_u64 v[172:173], v[172:173], 0, v[170:171]
	s_waitcnt vmcnt(0)
	v_lshlrev_b32_e32 v192, 16, v146
	v_and_b32_e32 v193, 0xffff0000, v146
	v_lshlrev_b32_e32 v218, 16, v148
	v_and_b32_e32 v219, 0xffff0000, v148
	v_lshlrev_b32_e32 v146, 16, v147
	v_and_b32_e32 v147, 0xffff0000, v147
	v_lshlrev_b32_e32 v148, 16, v149
	v_and_b32_e32 v149, 0xffff0000, v149
	v_lshlrev_b32_e32 v220, 16, v182
	v_and_b32_e32 v221, 0xffff0000, v182
	v_lshlrev_b32_e32 v222, 16, v184
	v_and_b32_e32 v223, 0xffff0000, v184
	v_lshlrev_b32_e32 v182, 16, v183
	v_and_b32_e32 v183, 0xffff0000, v183
	v_lshlrev_b32_e32 v184, 16, v185
	v_and_b32_e32 v185, 0xffff0000, v185
	v_pk_add_f32 v[124:125], v[124:125], v[192:193]
	v_pk_add_f32 v[126:127], v[126:127], v[146:147]
	v_pk_add_f32 v[122:123], v[122:123], v[148:149]
	v_pk_add_f32 v[116:117], v[116:117], v[220:221]
	v_pk_add_f32 v[146:147], v[112:113], v[222:223]
	v_pk_add_f32 v[118:119], v[118:119], v[182:183]
	v_pk_add_f32 v[148:149], v[114:115], v[184:185]
	v_lshlrev_b32_e32 v182, 16, v194
	v_and_b32_e32 v183, 0xffff0000, v194
	v_lshlrev_b32_e32 v184, 16, v196
	v_and_b32_e32 v185, 0xffff0000, v196
	v_lshlrev_b32_e32 v192, 16, v195
	v_and_b32_e32 v193, 0xffff0000, v195
	v_lshlrev_b32_e32 v194, 16, v197
	v_and_b32_e32 v195, 0xffff0000, v197
	v_pk_mul_f32 v[196:197], v[124:125], v[124:125]
	v_pk_add_f32 v[120:121], v[120:121], v[218:219]
	v_pk_mul_f32 v[218:219], v[126:127], v[126:127]
	v_cvt_pk_bf16_f32 v112, v124, v125
	v_cvt_pk_bf16_f32 v113, v126, v127
	v_pk_mul_f32 v[124:125], v[116:117], v[116:117]
	v_pk_mul_f32 v[126:127], v[118:119], v[118:119]
	v_pk_mul_f32 v[224:225], v[146:147], v[146:147]
	v_cvt_pk_bf16_f32 v116, v116, v117
	v_cvt_pk_bf16_f32 v117, v118, v119
	v_cvt_pk_bf16_f32 v118, v146, v147
	v_add_f32_e32 v146, v196, v197
	v_add_f32_e32 v146, v218, v146
	v_pk_mul_f32 v[220:221], v[120:121], v[120:121]
	v_add_f32_e32 v146, v219, v146
	v_add_f32_e32 v146, v220, v146
	v_pk_mul_f32 v[222:223], v[122:123], v[122:123]
	v_add_f32_e32 v146, v221, v146
	v_add_f32_e32 v146, v222, v146
	v_add_f32_e32 v146, v223, v146
	v_add_f32_e32 v124, v124, v146
	v_add_f32_e32 v124, v125, v124
	v_add_f32_e32 v124, v126, v124
	v_add_f32_e32 v124, v127, v124
	v_add_f32_e32 v124, v224, v124
	v_pk_mul_f32 v[226:227], v[148:149], v[148:149]
	v_add_f32_e32 v124, v225, v124
	v_add_f32_e32 v124, v226, v124
	v_add_f32_e32 v209, v227, v124
	v_lshlrev_b32_e32 v124, 16, v210
	v_and_b32_e32 v125, 0xffff0000, v210
	v_pk_add_f32 v[100:101], v[100:101], v[124:125]
	v_lshlrev_b32_e32 v124, 16, v212
	v_and_b32_e32 v125, 0xffff0000, v212
	v_pk_add_f32 v[124:125], v[92:93], v[124:125]
	v_lshlrev_b32_e32 v92, 16, v211
	v_and_b32_e32 v93, 0xffff0000, v211
	v_pk_add_f32 v[102:103], v[102:103], v[92:93]
	v_lshlrev_b32_e32 v92, 16, v213
	v_and_b32_e32 v93, 0xffff0000, v213
	v_pk_add_f32 v[126:127], v[94:95], v[92:93]
	v_lshlrev_b32_e32 v92, 16, v214
	v_and_b32_e32 v93, 0xffff0000, v214
	v_pk_add_f32 v[92:93], v[96:97], v[92:93]
	v_lshlrev_b32_e32 v96, 16, v217
	v_and_b32_e32 v97, 0xffff0000, v217
	v_lshlrev_b32_e32 v94, 16, v216
	v_and_b32_e32 v95, 0xffff0000, v216
	v_pk_add_f32 v[90:91], v[90:91], v[96:97]
	v_lshlrev_b32_e32 v96, 16, v136
	v_and_b32_e32 v97, 0xffff0000, v136
	v_pk_add_f32 v[88:89], v[88:89], v[94:95]
	v_lshlrev_b32_e32 v94, 16, v215
	v_and_b32_e32 v95, 0xffff0000, v215
	v_pk_add_f32 v[96:97], v[76:77], v[96:97]
	v_lshl_add_u64 v[76:77], v[168:169], 0, s[36:37]
	v_cvt_pk_bf16_f32 v114, v120, v121
	v_pk_add_f32 v[120:121], v[108:109], v[182:183]
	v_pk_add_f32 v[94:95], v[98:99], v[94:95]
	v_lshlrev_b64 v[182:183], 11, v[76:77]
	v_lshlrev_b32_e32 v98, 16, v138
	v_and_b32_e32 v99, 0xffff0000, v138
	v_pk_add_f32 v[108:109], v[104:105], v[184:185]
	v_lshl_add_u64 v[184:185], v[174:175], 0, v[182:183]
	v_pk_add_f32 v[98:99], v[72:73], v[98:99]
	v_lshlrev_b32_e32 v72, 16, v137
	v_and_b32_e32 v73, 0xffff0000, v137
	global_load_dwordx4 v[210:213], v[184:185], off
	global_load_dwordx4 v[218:221], v[184:185], off offset:256
	v_pk_add_f32 v[136:137], v[78:79], v[72:73]
	v_lshlrev_b32_e32 v72, 16, v139
	v_and_b32_e32 v73, 0xffff0000, v139
	v_pk_add_f32 v[138:139], v[74:75], v[72:73]
	v_lshlrev_b32_e32 v72, 16, v132
	v_and_b32_e32 v73, 0xffff0000, v132
	v_pk_add_f32 v[74:75], v[84:85], v[72:73]
	v_lshlrev_b32_e32 v72, 16, v134
	v_and_b32_e32 v73, 0xffff0000, v134
	v_pk_add_f32 v[78:79], v[80:81], v[72:73]
	v_lshlrev_b32_e32 v72, 16, v133
	v_and_b32_e32 v73, 0xffff0000, v133
	v_pk_add_f32 v[80:81], v[86:87], v[72:73]
	v_lshlrev_b32_e32 v72, 16, v135
	v_and_b32_e32 v73, 0xffff0000, v135
	v_pk_add_f32 v[82:83], v[82:83], v[72:73]
	v_lshl_add_u64 v[72:73], v[168:169], 0, s[10:11]
	v_lshlrev_b64 v[132:133], 11, v[72:73]
	v_lshl_add_u64 v[134:135], v[174:175], 0, v[132:133]
	v_lshlrev_b32_e32 v84, 16, v128
	v_and_b32_e32 v85, 0xffff0000, v128
	global_load_dwordx4 v[226:229], v[134:135], off
	global_load_dwordx4 v[234:237], v[134:135], off offset:256
	v_pk_add_f32 v[84:85], v[68:69], v[84:85]
	v_lshlrev_b32_e32 v68, 16, v130
	v_and_b32_e32 v69, 0xffff0000, v130
	v_pk_add_f32 v[86:87], v[64:65], v[68:69]
	v_lshlrev_b32_e32 v64, 16, v129
	v_and_b32_e32 v65, 0xffff0000, v129
	s_mov_b64 s[10:11], 0xa0
	v_pk_add_f32 v[128:129], v[70:71], v[64:65]
	v_lshl_add_u64 v[70:71], v[168:169], 0, s[10:11]
	s_mov_b64 s[10:11], 0xb0
	v_lshlrev_b32_e32 v64, 16, v131
	v_and_b32_e32 v65, 0xffff0000, v131
	v_lshlrev_b64 v[134:135], 11, v[70:71]
	v_lshl_add_u64 v[68:69], v[168:169], 0, s[10:11]
	v_pk_add_f32 v[130:131], v[66:67], v[64:65]
	v_lshl_add_u64 v[64:65], v[174:175], 0, v[134:135]
	v_lshlrev_b64 v[184:185], 11, v[68:69]
	global_load_dwordx4 v[238:241], v[64:65], off
	global_load_dwordx4 v[242:245], v[64:65], off offset:256
	v_lshl_add_u64 v[64:65], v[174:175], 0, v[184:185]
	global_load_dwordx4 v[246:249], v[64:65], off
	s_nop 0
	global_load_dwordx4 v[64:67], v[64:65], off offset:256
	v_cvt_pk_bf16_f32 v115, v122, v123
	v_cvt_pk_bf16_f32 v119, v148, v149
	v_pk_add_f32 v[110:111], v[110:111], v[192:193]
	v_pk_add_f32 v[122:123], v[106:107], v[194:195]
	global_store_dwordx4 v[172:173], v[112:115], off
	global_store_dwordx4 v[172:173], v[116:119], off offset:256
	v_cvt_pk_bf16_f32 v104, v120, v121
	v_lshl_add_u64 v[112:113], s[28:29], 0, v[176:177]
	v_cvt_pk_bf16_f32 v105, v110, v111
	v_cvt_pk_bf16_f32 v106, v108, v109
	v_cvt_pk_bf16_f32 v107, v122, v123
	v_lshl_add_u64 v[112:113], v[112:113], 0, v[170:171]
	v_cvt_pk_bf16_f32 v146, v100, v101
	v_cvt_pk_bf16_f32 v147, v102, v103
	v_cvt_pk_bf16_f32 v148, v124, v125
	v_cvt_pk_bf16_f32 v149, v126, v127
	global_store_dwordx4 v[112:113], v[104:107], off
	global_store_dwordx4 v[112:113], v[146:149], off offset:256
	v_cvt_pk_bf16_f32 v194, v92, v93
	v_lshl_add_u64 v[104:105], s[28:29], 0, v[180:181]
	v_cvt_pk_bf16_f32 v195, v94, v95
	v_cvt_pk_bf16_f32 v196, v88, v89
	v_cvt_pk_bf16_f32 v197, v90, v91
	v_lshl_add_u64 v[104:105], v[104:105], 0, v[170:171]
	v_cvt_pk_bf16_f32 v214, v96, v97
	v_cvt_pk_bf16_f32 v215, v136, v137
	v_cvt_pk_bf16_f32 v216, v98, v99
	v_cvt_pk_bf16_f32 v217, v138, v139
	global_store_dwordx4 v[104:105], v[194:197], off
	global_store_dwordx4 v[104:105], v[214:217], off offset:256
	v_lshl_add_u64 v[104:105], s[28:29], 0, v[178:179]
	v_cvt_pk_bf16_f32 v222, v74, v75
	v_cvt_pk_bf16_f32 v223, v80, v81
	v_cvt_pk_bf16_f32 v224, v78, v79
	v_cvt_pk_bf16_f32 v225, v82, v83
	v_lshl_add_u64 v[104:105], v[104:105], 0, v[170:171]
	v_cvt_pk_bf16_f32 v230, v84, v85
	v_cvt_pk_bf16_f32 v231, v128, v129
	v_cvt_pk_bf16_f32 v232, v86, v87
	v_cvt_pk_bf16_f32 v233, v130, v131
	global_store_dwordx4 v[104:105], v[222:225], off
	global_store_dwordx4 v[104:105], v[230:233], off offset:256
	s_waitcnt vmcnt(0)
	v_lshlrev_b32_e32 v104, 16, v210
	v_and_b32_e32 v105, 0xffff0000, v210
	v_pk_add_f32 v[60:61], v[60:61], v[104:105]
	v_lshlrev_b32_e32 v104, 16, v212
	v_and_b32_e32 v105, 0xffff0000, v212
	v_pk_add_f32 v[56:57], v[56:57], v[104:105]
	v_lshlrev_b32_e32 v104, 16, v211
	v_and_b32_e32 v105, 0xffff0000, v211
	v_pk_add_f32 v[62:63], v[62:63], v[104:105]
	v_lshlrev_b32_e32 v104, 16, v213
	v_and_b32_e32 v105, 0xffff0000, v213
	v_pk_add_f32 v[58:59], v[58:59], v[104:105]
	v_lshlrev_b32_e32 v104, 16, v218
	v_and_b32_e32 v105, 0xffff0000, v218
	v_pk_add_f32 v[52:53], v[52:53], v[104:105]
	v_lshlrev_b32_e32 v104, 16, v220
	v_and_b32_e32 v105, 0xffff0000, v220
	v_pk_add_f32 v[104:105], v[44:45], v[104:105]
	v_lshlrev_b32_e32 v44, 16, v219
	v_and_b32_e32 v45, 0xffff0000, v219
	v_pk_add_f32 v[54:55], v[54:55], v[44:45]
	v_lshlrev_b32_e32 v44, 16, v221
	v_and_b32_e32 v45, 0xffff0000, v221
	v_pk_add_f32 v[106:107], v[46:47], v[44:45]
	v_lshlrev_b32_e32 v44, 16, v226
	v_and_b32_e32 v45, 0xffff0000, v226
	v_pk_add_f32 v[44:45], v[48:49], v[44:45]
	v_lshlrev_b32_e32 v48, 16, v229
	v_and_b32_e32 v49, 0xffff0000, v229
	v_pk_add_f32 v[42:43], v[42:43], v[48:49]
	v_lshlrev_b32_e32 v48, 16, v234
	v_and_b32_e32 v49, 0xffff0000, v234
	v_pk_add_f32 v[36:37], v[36:37], v[48:49]
	v_lshlrev_b32_e32 v48, 16, v236
	v_and_b32_e32 v49, 0xffff0000, v236
	v_lshlrev_b32_e32 v46, 16, v228
	v_and_b32_e32 v47, 0xffff0000, v228
	v_pk_add_f32 v[48:49], v[28:29], v[48:49]
	v_lshlrev_b32_e32 v28, 16, v235
	v_and_b32_e32 v29, 0xffff0000, v235
	v_pk_add_f32 v[40:41], v[40:41], v[46:47]
	v_lshlrev_b32_e32 v46, 16, v227
	v_and_b32_e32 v47, 0xffff0000, v227
	v_pk_add_f32 v[38:39], v[38:39], v[28:29]
	v_lshlrev_b32_e32 v28, 16, v237
	v_and_b32_e32 v29, 0xffff0000, v237
	v_pk_add_f32 v[46:47], v[50:51], v[46:47]
	v_pk_add_f32 v[50:51], v[30:31], v[28:29]
	v_lshlrev_b32_e32 v28, 16, v238
	v_and_b32_e32 v29, 0xffff0000, v238
	v_lshlrev_b32_e32 v180, 16, v64
	v_and_b32_e32 v181, 0xffff0000, v64
	v_pk_add_f32 v[28:29], v[32:33], v[28:29]
	v_lshlrev_b32_e32 v32, 16, v241
	v_and_b32_e32 v33, 0xffff0000, v241
	v_pk_add_f32 v[4:5], v[4:5], v[180:181]
	v_lshlrev_b32_e32 v180, 16, v66
	v_and_b32_e32 v181, 0xffff0000, v66
	v_pk_add_f32 v[26:27], v[26:27], v[32:33]
	v_lshlrev_b32_e32 v32, 16, v242
	v_and_b32_e32 v33, 0xffff0000, v242
	v_pk_add_f32 v[0:1], v[0:1], v[180:181]
	v_lshl_add_u64 v[180:181], s[28:29], 0, v[182:183]
	v_cvt_pk_bf16_f32 v112, v60, v61
	v_cvt_pk_bf16_f32 v113, v62, v63
	v_cvt_pk_bf16_f32 v114, v56, v57
	v_cvt_pk_bf16_f32 v115, v58, v59
	v_pk_add_f32 v[20:21], v[20:21], v[32:33]
	v_lshlrev_b32_e32 v32, 16, v244
	v_and_b32_e32 v33, 0xffff0000, v244
	v_lshl_add_u64 v[180:181], v[180:181], 0, v[170:171]
	v_cvt_pk_bf16_f32 v116, v52, v53
	v_cvt_pk_bf16_f32 v117, v54, v55
	v_cvt_pk_bf16_f32 v118, v104, v105
	v_cvt_pk_bf16_f32 v119, v106, v107
	v_lshlrev_b32_e32 v30, 16, v240
	v_and_b32_e32 v31, 0xffff0000, v240
	v_pk_add_f32 v[32:33], v[12:13], v[32:33]
	v_lshlrev_b32_e32 v12, 16, v243
	v_and_b32_e32 v13, 0xffff0000, v243
	global_store_dwordx4 v[180:181], v[112:115], off
	global_store_dwordx4 v[180:181], v[116:119], off offset:256
	v_cvt_pk_bf16_f32 v146, v44, v45
	v_lshl_add_u64 v[112:113], s[28:29], 0, v[132:133]
	v_cvt_pk_bf16_f32 v147, v46, v47
	v_cvt_pk_bf16_f32 v148, v40, v41
	v_cvt_pk_bf16_f32 v149, v42, v43
	v_pk_add_f32 v[24:25], v[24:25], v[30:31]
	v_lshlrev_b32_e32 v30, 16, v239
	v_and_b32_e32 v31, 0xffff0000, v239
	v_pk_add_f32 v[22:23], v[22:23], v[12:13]
	v_lshlrev_b32_e32 v12, 16, v245
	v_and_b32_e32 v13, 0xffff0000, v245
	v_lshl_add_u64 v[112:113], v[112:113], 0, v[170:171]
	v_cvt_pk_bf16_f32 v172, v36, v37
	v_cvt_pk_bf16_f32 v173, v38, v39
	v_cvt_pk_bf16_f32 v174, v48, v49
	v_cvt_pk_bf16_f32 v175, v50, v51
	v_pk_add_f32 v[30:31], v[34:35], v[30:31]
	v_pk_add_f32 v[34:35], v[14:15], v[12:13]
	v_lshlrev_b32_e32 v12, 16, v246
	v_and_b32_e32 v13, 0xffff0000, v246
	v_lshlrev_b32_e32 v14, 16, v248
	v_and_b32_e32 v15, 0xffff0000, v248
	global_store_dwordx4 v[112:113], v[146:149], off
	global_store_dwordx4 v[112:113], v[172:175], off offset:256
	v_lshl_add_u64 v[112:113], s[28:29], 0, v[134:135]
	v_cvt_pk_bf16_f32 v176, v28, v29
	v_cvt_pk_bf16_f32 v177, v30, v31
	v_cvt_pk_bf16_f32 v178, v24, v25
	v_cvt_pk_bf16_f32 v179, v26, v27
	v_pk_add_f32 v[12:13], v[16:17], v[12:13]
	v_pk_add_f32 v[8:9], v[8:9], v[14:15]
	v_lshlrev_b32_e32 v14, 16, v247
	v_and_b32_e32 v15, 0xffff0000, v247
	v_lshlrev_b32_e32 v16, 16, v249
	v_and_b32_e32 v17, 0xffff0000, v249
	v_lshlrev_b32_e32 v64, 16, v65
	v_and_b32_e32 v65, 0xffff0000, v65
	v_lshl_add_u64 v[112:113], v[112:113], 0, v[170:171]
	v_cvt_pk_bf16_f32 v194, v20, v21
	v_cvt_pk_bf16_f32 v195, v22, v23
	v_cvt_pk_bf16_f32 v196, v32, v33
	v_cvt_pk_bf16_f32 v197, v34, v35
	v_pk_add_f32 v[14:15], v[18:19], v[14:15]
	v_pk_add_f32 v[10:11], v[10:11], v[16:17]
	v_pk_add_f32 v[6:7], v[6:7], v[64:65]
	v_lshlrev_b32_e32 v64, 16, v67
	v_and_b32_e32 v65, 0xffff0000, v67
	global_store_dwordx4 v[112:113], v[176:179], off
	global_store_dwordx4 v[112:113], v[194:197], off offset:256
	v_lshl_add_u64 v[112:113], s[28:29], 0, v[184:185]
	v_cvt_pk_bf16_f32 v16, v12, v13
	v_cvt_pk_bf16_f32 v17, v14, v15
	v_cvt_pk_bf16_f32 v18, v8, v9
	v_cvt_pk_bf16_f32 v19, v10, v11
	v_pk_add_f32 v[2:3], v[2:3], v[64:65]
	v_lshl_add_u64 v[112:113], v[112:113], 0, v[170:171]
	v_cvt_pk_bf16_f32 v64, v4, v5
	v_cvt_pk_bf16_f32 v65, v6, v7
	v_cvt_pk_bf16_f32 v66, v0, v1
	v_cvt_pk_bf16_f32 v67, v2, v3
	global_store_dwordx4 v[112:113], v[16:19], off
	global_store_dwordx4 v[112:113], v[64:67], off offset:256
	s_lshl_b32 s10, s85, 2
	v_and_b32_e32 v17, 64, v188
	v_xor_b32_e32 v16, 16, v188
	v_add_u32_e32 v17, 64, v17
	v_cmp_lt_i32_e32 vcc, v16, v17
	v_xor_b32_e32 v18, 32, v188
	s_ashr_i32 s11, s10, 31
	v_cndmask_b32_e32 v16, v188, v16, vcc
	v_lshlrev_b32_e32 v16, 2, v16
	ds_bpermute_b32 v19, v16, v209
	v_cmp_lt_i32_e32 vcc, v18, v17
	s_lshl_b64 s[10:11], s[10:11], 2
	s_add_u32 s50, s83, s10
	v_cndmask_b32_e32 v17, v188, v18, vcc
	v_lshlrev_b32_e32 v17, 2, v17
	s_waitcnt lgkmcnt(0)
	v_add_f32_e32 v18, v209, v19
	ds_bpermute_b32 v19, v17, v18
	s_addc_u32 s51, s84, s11
	s_and_saveexec_b64 s[52:53], s[42:43]
	s_cbranch_execz .LBB0_106
	s_waitcnt lgkmcnt(0)
	v_add_f32_e32 v64, v18, v19
	v_lshlrev_b64 v[18:19], 6, v[168:169]
	v_lshl_add_u64 v[18:19], s[50:51], 0, v[18:19]
	global_store_dword v[18:19], v64, off

.LBB0_248:
	s_add_u32 s6, s52, 0xfffc0080
	s_addc_u32 s19, s53, -1
	s_add_i32 s23, 0, 0x10000
	v_add_u32_e32 v146, s23, v206
	ds_read_b128 v[128:131], v146
	ds_read_b128 v[132:135], v146 offset:1024
	ds_read_b128 v[136:139], v146 offset:2048
	ds_read_b128 v[146:149], v146 offset:3072
	s_cmp_eq_u32 s82, 12
	s_cselect_b32 s59, s10, s19
	s_cselect_b32 s58, s11, s6
	s_cselect_b32 s55, s12, s51
	s_cselect_b32 s54, s35, s39
	v_lshl_add_u64 v[214:215], s[52:53], 0, v[158:159]
	s_add_i32 m0, s68, 0xc000
	ds_read_b128 v[162:165], v208
	ds_read_b128 v[166:169], v208 offset:1024
	ds_read_b128 v[170:173], v208 offset:2048
	ds_read_b128 v[174:177], v208 offset:3072
	ds_read_b128 v[178:181], v208 offset:4096
	ds_read_b128 v[182:185], v208 offset:5120
	ds_read_b128 v[194:197], v208 offset:6144
	ds_read_b128 v[210:213], v208 offset:7168
	global_load_lds_dwordx4 v[214:215], off
	v_lshl_add_u64 v[214:215], s[52:53], 0, v[160:161]
	s_add_i32 m0, s68, 0xe000
	s_nop 0
	global_load_lds_dwordx4 v[214:215], off
	s_add_i32 s6, 0, 0x14000
	v_add_u32_e32 v192, s6, v206
	ds_read_b128 v[214:217], v192
	ds_read_b128 v[218:221], v192 offset:1024
	ds_read_b128 v[222:225], v192 offset:2048
	ds_read_b128 v[226:229], v192 offset:3072
	s_nop 0
	s_waitcnt vmcnt(8)
	s_waitcnt lgkmcnt(0)
	s_barrier
	v_mfma_f32_16x16x32_bf16 v[124:127], v[128:131], v[162:165], v[124:127]
	v_mfma_f32_16x16x32_bf16 v[120:123], v[136:139], v[162:165], v[120:123]
	v_mfma_f32_16x16x32_bf16 v[108:111], v[128:131], v[170:173], v[108:111]
	v_mfma_f32_16x16x32_bf16 v[104:107], v[136:139], v[170:173], v[104:107]
	v_mfma_f32_16x16x32_bf16 v[96:99], v[128:131], v[178:181], v[96:99]
	v_mfma_f32_16x16x32_bf16 v[88:91], v[136:139], v[178:181], v[88:91]
	v_mfma_f32_16x16x32_bf16 v[84:87], v[128:131], v[194:197], v[84:87]
	v_mfma_f32_16x16x32_bf16 v[80:83], v[136:139], v[194:197], v[80:83]
	v_mfma_f32_16x16x32_bf16 v[124:127], v[132:135], v[166:169], v[124:127]
	v_mfma_f32_16x16x32_bf16 v[120:123], v[146:149], v[166:169], v[120:123]
	v_mfma_f32_16x16x32_bf16 v[108:111], v[132:135], v[174:177], v[108:111]
	v_mfma_f32_16x16x32_bf16 v[104:107], v[146:149], v[174:177], v[104:107]
	v_mfma_f32_16x16x32_bf16 v[96:99], v[132:135], v[182:185], v[96:99]
	v_mfma_f32_16x16x32_bf16 v[88:91], v[146:149], v[182:185], v[88:91]
	v_mfma_f32_16x16x32_bf16 v[84:87], v[132:135], v[210:213], v[84:87]
	v_mfma_f32_16x16x32_bf16 v[80:83], v[146:149], v[210:213], v[80:83]
	v_mfma_f32_16x16x32_bf16 v[116:119], v[214:217], v[162:165], v[116:119]
	v_mfma_f32_16x16x32_bf16 v[112:115], v[222:225], v[162:165], v[112:115]
	v_mfma_f32_16x16x32_bf16 v[100:103], v[214:217], v[170:173], v[100:103]
	v_mfma_f32_16x16x32_bf16 v[92:95], v[222:225], v[170:173], v[92:95]
	v_mfma_f32_16x16x32_bf16 v[76:79], v[214:217], v[178:181], v[76:79]
	v_mfma_f32_16x16x32_bf16 v[72:75], v[222:225], v[178:181], v[72:75]
	v_mfma_f32_16x16x32_bf16 v[68:71], v[214:217], v[194:197], v[68:71]
	v_mfma_f32_16x16x32_bf16 v[64:67], v[222:225], v[194:197], v[64:67]
	v_mfma_f32_16x16x32_bf16 v[116:119], v[218:221], v[166:169], v[116:119]
	v_mfma_f32_16x16x32_bf16 v[112:115], v[226:229], v[166:169], v[112:115]
	v_mfma_f32_16x16x32_bf16 v[100:103], v[218:221], v[174:177], v[100:103]
	v_mfma_f32_16x16x32_bf16 v[92:95], v[226:229], v[174:177], v[92:95]
	v_mfma_f32_16x16x32_bf16 v[76:79], v[218:221], v[182:185], v[76:79]
	v_mfma_f32_16x16x32_bf16 v[72:75], v[226:229], v[182:185], v[72:75]
	v_mfma_f32_16x16x32_bf16 v[68:71], v[218:221], v[210:213], v[68:71]
	v_mfma_f32_16x16x32_bf16 v[64:67], v[226:229], v[210:213], v[64:67]
	s_barrier
	s_add_i32 s19, s23, s57
	v_lshl_add_u64 v[230:231], s[54:55], 0, v[140:141]
	s_mov_b32 m0, s19
	s_nop 0
	global_load_lds_dwordx4 v[230:231], off
	v_lshl_add_u64 v[232:233], s[54:55], 0, v[150:151]
	s_add_i32 m0, s19, 0x2000
	s_nop 0
	global_load_lds_dwordx4 v[232:233], off
	s_mov_b32 m0, s68
	v_lshl_add_u64 v[234:235], s[58:59], 0, v[154:155]
	ds_read_b128 v[162:165], v208 offset:16384
	ds_read_b128 v[166:169], v208 offset:17408
	ds_read_b128 v[170:173], v208 offset:18432
	ds_read_b128 v[174:177], v208 offset:19456
	ds_read_b128 v[178:181], v208 offset:20480
	ds_read_b128 v[182:185], v208 offset:21504
	ds_read_b128 v[194:197], v208 offset:22528
	ds_read_b128 v[210:213], v208 offset:23552
	global_load_lds_dwordx4 v[234:235], off
	v_lshl_add_u64 v[236:237], s[58:59], 0, v[152:153]
	s_mov_b32 m0, s69
	s_nop 0
	global_load_lds_dwordx4 v[236:237], off
	s_add_u32 s84, s54, 0x40000
	s_addc_u32 s85, s55, 0
	s_add_i32 s6, s6, s57
	v_lshl_add_u64 v[250:251], s[84:85], 0, v[140:141]
	s_mov_b32 m0, s6
	s_nop 0
	global_load_lds_dwordx4 v[250:251], off
	v_lshl_add_u64 v[250:251], s[84:85], 0, v[150:151]
	s_add_i32 m0, s6, 0x2000
	s_nop 0
	global_load_lds_dwordx4 v[250:251], off
	s_waitcnt vmcnt(8)
	s_waitcnt lgkmcnt(0)
	s_barrier
	v_mfma_f32_16x16x32_bf16 v[60:63], v[128:131], v[162:165], v[60:63]
	v_mfma_f32_16x16x32_bf16 v[56:59], v[136:139], v[162:165], v[56:59]
	v_mfma_f32_16x16x32_bf16 v[48:51], v[128:131], v[170:173], v[48:51]
	v_mfma_f32_16x16x32_bf16 v[40:43], v[136:139], v[170:173], v[40:43]
	v_mfma_f32_16x16x32_bf16 v[32:35], v[128:131], v[178:181], v[32:35]
	v_mfma_f32_16x16x32_bf16 v[24:27], v[136:139], v[178:181], v[24:27]
	v_mfma_f32_16x16x32_bf16 v[16:19], v[128:131], v[194:197], v[16:19]
	v_mfma_f32_16x16x32_bf16 v[8:11], v[136:139], v[194:197], v[8:11]
	v_mfma_f32_16x16x32_bf16 v[60:63], v[132:135], v[166:169], v[60:63]
	v_mfma_f32_16x16x32_bf16 v[56:59], v[146:149], v[166:169], v[56:59]
	v_mfma_f32_16x16x32_bf16 v[48:51], v[132:135], v[174:177], v[48:51]
	v_mfma_f32_16x16x32_bf16 v[40:43], v[146:149], v[174:177], v[40:43]
	v_mfma_f32_16x16x32_bf16 v[32:35], v[132:135], v[182:185], v[32:35]
	v_mfma_f32_16x16x32_bf16 v[24:27], v[146:149], v[182:185], v[24:27]
	v_mfma_f32_16x16x32_bf16 v[16:19], v[132:135], v[210:213], v[16:19]
	v_mfma_f32_16x16x32_bf16 v[8:11], v[146:149], v[210:213], v[8:11]
	v_mfma_f32_16x16x32_bf16 v[52:55], v[214:217], v[162:165], v[52:55]
	v_mfma_f32_16x16x32_bf16 v[44:47], v[222:225], v[162:165], v[44:47]
	v_mfma_f32_16x16x32_bf16 v[36:39], v[214:217], v[170:173], v[36:39]
	v_mfma_f32_16x16x32_bf16 v[28:31], v[222:225], v[170:173], v[28:31]
	v_mfma_f32_16x16x32_bf16 v[20:23], v[214:217], v[178:181], v[20:23]
	v_mfma_f32_16x16x32_bf16 v[12:15], v[222:225], v[178:181], v[12:15]
	v_mfma_f32_16x16x32_bf16 v[4:7], v[214:217], v[194:197], v[4:7]
	v_mfma_f32_16x16x32_bf16 v[0:3], v[222:225], v[194:197], v[0:3]
	v_mfma_f32_16x16x32_bf16 v[52:55], v[218:221], v[166:169], v[52:55]
	v_mfma_f32_16x16x32_bf16 v[44:47], v[226:229], v[166:169], v[44:47]
	v_mfma_f32_16x16x32_bf16 v[36:39], v[218:221], v[174:177], v[36:39]
	v_mfma_f32_16x16x32_bf16 v[28:31], v[226:229], v[174:177], v[28:31]
	v_mfma_f32_16x16x32_bf16 v[20:23], v[218:221], v[182:185], v[20:23]
	v_mfma_f32_16x16x32_bf16 v[12:15], v[226:229], v[182:185], v[12:15]
	v_mfma_f32_16x16x32_bf16 v[4:7], v[218:221], v[210:213], v[4:7]
	v_mfma_f32_16x16x32_bf16 v[0:3], v[226:229], v[210:213], v[0:3]
	s_barrier
	s_add_i32 s6, 0, 0x18000
	v_add_u32_e32 v146, s6, v206
	ds_read_b128 v[128:131], v146
	ds_read_b128 v[132:135], v146 offset:1024
	ds_read_b128 v[136:139], v146 offset:2048
	ds_read_b128 v[146:149], v146 offset:3072
	s_add_u32 s58, s58, 0x40000
	s_addc_u32 s59, s59, 0
	s_mov_b32 m0, s70
	v_lshl_add_u64 v[214:215], s[58:59], 0, v[154:155]
	ds_read_b128 v[162:165], v208 offset:32768
	ds_read_b128 v[166:169], v208 offset:33792
	ds_read_b128 v[170:173], v208 offset:34816
	ds_read_b128 v[174:177], v208 offset:35840
	ds_read_b128 v[178:181], v208 offset:36864
	ds_read_b128 v[182:185], v208 offset:37888
	ds_read_b128 v[194:197], v208 offset:38912
	ds_read_b128 v[210:213], v208 offset:39936
	global_load_lds_dwordx4 v[214:215], off
	v_lshl_add_u64 v[214:215], s[58:59], 0, v[152:153]
	s_mov_b32 m0, s71
	s_nop 0
	global_load_lds_dwordx4 v[214:215], off
	s_add_i32 s19, 0, 0x1c000
	v_add_u32_e32 v192, s19, v206
	ds_read_b128 v[214:217], v192
	ds_read_b128 v[218:221], v192 offset:1024
	ds_read_b128 v[222:225], v192 offset:2048
	ds_read_b128 v[226:229], v192 offset:3072
	s_waitcnt vmcnt(8)
	s_waitcnt lgkmcnt(0)
	s_barrier
	v_mfma_f32_16x16x32_bf16 v[124:127], v[128:131], v[162:165], v[124:127]
	v_mfma_f32_16x16x32_bf16 v[120:123], v[136:139], v[162:165], v[120:123]
	v_mfma_f32_16x16x32_bf16 v[108:111], v[128:131], v[170:173], v[108:111]
	v_mfma_f32_16x16x32_bf16 v[104:107], v[136:139], v[170:173], v[104:107]
	v_mfma_f32_16x16x32_bf16 v[96:99], v[128:131], v[178:181], v[96:99]
	v_mfma_f32_16x16x32_bf16 v[88:91], v[136:139], v[178:181], v[88:91]
	v_mfma_f32_16x16x32_bf16 v[84:87], v[128:131], v[194:197], v[84:87]
	v_mfma_f32_16x16x32_bf16 v[80:83], v[136:139], v[194:197], v[80:83]
	v_mfma_f32_16x16x32_bf16 v[124:127], v[132:135], v[166:169], v[124:127]
	v_mfma_f32_16x16x32_bf16 v[120:123], v[146:149], v[166:169], v[120:123]
	v_mfma_f32_16x16x32_bf16 v[108:111], v[132:135], v[174:177], v[108:111]
	v_mfma_f32_16x16x32_bf16 v[104:107], v[146:149], v[174:177], v[104:107]
	v_mfma_f32_16x16x32_bf16 v[96:99], v[132:135], v[182:185], v[96:99]
	v_mfma_f32_16x16x32_bf16 v[88:91], v[146:149], v[182:185], v[88:91]
	v_mfma_f32_16x16x32_bf16 v[84:87], v[132:135], v[210:213], v[84:87]
	v_mfma_f32_16x16x32_bf16 v[80:83], v[146:149], v[210:213], v[80:83]
	v_mfma_f32_16x16x32_bf16 v[116:119], v[214:217], v[162:165], v[116:119]
	v_mfma_f32_16x16x32_bf16 v[112:115], v[222:225], v[162:165], v[112:115]
	v_mfma_f32_16x16x32_bf16 v[100:103], v[214:217], v[170:173], v[100:103]
	v_mfma_f32_16x16x32_bf16 v[92:95], v[222:225], v[170:173], v[92:95]
	v_mfma_f32_16x16x32_bf16 v[76:79], v[214:217], v[178:181], v[76:79]
	v_mfma_f32_16x16x32_bf16 v[72:75], v[222:225], v[178:181], v[72:75]
	v_mfma_f32_16x16x32_bf16 v[68:71], v[214:217], v[194:197], v[68:71]
	v_mfma_f32_16x16x32_bf16 v[64:67], v[222:225], v[194:197], v[64:67]
	v_mfma_f32_16x16x32_bf16 v[116:119], v[218:221], v[166:169], v[116:119]
	v_mfma_f32_16x16x32_bf16 v[112:115], v[226:229], v[166:169], v[112:115]
	v_mfma_f32_16x16x32_bf16 v[100:103], v[218:221], v[174:177], v[100:103]
	v_mfma_f32_16x16x32_bf16 v[92:95], v[226:229], v[174:177], v[92:95]
	v_mfma_f32_16x16x32_bf16 v[76:79], v[218:221], v[182:185], v[76:79]
	v_mfma_f32_16x16x32_bf16 v[72:75], v[226:229], v[182:185], v[72:75]
	v_mfma_f32_16x16x32_bf16 v[68:71], v[218:221], v[210:213], v[68:71]
	v_mfma_f32_16x16x32_bf16 v[64:67], v[226:229], v[210:213], v[64:67]
	s_barrier
	s_add_i32 s6, s6, s57
	v_lshl_add_u64 v[230:231], v[230:231], 0, s[36:37]
	s_mov_b32 m0, s6
	s_nop 0
	global_load_lds_dwordx4 v[230:231], off
	v_lshl_add_u64 v[230:231], v[232:233], 0, s[36:37]
	s_add_i32 m0, s6, 0x2000
	s_nop 0
	global_load_lds_dwordx4 v[230:231], off
	s_mov_b32 m0, s72
	v_lshl_add_u64 v[230:231], v[234:235], 0, s[36:37]
	ds_read_b128 v[162:165], v208 offset:49152
	ds_read_b128 v[166:169], v208 offset:50176
	ds_read_b128 v[170:173], v208 offset:51200
	ds_read_b128 v[174:177], v208 offset:52224
	ds_read_b128 v[178:181], v208 offset:53248
	ds_read_b128 v[182:185], v208 offset:54272
	ds_read_b128 v[194:197], v208 offset:55296
	ds_read_b128 v[210:213], v208 offset:56320
	global_load_lds_dwordx4 v[230:231], off
	v_lshl_add_u64 v[230:231], v[236:237], 0, s[36:37]
	s_mov_b32 m0, s73
	s_nop 0
	global_load_lds_dwordx4 v[230:231], off
	s_add_u32 s54, s54, 0x40080
	s_addc_u32 s55, s55, 0
	s_add_i32 s6, s19, s57
	v_lshl_add_u64 v[250:251], s[54:55], 0, v[140:141]
	s_mov_b32 m0, s6
	s_nop 0
	global_load_lds_dwordx4 v[250:251], off
	v_lshl_add_u64 v[250:251], s[54:55], 0, v[150:151]
	s_add_i32 m0, s6, 0x2000
	s_nop 0
	global_load_lds_dwordx4 v[250:251], off
	s_waitcnt vmcnt(8)
	s_waitcnt lgkmcnt(0)
	s_barrier
	v_mfma_f32_16x16x32_bf16 v[60:63], v[128:131], v[162:165], v[60:63]
	v_mfma_f32_16x16x32_bf16 v[56:59], v[136:139], v[162:165], v[56:59]
	v_mfma_f32_16x16x32_bf16 v[48:51], v[128:131], v[170:173], v[48:51]
	v_mfma_f32_16x16x32_bf16 v[40:43], v[136:139], v[170:173], v[40:43]
	v_mfma_f32_16x16x32_bf16 v[32:35], v[128:131], v[178:181], v[32:35]
	v_mfma_f32_16x16x32_bf16 v[24:27], v[136:139], v[178:181], v[24:27]
	v_mfma_f32_16x16x32_bf16 v[16:19], v[128:131], v[194:197], v[16:19]
	v_mfma_f32_16x16x32_bf16 v[8:11], v[136:139], v[194:197], v[8:11]
	v_mfma_f32_16x16x32_bf16 v[60:63], v[132:135], v[166:169], v[60:63]
	v_mfma_f32_16x16x32_bf16 v[56:59], v[146:149], v[166:169], v[56:59]
	v_mfma_f32_16x16x32_bf16 v[48:51], v[132:135], v[174:177], v[48:51]
	v_mfma_f32_16x16x32_bf16 v[40:43], v[146:149], v[174:177], v[40:43]
	v_mfma_f32_16x16x32_bf16 v[32:35], v[132:135], v[182:185], v[32:35]
	v_mfma_f32_16x16x32_bf16 v[24:27], v[146:149], v[182:185], v[24:27]
	v_mfma_f32_16x16x32_bf16 v[16:19], v[132:135], v[210:213], v[16:19]
	v_mfma_f32_16x16x32_bf16 v[8:11], v[146:149], v[210:213], v[8:11]
	v_mfma_f32_16x16x32_bf16 v[52:55], v[214:217], v[162:165], v[52:55]
	v_mfma_f32_16x16x32_bf16 v[44:47], v[222:225], v[162:165], v[44:47]
	v_mfma_f32_16x16x32_bf16 v[36:39], v[214:217], v[170:173], v[36:39]
	v_mfma_f32_16x16x32_bf16 v[28:31], v[222:225], v[170:173], v[28:31]
	v_mfma_f32_16x16x32_bf16 v[20:23], v[214:217], v[178:181], v[20:23]
	v_mfma_f32_16x16x32_bf16 v[12:15], v[222:225], v[178:181], v[12:15]
	v_mfma_f32_16x16x32_bf16 v[4:7], v[214:217], v[194:197], v[4:7]
	v_mfma_f32_16x16x32_bf16 v[0:3], v[222:225], v[194:197], v[0:3]
	v_mfma_f32_16x16x32_bf16 v[52:55], v[218:221], v[166:169], v[52:55]
	v_mfma_f32_16x16x32_bf16 v[44:47], v[226:229], v[166:169], v[44:47]
	v_mfma_f32_16x16x32_bf16 v[36:39], v[218:221], v[174:177], v[36:39]
	v_mfma_f32_16x16x32_bf16 v[28:31], v[226:229], v[174:177], v[28:31]
	v_mfma_f32_16x16x32_bf16 v[20:23], v[218:221], v[182:185], v[20:23]
	v_mfma_f32_16x16x32_bf16 v[12:15], v[226:229], v[182:185], v[12:15]
	v_mfma_f32_16x16x32_bf16 v[4:7], v[218:221], v[210:213], v[4:7]
	v_mfma_f32_16x16x32_bf16 v[0:3], v[226:229], v[210:213], v[0:3]
	s_add_i32 s82, s82, 2
	s_add_u32 s52, s52, 0x100
	s_addc_u32 s53, s53, 0
	s_add_u32 s39, s39, 0x100
	s_addc_u32 s51, s51, 0
	s_cmp_gt_u32 s82, 13
	s_barrier
	s_cbranch_scc0 .LBB0_248
	s_mov_b32 s100, 1
	s_ashr_i32 s51, s50, 31
	v_lshl_or_b32 v128, s81, 8, v207
	s_lshl_b64 s[10:11], s[50:51], 8
	v_ashrrev_i32_e32 v129, 31, v128
	v_lshl_add_u64 v[168:169], s[10:11], 0, v[156:157]
	v_lshlrev_b64 v[170:171], 1, v[128:129]
	v_lshl_add_u64 v[174:175], s[28:29], 0, v[170:171]
	v_lshlrev_b64 v[172:173], 11, v[168:169]
	v_lshl_add_u64 v[128:129], v[174:175], 0, v[172:173]
	global_load_dwordx4 v[146:149], v[128:129], off
	global_load_dwordx4 v[182:185], v[128:129], off offset:256
	v_or_b32_e32 v166, 16, v168
	v_mov_b32_e32 v167, v169
	v_lshlrev_b64 v[176:177], 11, v[166:167]
	v_lshl_add_u64 v[128:129], v[174:175], 0, v[176:177]
	global_load_dwordx4 v[194:197], v[128:129], off
	global_load_dwordx4 v[210:213], v[128:129], off offset:256
	v_or_b32_e32 v164, 32, v168
	v_mov_b32_e32 v165, v169
	v_or_b32_e32 v162, 48, v168
	v_mov_b32_e32 v163, v169
	v_lshlrev_b64 v[180:181], 11, v[164:165]
	v_lshlrev_b64 v[178:179], 11, v[162:163]
	v_lshl_add_u64 v[128:129], v[174:175], 0, v[180:181]
	v_lshl_add_u64 v[130:131], v[174:175], 0, v[178:179]
	global_load_dwordx4 v[214:217], v[128:129], off
	global_load_dwordx4 v[136:139], v[128:129], off offset:256
	global_load_dwordx4 v[132:135], v[130:131], off
	s_nop 0
	global_load_dwordx4 v[128:131], v[130:131], off offset:256
	s_mov_b64 s[10:11], 0x90
	v_lshl_add_u64 v[172:173], s[30:31], 0, v[172:173]
	v_lshl_add_u64 v[172:173], v[172:173], 0, v[170:171]
	s_waitcnt vmcnt(0)
	v_lshlrev_b32_e32 v218, 16, v146
	v_and_b32_e32 v219, 0xffff0000, v146
	v_lshlrev_b32_e32 v220, 16, v148
	v_and_b32_e32 v221, 0xffff0000, v148
	v_lshlrev_b32_e32 v146, 16, v147
	v_and_b32_e32 v147, 0xffff0000, v147
	v_lshlrev_b32_e32 v222, 16, v182
	v_and_b32_e32 v223, 0xffff0000, v182
	v_lshlrev_b32_e32 v224, 16, v184
	v_and_b32_e32 v225, 0xffff0000, v184
	v_lshlrev_b32_e32 v182, 16, v183
	v_and_b32_e32 v183, 0xffff0000, v183
	v_pk_add_f32 v[124:125], v[124:125], v[218:219]
	v_pk_add_f32 v[120:121], v[120:121], v[220:221]
	v_pk_add_f32 v[126:127], v[126:127], v[146:147]
	v_pk_add_f32 v[116:117], v[116:117], v[222:223]
	v_pk_add_f32 v[146:147], v[112:113], v[224:225]
	v_pk_add_f32 v[118:119], v[118:119], v[182:183]
	v_pk_mul_f32 v[220:221], v[124:125], v[124:125]
	v_pk_mul_f32 v[222:223], v[126:127], v[126:127]
	v_cvt_pk_bf16_f32 v112, v124, v125
	v_cvt_pk_bf16_f32 v113, v126, v127
	v_pk_mul_f32 v[124:125], v[116:117], v[116:117]
	v_pk_mul_f32 v[126:127], v[118:119], v[118:119]
	v_pk_mul_f32 v[228:229], v[146:147], v[146:147]
	v_cvt_pk_bf16_f32 v116, v116, v117
	v_cvt_pk_bf16_f32 v117, v118, v119
	v_cvt_pk_bf16_f32 v118, v146, v147
	v_add_f32_e32 v146, v220, v221
	v_add_f32_e32 v146, v222, v146
	v_lshlrev_b32_e32 v148, 16, v149
	v_and_b32_e32 v149, 0xffff0000, v149
	v_pk_mul_f32 v[224:225], v[120:121], v[120:121]
	v_add_f32_e32 v146, v223, v146
	v_pk_add_f32 v[122:123], v[122:123], v[148:149]
	v_add_f32_e32 v146, v224, v146
	v_pk_mul_f32 v[226:227], v[122:123], v[122:123]
	v_add_f32_e32 v146, v225, v146
	v_add_f32_e32 v146, v226, v146
	v_add_f32_e32 v146, v227, v146
	v_add_f32_e32 v124, v124, v146
	v_add_f32_e32 v124, v125, v124
	v_add_f32_e32 v124, v126, v124
	v_lshlrev_b32_e32 v184, 16, v185
	v_and_b32_e32 v185, 0xffff0000, v185
	v_add_f32_e32 v124, v127, v124
	v_pk_add_f32 v[148:149], v[114:115], v[184:185]
	v_add_f32_e32 v124, v228, v124
	v_pk_mul_f32 v[230:231], v[148:149], v[148:149]
	v_add_f32_e32 v124, v229, v124
	v_add_f32_e32 v124, v230, v124
	v_add_f32_e32 v209, v231, v124
	v_lshlrev_b32_e32 v124, 16, v212
	v_and_b32_e32 v125, 0xffff0000, v212
	v_pk_add_f32 v[124:125], v[92:93], v[124:125]
	v_lshlrev_b32_e32 v92, 16, v211
	v_and_b32_e32 v93, 0xffff0000, v211
	v_pk_add_f32 v[102:103], v[102:103], v[92:93]
	v_lshlrev_b32_e32 v92, 16, v213
	v_and_b32_e32 v93, 0xffff0000, v213
	v_pk_add_f32 v[126:127], v[94:95], v[92:93]
	v_lshlrev_b32_e32 v92, 16, v214
	v_and_b32_e32 v93, 0xffff0000, v214
	v_pk_add_f32 v[92:93], v[96:97], v[92:93]
	v_lshlrev_b32_e32 v96, 16, v217
	v_and_b32_e32 v97, 0xffff0000, v217
	v_lshlrev_b32_e32 v94, 16, v216
	v_and_b32_e32 v95, 0xffff0000, v216
	v_pk_add_f32 v[90:91], v[90:91], v[96:97]
	v_lshlrev_b32_e32 v96, 16, v136
	v_and_b32_e32 v97, 0xffff0000, v136
	v_lshlrev_b32_e32 v182, 16, v194
	v_and_b32_e32 v183, 0xffff0000, v194
	v_pk_add_f32 v[88:89], v[88:89], v[94:95]
	v_lshlrev_b32_e32 v94, 16, v215
	v_and_b32_e32 v95, 0xffff0000, v215
	v_pk_add_f32 v[96:97], v[76:77], v[96:97]
	v_lshl_add_u64 v[76:77], v[168:169], 0, s[36:37]
	v_lshlrev_b32_e32 v184, 16, v196
	v_and_b32_e32 v185, 0xffff0000, v196
	v_cvt_pk_bf16_f32 v114, v120, v121
	v_pk_add_f32 v[120:121], v[108:109], v[182:183]
	v_pk_add_f32 v[94:95], v[98:99], v[94:95]
	v_lshlrev_b64 v[182:183], 11, v[76:77]
	v_lshlrev_b32_e32 v98, 16, v138
	v_and_b32_e32 v99, 0xffff0000, v138
	v_pk_add_f32 v[108:109], v[104:105], v[184:185]
	v_lshl_add_u64 v[184:185], v[174:175], 0, v[182:183]
	v_pk_add_f32 v[98:99], v[72:73], v[98:99]
	v_lshlrev_b32_e32 v72, 16, v137
	v_and_b32_e32 v73, 0xffff0000, v137
	v_lshlrev_b32_e32 v218, 16, v210
	v_and_b32_e32 v219, 0xffff0000, v210
	global_load_dwordx4 v[210:213], v[184:185], off
	v_pk_add_f32 v[136:137], v[78:79], v[72:73]
	v_lshlrev_b32_e32 v72, 16, v139
	v_and_b32_e32 v73, 0xffff0000, v139
	v_pk_add_f32 v[138:139], v[74:75], v[72:73]
	v_lshlrev_b32_e32 v72, 16, v132
	v_and_b32_e32 v73, 0xffff0000, v132
	v_pk_add_f32 v[74:75], v[84:85], v[72:73]
	v_lshlrev_b32_e32 v72, 16, v134
	v_and_b32_e32 v73, 0xffff0000, v134
	v_pk_add_f32 v[78:79], v[80:81], v[72:73]
	v_lshlrev_b32_e32 v72, 16, v133
	v_and_b32_e32 v73, 0xffff0000, v133
	v_pk_add_f32 v[100:101], v[100:101], v[218:219]
	global_load_dwordx4 v[218:221], v[184:185], off offset:256
	v_pk_add_f32 v[80:81], v[86:87], v[72:73]
	v_lshlrev_b32_e32 v72, 16, v135
	v_and_b32_e32 v73, 0xffff0000, v135
	v_pk_add_f32 v[82:83], v[82:83], v[72:73]
	v_lshl_add_u64 v[72:73], v[168:169], 0, s[10:11]
	v_lshlrev_b64 v[132:133], 11, v[72:73]
	v_lshl_add_u64 v[134:135], v[174:175], 0, v[132:133]
	v_lshlrev_b32_e32 v84, 16, v128
	v_and_b32_e32 v85, 0xffff0000, v128
	global_load_dwordx4 v[226:229], v[134:135], off
	global_load_dwordx4 v[234:237], v[134:135], off offset:256
	v_pk_add_f32 v[84:85], v[68:69], v[84:85]
	v_lshlrev_b32_e32 v68, 16, v130
	v_and_b32_e32 v69, 0xffff0000, v130
	v_pk_add_f32 v[86:87], v[64:65], v[68:69]
	v_lshlrev_b32_e32 v64, 16, v129
	v_and_b32_e32 v65, 0xffff0000, v129
	s_mov_b64 s[10:11], 0xa0
	v_pk_add_f32 v[128:129], v[70:71], v[64:65]
	v_lshl_add_u64 v[70:71], v[168:169], 0, s[10:11]
	s_mov_b64 s[10:11], 0xb0
	v_lshlrev_b32_e32 v64, 16, v131
	v_and_b32_e32 v65, 0xffff0000, v131
	v_lshlrev_b64 v[134:135], 11, v[70:71]
	v_lshl_add_u64 v[68:69], v[168:169], 0, s[10:11]
	v_pk_add_f32 v[130:131], v[66:67], v[64:65]
	v_lshl_add_u64 v[64:65], v[174:175], 0, v[134:135]
	v_lshlrev_b64 v[184:185], 11, v[68:69]
	global_load_dwordx4 v[238:241], v[64:65], off
	global_load_dwordx4 v[242:245], v[64:65], off offset:256
	v_lshl_add_u64 v[64:65], v[174:175], 0, v[184:185]
	global_load_dwordx4 v[246:249], v[64:65], off
	s_nop 0
	global_load_dwordx4 v[64:67], v[64:65], off offset:256
	v_lshlrev_b32_e32 v194, 16, v195
	v_and_b32_e32 v195, 0xffff0000, v195
	v_lshlrev_b32_e32 v196, 16, v197
	v_and_b32_e32 v197, 0xffff0000, v197
	v_cvt_pk_bf16_f32 v115, v122, v123
	v_cvt_pk_bf16_f32 v119, v148, v149
	v_pk_add_f32 v[122:123], v[110:111], v[194:195]
	v_pk_add_f32 v[110:111], v[106:107], v[196:197]
	global_store_dwordx4 v[172:173], v[112:115], off
	global_store_dwordx4 v[172:173], v[116:119], off offset:256
	v_cvt_pk_bf16_f32 v104, v120, v121
	v_lshl_add_u64 v[112:113], s[30:31], 0, v[176:177]
	v_cvt_pk_bf16_f32 v105, v122, v123
	v_cvt_pk_bf16_f32 v106, v108, v109
	v_cvt_pk_bf16_f32 v107, v110, v111
	v_lshl_add_u64 v[112:113], v[112:113], 0, v[170:171]
	v_cvt_pk_bf16_f32 v146, v100, v101
	v_cvt_pk_bf16_f32 v147, v102, v103
	v_cvt_pk_bf16_f32 v148, v124, v125
	v_cvt_pk_bf16_f32 v149, v126, v127
	global_store_dwordx4 v[112:113], v[104:107], off
	global_store_dwordx4 v[112:113], v[146:149], off offset:256
	v_cvt_pk_bf16_f32 v194, v92, v93
	v_lshl_add_u64 v[104:105], s[30:31], 0, v[180:181]
	v_cvt_pk_bf16_f32 v195, v94, v95
	v_cvt_pk_bf16_f32 v196, v88, v89
	v_cvt_pk_bf16_f32 v197, v90, v91
	v_lshl_add_u64 v[104:105], v[104:105], 0, v[170:171]
	v_cvt_pk_bf16_f32 v214, v96, v97
	v_cvt_pk_bf16_f32 v215, v136, v137
	v_cvt_pk_bf16_f32 v216, v98, v99
	v_cvt_pk_bf16_f32 v217, v138, v139
	global_store_dwordx4 v[104:105], v[194:197], off
	global_store_dwordx4 v[104:105], v[214:217], off offset:256
	v_lshl_add_u64 v[104:105], s[30:31], 0, v[178:179]
	v_cvt_pk_bf16_f32 v222, v74, v75
	v_cvt_pk_bf16_f32 v223, v80, v81
	v_cvt_pk_bf16_f32 v224, v78, v79
	v_cvt_pk_bf16_f32 v225, v82, v83
	v_lshl_add_u64 v[104:105], v[104:105], 0, v[170:171]
	v_cvt_pk_bf16_f32 v230, v84, v85
	v_cvt_pk_bf16_f32 v231, v128, v129
	v_cvt_pk_bf16_f32 v232, v86, v87
	v_cvt_pk_bf16_f32 v233, v130, v131
	global_store_dwordx4 v[104:105], v[222:225], off
	global_store_dwordx4 v[104:105], v[230:233], off offset:256
	s_waitcnt vmcnt(0)
	v_lshlrev_b32_e32 v104, 16, v210
	v_and_b32_e32 v105, 0xffff0000, v210
	v_pk_add_f32 v[60:61], v[60:61], v[104:105]
	v_lshlrev_b32_e32 v104, 16, v212
	v_and_b32_e32 v105, 0xffff0000, v212
	v_pk_add_f32 v[56:57], v[56:57], v[104:105]
	v_lshlrev_b32_e32 v104, 16, v211
	v_and_b32_e32 v105, 0xffff0000, v211
	v_pk_add_f32 v[62:63], v[62:63], v[104:105]
	v_lshlrev_b32_e32 v104, 16, v213
	v_and_b32_e32 v105, 0xffff0000, v213
	v_pk_add_f32 v[58:59], v[58:59], v[104:105]
	v_lshlrev_b32_e32 v104, 16, v218
	v_and_b32_e32 v105, 0xffff0000, v218
	v_pk_add_f32 v[52:53], v[52:53], v[104:105]
	v_lshlrev_b32_e32 v104, 16, v220
	v_and_b32_e32 v105, 0xffff0000, v220
	v_pk_add_f32 v[104:105], v[44:45], v[104:105]
	v_lshlrev_b32_e32 v44, 16, v219
	v_and_b32_e32 v45, 0xffff0000, v219
	v_pk_add_f32 v[54:55], v[54:55], v[44:45]
	v_lshlrev_b32_e32 v44, 16, v221
	v_and_b32_e32 v45, 0xffff0000, v221
	v_pk_add_f32 v[106:107], v[46:47], v[44:45]
	v_lshlrev_b32_e32 v44, 16, v226
	v_and_b32_e32 v45, 0xffff0000, v226
	v_pk_add_f32 v[44:45], v[48:49], v[44:45]
	v_lshlrev_b32_e32 v48, 16, v229
	v_and_b32_e32 v49, 0xffff0000, v229
	v_pk_add_f32 v[42:43], v[42:43], v[48:49]
	v_lshlrev_b32_e32 v48, 16, v234
	v_and_b32_e32 v49, 0xffff0000, v234
	v_pk_add_f32 v[36:37], v[36:37], v[48:49]
	v_lshlrev_b32_e32 v48, 16, v236
	v_and_b32_e32 v49, 0xffff0000, v236
	v_lshlrev_b32_e32 v46, 16, v228
	v_and_b32_e32 v47, 0xffff0000, v228
	v_pk_add_f32 v[48:49], v[28:29], v[48:49]
	v_lshlrev_b32_e32 v28, 16, v235
	v_and_b32_e32 v29, 0xffff0000, v235
	v_pk_add_f32 v[40:41], v[40:41], v[46:47]
	v_lshlrev_b32_e32 v46, 16, v227
	v_and_b32_e32 v47, 0xffff0000, v227
	v_pk_add_f32 v[38:39], v[38:39], v[28:29]
	v_lshlrev_b32_e32 v28, 16, v237
	v_and_b32_e32 v29, 0xffff0000, v237
	v_pk_add_f32 v[46:47], v[50:51], v[46:47]
	v_pk_add_f32 v[50:51], v[30:31], v[28:29]
	v_lshlrev_b32_e32 v28, 16, v238
	v_and_b32_e32 v29, 0xffff0000, v238
	v_lshlrev_b32_e32 v180, 16, v64
	v_and_b32_e32 v181, 0xffff0000, v64
	v_pk_add_f32 v[28:29], v[32:33], v[28:29]
	v_lshlrev_b32_e32 v32, 16, v241
	v_and_b32_e32 v33, 0xffff0000, v241
	v_pk_add_f32 v[4:5], v[4:5], v[180:181]
	v_lshlrev_b32_e32 v180, 16, v66
	v_and_b32_e32 v181, 0xffff0000, v66
	v_pk_add_f32 v[26:27], v[26:27], v[32:33]
	v_lshlrev_b32_e32 v32, 16, v242
	v_and_b32_e32 v33, 0xffff0000, v242
	v_pk_add_f32 v[0:1], v[0:1], v[180:181]
	v_lshl_add_u64 v[180:181], s[30:31], 0, v[182:183]
	v_cvt_pk_bf16_f32 v112, v60, v61
	v_cvt_pk_bf16_f32 v113, v62, v63
	v_cvt_pk_bf16_f32 v114, v56, v57
	v_cvt_pk_bf16_f32 v115, v58, v59
	v_pk_add_f32 v[20:21], v[20:21], v[32:33]
	v_lshlrev_b32_e32 v32, 16, v244
	v_and_b32_e32 v33, 0xffff0000, v244
	v_lshl_add_u64 v[180:181], v[180:181], 0, v[170:171]
	v_cvt_pk_bf16_f32 v116, v52, v53
	v_cvt_pk_bf16_f32 v117, v54, v55
	v_cvt_pk_bf16_f32 v118, v104, v105
	v_cvt_pk_bf16_f32 v119, v106, v107
	v_lshlrev_b32_e32 v30, 16, v240
	v_and_b32_e32 v31, 0xffff0000, v240
	v_pk_add_f32 v[32:33], v[12:13], v[32:33]
	v_lshlrev_b32_e32 v12, 16, v243
	v_and_b32_e32 v13, 0xffff0000, v243
	global_store_dwordx4 v[180:181], v[112:115], off
	global_store_dwordx4 v[180:181], v[116:119], off offset:256
	v_cvt_pk_bf16_f32 v146, v44, v45
	v_lshl_add_u64 v[112:113], s[30:31], 0, v[132:133]
	v_cvt_pk_bf16_f32 v147, v46, v47
	v_cvt_pk_bf16_f32 v148, v40, v41
	v_cvt_pk_bf16_f32 v149, v42, v43
	v_pk_add_f32 v[24:25], v[24:25], v[30:31]
	v_lshlrev_b32_e32 v30, 16, v239
	v_and_b32_e32 v31, 0xffff0000, v239
	v_pk_add_f32 v[22:23], v[22:23], v[12:13]
	v_lshlrev_b32_e32 v12, 16, v245
	v_and_b32_e32 v13, 0xffff0000, v245
	v_lshl_add_u64 v[112:113], v[112:113], 0, v[170:171]
	v_cvt_pk_bf16_f32 v172, v36, v37
	v_cvt_pk_bf16_f32 v173, v38, v39
	v_cvt_pk_bf16_f32 v174, v48, v49
	v_cvt_pk_bf16_f32 v175, v50, v51
	v_pk_add_f32 v[30:31], v[34:35], v[30:31]
	v_pk_add_f32 v[34:35], v[14:15], v[12:13]
	v_lshlrev_b32_e32 v12, 16, v246
	v_and_b32_e32 v13, 0xffff0000, v246
	v_lshlrev_b32_e32 v14, 16, v248
	v_and_b32_e32 v15, 0xffff0000, v248
	global_store_dwordx4 v[112:113], v[146:149], off
	global_store_dwordx4 v[112:113], v[172:175], off offset:256
	v_lshl_add_u64 v[112:113], s[30:31], 0, v[134:135]
	v_cvt_pk_bf16_f32 v176, v28, v29
	v_cvt_pk_bf16_f32 v177, v30, v31
	v_cvt_pk_bf16_f32 v178, v24, v25
	v_cvt_pk_bf16_f32 v179, v26, v27
	v_pk_add_f32 v[12:13], v[16:17], v[12:13]
	v_pk_add_f32 v[8:9], v[8:9], v[14:15]
	v_lshlrev_b32_e32 v14, 16, v247
	v_and_b32_e32 v15, 0xffff0000, v247
	v_lshlrev_b32_e32 v16, 16, v249
	v_and_b32_e32 v17, 0xffff0000, v249
	v_lshlrev_b32_e32 v64, 16, v65
	v_and_b32_e32 v65, 0xffff0000, v65
	v_lshl_add_u64 v[112:113], v[112:113], 0, v[170:171]
	v_cvt_pk_bf16_f32 v194, v20, v21
	v_cvt_pk_bf16_f32 v195, v22, v23
	v_cvt_pk_bf16_f32 v196, v32, v33
	v_cvt_pk_bf16_f32 v197, v34, v35
	v_pk_add_f32 v[14:15], v[18:19], v[14:15]
	v_pk_add_f32 v[10:11], v[10:11], v[16:17]
	v_pk_add_f32 v[6:7], v[6:7], v[64:65]
	v_lshlrev_b32_e32 v64, 16, v67
	v_and_b32_e32 v65, 0xffff0000, v67
	global_store_dwordx4 v[112:113], v[176:179], off
	global_store_dwordx4 v[112:113], v[194:197], off offset:256
	v_lshl_add_u64 v[112:113], s[30:31], 0, v[184:185]
	v_cvt_pk_bf16_f32 v16, v12, v13
	v_cvt_pk_bf16_f32 v17, v14, v15
	v_cvt_pk_bf16_f32 v18, v8, v9
	v_cvt_pk_bf16_f32 v19, v10, v11
	v_pk_add_f32 v[2:3], v[2:3], v[64:65]
	v_lshl_add_u64 v[112:113], v[112:113], 0, v[170:171]
	v_cvt_pk_bf16_f32 v64, v4, v5
	v_cvt_pk_bf16_f32 v65, v6, v7
	v_cvt_pk_bf16_f32 v66, v0, v1
	v_cvt_pk_bf16_f32 v67, v2, v3
	global_store_dwordx4 v[112:113], v[16:19], off
	global_store_dwordx4 v[112:113], v[64:67], off offset:256
	s_lshl_b32 s10, s81, 2
	v_and_b32_e32 v17, 64, v188
	v_xor_b32_e32 v16, 16, v188
	v_add_u32_e32 v17, 64, v17
	v_cmp_lt_i32_e32 vcc, v16, v17
	v_xor_b32_e32 v18, 32, v188
	s_ashr_i32 s11, s10, 31
	v_cndmask_b32_e32 v16, v188, v16, vcc
	v_lshlrev_b32_e32 v16, 2, v16
	ds_bpermute_b32 v19, v16, v209
	v_cmp_lt_i32_e32 vcc, v18, v17
	s_lshl_b64 s[10:11], s[10:11], 2
	s_add_u32 s50, s75, s10
	v_cndmask_b32_e32 v17, v188, v18, vcc
	v_lshlrev_b32_e32 v17, 2, v17
	s_waitcnt lgkmcnt(0)
	v_add_f32_e32 v18, v209, v19
	ds_bpermute_b32 v19, v17, v18
	s_addc_u32 s51, s80, s11
	s_and_saveexec_b64 s[52:53], s[42:43]
	s_cbranch_execz .LBB0_251
	s_waitcnt lgkmcnt(0)
	v_add_f32_e32 v64, v18, v19
	v_lshlrev_b64 v[18:19], 6, v[168:169]
	v_lshl_add_u64 v[18:19], s[50:51], 0, v[18:19]
	global_store_dword v[18:19], v64, off

.Lm4ap_295:
	s_waitcnt lgkmcnt(0)
	s_barrier
	s_nop 0
	v_mfma_f32_16x16x32_bf16 v[124:127], v[146:149], v[170:173], 0
	v_mfma_f32_16x16x32_bf16 v[120:123], v[162:165], v[170:173], 0
	v_mfma_f32_16x16x32_bf16 v[116:119], v[146:149], v[178:181], 0
	v_mfma_f32_16x16x32_bf16 v[112:115], v[162:165], v[178:181], 0
	v_mfma_f32_16x16x32_bf16 v[108:111], v[146:149], v[194:197], 0
	v_mfma_f32_16x16x32_bf16 v[104:107], v[162:165], v[194:197], 0
	v_mfma_f32_16x16x32_bf16 v[100:103], v[146:149], v[210:213], 0
	v_mfma_f32_16x16x32_bf16 v[96:99], v[162:165], v[210:213], 0
	v_mfma_f32_16x16x32_bf16 v[124:127], v[158:161], v[174:177], v[124:127]
	v_mfma_f32_16x16x32_bf16 v[120:123], v[166:169], v[174:177], v[120:123]
	v_mfma_f32_16x16x32_bf16 v[116:119], v[158:161], v[182:185], v[116:119]
	v_mfma_f32_16x16x32_bf16 v[112:115], v[166:169], v[182:185], v[112:115]
	v_mfma_f32_16x16x32_bf16 v[108:111], v[158:161], v[206:209], v[108:111]
	v_mfma_f32_16x16x32_bf16 v[104:107], v[166:169], v[206:209], v[104:107]
	v_mfma_f32_16x16x32_bf16 v[100:103], v[158:161], v[214:217], v[100:103]
	v_mfma_f32_16x16x32_bf16 v[96:99], v[166:169], v[214:217], v[96:99]
	v_mfma_f32_16x16x32_bf16 v[92:95], v[218:221], v[170:173], 0
	v_mfma_f32_16x16x32_bf16 v[88:91], v[226:229], v[170:173], 0
	v_mfma_f32_16x16x32_bf16 v[84:87], v[218:221], v[178:181], 0
	v_mfma_f32_16x16x32_bf16 v[80:83], v[226:229], v[178:181], 0
	v_mfma_f32_16x16x32_bf16 v[76:79], v[218:221], v[194:197], 0
	v_mfma_f32_16x16x32_bf16 v[72:75], v[226:229], v[194:197], 0
	v_mfma_f32_16x16x32_bf16 v[68:71], v[218:221], v[210:213], 0
	v_mfma_f32_16x16x32_bf16 v[64:67], v[226:229], v[210:213], 0
	v_mfma_f32_16x16x32_bf16 v[92:95], v[222:225], v[174:177], v[92:95]
	v_mfma_f32_16x16x32_bf16 v[88:91], v[230:233], v[174:177], v[88:91]
	v_mfma_f32_16x16x32_bf16 v[84:87], v[222:225], v[182:185], v[84:87]
	v_mfma_f32_16x16x32_bf16 v[80:83], v[230:233], v[182:185], v[80:83]
	v_mfma_f32_16x16x32_bf16 v[76:79], v[222:225], v[206:209], v[76:79]
	v_mfma_f32_16x16x32_bf16 v[72:75], v[230:233], v[206:209], v[72:75]
	v_mfma_f32_16x16x32_bf16 v[68:71], v[222:225], v[214:217], v[68:71]
	v_mfma_f32_16x16x32_bf16 v[64:67], v[230:233], v[214:217], v[64:67]
	s_barrier
	s_add_i32 s19, s80, s57
	v_lshl_add_u64 v[234:235], s[50:51], 0, v[140:141]
	s_mov_b32 m0, s19
	s_nop 0
	global_load_lds_dwordx4 v[234:235], off
	v_lshl_add_u64 v[236:237], s[50:51], 0, v[132:133]
	s_add_i32 m0, s19, 0x2000
	s_nop 0
	global_load_lds_dwordx4 v[236:237], off
	s_mov_b32 m0, s58
	v_lshl_add_u64 v[238:239], s[52:53], 0, v[128:129]
	ds_read_b128 v[170:173], v157 offset:16384
	ds_read_b128 v[174:177], v157 offset:17408
	ds_read_b128 v[178:181], v157 offset:18432
	ds_read_b128 v[182:185], v157 offset:19456
	ds_read_b128 v[194:197], v157 offset:20480
	ds_read_b128 v[206:209], v157 offset:21504
	ds_read_b128 v[210:213], v157 offset:22528
	ds_read_b128 v[214:217], v157 offset:23552
	global_load_lds_dwordx4 v[238:239], off
	v_lshl_add_u64 v[240:241], s[52:53], 0, v[130:131]
	s_mov_b32 m0, s59
	s_nop 0
	global_load_lds_dwordx4 v[240:241], off
	s_add_u32 s80, s50, 0x40000
	s_addc_u32 s81, s51, 0
	s_add_i32 s6, s6, s57
	v_lshl_add_u64 v[250:251], s[80:81], 0, v[140:141]
	s_mov_b32 m0, s6
	s_nop 0
	global_load_lds_dwordx4 v[250:251], off
	v_lshl_add_u64 v[250:251], s[80:81], 0, v[132:133]
	s_add_i32 m0, s6, 0x2000
	s_nop 0
	global_load_lds_dwordx4 v[250:251], off
	s_waitcnt vmcnt(24)
	s_cmp_lg_u32 s100, 0
	s_cbranch_scc1 .Lm4bp_295
	s_waitcnt vmcnt(8)

.LBB0_341:
	s_add_u32 s46, s50, 0x100
	s_addc_u32 s47, s51, 0
	s_add_i32 s6, 0, 0x10000
	v_add_u32_e32 v146, s6, v206
	ds_read_b128 v[128:131], v146
	ds_read_b128 v[132:135], v146 offset:1024
	ds_read_b128 v[136:139], v146 offset:2048
	ds_read_b128 v[146:149], v146 offset:3072
	s_cmp_eq_u32 s12, 40
	s_cselect_b32 s53, s31, s47
	s_cselect_b32 s52, s30, s46
	s_cselect_b32 s49, s35, s11
	s_cselect_b32 s48, s34, s10
	v_lshl_add_u64 v[214:215], s[50:51], 0, v[158:159]
	s_add_i32 m0, s58, 0xc000
	ds_read_b128 v[162:165], v208
	ds_read_b128 v[166:169], v208 offset:1024
	ds_read_b128 v[170:173], v208 offset:2048
	ds_read_b128 v[174:177], v208 offset:3072
	ds_read_b128 v[178:181], v208 offset:4096
	ds_read_b128 v[182:185], v208 offset:5120
	ds_read_b128 v[194:197], v208 offset:6144
	ds_read_b128 v[210:213], v208 offset:7168
	global_load_lds_dwordx4 v[214:215], off
	v_lshl_add_u64 v[214:215], s[50:51], 0, v[160:161]
	s_add_i32 m0, s58, 0xe000
	s_nop 0
	global_load_lds_dwordx4 v[214:215], off
	s_add_i32 s19, 0, 0x14000
	v_add_u32_e32 v192, s19, v206
	ds_read_b128 v[214:217], v192
	ds_read_b128 v[218:221], v192 offset:1024
	ds_read_b128 v[222:225], v192 offset:2048
	ds_read_b128 v[226:229], v192 offset:3072
	s_nop 0
	s_waitcnt vmcnt(8)
	s_waitcnt lgkmcnt(0)
	s_barrier
	v_mfma_f32_16x16x32_bf16 v[124:127], v[128:131], v[162:165], v[124:127]
	v_mfma_f32_16x16x32_bf16 v[120:123], v[136:139], v[162:165], v[120:123]
	v_mfma_f32_16x16x32_bf16 v[108:111], v[128:131], v[170:173], v[108:111]
	v_mfma_f32_16x16x32_bf16 v[104:107], v[136:139], v[170:173], v[104:107]
	v_mfma_f32_16x16x32_bf16 v[96:99], v[128:131], v[178:181], v[96:99]
	v_mfma_f32_16x16x32_bf16 v[88:91], v[136:139], v[178:181], v[88:91]
	v_mfma_f32_16x16x32_bf16 v[84:87], v[128:131], v[194:197], v[84:87]
	v_mfma_f32_16x16x32_bf16 v[80:83], v[136:139], v[194:197], v[80:83]
	v_mfma_f32_16x16x32_bf16 v[124:127], v[132:135], v[166:169], v[124:127]
	v_mfma_f32_16x16x32_bf16 v[120:123], v[146:149], v[166:169], v[120:123]
	v_mfma_f32_16x16x32_bf16 v[108:111], v[132:135], v[174:177], v[108:111]
	v_mfma_f32_16x16x32_bf16 v[104:107], v[146:149], v[174:177], v[104:107]
	v_mfma_f32_16x16x32_bf16 v[96:99], v[132:135], v[182:185], v[96:99]
	v_mfma_f32_16x16x32_bf16 v[88:91], v[146:149], v[182:185], v[88:91]
	v_mfma_f32_16x16x32_bf16 v[84:87], v[132:135], v[210:213], v[84:87]
	v_mfma_f32_16x16x32_bf16 v[80:83], v[146:149], v[210:213], v[80:83]
	v_mfma_f32_16x16x32_bf16 v[116:119], v[214:217], v[162:165], v[116:119]
	v_mfma_f32_16x16x32_bf16 v[112:115], v[222:225], v[162:165], v[112:115]
	v_mfma_f32_16x16x32_bf16 v[100:103], v[214:217], v[170:173], v[100:103]
	v_mfma_f32_16x16x32_bf16 v[92:95], v[222:225], v[170:173], v[92:95]
	v_mfma_f32_16x16x32_bf16 v[76:79], v[214:217], v[178:181], v[76:79]
	v_mfma_f32_16x16x32_bf16 v[72:75], v[222:225], v[178:181], v[72:75]
	v_mfma_f32_16x16x32_bf16 v[68:71], v[214:217], v[194:197], v[68:71]
	v_mfma_f32_16x16x32_bf16 v[64:67], v[222:225], v[194:197], v[64:67]
	v_mfma_f32_16x16x32_bf16 v[116:119], v[218:221], v[166:169], v[116:119]
	v_mfma_f32_16x16x32_bf16 v[112:115], v[226:229], v[166:169], v[112:115]
	v_mfma_f32_16x16x32_bf16 v[100:103], v[218:221], v[174:177], v[100:103]
	v_mfma_f32_16x16x32_bf16 v[92:95], v[226:229], v[174:177], v[92:95]
	v_mfma_f32_16x16x32_bf16 v[76:79], v[218:221], v[182:185], v[76:79]
	v_mfma_f32_16x16x32_bf16 v[72:75], v[226:229], v[182:185], v[72:75]
	v_mfma_f32_16x16x32_bf16 v[68:71], v[218:221], v[210:213], v[68:71]
	v_mfma_f32_16x16x32_bf16 v[64:67], v[226:229], v[210:213], v[64:67]
	s_barrier
	s_add_i32 s6, s6, s57
	v_lshl_add_u64 v[230:231], s[48:49], 0, v[140:141]
	s_mov_b32 m0, s6
	s_nop 0
	global_load_lds_dwordx4 v[230:231], off
	v_lshl_add_u64 v[232:233], s[48:49], 0, v[150:151]
	s_add_i32 m0, s6, 0x2000
	s_nop 0
	global_load_lds_dwordx4 v[232:233], off
	s_mov_b32 m0, s58
	v_lshl_add_u64 v[234:235], s[52:53], 0, v[154:155]
	ds_read_b128 v[162:165], v208 offset:16384
	ds_read_b128 v[166:169], v208 offset:17408
	ds_read_b128 v[170:173], v208 offset:18432
	ds_read_b128 v[174:177], v208 offset:19456
	ds_read_b128 v[178:181], v208 offset:20480
	ds_read_b128 v[182:185], v208 offset:21504
	ds_read_b128 v[194:197], v208 offset:22528
	ds_read_b128 v[210:213], v208 offset:23552
	global_load_lds_dwordx4 v[234:235], off
	v_lshl_add_u64 v[236:237], s[52:53], 0, v[152:153]
	s_mov_b32 m0, s59
	s_nop 0
	global_load_lds_dwordx4 v[236:237], off
	s_add_u32 s50, s48, 0xb0000
	s_addc_u32 s51, s49, 0
	s_add_i32 s6, s19, s57
	v_lshl_add_u64 v[250:251], s[50:51], 0, v[140:141]
	s_mov_b32 m0, s6
	s_nop 0
	global_load_lds_dwordx4 v[250:251], off
	v_lshl_add_u64 v[250:251], s[50:51], 0, v[150:151]
	s_add_i32 m0, s6, 0x2000
	s_nop 0
	global_load_lds_dwordx4 v[250:251], off
	s_waitcnt vmcnt(8)
	s_waitcnt lgkmcnt(0)
	s_barrier
	v_mfma_f32_16x16x32_bf16 v[60:63], v[128:131], v[162:165], v[60:63]
	v_mfma_f32_16x16x32_bf16 v[56:59], v[136:139], v[162:165], v[56:59]
	v_mfma_f32_16x16x32_bf16 v[48:51], v[128:131], v[170:173], v[48:51]
	v_mfma_f32_16x16x32_bf16 v[40:43], v[136:139], v[170:173], v[40:43]
	v_mfma_f32_16x16x32_bf16 v[32:35], v[128:131], v[178:181], v[32:35]
	v_mfma_f32_16x16x32_bf16 v[24:27], v[136:139], v[178:181], v[24:27]
	v_mfma_f32_16x16x32_bf16 v[16:19], v[128:131], v[194:197], v[16:19]
	v_mfma_f32_16x16x32_bf16 v[8:11], v[136:139], v[194:197], v[8:11]
	v_mfma_f32_16x16x32_bf16 v[60:63], v[132:135], v[166:169], v[60:63]
	v_mfma_f32_16x16x32_bf16 v[56:59], v[146:149], v[166:169], v[56:59]
	v_mfma_f32_16x16x32_bf16 v[48:51], v[132:135], v[174:177], v[48:51]
	v_mfma_f32_16x16x32_bf16 v[40:43], v[146:149], v[174:177], v[40:43]
	v_mfma_f32_16x16x32_bf16 v[32:35], v[132:135], v[182:185], v[32:35]
	v_mfma_f32_16x16x32_bf16 v[24:27], v[146:149], v[182:185], v[24:27]
	v_mfma_f32_16x16x32_bf16 v[16:19], v[132:135], v[210:213], v[16:19]
	v_mfma_f32_16x16x32_bf16 v[8:11], v[146:149], v[210:213], v[8:11]
	v_mfma_f32_16x16x32_bf16 v[52:55], v[214:217], v[162:165], v[52:55]
	v_mfma_f32_16x16x32_bf16 v[44:47], v[222:225], v[162:165], v[44:47]
	v_mfma_f32_16x16x32_bf16 v[36:39], v[214:217], v[170:173], v[36:39]
	v_mfma_f32_16x16x32_bf16 v[28:31], v[222:225], v[170:173], v[28:31]
	v_mfma_f32_16x16x32_bf16 v[20:23], v[214:217], v[178:181], v[20:23]
	v_mfma_f32_16x16x32_bf16 v[12:15], v[222:225], v[178:181], v[12:15]
	v_mfma_f32_16x16x32_bf16 v[4:7], v[214:217], v[194:197], v[4:7]
	v_mfma_f32_16x16x32_bf16 v[0:3], v[222:225], v[194:197], v[0:3]
	v_mfma_f32_16x16x32_bf16 v[52:55], v[218:221], v[166:169], v[52:55]
	v_mfma_f32_16x16x32_bf16 v[44:47], v[226:229], v[166:169], v[44:47]
	v_mfma_f32_16x16x32_bf16 v[36:39], v[218:221], v[174:177], v[36:39]
	v_mfma_f32_16x16x32_bf16 v[28:31], v[226:229], v[174:177], v[28:31]
	v_mfma_f32_16x16x32_bf16 v[20:23], v[218:221], v[182:185], v[20:23]
	v_mfma_f32_16x16x32_bf16 v[12:15], v[226:229], v[182:185], v[12:15]
	v_mfma_f32_16x16x32_bf16 v[4:7], v[218:221], v[210:213], v[4:7]
	v_mfma_f32_16x16x32_bf16 v[0:3], v[226:229], v[210:213], v[0:3]
	s_barrier
	s_add_i32 s6, 0, 0x18000
	v_add_u32_e32 v146, s6, v206
	ds_read_b128 v[128:131], v146
	ds_read_b128 v[132:135], v146 offset:1024
	ds_read_b128 v[136:139], v146 offset:2048
	ds_read_b128 v[146:149], v146 offset:3072
	s_add_u32 s50, s52, 0xb0000
	s_addc_u32 s51, s53, 0
	s_mov_b32 m0, s68
	v_lshl_add_u64 v[214:215], s[50:51], 0, v[154:155]
	ds_read_b128 v[162:165], v208 offset:32768
	ds_read_b128 v[166:169], v208 offset:33792
	ds_read_b128 v[170:173], v208 offset:34816
	ds_read_b128 v[174:177], v208 offset:35840
	ds_read_b128 v[178:181], v208 offset:36864
	ds_read_b128 v[182:185], v208 offset:37888
	ds_read_b128 v[194:197], v208 offset:38912
	ds_read_b128 v[210:213], v208 offset:39936
	global_load_lds_dwordx4 v[214:215], off
	v_lshl_add_u64 v[214:215], s[50:51], 0, v[152:153]
	s_mov_b32 m0, s69
	s_nop 0
	global_load_lds_dwordx4 v[214:215], off
	s_add_i32 s19, 0, 0x1c000
	v_add_u32_e32 v192, s19, v206
	ds_read_b128 v[214:217], v192
	ds_read_b128 v[218:221], v192 offset:1024
	ds_read_b128 v[222:225], v192 offset:2048
	ds_read_b128 v[226:229], v192 offset:3072
	s_waitcnt vmcnt(8)
	s_waitcnt lgkmcnt(0)
	s_barrier
	v_mfma_f32_16x16x32_bf16 v[124:127], v[128:131], v[162:165], v[124:127]
	v_mfma_f32_16x16x32_bf16 v[120:123], v[136:139], v[162:165], v[120:123]
	v_mfma_f32_16x16x32_bf16 v[108:111], v[128:131], v[170:173], v[108:111]
	v_mfma_f32_16x16x32_bf16 v[104:107], v[136:139], v[170:173], v[104:107]
	v_mfma_f32_16x16x32_bf16 v[96:99], v[128:131], v[178:181], v[96:99]
	v_mfma_f32_16x16x32_bf16 v[88:91], v[136:139], v[178:181], v[88:91]
	v_mfma_f32_16x16x32_bf16 v[84:87], v[128:131], v[194:197], v[84:87]
	v_mfma_f32_16x16x32_bf16 v[80:83], v[136:139], v[194:197], v[80:83]
	v_mfma_f32_16x16x32_bf16 v[124:127], v[132:135], v[166:169], v[124:127]
	v_mfma_f32_16x16x32_bf16 v[120:123], v[146:149], v[166:169], v[120:123]
	v_mfma_f32_16x16x32_bf16 v[108:111], v[132:135], v[174:177], v[108:111]
	v_mfma_f32_16x16x32_bf16 v[104:107], v[146:149], v[174:177], v[104:107]
	v_mfma_f32_16x16x32_bf16 v[96:99], v[132:135], v[182:185], v[96:99]
	v_mfma_f32_16x16x32_bf16 v[88:91], v[146:149], v[182:185], v[88:91]
	v_mfma_f32_16x16x32_bf16 v[84:87], v[132:135], v[210:213], v[84:87]
	v_mfma_f32_16x16x32_bf16 v[80:83], v[146:149], v[210:213], v[80:83]
	v_mfma_f32_16x16x32_bf16 v[116:119], v[214:217], v[162:165], v[116:119]
	v_mfma_f32_16x16x32_bf16 v[112:115], v[222:225], v[162:165], v[112:115]
	v_mfma_f32_16x16x32_bf16 v[100:103], v[214:217], v[170:173], v[100:103]
	v_mfma_f32_16x16x32_bf16 v[92:95], v[222:225], v[170:173], v[92:95]
	v_mfma_f32_16x16x32_bf16 v[76:79], v[214:217], v[178:181], v[76:79]
	v_mfma_f32_16x16x32_bf16 v[72:75], v[222:225], v[178:181], v[72:75]
	v_mfma_f32_16x16x32_bf16 v[68:71], v[214:217], v[194:197], v[68:71]
	v_mfma_f32_16x16x32_bf16 v[64:67], v[222:225], v[194:197], v[64:67]
	v_mfma_f32_16x16x32_bf16 v[116:119], v[218:221], v[166:169], v[116:119]
	v_mfma_f32_16x16x32_bf16 v[112:115], v[226:229], v[166:169], v[112:115]
	v_mfma_f32_16x16x32_bf16 v[100:103], v[218:221], v[174:177], v[100:103]
	v_mfma_f32_16x16x32_bf16 v[92:95], v[226:229], v[174:177], v[92:95]
	v_mfma_f32_16x16x32_bf16 v[76:79], v[218:221], v[182:185], v[76:79]
	v_mfma_f32_16x16x32_bf16 v[72:75], v[226:229], v[182:185], v[72:75]
	v_mfma_f32_16x16x32_bf16 v[68:71], v[218:221], v[210:213], v[68:71]
	v_mfma_f32_16x16x32_bf16 v[64:67], v[226:229], v[210:213], v[64:67]
	s_barrier
	s_add_i32 s6, s6, s57
	v_lshl_add_u64 v[230:231], v[230:231], 0, s[36:37]
	s_mov_b32 m0, s6
	s_nop 0
	global_load_lds_dwordx4 v[230:231], off
	v_lshl_add_u64 v[230:231], v[232:233], 0, s[36:37]
	s_add_i32 m0, s6, 0x2000
	s_nop 0
	global_load_lds_dwordx4 v[230:231], off
	s_mov_b32 m0, s70
	v_lshl_add_u64 v[230:231], v[234:235], 0, s[36:37]
	ds_read_b128 v[162:165], v208 offset:49152
	ds_read_b128 v[166:169], v208 offset:50176
	ds_read_b128 v[170:173], v208 offset:51200
	ds_read_b128 v[174:177], v208 offset:52224
	ds_read_b128 v[178:181], v208 offset:53248
	ds_read_b128 v[182:185], v208 offset:54272
	ds_read_b128 v[194:197], v208 offset:55296
	ds_read_b128 v[210:213], v208 offset:56320
	global_load_lds_dwordx4 v[230:231], off
	v_lshl_add_u64 v[230:231], v[236:237], 0, s[36:37]
	s_mov_b32 m0, s71
	s_nop 0
	global_load_lds_dwordx4 v[230:231], off
	s_add_u32 s48, s48, 0xb0080
	s_addc_u32 s49, s49, 0
	s_add_i32 s6, s19, s57
	v_lshl_add_u64 v[250:251], s[48:49], 0, v[140:141]
	s_mov_b32 m0, s6
	s_nop 0
	global_load_lds_dwordx4 v[250:251], off
	v_lshl_add_u64 v[250:251], s[48:49], 0, v[150:151]
	s_add_i32 m0, s6, 0x2000
	s_nop 0
	global_load_lds_dwordx4 v[250:251], off
	s_waitcnt vmcnt(8)
	s_waitcnt lgkmcnt(0)
	s_barrier
	v_mfma_f32_16x16x32_bf16 v[60:63], v[128:131], v[162:165], v[60:63]
	v_mfma_f32_16x16x32_bf16 v[56:59], v[136:139], v[162:165], v[56:59]
	v_mfma_f32_16x16x32_bf16 v[48:51], v[128:131], v[170:173], v[48:51]
	v_mfma_f32_16x16x32_bf16 v[40:43], v[136:139], v[170:173], v[40:43]
	v_mfma_f32_16x16x32_bf16 v[32:35], v[128:131], v[178:181], v[32:35]
	v_mfma_f32_16x16x32_bf16 v[24:27], v[136:139], v[178:181], v[24:27]
	v_mfma_f32_16x16x32_bf16 v[16:19], v[128:131], v[194:197], v[16:19]
	v_mfma_f32_16x16x32_bf16 v[8:11], v[136:139], v[194:197], v[8:11]
	v_mfma_f32_16x16x32_bf16 v[60:63], v[132:135], v[166:169], v[60:63]
	v_mfma_f32_16x16x32_bf16 v[56:59], v[146:149], v[166:169], v[56:59]
	v_mfma_f32_16x16x32_bf16 v[48:51], v[132:135], v[174:177], v[48:51]
	v_mfma_f32_16x16x32_bf16 v[40:43], v[146:149], v[174:177], v[40:43]
	v_mfma_f32_16x16x32_bf16 v[32:35], v[132:135], v[182:185], v[32:35]
	v_mfma_f32_16x16x32_bf16 v[24:27], v[146:149], v[182:185], v[24:27]
	v_mfma_f32_16x16x32_bf16 v[16:19], v[132:135], v[210:213], v[16:19]
	v_mfma_f32_16x16x32_bf16 v[8:11], v[146:149], v[210:213], v[8:11]
	v_mfma_f32_16x16x32_bf16 v[52:55], v[214:217], v[162:165], v[52:55]
	v_mfma_f32_16x16x32_bf16 v[44:47], v[222:225], v[162:165], v[44:47]
	v_mfma_f32_16x16x32_bf16 v[36:39], v[214:217], v[170:173], v[36:39]
	v_mfma_f32_16x16x32_bf16 v[28:31], v[222:225], v[170:173], v[28:31]
	v_mfma_f32_16x16x32_bf16 v[20:23], v[214:217], v[178:181], v[20:23]
	v_mfma_f32_16x16x32_bf16 v[12:15], v[222:225], v[178:181], v[12:15]
	v_mfma_f32_16x16x32_bf16 v[4:7], v[214:217], v[194:197], v[4:7]
	v_mfma_f32_16x16x32_bf16 v[0:3], v[222:225], v[194:197], v[0:3]
	v_mfma_f32_16x16x32_bf16 v[52:55], v[218:221], v[166:169], v[52:55]
	v_mfma_f32_16x16x32_bf16 v[44:47], v[226:229], v[166:169], v[44:47]
	v_mfma_f32_16x16x32_bf16 v[36:39], v[218:221], v[174:177], v[36:39]
	v_mfma_f32_16x16x32_bf16 v[28:31], v[226:229], v[174:177], v[28:31]
	v_mfma_f32_16x16x32_bf16 v[20:23], v[218:221], v[182:185], v[20:23]
	v_mfma_f32_16x16x32_bf16 v[12:15], v[226:229], v[182:185], v[12:15]
	v_mfma_f32_16x16x32_bf16 v[4:7], v[218:221], v[210:213], v[4:7]
	v_mfma_f32_16x16x32_bf16 v[0:3], v[226:229], v[210:213], v[0:3]
	s_add_i32 s12, s12, 2
	s_add_u32 s10, s10, 0x100
	s_addc_u32 s11, s11, 0
	s_cmp_gt_u32 s12, 41
	s_mov_b64 s[50:51], s[46:47]
	s_barrier
	s_cbranch_scc0 .LBB0_341
	s_mov_b32 s100, 1
	s_ashr_i32 s39, s38, 31
	v_lshl_or_b32 v128, s81, 8, v207
	s_lshl_b64 s[10:11], s[38:39], 8
	v_ashrrev_i32_e32 v129, 31, v128
	v_lshl_add_u64 v[168:169], s[10:11], 0, v[156:157]
	v_lshlrev_b64 v[170:171], 1, v[128:129]
	v_lshl_add_u64 v[174:175], s[26:27], 0, v[170:171]
	v_lshlrev_b64 v[172:173], 11, v[168:169]
	v_lshl_add_u64 v[128:129], v[174:175], 0, v[172:173]
	global_load_dwordx4 v[182:185], v[128:129], off
	global_load_dwordx4 v[210:213], v[128:129], off offset:256
	v_or_b32_e32 v166, 16, v168
	v_mov_b32_e32 v167, v169
	v_lshlrev_b64 v[176:177], 11, v[166:167]
	v_lshl_add_u64 v[128:129], v[174:175], 0, v[176:177]
	global_load_dwordx4 v[214:217], v[128:129], off
	global_load_dwordx4 v[218:221], v[128:129], off offset:256
	v_or_b32_e32 v164, 32, v168
	v_mov_b32_e32 v165, v169
	v_or_b32_e32 v162, 48, v168
	v_mov_b32_e32 v163, v169
	v_lshlrev_b64 v[180:181], 11, v[164:165]
	v_lshlrev_b64 v[178:179], 11, v[162:163]
	v_lshl_add_u64 v[128:129], v[174:175], 0, v[180:181]
	v_lshl_add_u64 v[130:131], v[174:175], 0, v[178:179]
	global_load_dwordx4 v[222:225], v[128:129], off
	global_load_dwordx4 v[136:139], v[128:129], off offset:256
	global_load_dwordx4 v[132:135], v[130:131], off
	s_nop 0
	global_load_dwordx4 v[128:131], v[130:131], off offset:256
	s_mov_b64 s[10:11], 0x90
	v_lshl_add_u64 v[172:173], s[28:29], 0, v[172:173]
	v_lshl_add_u64 v[172:173], v[172:173], 0, v[170:171]
	s_waitcnt vmcnt(0)
	v_lshlrev_b32_e32 v146, 16, v182
	v_and_b32_e32 v147, 0xffff0000, v182
	v_lshlrev_b32_e32 v148, 16, v184
	v_and_b32_e32 v149, 0xffff0000, v184
	v_lshlrev_b32_e32 v182, 16, v183
	v_and_b32_e32 v183, 0xffff0000, v183
	v_lshlrev_b32_e32 v194, 16, v210
	v_and_b32_e32 v195, 0xffff0000, v210
	v_lshlrev_b32_e32 v196, 16, v212
	v_and_b32_e32 v197, 0xffff0000, v212
	v_lshlrev_b32_e32 v210, 16, v211
	v_and_b32_e32 v211, 0xffff0000, v211
	v_lshlrev_b32_e32 v212, 16, v213
	v_and_b32_e32 v213, 0xffff0000, v213
	v_pk_fma_f32 v[124:125], v[124:125], 0.5, v[146:147] op_sel_hi:[1,0,1]
	v_pk_fma_f32 v[120:121], v[120:121], 0.5, v[148:149] op_sel_hi:[1,0,1]
	v_pk_fma_f32 v[126:127], v[126:127], 0.5, v[182:183] op_sel_hi:[1,0,1]
	v_pk_fma_f32 v[116:117], v[116:117], 0.5, v[194:195] op_sel_hi:[1,0,1]
	v_pk_fma_f32 v[146:147], v[112:113], 0.5, v[196:197] op_sel_hi:[1,0,1]
	v_pk_fma_f32 v[118:119], v[118:119], 0.5, v[210:211] op_sel_hi:[1,0,1]
	v_pk_fma_f32 v[148:149], v[114:115], 0.5, v[212:213] op_sel_hi:[1,0,1]
	v_pk_mul_f32 v[212:213], v[124:125], v[124:125]
	v_lshlrev_b32_e32 v182, 16, v214
	v_and_b32_e32 v183, 0xffff0000, v214
	v_lshlrev_b32_e32 v194, 16, v215
	v_and_b32_e32 v195, 0xffff0000, v215
	v_pk_mul_f32 v[214:215], v[126:127], v[126:127]
	v_cvt_pk_bf16_f32 v112, v124, v125
	v_cvt_pk_bf16_f32 v113, v126, v127
	v_pk_mul_f32 v[124:125], v[116:117], v[116:117]
	v_pk_mul_f32 v[126:127], v[118:119], v[118:119]
	v_pk_mul_f32 v[228:229], v[146:147], v[146:147]
	v_cvt_pk_bf16_f32 v116, v116, v117
	v_cvt_pk_bf16_f32 v117, v118, v119
	v_cvt_pk_bf16_f32 v118, v146, v147
	v_add_f32_e32 v146, v212, v213
	v_lshlrev_b32_e32 v184, 16, v185
	v_and_b32_e32 v185, 0xffff0000, v185
	v_add_f32_e32 v146, v214, v146
	v_pk_fma_f32 v[122:123], v[122:123], 0.5, v[184:185] op_sel_hi:[1,0,1]
	v_lshlrev_b32_e32 v184, 16, v216
	v_and_b32_e32 v185, 0xffff0000, v216
	v_lshlrev_b32_e32 v196, 16, v217
	v_and_b32_e32 v197, 0xffff0000, v217
	v_pk_mul_f32 v[216:217], v[120:121], v[120:121]
	v_add_f32_e32 v146, v215, v146
	v_add_f32_e32 v146, v216, v146
	v_pk_mul_f32 v[226:227], v[122:123], v[122:123]
	v_add_f32_e32 v146, v217, v146
	v_add_f32_e32 v146, v226, v146
	v_add_f32_e32 v146, v227, v146
	v_add_f32_e32 v124, v124, v146
	v_add_f32_e32 v124, v125, v124
	v_add_f32_e32 v124, v126, v124
	v_add_f32_e32 v124, v127, v124
	v_add_f32_e32 v124, v228, v124
	v_pk_mul_f32 v[230:231], v[148:149], v[148:149]
	v_add_f32_e32 v124, v229, v124
	v_add_f32_e32 v124, v230, v124
	v_add_f32_e32 v209, v231, v124
	v_lshlrev_b32_e32 v124, 16, v220
	v_and_b32_e32 v125, 0xffff0000, v220
	v_pk_fma_f32 v[124:125], v[92:93], 0.5, v[124:125] op_sel_hi:[1,0,1]
	v_lshlrev_b32_e32 v92, 16, v219
	v_and_b32_e32 v93, 0xffff0000, v219
	v_pk_fma_f32 v[102:103], v[102:103], 0.5, v[92:93] op_sel_hi:[1,0,1]
	v_lshlrev_b32_e32 v92, 16, v221
	v_and_b32_e32 v93, 0xffff0000, v221
	v_pk_fma_f32 v[126:127], v[94:95], 0.5, v[92:93] op_sel_hi:[1,0,1]
	v_lshlrev_b32_e32 v92, 16, v222
	v_and_b32_e32 v93, 0xffff0000, v222
	v_pk_fma_f32 v[92:93], v[96:97], 0.5, v[92:93] op_sel_hi:[1,0,1]
	v_lshlrev_b32_e32 v96, 16, v225
	v_and_b32_e32 v97, 0xffff0000, v225
	v_lshlrev_b32_e32 v94, 16, v224
	v_and_b32_e32 v95, 0xffff0000, v224
	v_pk_fma_f32 v[90:91], v[90:91], 0.5, v[96:97] op_sel_hi:[1,0,1]
	v_lshlrev_b32_e32 v96, 16, v136
	v_and_b32_e32 v97, 0xffff0000, v136
	v_pk_fma_f32 v[88:89], v[88:89], 0.5, v[94:95] op_sel_hi:[1,0,1]
	v_lshlrev_b32_e32 v94, 16, v223
	v_and_b32_e32 v95, 0xffff0000, v223
	v_pk_fma_f32 v[96:97], v[76:77], 0.5, v[96:97] op_sel_hi:[1,0,1]
	v_lshl_add_u64 v[76:77], v[168:169], 0, s[36:37]
	v_cvt_pk_bf16_f32 v114, v120, v121
	v_pk_fma_f32 v[120:121], v[108:109], 0.5, v[182:183] op_sel_hi:[1,0,1]
	v_pk_fma_f32 v[94:95], v[98:99], 0.5, v[94:95] op_sel_hi:[1,0,1]
	v_lshlrev_b64 v[182:183], 11, v[76:77]
	v_lshlrev_b32_e32 v98, 16, v138
	v_and_b32_e32 v99, 0xffff0000, v138
	v_lshl_add_u64 v[146:147], v[174:175], 0, v[182:183]
	v_pk_fma_f32 v[98:99], v[72:73], 0.5, v[98:99] op_sel_hi:[1,0,1]
	v_lshlrev_b32_e32 v72, 16, v137
	v_and_b32_e32 v73, 0xffff0000, v137
	v_lshlrev_b32_e32 v210, 16, v218
	v_and_b32_e32 v211, 0xffff0000, v218
	global_load_dwordx4 v[218:221], v[146:147], off
	global_load_dwordx4 v[226:229], v[146:147], off offset:256
	v_pk_fma_f32 v[136:137], v[78:79], 0.5, v[72:73] op_sel_hi:[1,0,1]
	v_lshlrev_b32_e32 v72, 16, v139
	v_and_b32_e32 v73, 0xffff0000, v139
	v_pk_fma_f32 v[138:139], v[74:75], 0.5, v[72:73] op_sel_hi:[1,0,1]
	v_lshlrev_b32_e32 v72, 16, v132
	v_and_b32_e32 v73, 0xffff0000, v132
	v_pk_fma_f32 v[74:75], v[84:85], 0.5, v[72:73] op_sel_hi:[1,0,1]
	v_lshlrev_b32_e32 v72, 16, v134
	v_and_b32_e32 v73, 0xffff0000, v134
	v_pk_fma_f32 v[78:79], v[80:81], 0.5, v[72:73] op_sel_hi:[1,0,1]
	v_lshlrev_b32_e32 v72, 16, v133
	v_and_b32_e32 v73, 0xffff0000, v133
	v_pk_fma_f32 v[80:81], v[86:87], 0.5, v[72:73] op_sel_hi:[1,0,1]
	v_lshlrev_b32_e32 v72, 16, v135
	v_and_b32_e32 v73, 0xffff0000, v135
	v_pk_fma_f32 v[82:83], v[82:83], 0.5, v[72:73] op_sel_hi:[1,0,1]
	v_lshl_add_u64 v[72:73], v[168:169], 0, s[10:11]
	v_lshlrev_b64 v[132:133], 11, v[72:73]
	v_lshl_add_u64 v[134:135], v[174:175], 0, v[132:133]
	global_load_dwordx4 v[234:237], v[134:135], off
	global_load_dwordx4 v[242:245], v[134:135], off offset:256
	v_lshlrev_b32_e32 v84, 16, v128
	v_and_b32_e32 v85, 0xffff0000, v128
	v_pk_fma_f32 v[84:85], v[68:69], 0.5, v[84:85] op_sel_hi:[1,0,1]
	v_lshlrev_b32_e32 v68, 16, v130
	v_and_b32_e32 v69, 0xffff0000, v130
	v_pk_fma_f32 v[86:87], v[64:65], 0.5, v[68:69] op_sel_hi:[1,0,1]
	v_lshlrev_b32_e32 v64, 16, v129
	v_and_b32_e32 v65, 0xffff0000, v129
	s_mov_b64 s[10:11], 0xa0
	v_pk_fma_f32 v[128:129], v[70:71], 0.5, v[64:65] op_sel_hi:[1,0,1]
	v_lshl_add_u64 v[70:71], v[168:169], 0, s[10:11]
	v_lshlrev_b32_e32 v64, 16, v131
	v_and_b32_e32 v65, 0xffff0000, v131
	v_lshlrev_b64 v[134:135], 11, v[70:71]
	v_pk_fma_f32 v[130:131], v[66:67], 0.5, v[64:65] op_sel_hi:[1,0,1]
	v_lshl_add_u64 v[64:65], v[174:175], 0, v[134:135]
	v_cvt_pk_bf16_f32 v115, v122, v123
	v_pk_fma_f32 v[122:123], v[110:111], 0.5, v[194:195] op_sel_hi:[1,0,1]
	v_pk_fma_f32 v[110:111], v[106:107], 0.5, v[196:197] op_sel_hi:[1,0,1]
	global_load_dwordx4 v[246:249], v[64:65], off
	global_load_dwordx4 v[194:197], v[64:65], off offset:256
	s_mov_b64 s[10:11], 0xb0
	v_lshl_add_u64 v[68:69], v[168:169], 0, s[10:11]
	v_pk_fma_f32 v[108:109], v[104:105], 0.5, v[184:185] op_sel_hi:[1,0,1]
	v_lshlrev_b64 v[184:185], 11, v[68:69]
	v_lshl_add_u64 v[64:65], v[174:175], 0, v[184:185]
	v_cvt_pk_bf16_f32 v119, v148, v149
	global_load_dwordx4 v[146:149], v[64:65], off
	s_nop 0
	global_load_dwordx4 v[64:67], v[64:65], off offset:256
	global_store_dwordx4 v[172:173], v[112:115], off
	global_store_dwordx4 v[172:173], v[116:119], off offset:256
	v_cvt_pk_bf16_f32 v104, v120, v121
	v_lshl_add_u64 v[112:113], s[28:29], 0, v[176:177]
	v_cvt_pk_bf16_f32 v105, v122, v123
	v_cvt_pk_bf16_f32 v106, v108, v109
	v_cvt_pk_bf16_f32 v107, v110, v111
	v_pk_fma_f32 v[100:101], v[100:101], 0.5, v[210:211] op_sel_hi:[1,0,1]
	v_lshl_add_u64 v[112:113], v[112:113], 0, v[170:171]
	v_cvt_pk_bf16_f32 v210, v100, v101
	v_cvt_pk_bf16_f32 v211, v102, v103
	v_cvt_pk_bf16_f32 v212, v124, v125
	v_cvt_pk_bf16_f32 v213, v126, v127
	global_store_dwordx4 v[112:113], v[104:107], off
	global_store_dwordx4 v[112:113], v[210:213], off offset:256
	v_cvt_pk_bf16_f32 v214, v92, v93
	v_lshl_add_u64 v[104:105], s[28:29], 0, v[180:181]
	v_cvt_pk_bf16_f32 v215, v94, v95
	v_cvt_pk_bf16_f32 v216, v88, v89
	v_cvt_pk_bf16_f32 v217, v90, v91
	v_lshl_add_u64 v[104:105], v[104:105], 0, v[170:171]
	v_cvt_pk_bf16_f32 v222, v96, v97
	v_cvt_pk_bf16_f32 v223, v136, v137
	v_cvt_pk_bf16_f32 v224, v98, v99
	v_cvt_pk_bf16_f32 v225, v138, v139
	global_store_dwordx4 v[104:105], v[214:217], off
	global_store_dwordx4 v[104:105], v[222:225], off offset:256
	v_lshl_add_u64 v[104:105], s[28:29], 0, v[178:179]
	v_cvt_pk_bf16_f32 v230, v74, v75
	v_cvt_pk_bf16_f32 v231, v80, v81
	v_cvt_pk_bf16_f32 v232, v78, v79
	v_cvt_pk_bf16_f32 v233, v82, v83
	v_lshl_add_u64 v[104:105], v[104:105], 0, v[170:171]
	v_cvt_pk_bf16_f32 v238, v84, v85
	v_cvt_pk_bf16_f32 v239, v128, v129
	v_cvt_pk_bf16_f32 v240, v86, v87
	v_cvt_pk_bf16_f32 v241, v130, v131
	global_store_dwordx4 v[104:105], v[230:233], off
	global_store_dwordx4 v[104:105], v[238:241], off offset:256
	s_waitcnt vmcnt(0)
	v_lshlrev_b32_e32 v104, 16, v218
	v_and_b32_e32 v105, 0xffff0000, v218
	v_pk_fma_f32 v[60:61], v[60:61], 0.5, v[104:105] op_sel_hi:[1,0,1]
	v_lshlrev_b32_e32 v104, 16, v220
	v_and_b32_e32 v105, 0xffff0000, v220
	v_pk_fma_f32 v[56:57], v[56:57], 0.5, v[104:105] op_sel_hi:[1,0,1]
	v_lshlrev_b32_e32 v104, 16, v219
	v_and_b32_e32 v105, 0xffff0000, v219
	v_pk_fma_f32 v[62:63], v[62:63], 0.5, v[104:105] op_sel_hi:[1,0,1]
	v_lshlrev_b32_e32 v104, 16, v221
	v_and_b32_e32 v105, 0xffff0000, v221
	v_pk_fma_f32 v[58:59], v[58:59], 0.5, v[104:105] op_sel_hi:[1,0,1]
	v_lshlrev_b32_e32 v104, 16, v226
	v_and_b32_e32 v105, 0xffff0000, v226
	v_pk_fma_f32 v[52:53], v[52:53], 0.5, v[104:105] op_sel_hi:[1,0,1]
	v_lshlrev_b32_e32 v104, 16, v228
	v_and_b32_e32 v105, 0xffff0000, v228
	v_pk_fma_f32 v[104:105], v[44:45], 0.5, v[104:105] op_sel_hi:[1,0,1]
	v_lshlrev_b32_e32 v44, 16, v227
	v_and_b32_e32 v45, 0xffff0000, v227
	v_pk_fma_f32 v[54:55], v[54:55], 0.5, v[44:45] op_sel_hi:[1,0,1]
	v_lshlrev_b32_e32 v44, 16, v229
	v_and_b32_e32 v45, 0xffff0000, v229
	v_pk_fma_f32 v[106:107], v[46:47], 0.5, v[44:45] op_sel_hi:[1,0,1]
	v_lshlrev_b32_e32 v44, 16, v234
	v_and_b32_e32 v45, 0xffff0000, v234
	v_pk_fma_f32 v[44:45], v[48:49], 0.5, v[44:45] op_sel_hi:[1,0,1]
	v_lshlrev_b32_e32 v48, 16, v237
	v_and_b32_e32 v49, 0xffff0000, v237
	v_pk_fma_f32 v[42:43], v[42:43], 0.5, v[48:49] op_sel_hi:[1,0,1]
	v_lshlrev_b32_e32 v48, 16, v242
	v_and_b32_e32 v49, 0xffff0000, v242
	v_pk_fma_f32 v[36:37], v[36:37], 0.5, v[48:49] op_sel_hi:[1,0,1]
	v_lshlrev_b32_e32 v48, 16, v244
	v_and_b32_e32 v49, 0xffff0000, v244
	v_lshlrev_b32_e32 v46, 16, v236
	v_and_b32_e32 v47, 0xffff0000, v236
	v_pk_fma_f32 v[48:49], v[28:29], 0.5, v[48:49] op_sel_hi:[1,0,1]
	v_lshlrev_b32_e32 v28, 16, v243
	v_and_b32_e32 v29, 0xffff0000, v243
	v_pk_fma_f32 v[40:41], v[40:41], 0.5, v[46:47] op_sel_hi:[1,0,1]
	v_lshlrev_b32_e32 v46, 16, v235
	v_and_b32_e32 v47, 0xffff0000, v235
	v_pk_fma_f32 v[38:39], v[38:39], 0.5, v[28:29] op_sel_hi:[1,0,1]
	v_lshlrev_b32_e32 v28, 16, v245
	v_and_b32_e32 v29, 0xffff0000, v245
	v_pk_fma_f32 v[46:47], v[50:51], 0.5, v[46:47] op_sel_hi:[1,0,1]
	v_pk_fma_f32 v[50:51], v[30:31], 0.5, v[28:29] op_sel_hi:[1,0,1]
	v_lshlrev_b32_e32 v28, 16, v246
	v_and_b32_e32 v29, 0xffff0000, v246
	v_pk_fma_f32 v[28:29], v[32:33], 0.5, v[28:29] op_sel_hi:[1,0,1]
	v_lshlrev_b32_e32 v32, 16, v249
	v_and_b32_e32 v33, 0xffff0000, v249
	v_pk_fma_f32 v[26:27], v[26:27], 0.5, v[32:33] op_sel_hi:[1,0,1]
	v_lshlrev_b32_e32 v32, 16, v194
	v_and_b32_e32 v33, 0xffff0000, v194
	v_pk_fma_f32 v[20:21], v[20:21], 0.5, v[32:33] op_sel_hi:[1,0,1]
	v_lshlrev_b32_e32 v32, 16, v196
	v_and_b32_e32 v33, 0xffff0000, v196
	v_lshlrev_b32_e32 v30, 16, v248
	v_and_b32_e32 v31, 0xffff0000, v248
	v_pk_fma_f32 v[32:33], v[12:13], 0.5, v[32:33] op_sel_hi:[1,0,1]
	v_lshlrev_b32_e32 v12, 16, v195
	v_and_b32_e32 v13, 0xffff0000, v195
	v_pk_fma_f32 v[24:25], v[24:25], 0.5, v[30:31] op_sel_hi:[1,0,1]
	v_lshlrev_b32_e32 v30, 16, v247
	v_and_b32_e32 v31, 0xffff0000, v247
	v_pk_fma_f32 v[22:23], v[22:23], 0.5, v[12:13] op_sel_hi:[1,0,1]
	v_lshlrev_b32_e32 v12, 16, v197
	v_and_b32_e32 v13, 0xffff0000, v197
	v_pk_fma_f32 v[30:31], v[34:35], 0.5, v[30:31] op_sel_hi:[1,0,1]
	v_pk_fma_f32 v[34:35], v[14:15], 0.5, v[12:13] op_sel_hi:[1,0,1]
	v_lshlrev_b32_e32 v14, 16, v148
	v_and_b32_e32 v15, 0xffff0000, v148
	v_lshlrev_b32_e32 v12, 16, v146
	v_and_b32_e32 v13, 0xffff0000, v146
	v_pk_fma_f32 v[8:9], v[8:9], 0.5, v[14:15] op_sel_hi:[1,0,1]
	v_lshlrev_b32_e32 v14, 16, v147
	v_and_b32_e32 v15, 0xffff0000, v147
	v_lshlrev_b32_e32 v146, 16, v64
	v_and_b32_e32 v147, 0xffff0000, v64
	v_pk_fma_f32 v[4:5], v[4:5], 0.5, v[146:147] op_sel_hi:[1,0,1]
	v_lshlrev_b32_e32 v146, 16, v66
	v_and_b32_e32 v147, 0xffff0000, v66
	v_pk_fma_f32 v[0:1], v[0:1], 0.5, v[146:147] op_sel_hi:[1,0,1]
	v_lshl_add_u64 v[146:147], s[28:29], 0, v[182:183]
	v_cvt_pk_bf16_f32 v112, v60, v61
	v_cvt_pk_bf16_f32 v113, v62, v63
	v_cvt_pk_bf16_f32 v114, v56, v57
	v_cvt_pk_bf16_f32 v115, v58, v59
	v_lshl_add_u64 v[146:147], v[146:147], 0, v[170:171]
	v_cvt_pk_bf16_f32 v116, v52, v53
	v_cvt_pk_bf16_f32 v117, v54, v55
	v_cvt_pk_bf16_f32 v118, v104, v105
	v_cvt_pk_bf16_f32 v119, v106, v107
	global_store_dwordx4 v[146:147], v[112:115], off
	global_store_dwordx4 v[146:147], v[116:119], off offset:256
	v_cvt_pk_bf16_f32 v172, v44, v45
	v_lshl_add_u64 v[112:113], s[28:29], 0, v[132:133]
	v_cvt_pk_bf16_f32 v173, v46, v47
	v_cvt_pk_bf16_f32 v174, v40, v41
	v_cvt_pk_bf16_f32 v175, v42, v43
	v_lshl_add_u64 v[112:113], v[112:113], 0, v[170:171]
	v_cvt_pk_bf16_f32 v176, v36, v37
	v_cvt_pk_bf16_f32 v177, v38, v39
	v_cvt_pk_bf16_f32 v178, v48, v49
	v_cvt_pk_bf16_f32 v179, v50, v51
	global_store_dwordx4 v[112:113], v[172:175], off
	global_store_dwordx4 v[112:113], v[176:179], off offset:256
	v_lshl_add_u64 v[112:113], s[28:29], 0, v[134:135]
	v_cvt_pk_bf16_f32 v210, v28, v29
	v_cvt_pk_bf16_f32 v211, v30, v31
	v_cvt_pk_bf16_f32 v212, v24, v25
	v_cvt_pk_bf16_f32 v213, v26, v27
	v_pk_fma_f32 v[12:13], v[16:17], 0.5, v[12:13] op_sel_hi:[1,0,1]
	v_lshlrev_b32_e32 v16, 16, v149
	v_and_b32_e32 v17, 0xffff0000, v149
	v_lshlrev_b32_e32 v64, 16, v65
	v_and_b32_e32 v65, 0xffff0000, v65
	v_lshl_add_u64 v[112:113], v[112:113], 0, v[170:171]
	v_cvt_pk_bf16_f32 v194, v20, v21
	v_cvt_pk_bf16_f32 v195, v22, v23
	v_cvt_pk_bf16_f32 v196, v32, v33
	v_cvt_pk_bf16_f32 v197, v34, v35
	v_pk_fma_f32 v[14:15], v[18:19], 0.5, v[14:15] op_sel_hi:[1,0,1]
	v_pk_fma_f32 v[10:11], v[10:11], 0.5, v[16:17] op_sel_hi:[1,0,1]
	v_pk_fma_f32 v[6:7], v[6:7], 0.5, v[64:65] op_sel_hi:[1,0,1]
	v_lshlrev_b32_e32 v64, 16, v67
	v_and_b32_e32 v65, 0xffff0000, v67
	global_store_dwordx4 v[112:113], v[210:213], off
	global_store_dwordx4 v[112:113], v[194:197], off offset:256
	v_lshl_add_u64 v[112:113], s[28:29], 0, v[184:185]
	v_cvt_pk_bf16_f32 v16, v12, v13
	v_cvt_pk_bf16_f32 v17, v14, v15
	v_cvt_pk_bf16_f32 v18, v8, v9
	v_cvt_pk_bf16_f32 v19, v10, v11
	v_pk_fma_f32 v[2:3], v[2:3], 0.5, v[64:65] op_sel_hi:[1,0,1]
	v_lshl_add_u64 v[112:113], v[112:113], 0, v[170:171]
	v_cvt_pk_bf16_f32 v64, v4, v5
	v_cvt_pk_bf16_f32 v65, v6, v7
	v_cvt_pk_bf16_f32 v66, v0, v1
	v_cvt_pk_bf16_f32 v67, v2, v3
	global_store_dwordx4 v[112:113], v[16:19], off
	global_store_dwordx4 v[112:113], v[64:67], off offset:256
	s_lshl_b32 s10, s81, 2
	v_and_b32_e32 v17, 64, v188
	v_xor_b32_e32 v16, 16, v188
	v_add_u32_e32 v17, 64, v17
	v_cmp_lt_i32_e32 vcc, v16, v17
	v_xor_b32_e32 v18, 32, v188
	s_ashr_i32 s11, s10, 31
	v_cndmask_b32_e32 v16, v188, v16, vcc
	v_lshlrev_b32_e32 v16, 2, v16
	ds_bpermute_b32 v19, v16, v209
	v_cmp_lt_i32_e32 vcc, v18, v17
	s_lshl_b64 s[10:11], s[10:11], 2
	s_add_u32 s38, s73, s10
	v_cndmask_b32_e32 v17, v188, v18, vcc
	v_lshlrev_b32_e32 v17, 2, v17
	s_waitcnt lgkmcnt(0)
	v_add_f32_e32 v18, v209, v19
	ds_bpermute_b32 v19, v17, v18
	s_addc_u32 s39, s74, s11
	s_and_saveexec_b64 s[46:47], s[42:43]
	s_cbranch_execz .LBB0_344
	s_waitcnt lgkmcnt(0)
	v_add_f32_e32 v64, v18, v19
	v_lshlrev_b64 v[18:19], 6, v[168:169]
	v_lshl_add_u64 v[18:19], s[38:39], 0, v[18:19]
	global_store_dword v[18:19], v64, off

.Lm4ap_386:
	s_waitcnt lgkmcnt(0)
	s_barrier
	s_nop 0
	v_mfma_f32_16x16x32_bf16 v[124:127], v[158:161], v[174:177], 0
	v_mfma_f32_16x16x32_bf16 v[120:123], v[166:169], v[174:177], 0
	v_mfma_f32_16x16x32_bf16 v[116:119], v[158:161], v[182:185], 0
	v_mfma_f32_16x16x32_bf16 v[112:115], v[166:169], v[182:185], 0
	v_mfma_f32_16x16x32_bf16 v[108:111], v[158:161], v[210:213], 0
	v_mfma_f32_16x16x32_bf16 v[104:107], v[166:169], v[210:213], 0
	v_mfma_f32_16x16x32_bf16 v[100:103], v[158:161], v[218:221], 0
	v_mfma_f32_16x16x32_bf16 v[96:99], v[166:169], v[218:221], 0
	v_mfma_f32_16x16x32_bf16 v[124:127], v[162:165], v[178:181], v[124:127]
	v_mfma_f32_16x16x32_bf16 v[120:123], v[170:173], v[178:181], v[120:123]
	v_mfma_f32_16x16x32_bf16 v[116:119], v[162:165], v[206:209], v[116:119]
	v_mfma_f32_16x16x32_bf16 v[112:115], v[170:173], v[206:209], v[112:115]
	v_mfma_f32_16x16x32_bf16 v[108:111], v[162:165], v[214:217], v[108:111]
	v_mfma_f32_16x16x32_bf16 v[104:107], v[170:173], v[214:217], v[104:107]
	v_mfma_f32_16x16x32_bf16 v[100:103], v[162:165], v[222:225], v[100:103]
	v_mfma_f32_16x16x32_bf16 v[96:99], v[170:173], v[222:225], v[96:99]
	v_mfma_f32_16x16x32_bf16 v[92:95], v[226:229], v[174:177], 0
	v_mfma_f32_16x16x32_bf16 v[88:91], v[234:237], v[174:177], 0
	v_mfma_f32_16x16x32_bf16 v[84:87], v[226:229], v[182:185], 0
	v_mfma_f32_16x16x32_bf16 v[80:83], v[234:237], v[182:185], 0
	v_mfma_f32_16x16x32_bf16 v[76:79], v[226:229], v[210:213], 0
	v_mfma_f32_16x16x32_bf16 v[72:75], v[234:237], v[210:213], 0
	v_mfma_f32_16x16x32_bf16 v[68:71], v[226:229], v[218:221], 0
	v_mfma_f32_16x16x32_bf16 v[64:67], v[234:237], v[218:221], 0
	v_mfma_f32_16x16x32_bf16 v[92:95], v[230:233], v[178:181], v[92:95]
	v_mfma_f32_16x16x32_bf16 v[88:91], v[238:241], v[178:181], v[88:91]
	v_mfma_f32_16x16x32_bf16 v[84:87], v[230:233], v[206:209], v[84:87]
	v_mfma_f32_16x16x32_bf16 v[80:83], v[238:241], v[206:209], v[80:83]
	v_mfma_f32_16x16x32_bf16 v[76:79], v[230:233], v[214:217], v[76:79]
	v_mfma_f32_16x16x32_bf16 v[72:75], v[238:241], v[214:217], v[72:75]
	v_mfma_f32_16x16x32_bf16 v[68:71], v[230:233], v[222:225], v[68:71]
	v_mfma_f32_16x16x32_bf16 v[64:67], v[238:241], v[222:225], v[64:67]
	s_barrier
	s_add_i32 s19, s82, s57
	v_lshl_add_u64 v[146:147], s[54:55], 0, v[140:141]
	s_mov_b32 m0, s19
	v_lshl_add_u64 v[148:149], s[54:55], 0, v[132:133]
	global_load_lds_dwordx4 v[146:147], off
	s_add_i32 m0, s19, 0x2000
	s_nop 0
	global_load_lds_dwordx4 v[148:149], off
	s_mov_b32 m0, s68
	v_lshl_add_u64 v[194:195], s[58:59], 0, v[128:129]
	ds_read_b128 v[174:177], v157 offset:16384
	ds_read_b128 v[178:181], v157 offset:17408
	ds_read_b128 v[182:185], v157 offset:18432
	ds_read_b128 v[206:209], v157 offset:19456
	ds_read_b128 v[210:213], v157 offset:20480
	ds_read_b128 v[214:217], v157 offset:21504
	ds_read_b128 v[218:221], v157 offset:22528
	ds_read_b128 v[222:225], v157 offset:23552
	global_load_lds_dwordx4 v[194:195], off
	v_lshl_add_u64 v[196:197], s[58:59], 0, v[130:131]
	s_mov_b32 m0, s69
	s_nop 0
	global_load_lds_dwordx4 v[196:197], off
	s_add_u32 s82, s54, 0x40000
	s_addc_u32 s83, s55, 0
	s_add_i32 s6, s6, s57
	v_lshl_add_u64 v[250:251], s[82:83], 0, v[140:141]
	s_mov_b32 m0, s6
	s_nop 0
	global_load_lds_dwordx4 v[250:251], off
	v_lshl_add_u64 v[250:251], s[82:83], 0, v[132:133]
	s_add_i32 m0, s6, 0x2000
	s_nop 0
	global_load_lds_dwordx4 v[250:251], off
	s_waitcnt vmcnt(16)
	s_cmp_lg_u32 s100, 0
	s_cbranch_scc1 .Lm4bp_386
	s_waitcnt vmcnt(8)
.Lm4bp_386:
	s_waitcnt lgkmcnt(0)
	s_mov_b32 s100, 0
	s_barrier
	s_nop 0
	v_mfma_f32_16x16x32_bf16 v[60:63], v[158:161], v[174:177], 0
	v_mfma_f32_16x16x32_bf16 v[56:59], v[166:169], v[174:177], 0
	v_mfma_f32_16x16x32_bf16 v[52:55], v[158:161], v[182:185], 0
	v_mfma_f32_16x16x32_bf16 v[48:51], v[166:169], v[182:185], 0
	v_mfma_f32_16x16x32_bf16 v[44:47], v[158:161], v[210:213], 0
	v_mfma_f32_16x16x32_bf16 v[40:43], v[166:169], v[210:213], 0
	v_mfma_f32_16x16x32_bf16 v[36:39], v[158:161], v[218:221], 0
	v_mfma_f32_16x16x32_bf16 v[32:35], v[166:169], v[218:221], 0
	v_mfma_f32_16x16x32_bf16 v[60:63], v[162:165], v[178:181], v[60:63]
	v_mfma_f32_16x16x32_bf16 v[56:59], v[170:173], v[178:181], v[56:59]
	v_mfma_f32_16x16x32_bf16 v[52:55], v[162:165], v[206:209], v[52:55]
	v_mfma_f32_16x16x32_bf16 v[48:51], v[170:173], v[206:209], v[48:51]
	v_mfma_f32_16x16x32_bf16 v[44:47], v[162:165], v[214:217], v[44:47]
	v_mfma_f32_16x16x32_bf16 v[40:43], v[170:173], v[214:217], v[40:43]
	v_mfma_f32_16x16x32_bf16 v[36:39], v[162:165], v[222:225], v[36:39]
	v_mfma_f32_16x16x32_bf16 v[32:35], v[170:173], v[222:225], v[32:35]
	v_mfma_f32_16x16x32_bf16 v[28:31], v[226:229], v[174:177], 0
	v_mfma_f32_16x16x32_bf16 v[24:27], v[234:237], v[174:177], 0
	v_mfma_f32_16x16x32_bf16 v[20:23], v[226:229], v[182:185], 0
	v_mfma_f32_16x16x32_bf16 v[16:19], v[234:237], v[182:185], 0
	v_mfma_f32_16x16x32_bf16 v[12:15], v[226:229], v[210:213], 0
	v_mfma_f32_16x16x32_bf16 v[8:11], v[234:237], v[210:213], 0
	v_mfma_f32_16x16x32_bf16 v[4:7], v[226:229], v[218:221], 0
	v_mfma_f32_16x16x32_bf16 v[0:3], v[234:237], v[218:221], 0
	v_mfma_f32_16x16x32_bf16 v[28:31], v[230:233], v[178:181], v[28:31]
	v_mfma_f32_16x16x32_bf16 v[24:27], v[238:241], v[178:181], v[24:27]
	v_mfma_f32_16x16x32_bf16 v[20:23], v[230:233], v[206:209], v[20:23]
	v_mfma_f32_16x16x32_bf16 v[16:19], v[238:241], v[206:209], v[16:19]
	v_mfma_f32_16x16x32_bf16 v[12:15], v[230:233], v[214:217], v[12:15]
	v_mfma_f32_16x16x32_bf16 v[8:11], v[238:241], v[214:217], v[8:11]
	v_mfma_f32_16x16x32_bf16 v[4:7], v[230:233], v[222:225], v[4:7]
	v_mfma_f32_16x16x32_bf16 v[0:3], v[238:241], v[222:225], v[0:3]
	s_barrier
	s_add_i32 s6, 0, 0x18000
	v_add_u32_e32 v170, s6, v154
	ds_read_b128 v[158:161], v170
	ds_read_b128 v[162:165], v170 offset:1024
	ds_read_b128 v[166:169], v170 offset:2048
	ds_read_b128 v[170:173], v170 offset:3072
	s_add_u32 s58, s58, 0x40000
	s_addc_u32 s59, s59, 0
	s_mov_b32 m0, s70
	v_lshl_add_u64 v[226:227], s[58:59], 0, v[128:129]
	ds_read_b128 v[174:177], v157 offset:32768
	ds_read_b128 v[178:181], v157 offset:33792
	ds_read_b128 v[182:185], v157 offset:34816
	ds_read_b128 v[206:209], v157 offset:35840
	ds_read_b128 v[210:213], v157 offset:36864
	ds_read_b128 v[214:217], v157 offset:37888
	ds_read_b128 v[218:221], v157 offset:38912
	ds_read_b128 v[222:225], v157 offset:39936
	global_load_lds_dwordx4 v[226:227], off
	v_lshl_add_u64 v[226:227], s[58:59], 0, v[130:131]
	s_mov_b32 m0, s71
	s_nop 0
	global_load_lds_dwordx4 v[226:227], off
	s_add_i32 s19, 0, 0x1c000
	v_add_u32_e32 v192, s19, v154
	ds_read_b128 v[226:229], v192
	ds_read_b128 v[230:233], v192 offset:1024
	ds_read_b128 v[234:237], v192 offset:2048
	ds_read_b128 v[238:241], v192 offset:3072
	s_waitcnt vmcnt(8)
	s_waitcnt lgkmcnt(0)
	s_barrier
	v_mfma_f32_16x16x32_bf16 v[124:127], v[158:161], v[174:177], v[124:127]
	v_mfma_f32_16x16x32_bf16 v[120:123], v[166:169], v[174:177], v[120:123]
	v_mfma_f32_16x16x32_bf16 v[116:119], v[158:161], v[182:185], v[116:119]
	v_mfma_f32_16x16x32_bf16 v[112:115], v[166:169], v[182:185], v[112:115]
	v_mfma_f32_16x16x32_bf16 v[108:111], v[158:161], v[210:213], v[108:111]
	v_mfma_f32_16x16x32_bf16 v[104:107], v[166:169], v[210:213], v[104:107]
	v_mfma_f32_16x16x32_bf16 v[100:103], v[158:161], v[218:221], v[100:103]
	v_mfma_f32_16x16x32_bf16 v[96:99], v[166:169], v[218:221], v[96:99]
	v_mfma_f32_16x16x32_bf16 v[124:127], v[162:165], v[178:181], v[124:127]
	v_mfma_f32_16x16x32_bf16 v[120:123], v[170:173], v[178:181], v[120:123]
	v_mfma_f32_16x16x32_bf16 v[116:119], v[162:165], v[206:209], v[116:119]
	v_mfma_f32_16x16x32_bf16 v[112:115], v[170:173], v[206:209], v[112:115]
	v_mfma_f32_16x16x32_bf16 v[108:111], v[162:165], v[214:217], v[108:111]
	v_mfma_f32_16x16x32_bf16 v[104:107], v[170:173], v[214:217], v[104:107]
	v_mfma_f32_16x16x32_bf16 v[100:103], v[162:165], v[222:225], v[100:103]
	v_mfma_f32_16x16x32_bf16 v[96:99], v[170:173], v[222:225], v[96:99]
	v_mfma_f32_16x16x32_bf16 v[92:95], v[226:229], v[174:177], v[92:95]
	v_mfma_f32_16x16x32_bf16 v[88:91], v[234:237], v[174:177], v[88:91]
	v_mfma_f32_16x16x32_bf16 v[84:87], v[226:229], v[182:185], v[84:87]
	v_mfma_f32_16x16x32_bf16 v[80:83], v[234:237], v[182:185], v[80:83]
	v_mfma_f32_16x16x32_bf16 v[76:79], v[226:229], v[210:213], v[76:79]
	v_mfma_f32_16x16x32_bf16 v[72:75], v[234:237], v[210:213], v[72:75]
	v_mfma_f32_16x16x32_bf16 v[68:71], v[226:229], v[218:221], v[68:71]
	v_mfma_f32_16x16x32_bf16 v[64:67], v[234:237], v[218:221], v[64:67]
	v_mfma_f32_16x16x32_bf16 v[92:95], v[230:233], v[178:181], v[92:95]
	v_mfma_f32_16x16x32_bf16 v[88:91], v[238:241], v[178:181], v[88:91]
	v_mfma_f32_16x16x32_bf16 v[84:87], v[230:233], v[206:209], v[84:87]
	v_mfma_f32_16x16x32_bf16 v[80:83], v[238:241], v[206:209], v[80:83]
	v_mfma_f32_16x16x32_bf16 v[76:79], v[230:233], v[214:217], v[76:79]
	v_mfma_f32_16x16x32_bf16 v[72:75], v[238:241], v[214:217], v[72:75]
	v_mfma_f32_16x16x32_bf16 v[68:71], v[230:233], v[222:225], v[68:71]
	v_mfma_f32_16x16x32_bf16 v[64:67], v[238:241], v[222:225], v[64:67]
	s_barrier
	s_add_i32 s6, s6, s57
	v_lshl_add_u64 v[146:147], v[146:147], 0, s[36:37]
	s_mov_b32 m0, s6
	s_nop 0
	global_load_lds_dwordx4 v[146:147], off
	v_lshl_add_u64 v[146:147], v[148:149], 0, s[36:37]
	s_add_i32 m0, s6, 0x2000
	s_nop 0
	global_load_lds_dwordx4 v[146:147], off
	s_mov_b32 m0, s72
	v_lshl_add_u64 v[146:147], v[194:195], 0, s[36:37]
	ds_read_b128 v[174:177], v157 offset:49152
	ds_read_b128 v[178:181], v157 offset:50176
	ds_read_b128 v[182:185], v157 offset:51200
	ds_read_b128 v[206:209], v157 offset:52224
	ds_read_b128 v[210:213], v157 offset:53248
	ds_read_b128 v[214:217], v157 offset:54272
	ds_read_b128 v[218:221], v157 offset:55296
	ds_read_b128 v[222:225], v157 offset:56320
	global_load_lds_dwordx4 v[146:147], off
	v_lshl_add_u64 v[146:147], v[196:197], 0, s[36:37]
	s_mov_b32 m0, s73
	s_nop 0
	global_load_lds_dwordx4 v[146:147], off
	s_add_u32 s54, s54, 0x40080
	s_addc_u32 s55, s55, 0
	s_add_i32 s6, s19, s57
	v_lshl_add_u64 v[146:147], s[54:55], 0, v[140:141]
	s_mov_b32 m0, s6
	s_nop 0
	global_load_lds_dwordx4 v[146:147], off
	v_lshl_add_u64 v[146:147], s[54:55], 0, v[132:133]
	s_add_i32 m0, s6, 0x2000
	s_nop 0
	global_load_lds_dwordx4 v[146:147], off
	s_waitcnt vmcnt(8)
	s_waitcnt lgkmcnt(0)
	s_barrier
	v_mfma_f32_16x16x32_bf16 v[60:63], v[158:161], v[174:177], v[60:63]
	v_mfma_f32_16x16x32_bf16 v[56:59], v[166:169], v[174:177], v[56:59]
	v_mfma_f32_16x16x32_bf16 v[52:55], v[158:161], v[182:185], v[52:55]
	v_mfma_f32_16x16x32_bf16 v[48:51], v[166:169], v[182:185], v[48:51]
	v_mfma_f32_16x16x32_bf16 v[44:47], v[158:161], v[210:213], v[44:47]
	v_mfma_f32_16x16x32_bf16 v[40:43], v[166:169], v[210:213], v[40:43]
	v_mfma_f32_16x16x32_bf16 v[36:39], v[158:161], v[218:221], v[36:39]
	v_mfma_f32_16x16x32_bf16 v[32:35], v[166:169], v[218:221], v[32:35]
	v_mfma_f32_16x16x32_bf16 v[60:63], v[162:165], v[178:181], v[60:63]
	v_mfma_f32_16x16x32_bf16 v[56:59], v[170:173], v[178:181], v[56:59]
	v_mfma_f32_16x16x32_bf16 v[52:55], v[162:165], v[206:209], v[52:55]
	v_mfma_f32_16x16x32_bf16 v[48:51], v[170:173], v[206:209], v[48:51]
	v_mfma_f32_16x16x32_bf16 v[44:47], v[162:165], v[214:217], v[44:47]
	v_mfma_f32_16x16x32_bf16 v[40:43], v[170:173], v[214:217], v[40:43]
	v_mfma_f32_16x16x32_bf16 v[36:39], v[162:165], v[222:225], v[36:39]
	v_mfma_f32_16x16x32_bf16 v[32:35], v[170:173], v[222:225], v[32:35]
	v_mfma_f32_16x16x32_bf16 v[28:31], v[226:229], v[174:177], v[28:31]
	v_mfma_f32_16x16x32_bf16 v[24:27], v[234:237], v[174:177], v[24:27]
	v_mfma_f32_16x16x32_bf16 v[20:23], v[226:229], v[182:185], v[20:23]
	v_mfma_f32_16x16x32_bf16 v[16:19], v[234:237], v[182:185], v[16:19]
	v_mfma_f32_16x16x32_bf16 v[12:15], v[226:229], v[210:213], v[12:15]
	v_mfma_f32_16x16x32_bf16 v[8:11], v[234:237], v[210:213], v[8:11]
	v_mfma_f32_16x16x32_bf16 v[4:7], v[226:229], v[218:221], v[4:7]
	v_mfma_f32_16x16x32_bf16 v[0:3], v[234:237], v[218:221], v[0:3]
	v_mfma_f32_16x16x32_bf16 v[28:31], v[230:233], v[178:181], v[28:31]
	v_mfma_f32_16x16x32_bf16 v[24:27], v[238:241], v[178:181], v[24:27]
	v_mfma_f32_16x16x32_bf16 v[20:23], v[230:233], v[206:209], v[20:23]
	v_mfma_f32_16x16x32_bf16 v[16:19], v[238:241], v[206:209], v[16:19]
	v_mfma_f32_16x16x32_bf16 v[12:15], v[230:233], v[214:217], v[12:15]
	v_mfma_f32_16x16x32_bf16 v[8:11], v[238:241], v[214:217], v[8:11]
	v_mfma_f32_16x16x32_bf16 v[4:7], v[230:233], v[222:225], v[4:7]
	v_mfma_f32_16x16x32_bf16 v[0:3], v[238:241], v[222:225], v[0:3]
	s_add_i32 s81, s81, 2
	s_add_u32 s52, s52, 0x100
	s_addc_u32 s53, s53, 0
	s_cmp_gt_u32 s81, 13
	s_barrier
.LBB0_386:
	s_add_u32 s6, s28, s52
	s_addc_u32 s19, s29, s53
	s_add_u32 s6, s6, 0x100
	s_addc_u32 s19, s19, 0
	s_add_u32 s23, s10, s52
	s_addc_u32 s54, s11, s53
	s_add_i32 s82, 0, 0x10000
	v_add_u32_e32 v146, s82, v154
	ds_read_b128 v[158:161], v146
	ds_read_b128 v[162:165], v146 offset:1024
	ds_read_b128 v[166:169], v146 offset:2048
	ds_read_b128 v[170:173], v146 offset:3072
	s_cmpk_eq_i32 s52, 0x700
	s_cselect_b32 s59, s12, s19
	s_cselect_b32 s58, s35, s6
	s_cselect_b32 s55, s39, s54
	s_cselect_b32 s54, s47, s23
	v_lshl_add_u64 v[146:147], v[150:151], 0, s[52:53]
	s_add_i32 m0, s68, 0xc000
	ds_read_b128 v[174:177], v157
	ds_read_b128 v[178:181], v157 offset:1024
	ds_read_b128 v[182:185], v157 offset:2048
	ds_read_b128 v[206:209], v157 offset:3072
	ds_read_b128 v[210:213], v157 offset:4096
	ds_read_b128 v[214:217], v157 offset:5120
	ds_read_b128 v[218:221], v157 offset:6144
	ds_read_b128 v[222:225], v157 offset:7168
	global_load_lds_dwordx4 v[146:147], off
	v_lshl_add_u64 v[146:147], v[152:153], 0, s[52:53]
	s_add_i32 m0, s68, 0xe000
	s_nop 0
	global_load_lds_dwordx4 v[146:147], off
	s_add_i32 s6, 0, 0x14000
	v_add_u32_e32 v146, s6, v154
	ds_read_b128 v[226:229], v146
	ds_read_b128 v[230:233], v146 offset:1024
	ds_read_b128 v[234:237], v146 offset:2048
	ds_read_b128 v[238:241], v146 offset:3072
	s_waitcnt vmcnt(8)
	s_waitcnt lgkmcnt(0)
	s_barrier
	v_mfma_f32_16x16x32_bf16 v[124:127], v[158:161], v[174:177], v[124:127]
	v_mfma_f32_16x16x32_bf16 v[120:123], v[166:169], v[174:177], v[120:123]
	v_mfma_f32_16x16x32_bf16 v[116:119], v[158:161], v[182:185], v[116:119]
	v_mfma_f32_16x16x32_bf16 v[112:115], v[166:169], v[182:185], v[112:115]
	v_mfma_f32_16x16x32_bf16 v[108:111], v[158:161], v[210:213], v[108:111]
	v_mfma_f32_16x16x32_bf16 v[104:107], v[166:169], v[210:213], v[104:107]
	v_mfma_f32_16x16x32_bf16 v[100:103], v[158:161], v[218:221], v[100:103]
	v_mfma_f32_16x16x32_bf16 v[96:99], v[166:169], v[218:221], v[96:99]
	v_mfma_f32_16x16x32_bf16 v[124:127], v[162:165], v[178:181], v[124:127]
	v_mfma_f32_16x16x32_bf16 v[120:123], v[170:173], v[178:181], v[120:123]
	v_mfma_f32_16x16x32_bf16 v[116:119], v[162:165], v[206:209], v[116:119]
	v_mfma_f32_16x16x32_bf16 v[112:115], v[170:173], v[206:209], v[112:115]
	v_mfma_f32_16x16x32_bf16 v[108:111], v[162:165], v[214:217], v[108:111]
	v_mfma_f32_16x16x32_bf16 v[104:107], v[170:173], v[214:217], v[104:107]
	v_mfma_f32_16x16x32_bf16 v[100:103], v[162:165], v[222:225], v[100:103]
	v_mfma_f32_16x16x32_bf16 v[96:99], v[170:173], v[222:225], v[96:99]
	v_mfma_f32_16x16x32_bf16 v[92:95], v[226:229], v[174:177], v[92:95]
	v_mfma_f32_16x16x32_bf16 v[88:91], v[234:237], v[174:177], v[88:91]
	v_mfma_f32_16x16x32_bf16 v[84:87], v[226:229], v[182:185], v[84:87]
	v_mfma_f32_16x16x32_bf16 v[80:83], v[234:237], v[182:185], v[80:83]
	v_mfma_f32_16x16x32_bf16 v[76:79], v[226:229], v[210:213], v[76:79]
	v_mfma_f32_16x16x32_bf16 v[72:75], v[234:237], v[210:213], v[72:75]
	v_mfma_f32_16x16x32_bf16 v[68:71], v[226:229], v[218:221], v[68:71]
	v_mfma_f32_16x16x32_bf16 v[64:67], v[234:237], v[218:221], v[64:67]
	v_mfma_f32_16x16x32_bf16 v[92:95], v[230:233], v[178:181], v[92:95]
	v_mfma_f32_16x16x32_bf16 v[88:91], v[238:241], v[178:181], v[88:91]
	v_mfma_f32_16x16x32_bf16 v[84:87], v[230:233], v[206:209], v[84:87]
	v_mfma_f32_16x16x32_bf16 v[80:83], v[238:241], v[206:209], v[80:83]
	v_mfma_f32_16x16x32_bf16 v[76:79], v[230:233], v[214:217], v[76:79]
	v_mfma_f32_16x16x32_bf16 v[72:75], v[238:241], v[214:217], v[72:75]
	v_mfma_f32_16x16x32_bf16 v[68:71], v[230:233], v[222:225], v[68:71]
	v_mfma_f32_16x16x32_bf16 v[64:67], v[238:241], v[222:225], v[64:67]
	s_barrier
	s_add_i32 s19, s82, s57
	v_lshl_add_u64 v[146:147], s[54:55], 0, v[140:141]
	s_mov_b32 m0, s19
	v_lshl_add_u64 v[148:149], s[54:55], 0, v[132:133]
	global_load_lds_dwordx4 v[146:147], off
	s_add_i32 m0, s19, 0x2000
	s_nop 0
	global_load_lds_dwordx4 v[148:149], off
	s_mov_b32 m0, s68
	v_lshl_add_u64 v[194:195], s[58:59], 0, v[128:129]
	ds_read_b128 v[174:177], v157 offset:16384
	ds_read_b128 v[178:181], v157 offset:17408
	ds_read_b128 v[182:185], v157 offset:18432
	ds_read_b128 v[206:209], v157 offset:19456
	ds_read_b128 v[210:213], v157 offset:20480
	ds_read_b128 v[214:217], v157 offset:21504
	ds_read_b128 v[218:221], v157 offset:22528
	ds_read_b128 v[222:225], v157 offset:23552
	global_load_lds_dwordx4 v[194:195], off
	v_lshl_add_u64 v[196:197], s[58:59], 0, v[130:131]
	s_mov_b32 m0, s69
	s_nop 0
	global_load_lds_dwordx4 v[196:197], off
	s_add_u32 s82, s54, 0x40000
	s_addc_u32 s83, s55, 0
	s_add_i32 s6, s6, s57
	v_lshl_add_u64 v[250:251], s[82:83], 0, v[140:141]
	s_mov_b32 m0, s6
	s_nop 0
	global_load_lds_dwordx4 v[250:251], off
	v_lshl_add_u64 v[250:251], s[82:83], 0, v[132:133]
	s_add_i32 m0, s6, 0x2000
	s_nop 0
	global_load_lds_dwordx4 v[250:251], off
	s_nop 0
	s_waitcnt vmcnt(8)
	s_waitcnt lgkmcnt(0)
	s_barrier
	v_mfma_f32_16x16x32_bf16 v[60:63], v[158:161], v[174:177], v[60:63]
	v_mfma_f32_16x16x32_bf16 v[56:59], v[166:169], v[174:177], v[56:59]
	v_mfma_f32_16x16x32_bf16 v[52:55], v[158:161], v[182:185], v[52:55]
	v_mfma_f32_16x16x32_bf16 v[48:51], v[166:169], v[182:185], v[48:51]
	v_mfma_f32_16x16x32_bf16 v[44:47], v[158:161], v[210:213], v[44:47]
	v_mfma_f32_16x16x32_bf16 v[40:43], v[166:169], v[210:213], v[40:43]
	v_mfma_f32_16x16x32_bf16 v[36:39], v[158:161], v[218:221], v[36:39]
	v_mfma_f32_16x16x32_bf16 v[32:35], v[166:169], v[218:221], v[32:35]
	v_mfma_f32_16x16x32_bf16 v[60:63], v[162:165], v[178:181], v[60:63]
	v_mfma_f32_16x16x32_bf16 v[56:59], v[170:173], v[178:181], v[56:59]
	v_mfma_f32_16x16x32_bf16 v[52:55], v[162:165], v[206:209], v[52:55]
	v_mfma_f32_16x16x32_bf16 v[48:51], v[170:173], v[206:209], v[48:51]
	v_mfma_f32_16x16x32_bf16 v[44:47], v[162:165], v[214:217], v[44:47]
	v_mfma_f32_16x16x32_bf16 v[40:43], v[170:173], v[214:217], v[40:43]
	v_mfma_f32_16x16x32_bf16 v[36:39], v[162:165], v[222:225], v[36:39]
	v_mfma_f32_16x16x32_bf16 v[32:35], v[170:173], v[222:225], v[32:35]
	v_mfma_f32_16x16x32_bf16 v[28:31], v[226:229], v[174:177], v[28:31]
	v_mfma_f32_16x16x32_bf16 v[24:27], v[234:237], v[174:177], v[24:27]
	v_mfma_f32_16x16x32_bf16 v[20:23], v[226:229], v[182:185], v[20:23]
	v_mfma_f32_16x16x32_bf16 v[16:19], v[234:237], v[182:185], v[16:19]
	v_mfma_f32_16x16x32_bf16 v[12:15], v[226:229], v[210:213], v[12:15]
	v_mfma_f32_16x16x32_bf16 v[8:11], v[234:237], v[210:213], v[8:11]
	v_mfma_f32_16x16x32_bf16 v[4:7], v[226:229], v[218:221], v[4:7]
	v_mfma_f32_16x16x32_bf16 v[0:3], v[234:237], v[218:221], v[0:3]
	v_mfma_f32_16x16x32_bf16 v[28:31], v[230:233], v[178:181], v[28:31]
	v_mfma_f32_16x16x32_bf16 v[24:27], v[238:241], v[178:181], v[24:27]
	v_mfma_f32_16x16x32_bf16 v[20:23], v[230:233], v[206:209], v[20:23]
	v_mfma_f32_16x16x32_bf16 v[16:19], v[238:241], v[206:209], v[16:19]
	v_mfma_f32_16x16x32_bf16 v[12:15], v[230:233], v[214:217], v[12:15]
	v_mfma_f32_16x16x32_bf16 v[8:11], v[238:241], v[214:217], v[8:11]
	v_mfma_f32_16x16x32_bf16 v[4:7], v[230:233], v[222:225], v[4:7]
	v_mfma_f32_16x16x32_bf16 v[0:3], v[238:241], v[222:225], v[0:3]
	s_barrier
	s_add_i32 s6, 0, 0x18000
	v_add_u32_e32 v170, s6, v154
	ds_read_b128 v[158:161], v170
	ds_read_b128 v[162:165], v170 offset:1024
	ds_read_b128 v[166:169], v170 offset:2048
	ds_read_b128 v[170:173], v170 offset:3072
	s_add_u32 s58, s58, 0x40000
	s_addc_u32 s59, s59, 0
	s_mov_b32 m0, s70
	v_lshl_add_u64 v[226:227], s[58:59], 0, v[128:129]
	ds_read_b128 v[174:177], v157 offset:32768
	ds_read_b128 v[178:181], v157 offset:33792
	ds_read_b128 v[182:185], v157 offset:34816
	ds_read_b128 v[206:209], v157 offset:35840
	ds_read_b128 v[210:213], v157 offset:36864
	ds_read_b128 v[214:217], v157 offset:37888
	ds_read_b128 v[218:221], v157 offset:38912
	ds_read_b128 v[222:225], v157 offset:39936
	global_load_lds_dwordx4 v[226:227], off
	v_lshl_add_u64 v[226:227], s[58:59], 0, v[130:131]
	s_mov_b32 m0, s71
	s_nop 0
	global_load_lds_dwordx4 v[226:227], off
	s_add_i32 s19, 0, 0x1c000
	v_add_u32_e32 v192, s19, v154
	ds_read_b128 v[226:229], v192
	ds_read_b128 v[230:233], v192 offset:1024
	ds_read_b128 v[234:237], v192 offset:2048
	ds_read_b128 v[238:241], v192 offset:3072
	s_waitcnt vmcnt(8)
	s_waitcnt lgkmcnt(0)
	s_barrier
	v_mfma_f32_16x16x32_bf16 v[124:127], v[158:161], v[174:177], v[124:127]
	v_mfma_f32_16x16x32_bf16 v[120:123], v[166:169], v[174:177], v[120:123]
	v_mfma_f32_16x16x32_bf16 v[116:119], v[158:161], v[182:185], v[116:119]
	v_mfma_f32_16x16x32_bf16 v[112:115], v[166:169], v[182:185], v[112:115]
	v_mfma_f32_16x16x32_bf16 v[108:111], v[158:161], v[210:213], v[108:111]
	v_mfma_f32_16x16x32_bf16 v[104:107], v[166:169], v[210:213], v[104:107]
	v_mfma_f32_16x16x32_bf16 v[100:103], v[158:161], v[218:221], v[100:103]
	v_mfma_f32_16x16x32_bf16 v[96:99], v[166:169], v[218:221], v[96:99]
	v_mfma_f32_16x16x32_bf16 v[124:127], v[162:165], v[178:181], v[124:127]
	v_mfma_f32_16x16x32_bf16 v[120:123], v[170:173], v[178:181], v[120:123]
	v_mfma_f32_16x16x32_bf16 v[116:119], v[162:165], v[206:209], v[116:119]
	v_mfma_f32_16x16x32_bf16 v[112:115], v[170:173], v[206:209], v[112:115]
	v_mfma_f32_16x16x32_bf16 v[108:111], v[162:165], v[214:217], v[108:111]
	v_mfma_f32_16x16x32_bf16 v[104:107], v[170:173], v[214:217], v[104:107]
	v_mfma_f32_16x16x32_bf16 v[100:103], v[162:165], v[222:225], v[100:103]
	v_mfma_f32_16x16x32_bf16 v[96:99], v[170:173], v[222:225], v[96:99]
	v_mfma_f32_16x16x32_bf16 v[92:95], v[226:229], v[174:177], v[92:95]
	v_mfma_f32_16x16x32_bf16 v[88:91], v[234:237], v[174:177], v[88:91]
	v_mfma_f32_16x16x32_bf16 v[84:87], v[226:229], v[182:185], v[84:87]
	v_mfma_f32_16x16x32_bf16 v[80:83], v[234:237], v[182:185], v[80:83]
	v_mfma_f32_16x16x32_bf16 v[76:79], v[226:229], v[210:213], v[76:79]
	v_mfma_f32_16x16x32_bf16 v[72:75], v[234:237], v[210:213], v[72:75]
	v_mfma_f32_16x16x32_bf16 v[68:71], v[226:229], v[218:221], v[68:71]
	v_mfma_f32_16x16x32_bf16 v[64:67], v[234:237], v[218:221], v[64:67]
	v_mfma_f32_16x16x32_bf16 v[92:95], v[230:233], v[178:181], v[92:95]
	v_mfma_f32_16x16x32_bf16 v[88:91], v[238:241], v[178:181], v[88:91]
	v_mfma_f32_16x16x32_bf16 v[84:87], v[230:233], v[206:209], v[84:87]
	v_mfma_f32_16x16x32_bf16 v[80:83], v[238:241], v[206:209], v[80:83]
	v_mfma_f32_16x16x32_bf16 v[76:79], v[230:233], v[214:217], v[76:79]
	v_mfma_f32_16x16x32_bf16 v[72:75], v[238:241], v[214:217], v[72:75]
	v_mfma_f32_16x16x32_bf16 v[68:71], v[230:233], v[222:225], v[68:71]
	v_mfma_f32_16x16x32_bf16 v[64:67], v[238:241], v[222:225], v[64:67]
	s_barrier
	s_add_i32 s6, s6, s57
	v_lshl_add_u64 v[146:147], v[146:147], 0, s[36:37]
	s_mov_b32 m0, s6
	s_nop 0
	global_load_lds_dwordx4 v[146:147], off
	v_lshl_add_u64 v[146:147], v[148:149], 0, s[36:37]
	s_add_i32 m0, s6, 0x2000
	s_nop 0
	global_load_lds_dwordx4 v[146:147], off
	s_mov_b32 m0, s72
	v_lshl_add_u64 v[146:147], v[194:195], 0, s[36:37]
	ds_read_b128 v[174:177], v157 offset:49152
	ds_read_b128 v[178:181], v157 offset:50176
	ds_read_b128 v[182:185], v157 offset:51200
	ds_read_b128 v[206:209], v157 offset:52224
	ds_read_b128 v[210:213], v157 offset:53248
	ds_read_b128 v[214:217], v157 offset:54272
	ds_read_b128 v[218:221], v157 offset:55296
	ds_read_b128 v[222:225], v157 offset:56320
	global_load_lds_dwordx4 v[146:147], off
	v_lshl_add_u64 v[146:147], v[196:197], 0, s[36:37]
	s_mov_b32 m0, s73
	s_nop 0
	global_load_lds_dwordx4 v[146:147], off
	s_add_u32 s54, s54, 0x40080
	s_addc_u32 s55, s55, 0
	s_add_i32 s6, s19, s57
	v_lshl_add_u64 v[146:147], s[54:55], 0, v[140:141]
	s_mov_b32 m0, s6
	s_nop 0
	global_load_lds_dwordx4 v[146:147], off
	v_lshl_add_u64 v[146:147], s[54:55], 0, v[132:133]
	s_add_i32 m0, s6, 0x2000
	s_nop 0
	global_load_lds_dwordx4 v[146:147], off
	s_waitcnt vmcnt(8)
	s_waitcnt lgkmcnt(0)
	s_barrier
	v_mfma_f32_16x16x32_bf16 v[60:63], v[158:161], v[174:177], v[60:63]
	v_mfma_f32_16x16x32_bf16 v[56:59], v[166:169], v[174:177], v[56:59]
	v_mfma_f32_16x16x32_bf16 v[52:55], v[158:161], v[182:185], v[52:55]
	v_mfma_f32_16x16x32_bf16 v[48:51], v[166:169], v[182:185], v[48:51]
	v_mfma_f32_16x16x32_bf16 v[44:47], v[158:161], v[210:213], v[44:47]
	v_mfma_f32_16x16x32_bf16 v[40:43], v[166:169], v[210:213], v[40:43]
	v_mfma_f32_16x16x32_bf16 v[36:39], v[158:161], v[218:221], v[36:39]
	v_mfma_f32_16x16x32_bf16 v[32:35], v[166:169], v[218:221], v[32:35]
	v_mfma_f32_16x16x32_bf16 v[60:63], v[162:165], v[178:181], v[60:63]
	v_mfma_f32_16x16x32_bf16 v[56:59], v[170:173], v[178:181], v[56:59]
	v_mfma_f32_16x16x32_bf16 v[52:55], v[162:165], v[206:209], v[52:55]
	v_mfma_f32_16x16x32_bf16 v[48:51], v[170:173], v[206:209], v[48:51]
	v_mfma_f32_16x16x32_bf16 v[44:47], v[162:165], v[214:217], v[44:47]
	v_mfma_f32_16x16x32_bf16 v[40:43], v[170:173], v[214:217], v[40:43]
	v_mfma_f32_16x16x32_bf16 v[36:39], v[162:165], v[222:225], v[36:39]
	v_mfma_f32_16x16x32_bf16 v[32:35], v[170:173], v[222:225], v[32:35]
	v_mfma_f32_16x16x32_bf16 v[28:31], v[226:229], v[174:177], v[28:31]
	v_mfma_f32_16x16x32_bf16 v[24:27], v[234:237], v[174:177], v[24:27]
	v_mfma_f32_16x16x32_bf16 v[20:23], v[226:229], v[182:185], v[20:23]
	v_mfma_f32_16x16x32_bf16 v[16:19], v[234:237], v[182:185], v[16:19]
	v_mfma_f32_16x16x32_bf16 v[12:15], v[226:229], v[210:213], v[12:15]
	v_mfma_f32_16x16x32_bf16 v[8:11], v[234:237], v[210:213], v[8:11]
	v_mfma_f32_16x16x32_bf16 v[4:7], v[226:229], v[218:221], v[4:7]
	v_mfma_f32_16x16x32_bf16 v[0:3], v[234:237], v[218:221], v[0:3]
	v_mfma_f32_16x16x32_bf16 v[28:31], v[230:233], v[178:181], v[28:31]
	v_mfma_f32_16x16x32_bf16 v[24:27], v[238:241], v[178:181], v[24:27]
	v_mfma_f32_16x16x32_bf16 v[20:23], v[230:233], v[206:209], v[20:23]
	v_mfma_f32_16x16x32_bf16 v[16:19], v[238:241], v[206:209], v[16:19]
	v_mfma_f32_16x16x32_bf16 v[12:15], v[230:233], v[214:217], v[12:15]
	v_mfma_f32_16x16x32_bf16 v[8:11], v[238:241], v[214:217], v[8:11]
	v_mfma_f32_16x16x32_bf16 v[4:7], v[230:233], v[222:225], v[4:7]
	v_mfma_f32_16x16x32_bf16 v[0:3], v[238:241], v[222:225], v[0:3]
	s_add_i32 s81, s81, 2
	s_add_u32 s52, s52, 0x100
	s_addc_u32 s53, s53, 0
	s_cmp_gt_u32 s81, 13
	s_barrier
	s_cbranch_scc0 .LBB0_386
	s_mov_b32 s100, 1
	v_lshl_add_u32 v158, s75, 10, v155
	ds_read2_b32 v[146:147], v158 offset1:16
	s_add_u32 s52, s10, 0xffffff00
	s_addc_u32 s53, s11, -1
	s_ashr_i32 s35, s34, 31
	s_lshl_b64 s[10:11], s[34:35], 8
	s_waitcnt lgkmcnt(0)
	v_mul_f32_e32 v184, 0xbfb8aa3b, v146
	v_mul_f32_e32 v206, v146, v146
	v_pk_mul_f32 v[168:169], v[124:125], v[184:185] op_sel_hi:[1,0]
	v_pk_mul_f32 v[170:171], v[126:127], v[184:185] op_sel_hi:[1,0]
	v_pk_mul_f32 v[172:173], v[120:121], v[184:185] op_sel_hi:[1,0]
	v_pk_mul_f32 v[174:175], v[122:123], v[184:185] op_sel_hi:[1,0]
	v_exp_f32_e32 v168, v168
	v_exp_f32_e32 v169, v169
	v_exp_f32_e32 v170, v170
	v_exp_f32_e32 v171, v171
	v_exp_f32_e32 v172, v172
	v_exp_f32_e32 v173, v173
	v_exp_f32_e32 v174, v174
	v_exp_f32_e32 v175, v175
	v_pk_mul_f32 v[176:177], v[124:125], v[92:93]
	v_pk_mul_f32 v[178:179], v[126:127], v[94:95]
	v_pk_mul_f32 v[180:181], v[120:121], v[88:89]
	v_pk_mul_f32 v[182:183], v[122:123], v[90:91]
	v_pk_add_f32 v[168:169], v[168:169], 1.0 op_sel_hi:[1,0]
	v_pk_add_f32 v[170:171], v[170:171], 1.0 op_sel_hi:[1,0]
	v_pk_add_f32 v[172:173], v[172:173], 1.0 op_sel_hi:[1,0]
	v_pk_add_f32 v[174:175], v[174:175], 1.0 op_sel_hi:[1,0]
	v_rcp_f32_e32 v168, v168
	v_rcp_f32_e32 v169, v169
	v_rcp_f32_e32 v170, v170
	v_rcp_f32_e32 v171, v171
	v_rcp_f32_e32 v172, v172
	v_rcp_f32_e32 v173, v173
	v_rcp_f32_e32 v174, v174
	v_rcp_f32_e32 v175, v175
	v_pk_mul_f32 v[176:177], v[176:177], v[206:207] op_sel_hi:[1,0]
	v_pk_mul_f32 v[178:179], v[178:179], v[206:207] op_sel_hi:[1,0]
	v_pk_mul_f32 v[180:181], v[180:181], v[206:207] op_sel_hi:[1,0]
	v_pk_mul_f32 v[182:183], v[182:183], v[206:207] op_sel_hi:[1,0]
	v_pk_mul_f32 v[176:177], v[176:177], v[168:169]
	v_pk_mul_f32 v[178:179], v[178:179], v[170:171]
	v_pk_mul_f32 v[180:181], v[180:181], v[172:173]
	v_pk_mul_f32 v[182:183], v[182:183], v[174:175]
	v_cvt_pk_bf16_f32 v160, v176, v177
	v_cvt_pk_bf16_f32 v161, v178, v179
	v_cvt_pk_bf16_f32 v162, v180, v181
	v_cvt_pk_bf16_f32 v163, v182, v183
	v_lshl_add_u64 v[152:153], v[134:135], 0, s[10:11]
	s_movk_i32 s6, 0x1600
	v_lshl_or_b32 v150, s74, 7, v156
	v_ashrrev_i32_e32 v151, 31, v150
	s_nop 1
	v_mov_b64_e32 v[148:149], s[30:31]
	v_mad_u64_u32 v[148:149], s[10:11], v152, s6, v[148:149]
	v_mov_b32_e32 v146, v149
	v_mad_u64_u32 v[152:153], s[10:11], v153, s6, v[146:147]
	v_mov_b32_e32 v149, v152
	v_mov_b32_e32 v146, v147
	v_lshl_add_u64 v[150:151], v[150:151], 1, v[148:149]
	global_store_dwordx4 v[150:151], v[160:163], off
	v_mul_f32_e32 v184, 0xbfb8aa3b, v146
	v_mul_f32_e32 v206, v146, v146
	v_pk_mul_f32 v[168:169], v[116:117], v[184:185] op_sel_hi:[1,0]
	v_pk_mul_f32 v[170:171], v[118:119], v[184:185] op_sel_hi:[1,0]
	v_pk_mul_f32 v[172:173], v[112:113], v[184:185] op_sel_hi:[1,0]
	v_pk_mul_f32 v[174:175], v[114:115], v[184:185] op_sel_hi:[1,0]
	v_exp_f32_e32 v168, v168
	v_exp_f32_e32 v169, v169
	v_exp_f32_e32 v170, v170
	v_exp_f32_e32 v171, v171
	v_exp_f32_e32 v172, v172
	v_exp_f32_e32 v173, v173
	v_exp_f32_e32 v174, v174
	v_exp_f32_e32 v175, v175
	v_pk_mul_f32 v[176:177], v[116:117], v[84:85]
	v_pk_mul_f32 v[178:179], v[118:119], v[86:87]
	v_pk_mul_f32 v[180:181], v[112:113], v[80:81]
	v_pk_mul_f32 v[182:183], v[114:115], v[82:83]
	v_pk_add_f32 v[168:169], v[168:169], 1.0 op_sel_hi:[1,0]
	v_pk_add_f32 v[170:171], v[170:171], 1.0 op_sel_hi:[1,0]
	v_pk_add_f32 v[172:173], v[172:173], 1.0 op_sel_hi:[1,0]
	v_pk_add_f32 v[174:175], v[174:175], 1.0 op_sel_hi:[1,0]
	v_rcp_f32_e32 v168, v168
	v_rcp_f32_e32 v169, v169
	v_rcp_f32_e32 v170, v170
	v_rcp_f32_e32 v171, v171
	v_rcp_f32_e32 v172, v172
	v_rcp_f32_e32 v173, v173
	v_rcp_f32_e32 v174, v174
	v_rcp_f32_e32 v175, v175
	v_pk_mul_f32 v[176:177], v[176:177], v[206:207] op_sel_hi:[1,0]
	v_pk_mul_f32 v[178:179], v[178:179], v[206:207] op_sel_hi:[1,0]
	v_pk_mul_f32 v[180:181], v[180:181], v[206:207] op_sel_hi:[1,0]
	v_pk_mul_f32 v[182:183], v[182:183], v[206:207] op_sel_hi:[1,0]
	v_pk_mul_f32 v[176:177], v[176:177], v[168:169]
	v_pk_mul_f32 v[178:179], v[178:179], v[170:171]
	v_pk_mul_f32 v[180:181], v[180:181], v[172:173]
	v_pk_mul_f32 v[182:183], v[182:183], v[174:175]
	v_cvt_pk_bf16_f32 v160, v176, v177
	v_cvt_pk_bf16_f32 v161, v178, v179
	v_cvt_pk_bf16_f32 v162, v180, v181
	v_cvt_pk_bf16_f32 v163, v182, v183
	s_mov_b32 s6, 0x16000
	s_nop 1
	v_add_co_u32_e32 v146, vcc, s6, v150
	s_nop 0
	v_addc_co_u32_e32 v147, vcc, 0, v151, vcc
	global_store_dwordx4 v[146:147], v[160:163], off
	ds_read2_b32 v[146:147], v158 offset0:32 offset1:48
	s_mov_b32 s6, 0x2c000
	s_waitcnt lgkmcnt(0)
	v_mul_f32_e32 v184, 0xbfb8aa3b, v146
	v_mul_f32_e32 v206, v146, v146
	v_pk_mul_f32 v[168:169], v[108:109], v[184:185] op_sel_hi:[1,0]
	v_pk_mul_f32 v[170:171], v[110:111], v[184:185] op_sel_hi:[1,0]
	v_pk_mul_f32 v[172:173], v[104:105], v[184:185] op_sel_hi:[1,0]
	v_pk_mul_f32 v[174:175], v[106:107], v[184:185] op_sel_hi:[1,0]
	v_exp_f32_e32 v168, v168
	v_exp_f32_e32 v169, v169
	v_exp_f32_e32 v170, v170
	v_exp_f32_e32 v171, v171
	v_exp_f32_e32 v172, v172
	v_exp_f32_e32 v173, v173
	v_exp_f32_e32 v174, v174
	v_exp_f32_e32 v175, v175
	v_pk_mul_f32 v[176:177], v[108:109], v[76:77]
	v_pk_mul_f32 v[178:179], v[110:111], v[78:79]
	v_pk_mul_f32 v[180:181], v[104:105], v[72:73]
	v_pk_mul_f32 v[182:183], v[106:107], v[74:75]
	v_pk_add_f32 v[168:169], v[168:169], 1.0 op_sel_hi:[1,0]
	v_pk_add_f32 v[170:171], v[170:171], 1.0 op_sel_hi:[1,0]
	v_pk_add_f32 v[172:173], v[172:173], 1.0 op_sel_hi:[1,0]
	v_pk_add_f32 v[174:175], v[174:175], 1.0 op_sel_hi:[1,0]
	v_rcp_f32_e32 v168, v168
	v_rcp_f32_e32 v169, v169
	v_rcp_f32_e32 v170, v170
	v_rcp_f32_e32 v171, v171
	v_rcp_f32_e32 v172, v172
	v_rcp_f32_e32 v173, v173
	v_rcp_f32_e32 v174, v174
	v_rcp_f32_e32 v175, v175
	v_pk_mul_f32 v[176:177], v[176:177], v[206:207] op_sel_hi:[1,0]
	v_pk_mul_f32 v[178:179], v[178:179], v[206:207] op_sel_hi:[1,0]
	v_pk_mul_f32 v[180:181], v[180:181], v[206:207] op_sel_hi:[1,0]
	v_pk_mul_f32 v[182:183], v[182:183], v[206:207] op_sel_hi:[1,0]
	v_pk_mul_f32 v[176:177], v[176:177], v[168:169]
	v_pk_mul_f32 v[178:179], v[178:179], v[170:171]
	v_pk_mul_f32 v[180:181], v[180:181], v[172:173]
	v_pk_mul_f32 v[182:183], v[182:183], v[174:175]
	v_cvt_pk_bf16_f32 v160, v176, v177
	v_cvt_pk_bf16_f32 v161, v178, v179
	v_cvt_pk_bf16_f32 v162, v180, v181
	v_cvt_pk_bf16_f32 v163, v182, v183
	s_nop 1
	v_mov_b32_e32 v146, v147
	v_add_co_u32_e32 v148, vcc, s6, v150
	v_addc_co_u32_e32 v149, vcc, 0, v151, vcc
	global_store_dwordx4 v[148:149], v[160:163], off
	v_mul_f32_e32 v184, 0xbfb8aa3b, v146
	v_mul_f32_e32 v206, v146, v146
	v_pk_mul_f32 v[168:169], v[100:101], v[184:185] op_sel_hi:[1,0]
	v_pk_mul_f32 v[170:171], v[102:103], v[184:185] op_sel_hi:[1,0]
	v_pk_mul_f32 v[172:173], v[96:97], v[184:185] op_sel_hi:[1,0]
	v_pk_mul_f32 v[174:175], v[98:99], v[184:185] op_sel_hi:[1,0]
	v_exp_f32_e32 v168, v168
	v_exp_f32_e32 v169, v169
	v_exp_f32_e32 v170, v170
	v_exp_f32_e32 v171, v171
	v_exp_f32_e32 v172, v172
	v_exp_f32_e32 v173, v173
	v_exp_f32_e32 v174, v174
	v_exp_f32_e32 v175, v175
	v_pk_mul_f32 v[176:177], v[100:101], v[68:69]
	v_pk_mul_f32 v[178:179], v[102:103], v[70:71]
	v_pk_mul_f32 v[180:181], v[96:97], v[64:65]
	v_pk_mul_f32 v[182:183], v[98:99], v[66:67]
	v_pk_add_f32 v[168:169], v[168:169], 1.0 op_sel_hi:[1,0]
	v_pk_add_f32 v[170:171], v[170:171], 1.0 op_sel_hi:[1,0]
	v_pk_add_f32 v[172:173], v[172:173], 1.0 op_sel_hi:[1,0]
	v_pk_add_f32 v[174:175], v[174:175], 1.0 op_sel_hi:[1,0]
	v_rcp_f32_e32 v168, v168
	v_rcp_f32_e32 v169, v169
	v_rcp_f32_e32 v170, v170
	v_rcp_f32_e32 v171, v171
	v_rcp_f32_e32 v172, v172
	v_rcp_f32_e32 v173, v173
	v_rcp_f32_e32 v174, v174
	v_rcp_f32_e32 v175, v175
	v_pk_mul_f32 v[176:177], v[176:177], v[206:207] op_sel_hi:[1,0]
	v_pk_mul_f32 v[178:179], v[178:179], v[206:207] op_sel_hi:[1,0]
	v_pk_mul_f32 v[180:181], v[180:181], v[206:207] op_sel_hi:[1,0]
	v_pk_mul_f32 v[182:183], v[182:183], v[206:207] op_sel_hi:[1,0]
	v_pk_mul_f32 v[176:177], v[176:177], v[168:169]
	v_pk_mul_f32 v[178:179], v[178:179], v[170:171]
	v_pk_mul_f32 v[180:181], v[180:181], v[172:173]
	v_pk_mul_f32 v[182:183], v[182:183], v[174:175]
	v_cvt_pk_bf16_f32 v160, v176, v177
	v_cvt_pk_bf16_f32 v161, v178, v179
	v_cvt_pk_bf16_f32 v162, v180, v181
	v_cvt_pk_bf16_f32 v163, v182, v183
	s_mov_b32 s6, 0x42000
	s_nop 1
	v_add_co_u32_e32 v146, vcc, s6, v150
	s_nop 0
	v_addc_co_u32_e32 v147, vcc, 0, v151, vcc
	global_store_dwordx4 v[146:147], v[160:163], off
	ds_read2_b32 v[146:147], v158 offset0:128 offset1:144
	s_mov_b32 s6, 0xb0000
	s_waitcnt lgkmcnt(0)
	v_mul_f32_e32 v184, 0xbfb8aa3b, v146
	v_mul_f32_e32 v206, v146, v146
	v_pk_mul_f32 v[168:169], v[60:61], v[184:185] op_sel_hi:[1,0]
	v_pk_mul_f32 v[170:171], v[62:63], v[184:185] op_sel_hi:[1,0]
	v_pk_mul_f32 v[172:173], v[56:57], v[184:185] op_sel_hi:[1,0]
	v_pk_mul_f32 v[174:175], v[58:59], v[184:185] op_sel_hi:[1,0]
	v_exp_f32_e32 v168, v168
	v_exp_f32_e32 v169, v169
	v_exp_f32_e32 v170, v170
	v_exp_f32_e32 v171, v171
	v_exp_f32_e32 v172, v172
	v_exp_f32_e32 v173, v173
	v_exp_f32_e32 v174, v174
	v_exp_f32_e32 v175, v175
	v_pk_mul_f32 v[176:177], v[60:61], v[28:29]
	v_pk_mul_f32 v[178:179], v[62:63], v[30:31]
	v_pk_mul_f32 v[180:181], v[56:57], v[24:25]
	v_pk_mul_f32 v[182:183], v[58:59], v[26:27]
	v_pk_add_f32 v[168:169], v[168:169], 1.0 op_sel_hi:[1,0]
	v_pk_add_f32 v[170:171], v[170:171], 1.0 op_sel_hi:[1,0]
	v_pk_add_f32 v[172:173], v[172:173], 1.0 op_sel_hi:[1,0]
	v_pk_add_f32 v[174:175], v[174:175], 1.0 op_sel_hi:[1,0]
	v_rcp_f32_e32 v168, v168
	v_rcp_f32_e32 v169, v169
	v_rcp_f32_e32 v170, v170
	v_rcp_f32_e32 v171, v171
	v_rcp_f32_e32 v172, v172
	v_rcp_f32_e32 v173, v173
	v_rcp_f32_e32 v174, v174
	v_rcp_f32_e32 v175, v175
	v_pk_mul_f32 v[176:177], v[176:177], v[206:207] op_sel_hi:[1,0]
	v_pk_mul_f32 v[178:179], v[178:179], v[206:207] op_sel_hi:[1,0]
	v_pk_mul_f32 v[180:181], v[180:181], v[206:207] op_sel_hi:[1,0]
	v_pk_mul_f32 v[182:183], v[182:183], v[206:207] op_sel_hi:[1,0]
	v_pk_mul_f32 v[176:177], v[176:177], v[168:169]
	v_pk_mul_f32 v[178:179], v[178:179], v[170:171]
	v_pk_mul_f32 v[180:181], v[180:181], v[172:173]
	v_pk_mul_f32 v[182:183], v[182:183], v[174:175]
	v_cvt_pk_bf16_f32 v160, v176, v177
	v_cvt_pk_bf16_f32 v161, v178, v179
	v_cvt_pk_bf16_f32 v162, v180, v181
	v_cvt_pk_bf16_f32 v163, v182, v183
	s_nop 1
	v_mov_b32_e32 v146, v147
	v_add_co_u32_e32 v148, vcc, s6, v150
	v_addc_co_u32_e32 v149, vcc, 0, v151, vcc
	global_store_dwordx4 v[148:149], v[160:163], off
	v_mul_f32_e32 v184, 0xbfb8aa3b, v146
	v_mul_f32_e32 v206, v146, v146
	v_pk_mul_f32 v[168:169], v[52:53], v[184:185] op_sel_hi:[1,0]
	v_pk_mul_f32 v[170:171], v[54:55], v[184:185] op_sel_hi:[1,0]
	v_pk_mul_f32 v[172:173], v[48:49], v[184:185] op_sel_hi:[1,0]
	v_pk_mul_f32 v[174:175], v[50:51], v[184:185] op_sel_hi:[1,0]
	v_exp_f32_e32 v168, v168
	v_exp_f32_e32 v169, v169
	v_exp_f32_e32 v170, v170
	v_exp_f32_e32 v171, v171
	v_exp_f32_e32 v172, v172
	v_exp_f32_e32 v173, v173
	v_exp_f32_e32 v174, v174
	v_exp_f32_e32 v175, v175
	v_pk_mul_f32 v[176:177], v[52:53], v[20:21]
	v_pk_mul_f32 v[178:179], v[54:55], v[22:23]
	v_pk_mul_f32 v[180:181], v[48:49], v[16:17]
	v_pk_mul_f32 v[182:183], v[50:51], v[18:19]
	v_pk_add_f32 v[168:169], v[168:169], 1.0 op_sel_hi:[1,0]
	v_pk_add_f32 v[170:171], v[170:171], 1.0 op_sel_hi:[1,0]
	v_pk_add_f32 v[172:173], v[172:173], 1.0 op_sel_hi:[1,0]
	v_pk_add_f32 v[174:175], v[174:175], 1.0 op_sel_hi:[1,0]
	v_rcp_f32_e32 v168, v168
	v_rcp_f32_e32 v169, v169
	v_rcp_f32_e32 v170, v170
	v_rcp_f32_e32 v171, v171
	v_rcp_f32_e32 v172, v172
	v_rcp_f32_e32 v173, v173
	v_rcp_f32_e32 v174, v174
	v_rcp_f32_e32 v175, v175
	v_pk_mul_f32 v[176:177], v[176:177], v[206:207] op_sel_hi:[1,0]
	v_pk_mul_f32 v[178:179], v[178:179], v[206:207] op_sel_hi:[1,0]
	v_pk_mul_f32 v[180:181], v[180:181], v[206:207] op_sel_hi:[1,0]
	v_pk_mul_f32 v[182:183], v[182:183], v[206:207] op_sel_hi:[1,0]
	v_pk_mul_f32 v[176:177], v[176:177], v[168:169]
	v_pk_mul_f32 v[178:179], v[178:179], v[170:171]
	v_pk_mul_f32 v[180:181], v[180:181], v[172:173]
	v_pk_mul_f32 v[182:183], v[182:183], v[174:175]
	v_cvt_pk_bf16_f32 v160, v176, v177
	v_cvt_pk_bf16_f32 v161, v178, v179
	v_cvt_pk_bf16_f32 v162, v180, v181
	v_cvt_pk_bf16_f32 v163, v182, v183
	s_mov_b32 s6, 0xc6000
	s_nop 1
	v_add_co_u32_e32 v146, vcc, s6, v150
	s_nop 0
	v_addc_co_u32_e32 v147, vcc, 0, v151, vcc
	global_store_dwordx4 v[146:147], v[160:163], off
	ds_read2_b32 v[146:147], v158 offset0:160 offset1:176
	s_mov_b32 s6, 0xdc000
	s_waitcnt lgkmcnt(0)
	v_mul_f32_e32 v184, 0xbfb8aa3b, v146
	v_mul_f32_e32 v206, v146, v146
	v_pk_mul_f32 v[168:169], v[44:45], v[184:185] op_sel_hi:[1,0]
	v_pk_mul_f32 v[170:171], v[46:47], v[184:185] op_sel_hi:[1,0]
	v_pk_mul_f32 v[172:173], v[40:41], v[184:185] op_sel_hi:[1,0]
	v_pk_mul_f32 v[174:175], v[42:43], v[184:185] op_sel_hi:[1,0]
	v_exp_f32_e32 v168, v168
	v_exp_f32_e32 v169, v169
	v_exp_f32_e32 v170, v170
	v_exp_f32_e32 v171, v171
	v_exp_f32_e32 v172, v172
	v_exp_f32_e32 v173, v173
	v_exp_f32_e32 v174, v174
	v_exp_f32_e32 v175, v175
	v_pk_mul_f32 v[176:177], v[44:45], v[12:13]
	v_pk_mul_f32 v[178:179], v[46:47], v[14:15]
	v_pk_mul_f32 v[180:181], v[40:41], v[8:9]
	v_pk_mul_f32 v[182:183], v[42:43], v[10:11]
	v_pk_add_f32 v[168:169], v[168:169], 1.0 op_sel_hi:[1,0]
	v_pk_add_f32 v[170:171], v[170:171], 1.0 op_sel_hi:[1,0]
	v_pk_add_f32 v[172:173], v[172:173], 1.0 op_sel_hi:[1,0]
	v_pk_add_f32 v[174:175], v[174:175], 1.0 op_sel_hi:[1,0]
	v_rcp_f32_e32 v168, v168
	v_rcp_f32_e32 v169, v169
	v_rcp_f32_e32 v170, v170
	v_rcp_f32_e32 v171, v171
	v_rcp_f32_e32 v172, v172
	v_rcp_f32_e32 v173, v173
	v_rcp_f32_e32 v174, v174
	v_rcp_f32_e32 v175, v175
	v_pk_mul_f32 v[176:177], v[176:177], v[206:207] op_sel_hi:[1,0]
	v_pk_mul_f32 v[178:179], v[178:179], v[206:207] op_sel_hi:[1,0]
	v_pk_mul_f32 v[180:181], v[180:181], v[206:207] op_sel_hi:[1,0]
	v_pk_mul_f32 v[182:183], v[182:183], v[206:207] op_sel_hi:[1,0]
	v_pk_mul_f32 v[176:177], v[176:177], v[168:169]
	v_pk_mul_f32 v[178:179], v[178:179], v[170:171]
	v_pk_mul_f32 v[180:181], v[180:181], v[172:173]
	v_pk_mul_f32 v[182:183], v[182:183], v[174:175]
	v_cvt_pk_bf16_f32 v158, v176, v177
	v_cvt_pk_bf16_f32 v159, v178, v179
	v_cvt_pk_bf16_f32 v160, v180, v181
	v_cvt_pk_bf16_f32 v161, v182, v183
	s_nop 1
	v_mov_b32_e32 v146, v147
	v_add_co_u32_e32 v148, vcc, s6, v150
	v_addc_co_u32_e32 v149, vcc, 0, v151, vcc
	global_store_dwordx4 v[148:149], v[158:161], off
	v_mul_f32_e32 v184, 0xbfb8aa3b, v146
	v_mul_f32_e32 v206, v146, v146
	v_pk_mul_f32 v[168:169], v[36:37], v[184:185] op_sel_hi:[1,0]
	v_pk_mul_f32 v[170:171], v[38:39], v[184:185] op_sel_hi:[1,0]
	v_pk_mul_f32 v[172:173], v[32:33], v[184:185] op_sel_hi:[1,0]
	v_pk_mul_f32 v[174:175], v[34:35], v[184:185] op_sel_hi:[1,0]
	v_exp_f32_e32 v168, v168
	v_exp_f32_e32 v169, v169
	v_exp_f32_e32 v170, v170
	v_exp_f32_e32 v171, v171
	v_exp_f32_e32 v172, v172
	v_exp_f32_e32 v173, v173
	v_exp_f32_e32 v174, v174
	v_exp_f32_e32 v175, v175
	v_pk_mul_f32 v[176:177], v[36:37], v[4:5]
	v_pk_mul_f32 v[178:179], v[38:39], v[6:7]
	v_pk_mul_f32 v[180:181], v[32:33], v[0:1]
	v_pk_mul_f32 v[182:183], v[34:35], v[2:3]
	v_pk_add_f32 v[168:169], v[168:169], 1.0 op_sel_hi:[1,0]
	v_pk_add_f32 v[170:171], v[170:171], 1.0 op_sel_hi:[1,0]
	v_pk_add_f32 v[172:173], v[172:173], 1.0 op_sel_hi:[1,0]
	v_pk_add_f32 v[174:175], v[174:175], 1.0 op_sel_hi:[1,0]
	v_rcp_f32_e32 v168, v168
	v_rcp_f32_e32 v169, v169
	v_rcp_f32_e32 v170, v170
	v_rcp_f32_e32 v171, v171
	v_rcp_f32_e32 v172, v172
	v_rcp_f32_e32 v173, v173
	v_rcp_f32_e32 v174, v174
	v_rcp_f32_e32 v175, v175
	v_pk_mul_f32 v[176:177], v[176:177], v[206:207] op_sel_hi:[1,0]
	v_pk_mul_f32 v[178:179], v[178:179], v[206:207] op_sel_hi:[1,0]
	v_pk_mul_f32 v[180:181], v[180:181], v[206:207] op_sel_hi:[1,0]
	v_pk_mul_f32 v[182:183], v[182:183], v[206:207] op_sel_hi:[1,0]
	v_pk_mul_f32 v[176:177], v[176:177], v[168:169]
	v_pk_mul_f32 v[178:179], v[178:179], v[170:171]
	v_pk_mul_f32 v[180:181], v[180:181], v[172:173]
	v_pk_mul_f32 v[182:183], v[182:183], v[174:175]
	v_cvt_pk_bf16_f32 v158, v176, v177
	v_cvt_pk_bf16_f32 v159, v178, v179
	v_cvt_pk_bf16_f32 v160, v180, v181
	v_cvt_pk_bf16_f32 v161, v182, v183
	s_nop 1
	v_add_co_u32_e32 v146, vcc, 0xf2000, v150
	s_nop 0
	v_addc_co_u32_e32 v147, vcc, 0, v151, vcc
	s_andn2_b64 vcc, exec, s[44:45]
	global_store_dwordx4 v[146:147], v[158:161], off
	s_cbranch_vccz .LBB0_382
	s_mov_b64 s[48:49], s[52:53]
	s_andn2_b64 vcc, exec, s[42:43]
	s_mov_b64 s[52:53], s[48:49]
	s_cbranch_vccnz .LBB0_383

.LBB0_773:
	s_add_u32 s12, s26, s6
	s_addc_u32 s19, s27, 0
	s_add_u32 s23, s12, 0x100
	s_addc_u32 s29, s19, 0
	s_and_b64 s[10:11], s[46:47], exec
	s_cselect_b32 s53, s35, s29
	s_cselect_b32 s52, s34, s23
	s_add_u32 s6, s4, s6
	s_addc_u32 s10, s5, 0
	s_add_u32 s6, s6, 0x100
	s_addc_u32 s23, s10, 0
	s_add_i32 s84, 0, 0x10000
	s_and_b64 s[10:11], s[46:47], exec
	s_cselect_b32 s55, s39, s23
	s_cselect_b32 s54, s38, s6
	s_add_u32 s58, s12, 0x80080
	s_addc_u32 s59, s19, 0
	s_add_i32 s88, s84, s68
	s_add_i32 m0, s69, 0xc000
	s_add_i32 s23, s69, 0xe000
	s_add_i32 s87, 0, 0x14000
	s_add_i32 s86, s88, 0x2000
	s_add_u32 s50, s54, 0x40000
	v_add_u32_e32 v136, s84, v138
	s_addc_u32 s51, s55, 0
	s_add_i32 s29, s87, s68
	ds_read_b128 v[146:149], v136
	ds_read_b128 v[152:155], v136 offset:1024
	ds_read_b128 v[156:159], v136 offset:2048
	ds_read_b128 v[160:163], v136 offset:3072
	s_add_i32 s19, s29, 0x2000
	s_add_i32 s12, 0, 0x18000
	s_add_u32 s48, s52, 0x80000
	s_addc_u32 s49, s53, 0
	s_add_i32 s11, s12, s68
	s_add_i32 s10, 0, 0x1c000
	s_add_i32 s6, s11, 0x2000
	s_add_u32 s46, s54, 0x40080
	s_addc_u32 s47, s55, 0
	s_add_i32 s85, s10, s68
	s_add_i32 s84, s85, 0x2000
	v_lshl_add_u64 v[136:137], s[58:59], 0, v[132:133]
	ds_read_b128 v[164:167], v150
	ds_read_b128 v[168:171], v150 offset:1024
	ds_read_b128 v[172:175], v150 offset:2048
	ds_read_b128 v[176:179], v150 offset:3072
	ds_read_b128 v[180:183], v150 offset:4096
	ds_read_b128 v[194:197], v150 offset:5120
	ds_read_b128 v[206:209], v150 offset:6144
	ds_read_b128 v[210:213], v150 offset:7168
	global_load_lds_dwordx4 v[136:137], off
	v_lshl_add_u64 v[136:137], s[58:59], 0, v[130:131]
	s_mov_b32 m0, s23
	s_nop 0
	global_load_lds_dwordx4 v[136:137], off
	s_waitcnt lgkmcnt(8)
	s_barrier
	s_setprio 1
	s_waitcnt lgkmcnt(7)
	v_mfma_f32_16x16x32_bf16 v[124:127], v[146:149], v[164:167], v[124:127]
	v_mfma_f32_16x16x32_bf16 v[120:123], v[156:159], v[164:167], v[120:123]
	s_waitcnt lgkmcnt(5)
	v_mfma_f32_16x16x32_bf16 v[116:119], v[146:149], v[172:175], v[116:119]
	v_mfma_f32_16x16x32_bf16 v[112:115], v[156:159], v[172:175], v[112:115]
	s_waitcnt lgkmcnt(3)
	v_mfma_f32_16x16x32_bf16 v[108:111], v[146:149], v[180:183], v[108:111]
	v_mfma_f32_16x16x32_bf16 v[104:107], v[156:159], v[180:183], v[104:107]
	s_waitcnt lgkmcnt(1)
	v_mfma_f32_16x16x32_bf16 v[100:103], v[146:149], v[206:209], v[100:103]
	v_mfma_f32_16x16x32_bf16 v[96:99], v[156:159], v[206:209], v[96:99]
	v_mfma_f32_16x16x32_bf16 v[124:127], v[152:155], v[168:171], v[124:127]
	v_mfma_f32_16x16x32_bf16 v[120:123], v[160:163], v[168:171], v[120:123]
	v_mfma_f32_16x16x32_bf16 v[116:119], v[152:155], v[176:179], v[116:119]
	v_mfma_f32_16x16x32_bf16 v[112:115], v[160:163], v[176:179], v[112:115]
	v_mfma_f32_16x16x32_bf16 v[108:111], v[152:155], v[194:197], v[108:111]
	v_mfma_f32_16x16x32_bf16 v[104:107], v[160:163], v[194:197], v[104:107]
	s_waitcnt lgkmcnt(0)
	v_mfma_f32_16x16x32_bf16 v[100:103], v[152:155], v[210:213], v[100:103]
	v_mfma_f32_16x16x32_bf16 v[96:99], v[160:163], v[210:213], v[96:99]
	s_setprio 0
	s_barrier
	v_add_u32_e32 v136, s87, v138
	s_mov_b32 m0, s88
	ds_read_b128 v[214:217], v136
	ds_read_b128 v[218:221], v136 offset:1024
	ds_read_b128 v[222:225], v136 offset:2048
	ds_read_b128 v[226:229], v136 offset:3072
	v_lshl_add_u64 v[136:137], s[54:55], 0, v[140:141]
	global_load_lds_dwordx4 v[136:137], off
	v_lshl_add_u64 v[184:185], s[54:55], 0, v[128:129]
	s_mov_b32 m0, s86
	s_nop 0
	global_load_lds_dwordx4 v[184:185], off
	s_barrier
	s_setprio 1
	s_waitcnt lgkmcnt(3)
	v_mfma_f32_16x16x32_bf16 v[92:95], v[214:217], v[164:167], v[92:95]
	s_waitcnt lgkmcnt(1)
	v_mfma_f32_16x16x32_bf16 v[88:91], v[222:225], v[164:167], v[88:91]
	v_mfma_f32_16x16x32_bf16 v[84:87], v[214:217], v[172:175], v[84:87]
	v_mfma_f32_16x16x32_bf16 v[80:83], v[222:225], v[172:175], v[80:83]
	v_mfma_f32_16x16x32_bf16 v[76:79], v[214:217], v[180:183], v[76:79]
	v_mfma_f32_16x16x32_bf16 v[72:75], v[222:225], v[180:183], v[72:75]
	v_mfma_f32_16x16x32_bf16 v[68:71], v[214:217], v[206:209], v[68:71]
	v_mfma_f32_16x16x32_bf16 v[64:67], v[222:225], v[206:209], v[64:67]
	v_mfma_f32_16x16x32_bf16 v[92:95], v[218:221], v[168:171], v[92:95]
	s_waitcnt lgkmcnt(0)
	v_mfma_f32_16x16x32_bf16 v[88:91], v[226:229], v[168:171], v[88:91]
	v_mfma_f32_16x16x32_bf16 v[84:87], v[218:221], v[176:179], v[84:87]
	v_mfma_f32_16x16x32_bf16 v[80:83], v[226:229], v[176:179], v[80:83]
	v_mfma_f32_16x16x32_bf16 v[76:79], v[218:221], v[194:197], v[76:79]
	v_mfma_f32_16x16x32_bf16 v[72:75], v[226:229], v[194:197], v[72:75]
	v_mfma_f32_16x16x32_bf16 v[68:71], v[218:221], v[210:213], v[68:71]
	v_mfma_f32_16x16x32_bf16 v[64:67], v[226:229], v[210:213], v[64:67]
	s_setprio 0
	s_mov_b32 m0, s69
	v_lshl_add_u64 v[192:193], s[52:53], 0, v[132:133]
	s_barrier
	ds_read_b128 v[164:167], v150 offset:16384
	ds_read_b128 v[168:171], v150 offset:17408
	ds_read_b128 v[172:175], v150 offset:18432
	ds_read_b128 v[176:179], v150 offset:19456
	ds_read_b128 v[180:183], v150 offset:20480
	ds_read_b128 v[194:197], v150 offset:21504
	ds_read_b128 v[206:209], v150 offset:22528
	ds_read_b128 v[210:213], v150 offset:23552
	global_load_lds_dwordx4 v[192:193], off
	v_lshl_add_u64 v[230:231], s[52:53], 0, v[130:131]
	s_mov_b32 m0, s70
	s_nop 0
	global_load_lds_dwordx4 v[230:231], off
	s_barrier
	s_setprio 1
	s_waitcnt lgkmcnt(7)
	v_mfma_f32_16x16x32_bf16 v[60:63], v[146:149], v[164:167], v[60:63]
	v_mfma_f32_16x16x32_bf16 v[56:59], v[156:159], v[164:167], v[56:59]
	s_waitcnt lgkmcnt(5)
	v_mfma_f32_16x16x32_bf16 v[52:55], v[146:149], v[172:175], v[52:55]
	v_mfma_f32_16x16x32_bf16 v[48:51], v[156:159], v[172:175], v[48:51]
	s_waitcnt lgkmcnt(3)
	v_mfma_f32_16x16x32_bf16 v[44:47], v[146:149], v[180:183], v[44:47]
	v_mfma_f32_16x16x32_bf16 v[40:43], v[156:159], v[180:183], v[40:43]
	s_waitcnt lgkmcnt(1)
	v_mfma_f32_16x16x32_bf16 v[36:39], v[146:149], v[206:209], v[36:39]
	v_mfma_f32_16x16x32_bf16 v[32:35], v[156:159], v[206:209], v[32:35]
	v_mfma_f32_16x16x32_bf16 v[60:63], v[152:155], v[168:171], v[60:63]
	v_mfma_f32_16x16x32_bf16 v[56:59], v[160:163], v[168:171], v[56:59]
	v_mfma_f32_16x16x32_bf16 v[52:55], v[152:155], v[176:179], v[52:55]
	v_mfma_f32_16x16x32_bf16 v[48:51], v[160:163], v[176:179], v[48:51]
	v_mfma_f32_16x16x32_bf16 v[44:47], v[152:155], v[194:197], v[44:47]
	v_mfma_f32_16x16x32_bf16 v[40:43], v[160:163], v[194:197], v[40:43]
	s_waitcnt lgkmcnt(0)
	v_mfma_f32_16x16x32_bf16 v[36:39], v[152:155], v[210:213], v[36:39]
	v_mfma_f32_16x16x32_bf16 v[32:35], v[160:163], v[210:213], v[32:35]
	s_setprio 0
	s_barrier
	s_mov_b32 m0, s29
	v_lshl_add_u64 v[146:147], s[50:51], 0, v[140:141]
	global_load_lds_dwordx4 v[146:147], off
	v_lshl_add_u64 v[146:147], s[50:51], 0, v[128:129]
	s_mov_b32 m0, s19
	s_nop 0
	global_load_lds_dwordx4 v[146:147], off
	s_waitcnt vmcnt(6)
	s_barrier
	s_setprio 1
	v_mfma_f32_16x16x32_bf16 v[28:31], v[214:217], v[164:167], v[28:31]
	v_mfma_f32_16x16x32_bf16 v[24:27], v[222:225], v[164:167], v[24:27]
	v_mfma_f32_16x16x32_bf16 v[20:23], v[214:217], v[172:175], v[20:23]
	v_mfma_f32_16x16x32_bf16 v[16:19], v[222:225], v[172:175], v[16:19]
	v_mfma_f32_16x16x32_bf16 v[12:15], v[214:217], v[180:183], v[12:15]
	v_mfma_f32_16x16x32_bf16 v[8:11], v[222:225], v[180:183], v[8:11]
	v_mfma_f32_16x16x32_bf16 v[4:7], v[214:217], v[206:209], v[4:7]
	v_mfma_f32_16x16x32_bf16 v[0:3], v[222:225], v[206:209], v[0:3]
	v_mfma_f32_16x16x32_bf16 v[28:31], v[218:221], v[168:171], v[28:31]
	v_mfma_f32_16x16x32_bf16 v[24:27], v[226:229], v[168:171], v[24:27]
	v_mfma_f32_16x16x32_bf16 v[20:23], v[218:221], v[176:179], v[20:23]
	v_mfma_f32_16x16x32_bf16 v[16:19], v[226:229], v[176:179], v[16:19]
	v_mfma_f32_16x16x32_bf16 v[12:15], v[218:221], v[194:197], v[12:15]
	v_mfma_f32_16x16x32_bf16 v[8:11], v[226:229], v[194:197], v[8:11]
	v_mfma_f32_16x16x32_bf16 v[4:7], v[218:221], v[210:213], v[4:7]
	v_mfma_f32_16x16x32_bf16 v[0:3], v[226:229], v[210:213], v[0:3]
	s_setprio 0
	v_add_u32_e32 v151, s12, v138
	s_barrier
	ds_read_b128 v[146:149], v151
	ds_read_b128 v[152:155], v151 offset:1024
	ds_read_b128 v[156:159], v151 offset:2048
	ds_read_b128 v[160:163], v151 offset:3072
	s_mov_b32 m0, s71
	v_lshl_add_u64 v[214:215], s[48:49], 0, v[132:133]
	ds_read_b128 v[164:167], v150 offset:32768
	ds_read_b128 v[168:171], v150 offset:33792
	ds_read_b128 v[172:175], v150 offset:34816
	ds_read_b128 v[176:179], v150 offset:35840
	ds_read_b128 v[180:183], v150 offset:36864
	ds_read_b128 v[194:197], v150 offset:37888
	ds_read_b128 v[206:209], v150 offset:38912
	ds_read_b128 v[210:213], v150 offset:39936
	global_load_lds_dwordx4 v[214:215], off
	v_lshl_add_u64 v[214:215], s[48:49], 0, v[130:131]
	s_mov_b32 m0, s72
	s_nop 0
	global_load_lds_dwordx4 v[214:215], off
	s_waitcnt lgkmcnt(8)
	s_barrier
	s_setprio 1
	s_waitcnt lgkmcnt(7)
	v_mfma_f32_16x16x32_bf16 v[124:127], v[146:149], v[164:167], v[124:127]
	v_mfma_f32_16x16x32_bf16 v[120:123], v[156:159], v[164:167], v[120:123]
	s_waitcnt lgkmcnt(5)
	v_mfma_f32_16x16x32_bf16 v[116:119], v[146:149], v[172:175], v[116:119]
	v_mfma_f32_16x16x32_bf16 v[112:115], v[156:159], v[172:175], v[112:115]
	s_waitcnt lgkmcnt(3)
	v_mfma_f32_16x16x32_bf16 v[108:111], v[146:149], v[180:183], v[108:111]
	v_mfma_f32_16x16x32_bf16 v[104:107], v[156:159], v[180:183], v[104:107]
	s_waitcnt lgkmcnt(1)
	v_mfma_f32_16x16x32_bf16 v[100:103], v[146:149], v[206:209], v[100:103]
	v_mfma_f32_16x16x32_bf16 v[96:99], v[156:159], v[206:209], v[96:99]
	v_mfma_f32_16x16x32_bf16 v[124:127], v[152:155], v[168:171], v[124:127]
	v_mfma_f32_16x16x32_bf16 v[120:123], v[160:163], v[168:171], v[120:123]
	v_mfma_f32_16x16x32_bf16 v[116:119], v[152:155], v[176:179], v[116:119]
	v_mfma_f32_16x16x32_bf16 v[112:115], v[160:163], v[176:179], v[112:115]
	v_mfma_f32_16x16x32_bf16 v[108:111], v[152:155], v[194:197], v[108:111]
	v_mfma_f32_16x16x32_bf16 v[104:107], v[160:163], v[194:197], v[104:107]
	s_waitcnt lgkmcnt(0)
	v_mfma_f32_16x16x32_bf16 v[100:103], v[152:155], v[210:213], v[100:103]
	v_mfma_f32_16x16x32_bf16 v[96:99], v[160:163], v[210:213], v[96:99]
	s_setprio 0
	s_barrier
	s_mov_b32 m0, s11
	v_add_u32_e32 v151, s10, v138
	v_lshl_add_u64 v[136:137], v[136:137], 0, s[36:37]
	ds_read_b128 v[214:217], v151
	ds_read_b128 v[218:221], v151 offset:1024
	ds_read_b128 v[222:225], v151 offset:2048
	ds_read_b128 v[226:229], v151 offset:3072
	global_load_lds_dwordx4 v[136:137], off
	v_lshl_add_u64 v[136:137], v[184:185], 0, s[36:37]
	s_mov_b32 m0, s6
	s_nop 0
	global_load_lds_dwordx4 v[136:137], off
	s_barrier
	s_setprio 1
	s_waitcnt lgkmcnt(3)
	v_mfma_f32_16x16x32_bf16 v[92:95], v[214:217], v[164:167], v[92:95]
	s_waitcnt lgkmcnt(1)
	v_mfma_f32_16x16x32_bf16 v[88:91], v[222:225], v[164:167], v[88:91]
	v_mfma_f32_16x16x32_bf16 v[84:87], v[214:217], v[172:175], v[84:87]
	v_mfma_f32_16x16x32_bf16 v[80:83], v[222:225], v[172:175], v[80:83]
	v_mfma_f32_16x16x32_bf16 v[76:79], v[214:217], v[180:183], v[76:79]
	v_mfma_f32_16x16x32_bf16 v[72:75], v[222:225], v[180:183], v[72:75]
	v_mfma_f32_16x16x32_bf16 v[68:71], v[214:217], v[206:209], v[68:71]
	v_mfma_f32_16x16x32_bf16 v[64:67], v[222:225], v[206:209], v[64:67]
	v_mfma_f32_16x16x32_bf16 v[92:95], v[218:221], v[168:171], v[92:95]
	s_waitcnt lgkmcnt(0)
	v_mfma_f32_16x16x32_bf16 v[88:91], v[226:229], v[168:171], v[88:91]
	v_mfma_f32_16x16x32_bf16 v[84:87], v[218:221], v[176:179], v[84:87]
	v_mfma_f32_16x16x32_bf16 v[80:83], v[226:229], v[176:179], v[80:83]
	v_mfma_f32_16x16x32_bf16 v[76:79], v[218:221], v[194:197], v[76:79]
	v_mfma_f32_16x16x32_bf16 v[72:75], v[226:229], v[194:197], v[72:75]
	v_mfma_f32_16x16x32_bf16 v[68:71], v[218:221], v[210:213], v[68:71]
	v_mfma_f32_16x16x32_bf16 v[64:67], v[226:229], v[210:213], v[64:67]
	s_setprio 0
	s_mov_b32 m0, s75
	v_lshl_add_u64 v[136:137], v[192:193], 0, s[36:37]
	s_barrier
	ds_read_b128 v[164:167], v150 offset:49152
	ds_read_b128 v[168:171], v150 offset:50176
	ds_read_b128 v[172:175], v150 offset:51200
	ds_read_b128 v[176:179], v150 offset:52224
	ds_read_b128 v[180:183], v150 offset:53248
	ds_read_b128 v[194:197], v150 offset:54272
	ds_read_b128 v[206:209], v150 offset:55296
	ds_read_b128 v[210:213], v150 offset:56320
	global_load_lds_dwordx4 v[136:137], off
	v_lshl_add_u64 v[136:137], v[230:231], 0, s[36:37]
	s_mov_b32 m0, s76
	s_nop 0
	global_load_lds_dwordx4 v[136:137], off
	s_barrier
	s_setprio 1
	s_waitcnt lgkmcnt(7)
	v_mfma_f32_16x16x32_bf16 v[60:63], v[146:149], v[164:167], v[60:63]
	v_mfma_f32_16x16x32_bf16 v[56:59], v[156:159], v[164:167], v[56:59]
	s_waitcnt lgkmcnt(5)
	v_mfma_f32_16x16x32_bf16 v[52:55], v[146:149], v[172:175], v[52:55]
	v_mfma_f32_16x16x32_bf16 v[48:51], v[156:159], v[172:175], v[48:51]
	s_waitcnt lgkmcnt(3)
	v_mfma_f32_16x16x32_bf16 v[44:47], v[146:149], v[180:183], v[44:47]
	v_mfma_f32_16x16x32_bf16 v[40:43], v[156:159], v[180:183], v[40:43]
	s_waitcnt lgkmcnt(1)
	v_mfma_f32_16x16x32_bf16 v[36:39], v[146:149], v[206:209], v[36:39]
	v_mfma_f32_16x16x32_bf16 v[32:35], v[156:159], v[206:209], v[32:35]
	v_mfma_f32_16x16x32_bf16 v[60:63], v[152:155], v[168:171], v[60:63]
	v_mfma_f32_16x16x32_bf16 v[56:59], v[160:163], v[168:171], v[56:59]
	v_mfma_f32_16x16x32_bf16 v[52:55], v[152:155], v[176:179], v[52:55]
	v_mfma_f32_16x16x32_bf16 v[48:51], v[160:163], v[176:179], v[48:51]
	v_mfma_f32_16x16x32_bf16 v[44:47], v[152:155], v[194:197], v[44:47]
	v_mfma_f32_16x16x32_bf16 v[40:43], v[160:163], v[194:197], v[40:43]
	s_waitcnt lgkmcnt(0)
	v_mfma_f32_16x16x32_bf16 v[36:39], v[152:155], v[210:213], v[36:39]
	v_mfma_f32_16x16x32_bf16 v[32:35], v[160:163], v[210:213], v[32:35]
	s_setprio 0
	s_barrier
	s_mov_b32 m0, s85
	v_lshl_add_u64 v[136:137], s[46:47], 0, v[140:141]
	global_load_lds_dwordx4 v[136:137], off
	v_lshl_add_u64 v[136:137], s[46:47], 0, v[128:129]
	s_mov_b32 m0, s84
	s_nop 0
	global_load_lds_dwordx4 v[136:137], off
	s_nop 0
	s_waitcnt vmcnt(6)
	s_barrier
	s_setprio 1
	v_mfma_f32_16x16x32_bf16 v[28:31], v[214:217], v[164:167], v[28:31]
	v_mfma_f32_16x16x32_bf16 v[24:27], v[222:225], v[164:167], v[24:27]
	v_mfma_f32_16x16x32_bf16 v[20:23], v[214:217], v[172:175], v[20:23]
	v_mfma_f32_16x16x32_bf16 v[16:19], v[222:225], v[172:175], v[16:19]
	v_mfma_f32_16x16x32_bf16 v[12:15], v[214:217], v[180:183], v[12:15]
	v_mfma_f32_16x16x32_bf16 v[8:11], v[222:225], v[180:183], v[8:11]
	v_mfma_f32_16x16x32_bf16 v[4:7], v[214:217], v[206:209], v[4:7]
	v_mfma_f32_16x16x32_bf16 v[0:3], v[222:225], v[206:209], v[0:3]
	v_mfma_f32_16x16x32_bf16 v[28:31], v[218:221], v[168:171], v[28:31]
	v_mfma_f32_16x16x32_bf16 v[24:27], v[226:229], v[168:171], v[24:27]
	v_mfma_f32_16x16x32_bf16 v[20:23], v[218:221], v[176:179], v[20:23]
	v_mfma_f32_16x16x32_bf16 v[16:19], v[226:229], v[176:179], v[16:19]
	v_mfma_f32_16x16x32_bf16 v[12:15], v[218:221], v[194:197], v[12:15]
	v_mfma_f32_16x16x32_bf16 v[8:11], v[226:229], v[194:197], v[8:11]
	v_mfma_f32_16x16x32_bf16 v[4:7], v[218:221], v[210:213], v[4:7]
	v_mfma_f32_16x16x32_bf16 v[0:3], v[226:229], v[210:213], v[0:3]
	s_setprio 0
	s_movk_i32 s6, 0x100
	s_andn2_b64 vcc, exec, s[44:45]
	s_mov_b64 s[46:47], -1
	s_mov_b64 s[44:45], 0
	s_barrier
	s_cbranch_vccz .LBB0_773
	s_ashr_i32 s10, s81, 2
	s_ashr_i32 s11, s10, 31
	s_lshl_b64 s[10:11], s[10:11], 21
	s_add_u32 s6, s73, s10
	s_addc_u32 s11, s74, s11
	s_lshl_b32 s10, s81, 19
	s_and_b32 s10, s10, 0x180000
	s_add_u32 s10, s6, s10
	v_lshl_or_b32 v136, s77, 8, v139
	s_addc_u32 s11, s11, 0
	v_ashrrev_i32_e32 v137, 31, v136
	v_lshl_add_u64 v[136:137], v[136:137], 1, s[10:11]
	v_pk_mul_f32 v[148:149], v[126:127], s[40:41] op_sel_hi:[1,0]
	v_pk_mul_f32 v[146:147], v[124:125], s[40:41] op_sel_hi:[1,0]
	v_pk_mul_f32 v[152:153], v[122:123], s[40:41] op_sel_hi:[1,0]
	v_pk_mul_f32 v[154:155], v[120:121], s[40:41] op_sel_hi:[1,0]
	v_lshl_add_u64 v[136:137], v[136:137], 0, v[134:135]
	v_cvt_pk_bf16_f32 v146, v146, v147
	v_cvt_pk_bf16_f32 v147, v148, v149
	v_cvt_pk_bf16_f32 v148, v154, v155
	v_cvt_pk_bf16_f32 v149, v152, v153
	global_store_dwordx4 v[136:137], v[146:149], off
	v_pk_mul_f32 v[152:153], v[90:91], s[40:41] op_sel_hi:[1,0]
	v_pk_mul_f32 v[154:155], v[88:89], s[40:41] op_sel_hi:[1,0]
	v_pk_mul_f32 v[148:149], v[94:95], s[40:41] op_sel_hi:[1,0]
	v_pk_mul_f32 v[146:147], v[92:93], s[40:41] op_sel_hi:[1,0]
	v_pk_mul_f32 v[156:157], v[80:81], s[40:41] op_sel_hi:[1,0]
	v_cvt_pk_bf16_f32 v146, v146, v147
	v_cvt_pk_bf16_f32 v147, v148, v149
	v_cvt_pk_bf16_f32 v148, v154, v155
	v_cvt_pk_bf16_f32 v149, v152, v153
	global_store_dwordx4 v[136:137], v[146:149], off offset:256
	v_pk_mul_f32 v[152:153], v[114:115], s[40:41] op_sel_hi:[1,0]
	v_pk_mul_f32 v[154:155], v[112:113], s[40:41] op_sel_hi:[1,0]
	v_pk_mul_f32 v[148:149], v[118:119], s[40:41] op_sel_hi:[1,0]
	v_pk_mul_f32 v[146:147], v[116:117], s[40:41] op_sel_hi:[1,0]
	s_mov_b32 s6, 0x40000
	v_cvt_pk_bf16_f32 v146, v146, v147
	v_cvt_pk_bf16_f32 v147, v148, v149
	v_cvt_pk_bf16_f32 v149, v152, v153
	v_add_co_u32_e32 v152, vcc, s65, v136
	v_cvt_pk_bf16_f32 v148, v154, v155
	s_nop 0
	v_addc_co_u32_e32 v153, vcc, 0, v137, vcc
	global_store_dwordx4 v[152:153], v[146:149], off
	v_pk_mul_f32 v[154:155], v[82:83], s[40:41] op_sel_hi:[1,0]
	s_nop 0
	v_pk_mul_f32 v[148:149], v[86:87], s[40:41] op_sel_hi:[1,0]
	v_pk_mul_f32 v[146:147], v[84:85], s[40:41] op_sel_hi:[1,0]
	s_nop 0
	v_cvt_pk_bf16_f32 v146, v146, v147
	v_cvt_pk_bf16_f32 v147, v148, v149
	v_cvt_pk_bf16_f32 v148, v156, v157
	v_cvt_pk_bf16_f32 v149, v154, v155
	global_store_dwordx4 v[152:153], v[146:149], off offset:256
	v_pk_mul_f32 v[152:153], v[106:107], s[40:41] op_sel_hi:[1,0]
	v_pk_mul_f32 v[154:155], v[104:105], s[40:41] op_sel_hi:[1,0]
	v_pk_mul_f32 v[148:149], v[110:111], s[40:41] op_sel_hi:[1,0]
	v_pk_mul_f32 v[146:147], v[108:109], s[40:41] op_sel_hi:[1,0]
	v_pk_mul_f32 v[156:157], v[72:73], s[40:41] op_sel_hi:[1,0]
	v_cvt_pk_bf16_f32 v146, v146, v147
	v_cvt_pk_bf16_f32 v147, v148, v149
	v_cvt_pk_bf16_f32 v149, v152, v153
	v_add_co_u32_e32 v152, vcc, s66, v136
	v_cvt_pk_bf16_f32 v148, v154, v155
	s_nop 0
	v_addc_co_u32_e32 v153, vcc, 0, v137, vcc
	global_store_dwordx4 v[152:153], v[146:149], off
	v_pk_mul_f32 v[154:155], v[74:75], s[40:41] op_sel_hi:[1,0]
	s_nop 0
	v_pk_mul_f32 v[148:149], v[78:79], s[40:41] op_sel_hi:[1,0]
	v_pk_mul_f32 v[146:147], v[76:77], s[40:41] op_sel_hi:[1,0]
	s_nop 0
	v_cvt_pk_bf16_f32 v146, v146, v147
	v_cvt_pk_bf16_f32 v147, v148, v149
	v_cvt_pk_bf16_f32 v148, v156, v157
	v_cvt_pk_bf16_f32 v149, v154, v155
	global_store_dwordx4 v[152:153], v[146:149], off offset:256
	v_pk_mul_f32 v[152:153], v[98:99], s[40:41] op_sel_hi:[1,0]
	v_pk_mul_f32 v[154:155], v[96:97], s[40:41] op_sel_hi:[1,0]
	v_pk_mul_f32 v[148:149], v[102:103], s[40:41] op_sel_hi:[1,0]
	v_pk_mul_f32 v[146:147], v[100:101], s[40:41] op_sel_hi:[1,0]
	v_pk_mul_f32 v[156:157], v[64:65], s[40:41] op_sel_hi:[1,0]
	v_cvt_pk_bf16_f32 v146, v146, v147
	v_cvt_pk_bf16_f32 v147, v148, v149
	v_cvt_pk_bf16_f32 v149, v152, v153
	v_add_co_u32_e32 v152, vcc, s64, v136
	v_cvt_pk_bf16_f32 v148, v154, v155
	s_nop 0
	v_addc_co_u32_e32 v153, vcc, 0, v137, vcc
	global_store_dwordx4 v[152:153], v[146:149], off
	v_pk_mul_f32 v[154:155], v[66:67], s[40:41] op_sel_hi:[1,0]
	s_nop 0
	v_pk_mul_f32 v[148:149], v[70:71], s[40:41] op_sel_hi:[1,0]
	v_pk_mul_f32 v[146:147], v[68:69], s[40:41] op_sel_hi:[1,0]
	s_nop 0
	v_cvt_pk_bf16_f32 v146, v146, v147
	v_cvt_pk_bf16_f32 v147, v148, v149
	v_cvt_pk_bf16_f32 v148, v156, v157
	v_cvt_pk_bf16_f32 v149, v154, v155
	global_store_dwordx4 v[152:153], v[146:149], off offset:256
	v_pk_mul_f32 v[152:153], v[58:59], s[40:41] op_sel_hi:[1,0]
	v_pk_mul_f32 v[154:155], v[56:57], s[40:41] op_sel_hi:[1,0]
	v_pk_mul_f32 v[148:149], v[62:63], s[40:41] op_sel_hi:[1,0]
	v_pk_mul_f32 v[146:147], v[60:61], s[40:41] op_sel_hi:[1,0]
	v_pk_mul_f32 v[156:157], v[24:25], s[40:41] op_sel_hi:[1,0]
	v_cvt_pk_bf16_f32 v146, v146, v147
	v_cvt_pk_bf16_f32 v147, v148, v149
	v_cvt_pk_bf16_f32 v149, v152, v153
	v_add_co_u32_e32 v152, vcc, s6, v136
	v_cvt_pk_bf16_f32 v148, v154, v155
	s_nop 0
	v_addc_co_u32_e32 v153, vcc, 0, v137, vcc
	global_store_dwordx4 v[152:153], v[146:149], off
	v_pk_mul_f32 v[154:155], v[26:27], s[40:41] op_sel_hi:[1,0]
	s_mov_b32 s6, 0x48000
	v_pk_mul_f32 v[148:149], v[30:31], s[40:41] op_sel_hi:[1,0]
	v_pk_mul_f32 v[146:147], v[28:29], s[40:41] op_sel_hi:[1,0]
	s_nop 0
	v_cvt_pk_bf16_f32 v146, v146, v147
	v_cvt_pk_bf16_f32 v147, v148, v149
	v_cvt_pk_bf16_f32 v148, v156, v157
	v_cvt_pk_bf16_f32 v149, v154, v155
	global_store_dwordx4 v[152:153], v[146:149], off offset:256
	v_pk_mul_f32 v[152:153], v[50:51], s[40:41] op_sel_hi:[1,0]
	v_pk_mul_f32 v[154:155], v[48:49], s[40:41] op_sel_hi:[1,0]
	v_pk_mul_f32 v[148:149], v[54:55], s[40:41] op_sel_hi:[1,0]
	v_pk_mul_f32 v[146:147], v[52:53], s[40:41] op_sel_hi:[1,0]
	v_pk_mul_f32 v[156:157], v[16:17], s[40:41] op_sel_hi:[1,0]
	v_cvt_pk_bf16_f32 v146, v146, v147
	v_cvt_pk_bf16_f32 v147, v148, v149
	v_cvt_pk_bf16_f32 v149, v152, v153
	v_add_co_u32_e32 v152, vcc, s6, v136
	v_cvt_pk_bf16_f32 v148, v154, v155
	s_nop 0
	v_addc_co_u32_e32 v153, vcc, 0, v137, vcc
	global_store_dwordx4 v[152:153], v[146:149], off
	v_pk_mul_f32 v[154:155], v[18:19], s[40:41] op_sel_hi:[1,0]
	s_mov_b32 s6, 0x50000
	v_pk_mul_f32 v[148:149], v[22:23], s[40:41] op_sel_hi:[1,0]
	v_pk_mul_f32 v[146:147], v[20:21], s[40:41] op_sel_hi:[1,0]
	s_nop 0
	v_cvt_pk_bf16_f32 v146, v146, v147
	v_cvt_pk_bf16_f32 v147, v148, v149
	v_cvt_pk_bf16_f32 v148, v156, v157
	v_cvt_pk_bf16_f32 v149, v154, v155
	global_store_dwordx4 v[152:153], v[146:149], off offset:256
	v_pk_mul_f32 v[152:153], v[42:43], s[40:41] op_sel_hi:[1,0]
	v_pk_mul_f32 v[154:155], v[40:41], s[40:41] op_sel_hi:[1,0]
	v_pk_mul_f32 v[148:149], v[46:47], s[40:41] op_sel_hi:[1,0]
	v_pk_mul_f32 v[146:147], v[44:45], s[40:41] op_sel_hi:[1,0]
	v_pk_mul_f32 v[156:157], v[8:9], s[40:41] op_sel_hi:[1,0]
	v_cvt_pk_bf16_f32 v146, v146, v147
	v_cvt_pk_bf16_f32 v147, v148, v149
	v_cvt_pk_bf16_f32 v149, v152, v153
	v_add_co_u32_e32 v152, vcc, s6, v136
	v_cvt_pk_bf16_f32 v148, v154, v155
	s_nop 0
	v_addc_co_u32_e32 v153, vcc, 0, v137, vcc
	global_store_dwordx4 v[152:153], v[146:149], off
	v_pk_mul_f32 v[154:155], v[10:11], s[40:41] op_sel_hi:[1,0]
	s_mov_b32 s6, 0x58000
	v_pk_mul_f32 v[148:149], v[14:15], s[40:41] op_sel_hi:[1,0]
	v_pk_mul_f32 v[146:147], v[12:13], s[40:41] op_sel_hi:[1,0]
	v_add_co_u32_e32 v136, vcc, s6, v136
	v_cvt_pk_bf16_f32 v146, v146, v147
	v_cvt_pk_bf16_f32 v147, v148, v149
	v_cvt_pk_bf16_f32 v148, v156, v157
	v_cvt_pk_bf16_f32 v149, v154, v155
	global_store_dwordx4 v[152:153], v[146:149], off offset:256
	v_pk_mul_f32 v[152:153], v[34:35], s[40:41] op_sel_hi:[1,0]
	v_pk_mul_f32 v[154:155], v[32:33], s[40:41] op_sel_hi:[1,0]
	v_pk_mul_f32 v[148:149], v[38:39], s[40:41] op_sel_hi:[1,0]
	v_pk_mul_f32 v[146:147], v[36:37], s[40:41] op_sel_hi:[1,0]
	v_addc_co_u32_e32 v137, vcc, 0, v137, vcc
	v_cvt_pk_bf16_f32 v146, v146, v147
	v_cvt_pk_bf16_f32 v147, v148, v149
	v_cvt_pk_bf16_f32 v148, v154, v155
	v_cvt_pk_bf16_f32 v149, v152, v153
	global_store_dwordx4 v[136:137], v[146:149], off
	v_pk_mul_f32 v[152:153], v[2:3], s[40:41] op_sel_hi:[1,0]
	v_pk_mul_f32 v[154:155], v[0:1], s[40:41] op_sel_hi:[1,0]
	v_pk_mul_f32 v[148:149], v[6:7], s[40:41] op_sel_hi:[1,0]
	v_pk_mul_f32 v[146:147], v[4:5], s[40:41] op_sel_hi:[1,0]
	s_and_b64 vcc, exec, s[42:43]
	v_cvt_pk_bf16_f32 v146, v146, v147
	v_cvt_pk_bf16_f32 v147, v148, v149
	v_cvt_pk_bf16_f32 v148, v154, v155
	v_cvt_pk_bf16_f32 v149, v152, v153
	global_store_dwordx4 v[136:137], v[146:149], off offset:256
	s_cbranch_vccnz .LBB0_761
	v_mov_b32_e32 v0, 0
	s_mov_b32 s77, s28
	s_mov_b32 s81, s82
	s_mov_b64 s[4:5], s[38:39]
	s_mov_b64 s[26:27], s[34:35]
	s_mov_b32 s80, s83
	v_mov_b32_e32 v1, v0
	v_mov_b32_e32 v2, v0
	v_mov_b32_e32 v3, v0
	v_mov_b32_e32 v4, v0
	v_mov_b32_e32 v5, v0
	v_mov_b32_e32 v6, v0
	v_mov_b32_e32 v7, v0
	v_mov_b32_e32 v8, v0
	v_mov_b32_e32 v9, v0
	v_mov_b32_e32 v10, v0
	v_mov_b32_e32 v11, v0
	v_mov_b32_e32 v12, v0
	v_mov_b32_e32 v13, v0
	v_mov_b32_e32 v14, v0
	v_mov_b32_e32 v15, v0
	v_mov_b32_e32 v16, v0
	v_mov_b32_e32 v17, v0
	v_mov_b32_e32 v18, v0
	v_mov_b32_e32 v19, v0
	v_mov_b32_e32 v20, v0
	v_mov_b32_e32 v21, v0
	v_mov_b32_e32 v22, v0
	v_mov_b32_e32 v23, v0
	v_mov_b32_e32 v24, v0
	v_mov_b32_e32 v25, v0
	v_mov_b32_e32 v26, v0
	v_mov_b32_e32 v27, v0
	v_mov_b32_e32 v28, v0
	v_mov_b32_e32 v29, v0
	v_mov_b32_e32 v30, v0
	v_mov_b32_e32 v31, v0
	v_mov_b32_e32 v32, v0
	v_mov_b32_e32 v33, v0
	v_mov_b32_e32 v34, v0
	v_mov_b32_e32 v35, v0
	v_mov_b32_e32 v36, v0
	v_mov_b32_e32 v37, v0
	v_mov_b32_e32 v38, v0
	v_mov_b32_e32 v39, v0
	v_mov_b32_e32 v40, v0
	v_mov_b32_e32 v41, v0
	v_mov_b32_e32 v42, v0
	v_mov_b32_e32 v43, v0
	v_mov_b32_e32 v44, v0
	v_mov_b32_e32 v45, v0
	v_mov_b32_e32 v46, v0
	v_mov_b32_e32 v47, v0
	v_mov_b32_e32 v48, v0
	v_mov_b32_e32 v49, v0
	v_mov_b32_e32 v50, v0
	v_mov_b32_e32 v51, v0
	v_mov_b32_e32 v52, v0
	v_mov_b32_e32 v53, v0
	v_mov_b32_e32 v54, v0
	v_mov_b32_e32 v55, v0
	v_mov_b32_e32 v56, v0
	v_mov_b32_e32 v57, v0
	v_mov_b32_e32 v58, v0
	v_mov_b32_e32 v59, v0
	v_mov_b32_e32 v60, v0
	v_mov_b32_e32 v61, v0
	v_mov_b32_e32 v62, v0
	v_mov_b32_e32 v63, v0
	v_mov_b32_e32 v64, v0
	v_mov_b32_e32 v65, v0
	v_mov_b32_e32 v66, v0
	v_mov_b32_e32 v67, v0
	v_mov_b32_e32 v68, v0
	v_mov_b32_e32 v69, v0
	v_mov_b32_e32 v70, v0
	v_mov_b32_e32 v71, v0
	v_mov_b32_e32 v72, v0
	v_mov_b32_e32 v73, v0
	v_mov_b32_e32 v74, v0
	v_mov_b32_e32 v75, v0
	v_mov_b32_e32 v76, v0
	v_mov_b32_e32 v77, v0
	v_mov_b32_e32 v78, v0
	v_mov_b32_e32 v79, v0
	v_mov_b32_e32 v80, v0
	v_mov_b32_e32 v81, v0
	v_mov_b32_e32 v82, v0
	v_mov_b32_e32 v83, v0
	v_mov_b32_e32 v84, v0
	v_mov_b32_e32 v85, v0
	v_mov_b32_e32 v86, v0
	v_mov_b32_e32 v87, v0
	v_mov_b32_e32 v88, v0
	v_mov_b32_e32 v89, v0
	v_mov_b32_e32 v90, v0
	v_mov_b32_e32 v91, v0
	v_mov_b32_e32 v92, v0
	v_mov_b32_e32 v93, v0
	v_mov_b32_e32 v94, v0
	v_mov_b32_e32 v95, v0
	v_mov_b32_e32 v96, v0
	v_mov_b32_e32 v97, v0
	v_mov_b32_e32 v98, v0
	v_mov_b32_e32 v99, v0
	v_mov_b32_e32 v100, v0
	v_mov_b32_e32 v101, v0
	v_mov_b32_e32 v102, v0
	v_mov_b32_e32 v103, v0
	v_mov_b32_e32 v104, v0
	v_mov_b32_e32 v105, v0
	v_mov_b32_e32 v106, v0
	v_mov_b32_e32 v107, v0
	v_mov_b32_e32 v108, v0
	v_mov_b32_e32 v109, v0
	v_mov_b32_e32 v110, v0
	v_mov_b32_e32 v111, v0
	v_mov_b32_e32 v112, v0
	v_mov_b32_e32 v113, v0
	v_mov_b32_e32 v114, v0
	v_mov_b32_e32 v115, v0
	v_mov_b32_e32 v116, v0
	v_mov_b32_e32 v117, v0
	v_mov_b32_e32 v118, v0
	v_mov_b32_e32 v119, v0
	v_mov_b32_e32 v120, v0
	v_mov_b32_e32 v121, v0
	v_mov_b32_e32 v122, v0
	v_mov_b32_e32 v123, v0
	v_mov_b32_e32 v124, v0
	v_mov_b32_e32 v125, v0
	v_mov_b32_e32 v126, v0
	v_mov_b32_e32 v127, v0
	s_branch .LBB0_761

.LBB0_797:
	s_add_u32 s6, s28, s5
	s_addc_u32 s12, s29, 0
	s_add_u32 s19, s6, 0x100
	s_addc_u32 s23, s12, 0
	s_and_b64 s[10:11], s[48:49], exec
	s_cselect_b32 s55, s39, s23
	s_cselect_b32 s54, s38, s19
	s_add_u32 s5, s26, s5
	s_addc_u32 s10, s27, 0
	s_add_u32 s5, s5, 0x100
	s_addc_u32 s19, s10, 0
	s_add_i32 s23, 0, 0x10000
	s_and_b64 s[10:11], s[48:49], exec
	s_cselect_b32 s59, s45, s19
	s_cselect_b32 s58, s44, s5
	s_add_u32 s68, s6, 0x40080
	s_addc_u32 s69, s12, 0
	s_add_i32 s88, s23, s70
	s_add_i32 m0, s72, 0xc000
	s_add_i32 s89, s72, 0xe000
	s_add_i32 s87, 0, 0x14000
	s_add_i32 s86, s88, 0x2000
	s_add_u32 s52, s58, 0x80000
	v_add_u32_e32 v158, s23, v138
	s_addc_u32 s53, s59, 0
	s_add_i32 s19, s87, s70
	ds_read_b128 v[146:149], v158
	ds_read_b128 v[150:153], v158 offset:1024
	ds_read_b128 v[154:157], v158 offset:2048
	ds_read_b128 v[158:161], v158 offset:3072
	s_add_i32 s12, s19, 0x2000
	s_add_i32 s11, 0, 0x18000
	s_add_u32 s50, s54, 0x40000
	s_addc_u32 s51, s55, 0
	s_add_i32 s10, s11, s70
	s_add_i32 s6, 0, 0x1c000
	s_add_i32 s5, s10, 0x2000
	s_add_u32 s48, s58, 0x80080
	s_addc_u32 s49, s59, 0
	s_add_i32 s85, s6, s70
	s_add_i32 s31, s85, 0x2000
	v_lshl_add_u64 v[192:193], s[68:69], 0, v[128:129]
	ds_read_b128 v[162:165], v139
	ds_read_b128 v[166:169], v139 offset:1024
	ds_read_b128 v[170:173], v139 offset:2048
	ds_read_b128 v[174:177], v139 offset:3072
	ds_read_b128 v[178:181], v139 offset:4096
	ds_read_b128 v[182:185], v139 offset:5120
	ds_read_b128 v[194:197], v139 offset:6144
	ds_read_b128 v[206:209], v139 offset:7168
	global_load_lds_dwordx4 v[192:193], off
	v_lshl_add_u64 v[192:193], s[68:69], 0, v[132:133]
	s_mov_b32 m0, s89
	s_nop 0
	global_load_lds_dwordx4 v[192:193], off
	s_waitcnt lgkmcnt(8)
	s_barrier
	s_setprio 1
	s_waitcnt lgkmcnt(7)
	v_mfma_f32_16x16x32_bf16 v[124:127], v[146:149], v[162:165], v[124:127]
	v_mfma_f32_16x16x32_bf16 v[120:123], v[154:157], v[162:165], v[120:123]
	s_waitcnt lgkmcnt(5)
	v_mfma_f32_16x16x32_bf16 v[116:119], v[146:149], v[170:173], v[116:119]
	v_mfma_f32_16x16x32_bf16 v[112:115], v[154:157], v[170:173], v[112:115]
	s_waitcnt lgkmcnt(3)
	v_mfma_f32_16x16x32_bf16 v[108:111], v[146:149], v[178:181], v[108:111]
	v_mfma_f32_16x16x32_bf16 v[104:107], v[154:157], v[178:181], v[104:107]
	s_waitcnt lgkmcnt(1)
	v_mfma_f32_16x16x32_bf16 v[100:103], v[146:149], v[194:197], v[100:103]
	v_mfma_f32_16x16x32_bf16 v[96:99], v[154:157], v[194:197], v[96:99]
	v_mfma_f32_16x16x32_bf16 v[124:127], v[150:153], v[166:169], v[124:127]
	v_mfma_f32_16x16x32_bf16 v[120:123], v[158:161], v[166:169], v[120:123]
	v_mfma_f32_16x16x32_bf16 v[116:119], v[150:153], v[174:177], v[116:119]
	v_mfma_f32_16x16x32_bf16 v[112:115], v[158:161], v[174:177], v[112:115]
	v_mfma_f32_16x16x32_bf16 v[108:111], v[150:153], v[182:185], v[108:111]
	v_mfma_f32_16x16x32_bf16 v[104:107], v[158:161], v[182:185], v[104:107]
	s_waitcnt lgkmcnt(0)
	v_mfma_f32_16x16x32_bf16 v[100:103], v[150:153], v[206:209], v[100:103]
	v_mfma_f32_16x16x32_bf16 v[96:99], v[158:161], v[206:209], v[96:99]
	s_setprio 0
	s_barrier
	v_add_u32_e32 v192, s87, v138
	s_mov_b32 m0, s88
	ds_read_b128 v[210:213], v192
	ds_read_b128 v[214:217], v192 offset:1024
	ds_read_b128 v[218:221], v192 offset:2048
	ds_read_b128 v[222:225], v192 offset:3072
	v_lshl_add_u64 v[192:193], s[58:59], 0, v[130:131]
	global_load_lds_dwordx4 v[192:193], off
	v_lshl_add_u64 v[226:227], s[58:59], 0, v[134:135]
	s_mov_b32 m0, s86
	s_nop 0
	global_load_lds_dwordx4 v[226:227], off
	s_barrier
	s_setprio 1
	s_waitcnt lgkmcnt(3)
	v_mfma_f32_16x16x32_bf16 v[92:95], v[210:213], v[162:165], v[92:95]
	s_waitcnt lgkmcnt(1)
	v_mfma_f32_16x16x32_bf16 v[88:91], v[218:221], v[162:165], v[88:91]
	v_mfma_f32_16x16x32_bf16 v[84:87], v[210:213], v[170:173], v[84:87]
	v_mfma_f32_16x16x32_bf16 v[80:83], v[218:221], v[170:173], v[80:83]
	v_mfma_f32_16x16x32_bf16 v[76:79], v[210:213], v[178:181], v[76:79]
	v_mfma_f32_16x16x32_bf16 v[72:75], v[218:221], v[178:181], v[72:75]
	v_mfma_f32_16x16x32_bf16 v[68:71], v[210:213], v[194:197], v[68:71]
	v_mfma_f32_16x16x32_bf16 v[64:67], v[218:221], v[194:197], v[64:67]
	v_mfma_f32_16x16x32_bf16 v[92:95], v[214:217], v[166:169], v[92:95]
	s_waitcnt lgkmcnt(0)
	v_mfma_f32_16x16x32_bf16 v[88:91], v[222:225], v[166:169], v[88:91]
	v_mfma_f32_16x16x32_bf16 v[84:87], v[214:217], v[174:177], v[84:87]
	v_mfma_f32_16x16x32_bf16 v[80:83], v[222:225], v[174:177], v[80:83]
	v_mfma_f32_16x16x32_bf16 v[76:79], v[214:217], v[182:185], v[76:79]
	v_mfma_f32_16x16x32_bf16 v[72:75], v[222:225], v[182:185], v[72:75]
	v_mfma_f32_16x16x32_bf16 v[68:71], v[214:217], v[206:209], v[68:71]
	v_mfma_f32_16x16x32_bf16 v[64:67], v[222:225], v[206:209], v[64:67]
	s_setprio 0
	s_mov_b32 m0, s72
	v_lshl_add_u64 v[228:229], s[54:55], 0, v[128:129]
	s_barrier
	ds_read_b128 v[162:165], v139 offset:16384
	ds_read_b128 v[166:169], v139 offset:17408
	ds_read_b128 v[170:173], v139 offset:18432
	ds_read_b128 v[174:177], v139 offset:19456
	ds_read_b128 v[178:181], v139 offset:20480
	ds_read_b128 v[182:185], v139 offset:21504
	ds_read_b128 v[194:197], v139 offset:22528
	ds_read_b128 v[206:209], v139 offset:23552
	global_load_lds_dwordx4 v[228:229], off
	v_lshl_add_u64 v[230:231], s[54:55], 0, v[132:133]
	s_mov_b32 m0, s73
	s_nop 0
	global_load_lds_dwordx4 v[230:231], off
	s_barrier
	s_setprio 1
	s_waitcnt lgkmcnt(7)
	v_mfma_f32_16x16x32_bf16 v[60:63], v[146:149], v[162:165], v[60:63]
	v_mfma_f32_16x16x32_bf16 v[56:59], v[154:157], v[162:165], v[56:59]
	s_waitcnt lgkmcnt(5)
	v_mfma_f32_16x16x32_bf16 v[52:55], v[146:149], v[170:173], v[52:55]
	v_mfma_f32_16x16x32_bf16 v[48:51], v[154:157], v[170:173], v[48:51]
	s_waitcnt lgkmcnt(3)
	v_mfma_f32_16x16x32_bf16 v[44:47], v[146:149], v[178:181], v[44:47]
	v_mfma_f32_16x16x32_bf16 v[40:43], v[154:157], v[178:181], v[40:43]
	s_waitcnt lgkmcnt(1)
	v_mfma_f32_16x16x32_bf16 v[36:39], v[146:149], v[194:197], v[36:39]
	v_mfma_f32_16x16x32_bf16 v[32:35], v[154:157], v[194:197], v[32:35]
	v_mfma_f32_16x16x32_bf16 v[60:63], v[150:153], v[166:169], v[60:63]
	v_mfma_f32_16x16x32_bf16 v[56:59], v[158:161], v[166:169], v[56:59]
	v_mfma_f32_16x16x32_bf16 v[52:55], v[150:153], v[174:177], v[52:55]
	v_mfma_f32_16x16x32_bf16 v[48:51], v[158:161], v[174:177], v[48:51]
	v_mfma_f32_16x16x32_bf16 v[44:47], v[150:153], v[182:185], v[44:47]
	v_mfma_f32_16x16x32_bf16 v[40:43], v[158:161], v[182:185], v[40:43]
	s_waitcnt lgkmcnt(0)
	v_mfma_f32_16x16x32_bf16 v[36:39], v[150:153], v[206:209], v[36:39]
	v_mfma_f32_16x16x32_bf16 v[32:35], v[158:161], v[206:209], v[32:35]
	s_setprio 0
	s_barrier
	s_mov_b32 m0, s19
	v_lshl_add_u64 v[146:147], s[52:53], 0, v[130:131]
	global_load_lds_dwordx4 v[146:147], off
	v_lshl_add_u64 v[146:147], s[52:53], 0, v[134:135]
	s_mov_b32 m0, s12
	s_nop 0
	global_load_lds_dwordx4 v[146:147], off
	s_nop 0
	s_waitcnt vmcnt(6)
	s_barrier
	s_setprio 1
	v_mfma_f32_16x16x32_bf16 v[28:31], v[210:213], v[162:165], v[28:31]
	v_mfma_f32_16x16x32_bf16 v[24:27], v[218:221], v[162:165], v[24:27]
	v_mfma_f32_16x16x32_bf16 v[20:23], v[210:213], v[170:173], v[20:23]
	v_mfma_f32_16x16x32_bf16 v[16:19], v[218:221], v[170:173], v[16:19]
	v_mfma_f32_16x16x32_bf16 v[12:15], v[210:213], v[178:181], v[12:15]
	v_mfma_f32_16x16x32_bf16 v[8:11], v[218:221], v[178:181], v[8:11]
	v_mfma_f32_16x16x32_bf16 v[4:7], v[210:213], v[194:197], v[4:7]
	v_mfma_f32_16x16x32_bf16 v[0:3], v[218:221], v[194:197], v[0:3]
	v_mfma_f32_16x16x32_bf16 v[28:31], v[214:217], v[166:169], v[28:31]
	v_mfma_f32_16x16x32_bf16 v[24:27], v[222:225], v[166:169], v[24:27]
	v_mfma_f32_16x16x32_bf16 v[20:23], v[214:217], v[174:177], v[20:23]
	v_mfma_f32_16x16x32_bf16 v[16:19], v[222:225], v[174:177], v[16:19]
	v_mfma_f32_16x16x32_bf16 v[12:15], v[214:217], v[182:185], v[12:15]
	v_mfma_f32_16x16x32_bf16 v[8:11], v[222:225], v[182:185], v[8:11]
	v_mfma_f32_16x16x32_bf16 v[4:7], v[214:217], v[206:209], v[4:7]
	v_mfma_f32_16x16x32_bf16 v[0:3], v[222:225], v[206:209], v[0:3]
	s_setprio 0
	v_add_u32_e32 v158, s11, v138
	s_barrier
	ds_read_b128 v[146:149], v158
	ds_read_b128 v[150:153], v158 offset:1024
	ds_read_b128 v[154:157], v158 offset:2048
	ds_read_b128 v[158:161], v158 offset:3072
	s_mov_b32 m0, s74
	v_lshl_add_u64 v[210:211], s[50:51], 0, v[128:129]
	ds_read_b128 v[162:165], v139 offset:32768
	ds_read_b128 v[166:169], v139 offset:33792
	ds_read_b128 v[170:173], v139 offset:34816
	ds_read_b128 v[174:177], v139 offset:35840
	ds_read_b128 v[178:181], v139 offset:36864
	ds_read_b128 v[182:185], v139 offset:37888
	ds_read_b128 v[194:197], v139 offset:38912
	ds_read_b128 v[206:209], v139 offset:39936
	global_load_lds_dwordx4 v[210:211], off
	v_lshl_add_u64 v[210:211], s[50:51], 0, v[132:133]
	s_mov_b32 m0, s75
	s_nop 0
	global_load_lds_dwordx4 v[210:211], off
	s_waitcnt lgkmcnt(8)
	s_barrier
	s_setprio 1
	s_waitcnt lgkmcnt(7)
	v_mfma_f32_16x16x32_bf16 v[124:127], v[146:149], v[162:165], v[124:127]
	v_mfma_f32_16x16x32_bf16 v[120:123], v[154:157], v[162:165], v[120:123]
	s_waitcnt lgkmcnt(5)
	v_mfma_f32_16x16x32_bf16 v[116:119], v[146:149], v[170:173], v[116:119]
	v_mfma_f32_16x16x32_bf16 v[112:115], v[154:157], v[170:173], v[112:115]
	s_waitcnt lgkmcnt(3)
	v_mfma_f32_16x16x32_bf16 v[108:111], v[146:149], v[178:181], v[108:111]
	v_mfma_f32_16x16x32_bf16 v[104:107], v[154:157], v[178:181], v[104:107]
	s_waitcnt lgkmcnt(1)
	v_mfma_f32_16x16x32_bf16 v[100:103], v[146:149], v[194:197], v[100:103]
	v_mfma_f32_16x16x32_bf16 v[96:99], v[154:157], v[194:197], v[96:99]
	v_mfma_f32_16x16x32_bf16 v[124:127], v[150:153], v[166:169], v[124:127]
	v_mfma_f32_16x16x32_bf16 v[120:123], v[158:161], v[166:169], v[120:123]
	v_mfma_f32_16x16x32_bf16 v[116:119], v[150:153], v[174:177], v[116:119]
	v_mfma_f32_16x16x32_bf16 v[112:115], v[158:161], v[174:177], v[112:115]
	v_mfma_f32_16x16x32_bf16 v[108:111], v[150:153], v[182:185], v[108:111]
	v_mfma_f32_16x16x32_bf16 v[104:107], v[158:161], v[182:185], v[104:107]
	s_waitcnt lgkmcnt(0)
	v_mfma_f32_16x16x32_bf16 v[100:103], v[150:153], v[206:209], v[100:103]
	v_mfma_f32_16x16x32_bf16 v[96:99], v[158:161], v[206:209], v[96:99]
	s_setprio 0
	s_barrier
	s_mov_b32 m0, s10
	v_add_u32_e32 v222, s6, v138
	v_lshl_add_u64 v[192:193], v[192:193], 0, s[36:37]
	ds_read_b128 v[210:213], v222
	ds_read_b128 v[214:217], v222 offset:1024
	ds_read_b128 v[218:221], v222 offset:2048
	ds_read_b128 v[222:225], v222 offset:3072
	global_load_lds_dwordx4 v[192:193], off
	v_lshl_add_u64 v[192:193], v[226:227], 0, s[36:37]
	s_mov_b32 m0, s5
	s_nop 0
	global_load_lds_dwordx4 v[192:193], off
	s_barrier
	s_setprio 1
	s_waitcnt lgkmcnt(3)
	v_mfma_f32_16x16x32_bf16 v[92:95], v[210:213], v[162:165], v[92:95]
	s_waitcnt lgkmcnt(1)
	v_mfma_f32_16x16x32_bf16 v[88:91], v[218:221], v[162:165], v[88:91]
	v_mfma_f32_16x16x32_bf16 v[84:87], v[210:213], v[170:173], v[84:87]
	v_mfma_f32_16x16x32_bf16 v[80:83], v[218:221], v[170:173], v[80:83]
	v_mfma_f32_16x16x32_bf16 v[76:79], v[210:213], v[178:181], v[76:79]
	v_mfma_f32_16x16x32_bf16 v[72:75], v[218:221], v[178:181], v[72:75]
	v_mfma_f32_16x16x32_bf16 v[68:71], v[210:213], v[194:197], v[68:71]
	v_mfma_f32_16x16x32_bf16 v[64:67], v[218:221], v[194:197], v[64:67]
	v_mfma_f32_16x16x32_bf16 v[92:95], v[214:217], v[166:169], v[92:95]
	s_waitcnt lgkmcnt(0)
	v_mfma_f32_16x16x32_bf16 v[88:91], v[222:225], v[166:169], v[88:91]
	v_mfma_f32_16x16x32_bf16 v[84:87], v[214:217], v[174:177], v[84:87]
	v_mfma_f32_16x16x32_bf16 v[80:83], v[222:225], v[174:177], v[80:83]
	v_mfma_f32_16x16x32_bf16 v[76:79], v[214:217], v[182:185], v[76:79]
	v_mfma_f32_16x16x32_bf16 v[72:75], v[222:225], v[182:185], v[72:75]
	v_mfma_f32_16x16x32_bf16 v[68:71], v[214:217], v[206:209], v[68:71]
	v_mfma_f32_16x16x32_bf16 v[64:67], v[222:225], v[206:209], v[64:67]
	s_setprio 0
	s_mov_b32 m0, s80
	v_lshl_add_u64 v[192:193], v[228:229], 0, s[36:37]
	s_barrier
	ds_read_b128 v[162:165], v139 offset:49152
	ds_read_b128 v[166:169], v139 offset:50176
	ds_read_b128 v[170:173], v139 offset:51200
	ds_read_b128 v[174:177], v139 offset:52224
	ds_read_b128 v[178:181], v139 offset:53248
	ds_read_b128 v[182:185], v139 offset:54272
	ds_read_b128 v[194:197], v139 offset:55296
	ds_read_b128 v[206:209], v139 offset:56320
	global_load_lds_dwordx4 v[192:193], off
	v_lshl_add_u64 v[192:193], v[230:231], 0, s[36:37]
	s_mov_b32 m0, s81
	s_nop 0
	global_load_lds_dwordx4 v[192:193], off
	s_barrier
	s_setprio 1
	s_waitcnt lgkmcnt(7)
	v_mfma_f32_16x16x32_bf16 v[60:63], v[146:149], v[162:165], v[60:63]
	v_mfma_f32_16x16x32_bf16 v[56:59], v[154:157], v[162:165], v[56:59]
	s_waitcnt lgkmcnt(5)
	v_mfma_f32_16x16x32_bf16 v[52:55], v[146:149], v[170:173], v[52:55]
	v_mfma_f32_16x16x32_bf16 v[48:51], v[154:157], v[170:173], v[48:51]
	s_waitcnt lgkmcnt(3)
	v_mfma_f32_16x16x32_bf16 v[44:47], v[146:149], v[178:181], v[44:47]
	v_mfma_f32_16x16x32_bf16 v[40:43], v[154:157], v[178:181], v[40:43]
	s_waitcnt lgkmcnt(1)
	v_mfma_f32_16x16x32_bf16 v[36:39], v[146:149], v[194:197], v[36:39]
	v_mfma_f32_16x16x32_bf16 v[32:35], v[154:157], v[194:197], v[32:35]
	v_mfma_f32_16x16x32_bf16 v[60:63], v[150:153], v[166:169], v[60:63]
	v_mfma_f32_16x16x32_bf16 v[56:59], v[158:161], v[166:169], v[56:59]
	v_mfma_f32_16x16x32_bf16 v[52:55], v[150:153], v[174:177], v[52:55]
	v_mfma_f32_16x16x32_bf16 v[48:51], v[158:161], v[174:177], v[48:51]
	v_mfma_f32_16x16x32_bf16 v[44:47], v[150:153], v[182:185], v[44:47]
	v_mfma_f32_16x16x32_bf16 v[40:43], v[158:161], v[182:185], v[40:43]
	s_waitcnt lgkmcnt(0)
	v_mfma_f32_16x16x32_bf16 v[36:39], v[150:153], v[206:209], v[36:39]
	v_mfma_f32_16x16x32_bf16 v[32:35], v[158:161], v[206:209], v[32:35]
	s_setprio 0
	s_barrier
	s_mov_b32 m0, s85
	v_lshl_add_u64 v[146:147], s[48:49], 0, v[130:131]
	global_load_lds_dwordx4 v[146:147], off
	v_lshl_add_u64 v[146:147], s[48:49], 0, v[134:135]
	s_mov_b32 m0, s31
	s_nop 0
	global_load_lds_dwordx4 v[146:147], off
	s_nop 0
	s_waitcnt vmcnt(6)
	s_barrier
	s_setprio 1
	v_mfma_f32_16x16x32_bf16 v[28:31], v[210:213], v[162:165], v[28:31]
	v_mfma_f32_16x16x32_bf16 v[24:27], v[218:221], v[162:165], v[24:27]
	v_mfma_f32_16x16x32_bf16 v[20:23], v[210:213], v[170:173], v[20:23]
	v_mfma_f32_16x16x32_bf16 v[16:19], v[218:221], v[170:173], v[16:19]
	v_mfma_f32_16x16x32_bf16 v[12:15], v[210:213], v[178:181], v[12:15]
	v_mfma_f32_16x16x32_bf16 v[8:11], v[218:221], v[178:181], v[8:11]
	v_mfma_f32_16x16x32_bf16 v[4:7], v[210:213], v[194:197], v[4:7]
	v_mfma_f32_16x16x32_bf16 v[0:3], v[218:221], v[194:197], v[0:3]
	v_mfma_f32_16x16x32_bf16 v[28:31], v[214:217], v[166:169], v[28:31]
	v_mfma_f32_16x16x32_bf16 v[24:27], v[222:225], v[166:169], v[24:27]
	v_mfma_f32_16x16x32_bf16 v[20:23], v[214:217], v[174:177], v[20:23]
	v_mfma_f32_16x16x32_bf16 v[16:19], v[222:225], v[174:177], v[16:19]
	v_mfma_f32_16x16x32_bf16 v[12:15], v[214:217], v[182:185], v[12:15]
	v_mfma_f32_16x16x32_bf16 v[8:11], v[222:225], v[182:185], v[8:11]
	v_mfma_f32_16x16x32_bf16 v[4:7], v[214:217], v[206:209], v[4:7]
	v_mfma_f32_16x16x32_bf16 v[0:3], v[222:225], v[206:209], v[0:3]
	s_setprio 0
	s_movk_i32 s5, 0x100
	s_andn2_b64 vcc, exec, s[46:47]
	s_mov_b64 s[48:49], -1
	s_mov_b64 s[46:47], 0
	s_barrier
	s_cbranch_vccz .LBB0_797
	s_ashr_i32 s10, s71, 2
	s_ashr_i32 s11, s10, 31
	s_lshl_b64 s[10:11], s[10:11], 21
	s_add_u32 s5, s76, s10
	s_addc_u32 s6, s77, s11
	s_lshl_b32 s10, s71, 9
	s_and_b32 s10, s10, 0x600
	s_add_u32 s10, s5, s10
	s_addc_u32 s11, s6, 0
	s_ashr_i32 s5, s4, 31
	v_lshl_add_u64 v[146:147], s[10:11], 0, v[140:141]
	s_lshl_b64 s[10:11], s[4:5], 19
	v_lshl_add_u64 v[146:147], v[146:147], 0, s[10:11]
	v_lshl_add_u64 v[150:151], v[146:147], 0, v[136:137]
	v_cvt_pk_bf16_f32 v146, v124, v125
	v_cvt_pk_bf16_f32 v147, v126, v127
	v_cvt_pk_bf16_f32 v148, v120, v121
	v_cvt_pk_bf16_f32 v149, v122, v123
	global_store_dwordx4 v[150:151], v[146:149], off
	v_add_co_u32_e32 v152, vcc, s65, v150
	s_nop 0
	v_cvt_pk_bf16_f32 v146, v92, v93
	v_cvt_pk_bf16_f32 v147, v94, v95
	v_cvt_pk_bf16_f32 v148, v88, v89
	v_cvt_pk_bf16_f32 v149, v90, v91
	global_store_dwordx4 v[150:151], v[146:149], off offset:256
	v_addc_co_u32_e32 v153, vcc, 0, v151, vcc
	s_nop 0
	v_cvt_pk_bf16_f32 v146, v116, v117
	v_cvt_pk_bf16_f32 v147, v118, v119
	v_cvt_pk_bf16_f32 v148, v112, v113
	v_cvt_pk_bf16_f32 v149, v114, v115
	global_store_dwordx4 v[152:153], v[146:149], off
	s_mov_b32 s5, 0x40000
	s_nop 0
	v_cvt_pk_bf16_f32 v146, v84, v85
	v_cvt_pk_bf16_f32 v147, v86, v87
	v_cvt_pk_bf16_f32 v148, v80, v81
	v_cvt_pk_bf16_f32 v149, v82, v83
	global_store_dwordx4 v[152:153], v[146:149], off offset:256
	v_add_co_u32_e32 v152, vcc, s66, v150
	s_nop 0
	v_cvt_pk_bf16_f32 v146, v108, v109
	v_cvt_pk_bf16_f32 v147, v110, v111
	v_cvt_pk_bf16_f32 v148, v104, v105
	v_cvt_pk_bf16_f32 v149, v106, v107
	v_addc_co_u32_e32 v153, vcc, 0, v151, vcc
	global_store_dwordx4 v[152:153], v[146:149], off
	s_nop 1
	v_cvt_pk_bf16_f32 v146, v76, v77
	v_cvt_pk_bf16_f32 v147, v78, v79
	v_cvt_pk_bf16_f32 v148, v72, v73
	v_cvt_pk_bf16_f32 v149, v74, v75
	global_store_dwordx4 v[152:153], v[146:149], off offset:256
	v_add_co_u32_e32 v152, vcc, s64, v150
	s_nop 0
	v_cvt_pk_bf16_f32 v146, v100, v101
	v_cvt_pk_bf16_f32 v147, v102, v103
	v_cvt_pk_bf16_f32 v148, v96, v97
	v_cvt_pk_bf16_f32 v149, v98, v99
	v_addc_co_u32_e32 v153, vcc, 0, v151, vcc
	global_store_dwordx4 v[152:153], v[146:149], off
	s_nop 1
	v_cvt_pk_bf16_f32 v146, v68, v69
	v_cvt_pk_bf16_f32 v147, v70, v71
	v_cvt_pk_bf16_f32 v148, v64, v65
	v_cvt_pk_bf16_f32 v149, v66, v67
	global_store_dwordx4 v[152:153], v[146:149], off offset:256
	v_add_co_u32_e32 v152, vcc, s5, v150
	s_nop 0
	v_cvt_pk_bf16_f32 v146, v60, v61
	v_cvt_pk_bf16_f32 v147, v62, v63
	v_cvt_pk_bf16_f32 v148, v56, v57
	v_cvt_pk_bf16_f32 v149, v58, v59
	v_addc_co_u32_e32 v153, vcc, 0, v151, vcc
	global_store_dwordx4 v[152:153], v[146:149], off
	s_mov_b32 s5, 0x48000
	s_nop 0
	v_cvt_pk_bf16_f32 v146, v28, v29
	v_cvt_pk_bf16_f32 v147, v30, v31
	v_cvt_pk_bf16_f32 v148, v24, v25
	v_cvt_pk_bf16_f32 v149, v26, v27
	global_store_dwordx4 v[152:153], v[146:149], off offset:256
	v_add_co_u32_e32 v152, vcc, s5, v150
	s_nop 0
	v_cvt_pk_bf16_f32 v146, v52, v53
	v_cvt_pk_bf16_f32 v147, v54, v55
	v_cvt_pk_bf16_f32 v148, v48, v49
	v_cvt_pk_bf16_f32 v149, v50, v51
	v_addc_co_u32_e32 v153, vcc, 0, v151, vcc
	global_store_dwordx4 v[152:153], v[146:149], off
	s_mov_b32 s5, 0x50000
	s_nop 0
	v_cvt_pk_bf16_f32 v146, v20, v21
	v_cvt_pk_bf16_f32 v147, v22, v23
	v_cvt_pk_bf16_f32 v148, v16, v17
	v_cvt_pk_bf16_f32 v149, v18, v19
	global_store_dwordx4 v[152:153], v[146:149], off offset:256
	v_add_co_u32_e32 v152, vcc, s5, v150
	s_nop 0
	v_cvt_pk_bf16_f32 v146, v44, v45
	v_cvt_pk_bf16_f32 v147, v46, v47
	v_cvt_pk_bf16_f32 v148, v40, v41
	v_cvt_pk_bf16_f32 v149, v42, v43
	v_addc_co_u32_e32 v153, vcc, 0, v151, vcc
	s_mov_b32 s5, 0x58000
	global_store_dwordx4 v[152:153], v[146:149], off
	v_add_co_u32_e32 v150, vcc, s5, v150
	s_nop 0
	v_cvt_pk_bf16_f32 v146, v12, v13
	v_cvt_pk_bf16_f32 v147, v14, v15
	v_cvt_pk_bf16_f32 v148, v8, v9
	v_cvt_pk_bf16_f32 v149, v10, v11
	global_store_dwordx4 v[152:153], v[146:149], off offset:256
	v_addc_co_u32_e32 v151, vcc, 0, v151, vcc
	s_nop 0
	v_cvt_pk_bf16_f32 v146, v36, v37
	v_cvt_pk_bf16_f32 v147, v38, v39
	v_cvt_pk_bf16_f32 v148, v32, v33
	v_cvt_pk_bf16_f32 v149, v34, v35
	global_store_dwordx4 v[150:151], v[146:149], off
	s_and_b64 vcc, exec, s[42:43]
	s_nop 0
	v_cvt_pk_bf16_f32 v146, v4, v5
	v_cvt_pk_bf16_f32 v147, v6, v7
	v_cvt_pk_bf16_f32 v148, v0, v1
	v_cvt_pk_bf16_f32 v149, v2, v3
	global_store_dwordx4 v[150:151], v[146:149], off offset:256
	s_cbranch_vccnz .LBB0_785
	v_mov_b32_e32 v0, 0
	s_mov_b32 s4, s30
	s_mov_b32 s71, s83
	s_mov_b64 s[26:27], s[44:45]
	s_mov_b64 s[28:29], s[38:39]
	s_mov_b32 s82, s84
	v_mov_b32_e32 v1, v0
	v_mov_b32_e32 v2, v0
	v_mov_b32_e32 v3, v0
	v_mov_b32_e32 v4, v0
	v_mov_b32_e32 v5, v0
	v_mov_b32_e32 v6, v0
	v_mov_b32_e32 v7, v0
	v_mov_b32_e32 v8, v0
	v_mov_b32_e32 v9, v0
	v_mov_b32_e32 v10, v0
	v_mov_b32_e32 v11, v0
	v_mov_b32_e32 v12, v0
	v_mov_b32_e32 v13, v0
	v_mov_b32_e32 v14, v0
	v_mov_b32_e32 v15, v0
	v_mov_b32_e32 v16, v0
	v_mov_b32_e32 v17, v0
	v_mov_b32_e32 v18, v0
	v_mov_b32_e32 v19, v0
	v_mov_b32_e32 v20, v0
	v_mov_b32_e32 v21, v0
	v_mov_b32_e32 v22, v0
	v_mov_b32_e32 v23, v0
	v_mov_b32_e32 v24, v0
	v_mov_b32_e32 v25, v0
	v_mov_b32_e32 v26, v0
	v_mov_b32_e32 v27, v0
	v_mov_b32_e32 v28, v0
	v_mov_b32_e32 v29, v0
	v_mov_b32_e32 v30, v0
	v_mov_b32_e32 v31, v0
	v_mov_b32_e32 v32, v0
	v_mov_b32_e32 v33, v0
	v_mov_b32_e32 v34, v0
	v_mov_b32_e32 v35, v0
	v_mov_b32_e32 v36, v0
	v_mov_b32_e32 v37, v0
	v_mov_b32_e32 v38, v0
	v_mov_b32_e32 v39, v0
	v_mov_b32_e32 v40, v0
	v_mov_b32_e32 v41, v0
	v_mov_b32_e32 v42, v0
	v_mov_b32_e32 v43, v0
	v_mov_b32_e32 v44, v0
	v_mov_b32_e32 v45, v0
	v_mov_b32_e32 v46, v0
	v_mov_b32_e32 v47, v0
	v_mov_b32_e32 v48, v0
	v_mov_b32_e32 v49, v0
	v_mov_b32_e32 v50, v0
	v_mov_b32_e32 v51, v0
	v_mov_b32_e32 v52, v0
	v_mov_b32_e32 v53, v0
	v_mov_b32_e32 v54, v0
	v_mov_b32_e32 v55, v0
	v_mov_b32_e32 v56, v0
	v_mov_b32_e32 v57, v0
	v_mov_b32_e32 v58, v0
	v_mov_b32_e32 v59, v0
	v_mov_b32_e32 v60, v0
	v_mov_b32_e32 v61, v0
	v_mov_b32_e32 v62, v0
	v_mov_b32_e32 v63, v0
	v_mov_b32_e32 v64, v0
	v_mov_b32_e32 v65, v0
	v_mov_b32_e32 v66, v0
	v_mov_b32_e32 v67, v0
	v_mov_b32_e32 v68, v0
	v_mov_b32_e32 v69, v0
	v_mov_b32_e32 v70, v0
	v_mov_b32_e32 v71, v0
	v_mov_b32_e32 v72, v0
	v_mov_b32_e32 v73, v0
	v_mov_b32_e32 v74, v0
	v_mov_b32_e32 v75, v0
	v_mov_b32_e32 v76, v0
	v_mov_b32_e32 v77, v0
	v_mov_b32_e32 v78, v0
	v_mov_b32_e32 v79, v0
	v_mov_b32_e32 v80, v0
	v_mov_b32_e32 v81, v0
	v_mov_b32_e32 v82, v0
	v_mov_b32_e32 v83, v0
	v_mov_b32_e32 v84, v0
	v_mov_b32_e32 v85, v0
	v_mov_b32_e32 v86, v0
	v_mov_b32_e32 v87, v0
	v_mov_b32_e32 v88, v0
	v_mov_b32_e32 v89, v0
	v_mov_b32_e32 v90, v0
	v_mov_b32_e32 v91, v0
	v_mov_b32_e32 v92, v0
	v_mov_b32_e32 v93, v0
	v_mov_b32_e32 v94, v0
	v_mov_b32_e32 v95, v0
	v_mov_b32_e32 v96, v0
	v_mov_b32_e32 v97, v0
	v_mov_b32_e32 v98, v0
	v_mov_b32_e32 v99, v0
	v_mov_b32_e32 v100, v0
	v_mov_b32_e32 v101, v0
	v_mov_b32_e32 v102, v0
	v_mov_b32_e32 v103, v0
	v_mov_b32_e32 v104, v0
	v_mov_b32_e32 v105, v0
	v_mov_b32_e32 v106, v0
	v_mov_b32_e32 v107, v0
	v_mov_b32_e32 v108, v0
	v_mov_b32_e32 v109, v0
	v_mov_b32_e32 v110, v0
	v_mov_b32_e32 v111, v0
	v_mov_b32_e32 v112, v0
	v_mov_b32_e32 v113, v0
	v_mov_b32_e32 v114, v0
	v_mov_b32_e32 v115, v0
	v_mov_b32_e32 v116, v0
	v_mov_b32_e32 v117, v0
	v_mov_b32_e32 v118, v0
	v_mov_b32_e32 v119, v0
	v_mov_b32_e32 v120, v0
	v_mov_b32_e32 v121, v0
	v_mov_b32_e32 v122, v0
	v_mov_b32_e32 v123, v0
	v_mov_b32_e32 v124, v0
	v_mov_b32_e32 v125, v0
	v_mov_b32_e32 v126, v0
	v_mov_b32_e32 v127, v0
	s_branch .LBB0_785
